# speedup vs baseline: 1.0073x; 1.0002x over previous
;     ...
;       const int tid3 = opaque_tid(wave);
;       const int wr3 = tid3 >> 8, wc3 = (tid3 >> 6) & 3, fr3 = tid3 & 15, fq3 = (tid3 & 63) >> 4;
;       const int ebase3 = (brow + wr3 * 64 + fr3) * DM + pn * BM + wc3 * 32 + fq3 * 4;
;       const int vo4b = ebase3 * 4, vo2 = ebase3 * 2, vo1 = ebase3;
;       (void)vo4b; (void)vo2; (void)vo1;
;       if constexpr (OUTF) {
;         _Pragma("unroll") for (int bj = 0; bj < 2; ++bj) _Pragma("unroll") for (int n = 0; n < 2; ++n) {
;           const int col = pn * BM + bj * HALF + wc3 * 32 + n * 16 + fq3 * 4;
;           const float4 gm = *reinterpret_cast<const float4*>(g.gam + col), bt = *reinterpret_cast<const float4*>(g.bet + col);
;           _Pragma("unroll") for (int ai = 0; ai < 2; ++ai) _Pragma("unroll") for (int m = 0; m < 4; ++m) {
;             const int rl = ai * HALF + wr3 * 64 + m * 16 + fr3;
;             const float2 ms = *reinterpret_cast<const float2*>(mr + rl * 2);
;             f32x4 y = acc[ai][bj][m][n];
;             u32x4 o;
;             o[0] = __float_as_uint((y[0] - ms.x) * ms.y * gm.x + bt.x); o[1] = __float_as_uint((y[1] - ms.x) * ms.y * gm.y + bt.y);
;             o[2] = __float_as_uint((y[2] - ms.x) * ms.y * gm.z + bt.z); o[3] = __float_as_uint((y[3] - ms.x) * ms.y * gm.w + bt.w);
;             __builtin_amdgcn_raw_buffer_store_b128(o, rsO, vo4b + ((ai * HALF + m * 16) * DM + bj * HALF + n * 16) * 4, 0, 0);
;           }
;         }
;       } else {
;         constexpr int PIECE = 1024 + 16, LOBASE = 64 * PIECE;
;         const int lane3 = tid3 & 63;
;         const int hvo = (lane3 >> 5) * (DM * 2) + (lane3 & 31) * 16;
;         const int lvo = (lane3 >> 4) * DM + (lane3 & 15) * 16;
;         _Pragma("unroll") for (int ai = 0; ai < 2; ++ai) {
;           _Pragma("unroll") for (int bj = 0; bj < 2; ++bj) _Pragma("unroll") for (int n = 0; n < 2; ++n) {
;             const int cc = bj * HALF + wc3 * 32 + n * 16 + fq3 * 4;
;             const float4 gm = *reinterpret_cast<const float4*>(g.gam + pn * BM + cc), bt = *reinterpret_cast<const float4*>(g.bet + pn * BM + cc);
;             _Pragma("unroll") for (int m = 0; m < 4; ++m) {
;               const int rr = wr3 * 64 + m * 16 + fr3;
;               const float2 ms = *reinterpret_cast<const float2*>(mr + (ai * HALF + rr) * 2);
;               f32x4 y = acc[ai][bj][m][n];
.LBB0_320:
	s_or_b64 exec, exec, s[6:7]
	s_waitcnt lgkmcnt(0)
	s_barrier
	v_mbcnt_lo_u32_b32 v0, -1, 0
	v_mbcnt_hi_u32_b32 v0, -1, v0
	s_movk_i32 s4, 0x60
	v_add_u32_e32 v1, s34, v0
	v_ashrrev_i32_e32 v5, 2, v1
	v_lshrrev_b32_e32 v6, 1, v1
	v_lshlrev_b32_e32 v1, 4, v1
	v_bfe_u32 v4, v0, 4, 2
	v_lshlrev_b32_e32 v12, 7, v0
	v_and_b32_e32 v13, 0x1f0, v1
	v_lshlrev_b32_e32 v7, 2, v4
	v_and_or_b32 v148, v12, s29, v13
	s_ashr_i32 s29, s28, 31
	v_and_or_b32 v12, v6, s4, v7
	s_lshl_b64 s[4:5], s[28:29], 2
	s_add_u32 s6, s86, s4
	v_and_b32_e32 v2, 15, v0
	v_and_b32_e32 v3, 63, v0
	v_and_b32_e32 v1, 0xf0, v1
	v_lshlrev_b32_e32 v13, 9, v0
	v_lshlrev_b32_e32 v0, 8, v0
	s_addc_u32 s7, s87, s5
	v_lshlrev_b32_e32 v150, 2, v12
	v_lshl_or_b32 v146, v4, 11, v1
	v_and_or_b32 v155, v5, s64, v2
	v_and_b32_e32 v14, 0x300, v0
	v_lshlrev_b32_e32 v151, 4, v3
	global_load_dwordx4 v[220:223], v150, s[6:7]
	global_load_dwordx4 v[224:227], v150, s[6:7] offset:64
	global_load_dwordx4 v[228:231], v150, s[6:7] offset:512
	global_load_dwordx4 v[232:235], v150, s[6:7] offset:576
	v_readlane_b32 s64, v255, 0
	v_readlane_b32 s65, v255, 1
	s_add_u32 s4, s64, s4
	s_addc_u32 s5, s65, s5
	global_load_dwordx4 v[236:239], v150, s[4:5]
	global_load_dwordx4 v[240:243], v150, s[4:5] offset:64
	global_load_dwordx4 v[244:247], v150, s[4:5] offset:512
	global_load_dwordx4 v[248:251], v150, s[4:5] offset:576
	s_movk_i32 s22, 0x200
	v_lshl_add_u32 v149, v155, 3, v219
	v_add_u32_e32 v147, s56, v151
	s_andn2_b64 vcc, exec, s[14:15]
	s_movk_i32 s46, 0x100
	v_readlane_b32 s66, v255, 2
	v_readlane_b32 s67, v255, 3
	v_readlane_b32 s68, v255, 4
	v_readlane_b32 s69, v255, 5
	v_readlane_b32 s70, v255, 6
	v_readlane_b32 s71, v255, 7
	v_readlane_b32 s72, v255, 8
	v_readlane_b32 s73, v255, 9
	v_readlane_b32 s74, v255, 10
	v_readlane_b32 s75, v255, 11
	v_readlane_b32 s76, v255, 12
	v_readlane_b32 s77, v255, 13
	v_readlane_b32 s78, v255, 14
	v_readlane_b32 s79, v255, 15
	s_waitcnt vmcnt(0)
	v_mov_b32_e32 v0, v220
	v_mov_b32_e32 v1, v221
	v_mov_b32_e32 v2, v222
	v_mov_b32_e32 v3, v223
	v_mov_b32_e32 v4, v236
	v_mov_b32_e32 v5, v237
	v_mov_b32_e32 v6, v238
	v_mov_b32_e32 v7, v239
	v_mov_b32_e32 v22, v1
	v_lshlrev_b32_e32 v1, 1, v12
	v_and_or_b32 v154, v13, s22, v1
	s_mov_b32 s22, 0x10400
	v_mov_b32_e32 v23, v2
	v_or3_b32 v2, v14, v12, s22
	ds_read_b64 v[12:13], v149
	v_mov_b32_e32 v144, v5
	v_mov_b32_e32 v145, v6
	v_mov_b32_e32 v1, v3
	v_mov_b32_e32 v5, v7
	s_waitcnt lgkmcnt(0)
	v_mov_b32_e32 v202, v12
	v_mov_b32_e32 v203, v13
	v_pk_add_f32 v[14:15], v[132:133], v[12:13] op_sel_hi:[1,0] neg_lo:[0,1] neg_hi:[0,1]
	v_pk_add_f32 v[18:19], v[130:131], v[12:13] op_sel_hi:[1,0] neg_lo:[0,1] neg_hi:[0,1]
	v_pk_mul_f32 v[14:15], v[12:13], v[14:15] op_sel:[1,0]
	v_pk_mul_f32 v[12:13], v[12:13], v[18:19] op_sel:[1,0]
	v_pk_fma_f32 v[14:15], v[22:23], v[14:15], v[144:145]
	v_pk_fma_f32 v[6:7], v[0:1], v[12:13], v[4:5]
	v_and_b32_sdwa v12, v14, v216 dst_sel:DWORD dst_unused:UNUSED_PAD src0_sel:WORD_1 src1_sel:DWORD
	v_add3_u32 v12, v14, v12, s84
	v_and_b32_e32 v18, 0xffff0000, v12
	v_and_b32_sdwa v12, v7, v216 dst_sel:DWORD dst_unused:UNUSED_PAD src0_sel:WORD_1 src1_sel:DWORD
	v_and_b32_sdwa v3, v15, v216 dst_sel:DWORD dst_unused:UNUSED_PAD src0_sel:WORD_1 src1_sel:DWORD
	v_and_b32_sdwa v13, v6, v216 dst_sel:DWORD dst_unused:UNUSED_PAD src0_sel:WORD_1 src1_sel:DWORD
	v_add3_u32 v12, v7, v12, s84
	v_lshrrev_b32_e32 v131, 1, v155
	v_add3_u32 v3, v15, v3, s84
	v_add3_u32 v19, v6, v13, s84
	v_and_b32_e32 v130, 0xffff0000, v12
	v_mul_lo_u32 v152, v131, s63
	v_or_b32_sdwa v13, v130, v3 dst_sel:DWORD dst_unused:UNUSED_PAD src0_sel:DWORD src1_sel:WORD_1
	v_or_b32_sdwa v12, v19, v18 dst_sel:DWORD dst_unused:UNUSED_PAD src0_sel:WORD_1 src1_sel:DWORD
	v_add_u32_e32 v132, v154, v152
	ds_write_b64 v132, v[12:13]
	v_and_b32_e32 v12, 0xffff0000, v19
	v_sub_u32_e32 v6, v6, v12
	v_sub_u32_e32 v12, v14, v18
	v_and_b32_e32 v3, 0xffff0000, v3
	v_add_u32_e32 v12, 0x80, v12
	v_sub_u32_e32 v3, v15, v3
	v_sub_u32_e32 v7, v7, v130
	v_add_u32_e32 v6, 0x80, v6
	v_ashrrev_i32_e32 v12, 8, v12
	v_add_u32_e32 v3, 0x80, v3
	v_add_u32_e32 v7, 0x80, v7
	v_ashrrev_i32_e32 v6, 8, v6
	v_min_i32_e32 v12, 0x7f, v12
	v_ashrrev_i32_e32 v3, 8, v3
	v_ashrrev_i32_e32 v7, 8, v7
	v_min_i32_e32 v6, 0x7f, v6
	v_min_i32_sdwa v3, v3, s85 dst_sel:WORD_1 dst_unused:UNUSED_PAD src0_sel:DWORD src1_sel:DWORD
	v_min_i32_e32 v7, 0x7f, v7
	v_lshlrev_b32_e32 v12, 8, v12
	v_and_b32_e32 v12, 0xff00, v12
	v_and_b32_e32 v3, 0xff0000, v3
	v_perm_b32 v6, v7, v6, s92
	v_or3_b32 v3, v6, v12, v3
	v_lshrrev_b32_e32 v6, 2, v155
	v_mad_u64_u32 v[12:13], s[22:23], v6, s63, v[2:3]
	ds_write_b32 v12, v3
	v_or_b32_e32 v3, 16, v155
	v_lshl_add_u32 v13, v3, 3, v219
	ds_read_b64 v[6:7], v13
	v_lshrrev_b32_e32 v133, 1, v3
	v_mul_lo_u32 v153, v133, s63
	v_add_u32_e32 v133, v154, v153
	v_lshrrev_b32_e32 v3, 2, v3
	s_waitcnt lgkmcnt(0)
;     ...
;             _Pragma("unroll") for (int m = 0; m < 4; ++m) {
;               const int rr = wr3 * 64 + m * 16 + fr3;
;               const float2 ms = *reinterpret_cast<const float2*>(mr + (ai * HALF + rr) * 2);
;               f32x4 y = acc[ai][bj][m][n];
;               const float o0 = (y[0] - ms.x) * ms.y * gm.x + bt.x, o1 = (y[1] - ms.x) * ms.y * gm.y + bt.y;
;               const float o2 = (y[2] - ms.x) * ms.y * gm.z + bt.z, o3 = (y[3] - ms.x) * ms.y * gm.w + bt.w;
;               const unsigned h0 = f2bf(o0), h1 = f2bf(o1), h2 = f2bf(o2), h3 = f2bf(o3);
;               u32x2 ob; ob[0] = h0 | (h1 << 16); ob[1] = h2 | (h3 << 16);
;               *reinterpret_cast<u32x2*>(smem + (rr >> 1) * PIECE + (rr & 1) * 512 + cc * 2) = ob;
;               const int l0 = min(((int)__float_as_uint(o0) - (int)(h0 << 16) + 128) >> 8, 127);
;               const int l1 = min(((int)__float_as_uint(o1) - (int)(h1 << 16) + 128) >> 8, 127);
;               const int l2 = min(((int)__float_as_uint(o2) - (int)(h2 << 16) + 128) >> 8, 127);
;               const int l3 = min(((int)__float_as_uint(o3) - (int)(h3 << 16) + 128) >> 8, 127);
;               *reinterpret_cast<unsigned*>(smem + LOBASE + (rr >> 2) * PIECE + (rr & 3) * 256 + cc) =
;                   (unsigned)(l0 & 255) | ((unsigned)(l1 & 255) << 8) | ((unsigned)(l2 & 255) << 16) | ((unsigned)l3 << 24);
;             }
	v_mov_b32_e32 v204, v6
	v_mov_b32_e32 v205, v7
	v_pk_add_f32 v[14:15], v[122:123], v[6:7] op_sel_hi:[1,0] neg_lo:[0,1] neg_hi:[0,1]
	v_pk_add_f32 v[18:19], v[134:135], v[6:7] op_sel_hi:[1,0] neg_lo:[0,1] neg_hi:[0,1]
	v_pk_mul_f32 v[14:15], v[6:7], v[14:15] op_sel:[1,0]
	v_pk_mul_f32 v[6:7], v[6:7], v[18:19] op_sel:[1,0]
	v_pk_fma_f32 v[14:15], v[22:23], v[14:15], v[144:145]
	v_pk_fma_f32 v[6:7], v[0:1], v[6:7], v[4:5]
	v_and_b32_sdwa v18, v15, v216 dst_sel:DWORD dst_unused:UNUSED_PAD src0_sel:WORD_1 src1_sel:DWORD
	v_and_b32_sdwa v19, v14, v216 dst_sel:DWORD dst_unused:UNUSED_PAD src0_sel:WORD_1 src1_sel:DWORD
	v_add3_u32 v122, v15, v18, s84
	v_add3_u32 v18, v14, v19, s84
	v_and_b32_e32 v123, 0xffff0000, v18
	v_and_b32_sdwa v18, v7, v216 dst_sel:DWORD dst_unused:UNUSED_PAD src0_sel:WORD_1 src1_sel:DWORD
	v_and_b32_sdwa v19, v6, v216 dst_sel:DWORD dst_unused:UNUSED_PAD src0_sel:WORD_1 src1_sel:DWORD
	v_add3_u32 v18, v7, v18, s84
	v_add3_u32 v130, v6, v19, s84
	v_and_b32_e32 v131, 0xffff0000, v18
	v_or_b32_sdwa v19, v131, v122 dst_sel:DWORD dst_unused:UNUSED_PAD src0_sel:DWORD src1_sel:WORD_1
	v_or_b32_sdwa v18, v130, v123 dst_sel:DWORD dst_unused:UNUSED_PAD src0_sel:WORD_1 src1_sel:DWORD
	ds_write_b64 v133, v[18:19]
	v_and_b32_e32 v18, 0xffff0000, v130
	v_sub_u32_e32 v6, v6, v18
	v_sub_u32_e32 v14, v14, v123
	v_and_b32_e32 v18, 0xffff0000, v122
	v_add_u32_e32 v14, 0x80, v14
	v_sub_u32_e32 v15, v15, v18
	v_sub_u32_e32 v7, v7, v131
	v_add_u32_e32 v6, 0x80, v6
	v_ashrrev_i32_e32 v14, 8, v14
	v_add_u32_e32 v15, 0x80, v15
	v_add_u32_e32 v7, 0x80, v7
	v_ashrrev_i32_e32 v6, 8, v6
	v_min_i32_e32 v14, 0x7f, v14
	v_ashrrev_i32_e32 v15, 8, v15
	v_ashrrev_i32_e32 v7, 8, v7
	v_min_i32_e32 v6, 0x7f, v6
	v_min_i32_sdwa v15, v15, s85 dst_sel:WORD_1 dst_unused:UNUSED_PAD src0_sel:DWORD src1_sel:DWORD
	v_min_i32_e32 v7, 0x7f, v7
	v_lshlrev_b32_e32 v14, 8, v14
	v_and_b32_e32 v14, 0xff00, v14
	v_and_b32_e32 v15, 0xff0000, v15
	v_perm_b32 v6, v7, v6, s92
	v_or3_b32 v6, v6, v14, v15
	v_mad_u64_u32 v[14:15], s[22:23], v3, s63, v[2:3]
	v_or_b32_e32 v3, 32, v155
	ds_write_b32 v14, v6
	v_lshl_add_u32 v15, v3, 3, v219
	ds_read_b64 v[6:7], v15
	v_lshrrev_b32_e32 v134, 1, v3
	v_lshrrev_b32_e32 v3, 2, v3
	s_waitcnt lgkmcnt(0)
	v_mov_b32_e32 v206, v6
	v_mov_b32_e32 v207, v7
	v_pk_add_f32 v[18:19], v[136:137], v[6:7] op_sel_hi:[1,0] neg_lo:[0,1] neg_hi:[0,1]
	s_nop 0
	v_pk_mul_f32 v[18:19], v[6:7], v[18:19] op_sel:[1,0]
	v_pk_add_f32 v[122:123], v[138:139], v[6:7] op_sel_hi:[1,0] neg_lo:[0,1] neg_hi:[0,1]
	v_pk_fma_f32 v[18:19], v[22:23], v[18:19], v[144:145]
	v_pk_mul_f32 v[6:7], v[6:7], v[122:123] op_sel:[1,0]
	v_and_b32_sdwa v122, v19, v216 dst_sel:DWORD dst_unused:UNUSED_PAD src0_sel:WORD_1 src1_sel:DWORD
	v_and_b32_sdwa v123, v18, v216 dst_sel:DWORD dst_unused:UNUSED_PAD src0_sel:WORD_1 src1_sel:DWORD
	v_pk_fma_f32 v[6:7], v[0:1], v[6:7], v[4:5]
	v_add3_u32 v130, v19, v122, s84
	v_add3_u32 v122, v18, v123, s84
	v_and_b32_e32 v131, 0xffff0000, v122
	v_and_b32_sdwa v122, v7, v216 dst_sel:DWORD dst_unused:UNUSED_PAD src0_sel:WORD_1 src1_sel:DWORD
	v_and_b32_sdwa v123, v6, v216 dst_sel:DWORD dst_unused:UNUSED_PAD src0_sel:WORD_1 src1_sel:DWORD
	v_add3_u32 v122, v7, v122, s84
	v_add3_u32 v135, v6, v123, s84
	v_and_b32_e32 v136, 0xffff0000, v122
	v_mul_lo_u32 v137, v134, s63
	v_or_b32_sdwa v123, v136, v130 dst_sel:DWORD dst_unused:UNUSED_PAD src0_sel:DWORD src1_sel:WORD_1
	v_or_b32_sdwa v122, v135, v131 dst_sel:DWORD dst_unused:UNUSED_PAD src0_sel:WORD_1 src1_sel:DWORD
	v_add_u32_e32 v134, v154, v137
	ds_write_b64 v134, v[122:123]
	v_and_b32_e32 v122, 0xffff0000, v135
	v_sub_u32_e32 v6, v6, v122
	v_sub_u32_e32 v18, v18, v131
	v_and_b32_e32 v122, 0xffff0000, v130
	v_add_u32_e32 v18, 0x80, v18
	v_sub_u32_e32 v19, v19, v122
	v_sub_u32_e32 v7, v7, v136
	v_add_u32_e32 v6, 0x80, v6
	v_ashrrev_i32_e32 v18, 8, v18
	v_add_u32_e32 v19, 0x80, v19
	v_add_u32_e32 v7, 0x80, v7
	v_ashrrev_i32_e32 v6, 8, v6
	v_min_i32_e32 v18, 0x7f, v18
	v_ashrrev_i32_e32 v19, 8, v19
	v_ashrrev_i32_e32 v7, 8, v7
	v_min_i32_e32 v6, 0x7f, v6
	v_min_i32_sdwa v19, v19, s85 dst_sel:WORD_1 dst_unused:UNUSED_PAD src0_sel:DWORD src1_sel:DWORD
	v_min_i32_e32 v7, 0x7f, v7
	v_lshlrev_b32_e32 v18, 8, v18
	v_and_b32_e32 v18, 0xff00, v18
	v_and_b32_e32 v19, 0xff0000, v19
	v_perm_b32 v6, v7, v6, s92
	v_or3_b32 v6, v6, v18, v19
	v_mad_u64_u32 v[18:19], s[22:23], v3, s63, v[2:3]
	v_or_b32_e32 v3, 48, v155
	ds_write_b32 v18, v6
	v_lshl_add_u32 v19, v3, 3, v219
	ds_read_b64 v[6:7], v19
	v_lshrrev_b32_e32 v130, 1, v3
	v_mul_lo_u32 v136, v130, s63
	v_add_u32_e32 v135, v154, v136
	s_waitcnt lgkmcnt(0)
;     ...
;           _Pragma("unroll") for (int bj = 0; bj < 2; ++bj) _Pragma("unroll") for (int n = 0; n < 2; ++n) {
;             const int cc = bj * HALF + wc3 * 32 + n * 16 + fq3 * 4;
;             const float4 gm = *reinterpret_cast<const float4*>(g.gam + pn * BM + cc), bt = *reinterpret_cast<const float4*>(g.bet + pn * BM + cc);
;             _Pragma("unroll") for (int m = 0; m < 4; ++m) {
;               const int rr = wr3 * 64 + m * 16 + fr3;
;               const float2 ms = *reinterpret_cast<const float2*>(mr + (ai * HALF + rr) * 2);
;               f32x4 y = acc[ai][bj][m][n];
;               const float o0 = (y[0] - ms.x) * ms.y * gm.x + bt.x, o1 = (y[1] - ms.x) * ms.y * gm.y + bt.y;
;               const float o2 = (y[2] - ms.x) * ms.y * gm.z + bt.z, o3 = (y[3] - ms.x) * ms.y * gm.w + bt.w;
;               const unsigned h0 = f2bf(o0), h1 = f2bf(o1), h2 = f2bf(o2), h3 = f2bf(o3);
;               u32x2 ob; ob[0] = h0 | (h1 << 16); ob[1] = h2 | (h3 << 16);
;               *reinterpret_cast<u32x2*>(smem + (rr >> 1) * PIECE + (rr & 1) * 512 + cc * 2) = ob;
;               const int l0 = min(((int)__float_as_uint(o0) - (int)(h0 << 16) + 128) >> 8, 127);
;               const int l1 = min(((int)__float_as_uint(o1) - (int)(h1 << 16) + 128) >> 8, 127);
;               const int l2 = min(((int)__float_as_uint(o2) - (int)(h2 << 16) + 128) >> 8, 127);
;               const int l3 = min(((int)__float_as_uint(o3) - (int)(h3 << 16) + 128) >> 8, 127);
;               *reinterpret_cast<unsigned*>(smem + LOBASE + (rr >> 2) * PIECE + (rr & 3) * 256 + cc) =
;                   (unsigned)(l0 & 255) | ((unsigned)(l1 & 255) << 8) | ((unsigned)(l2 & 255) << 16) | ((unsigned)l3 << 24);
;             }
	v_mov_b32_e32 v208, v6
	v_mov_b32_e32 v209, v7
	v_pk_add_f32 v[122:123], v[140:141], v[6:7] op_sel_hi:[1,0] neg_lo:[0,1] neg_hi:[0,1]
	s_nop 0
	v_pk_mul_f32 v[122:123], v[6:7], v[122:123] op_sel:[1,0]
	s_nop 0
	v_pk_fma_f32 v[22:23], v[22:23], v[122:123], v[144:145]
	v_pk_add_f32 v[122:123], v[142:143], v[6:7] op_sel_hi:[1,0] neg_lo:[0,1] neg_hi:[0,1]
	s_nop 0
	v_pk_mul_f32 v[6:7], v[6:7], v[122:123] op_sel:[1,0]
	s_nop 0
	v_pk_fma_f32 v[0:1], v[0:1], v[6:7], v[4:5]
	v_and_b32_sdwa v4, v23, v216 dst_sel:DWORD dst_unused:UNUSED_PAD src0_sel:WORD_1 src1_sel:DWORD
	v_and_b32_sdwa v5, v22, v216 dst_sel:DWORD dst_unused:UNUSED_PAD src0_sel:WORD_1 src1_sel:DWORD
	v_add3_u32 v6, v23, v4, s84
	v_add3_u32 v4, v22, v5, s84
	v_and_b32_e32 v7, 0xffff0000, v4
	v_and_b32_sdwa v4, v1, v216 dst_sel:DWORD dst_unused:UNUSED_PAD src0_sel:WORD_1 src1_sel:DWORD
	v_and_b32_sdwa v5, v0, v216 dst_sel:DWORD dst_unused:UNUSED_PAD src0_sel:WORD_1 src1_sel:DWORD
	v_add3_u32 v4, v1, v4, s84
	v_add3_u32 v122, v0, v5, s84
	v_and_b32_e32 v123, 0xffff0000, v4
	v_or_b32_sdwa v5, v123, v6 dst_sel:DWORD dst_unused:UNUSED_PAD src0_sel:DWORD src1_sel:WORD_1
	v_or_b32_sdwa v4, v122, v7 dst_sel:DWORD dst_unused:UNUSED_PAD src0_sel:WORD_1 src1_sel:DWORD
	ds_write_b64 v135, v[4:5]
	v_and_b32_e32 v4, 0xffff0000, v122
	v_sub_u32_e32 v0, v0, v4
	v_sub_u32_e32 v4, v22, v7
	v_and_b32_e32 v5, 0xffff0000, v6
	v_add_u32_e32 v4, 0x80, v4
	v_sub_u32_e32 v5, v23, v5
	v_sub_u32_e32 v1, v1, v123
	v_add_u32_e32 v0, 0x80, v0
	v_ashrrev_i32_e32 v4, 8, v4
	v_add_u32_e32 v5, 0x80, v5
	v_add_u32_e32 v1, 0x80, v1
	v_ashrrev_i32_e32 v0, 8, v0
	v_min_i32_e32 v4, 0x7f, v4
	v_ashrrev_i32_e32 v5, 8, v5
	v_ashrrev_i32_e32 v1, 8, v1
	v_min_i32_e32 v0, 0x7f, v0
	v_min_i32_sdwa v5, v5, s85 dst_sel:WORD_1 dst_unused:UNUSED_PAD src0_sel:DWORD src1_sel:DWORD
	v_min_i32_e32 v1, 0x7f, v1
	v_lshlrev_b32_e32 v4, 8, v4
	v_and_b32_e32 v4, 0xff00, v4
	v_and_b32_e32 v5, 0xff0000, v5
	v_perm_b32 v0, v1, v0, s92
	v_lshrrev_b32_e32 v1, 2, v3
	v_or3_b32 v0, v0, v4, v5
	v_mad_u64_u32 v[22:23], s[22:23], v1, s63, v[2:3]
	ds_write_b32 v22, v0
	v_mov_b32_e32 v0, v224
	v_mov_b32_e32 v1, v225
	v_mov_b32_e32 v2, v226
	v_mov_b32_e32 v3, v227
	v_mov_b32_e32 v4, v240
	v_mov_b32_e32 v5, v241
	v_mov_b32_e32 v6, v242
	v_mov_b32_e32 v7, v243
	v_mov_b32_e32 v138, v202
	v_mov_b32_e32 v139, v203
	s_mov_b32 s22, s18
	s_mov_b32 s23, s19
	v_pk_add_f32 v[128:129], v[128:129], v[138:139] op_sel_hi:[1,0] neg_lo:[0,1] neg_hi:[0,1]
	s_nop 0
	v_pk_mul_f32 v[128:129], v[138:139], v[128:129] op_sel:[1,0]
	v_pk_add_f32 v[126:127], v[126:127], v[138:139] op_sel_hi:[1,0] neg_lo:[0,1] neg_hi:[0,1]
	v_mov_b32_e32 v122, v1
	v_mov_b32_e32 v123, v2
	v_mov_b32_e32 v130, v5
	v_mov_b32_e32 v131, v6
	v_pk_fma_f32 v[128:129], v[122:123], v[128:129], v[130:131]
	v_pk_mul_f32 v[126:127], v[138:139], v[126:127] op_sel:[1,0]
	v_mov_b32_e32 v1, v3
	v_mov_b32_e32 v5, v7
	v_and_b32_sdwa v23, v128, v216 dst_sel:DWORD dst_unused:UNUSED_PAD src0_sel:WORD_1 src1_sel:DWORD
	v_pk_fma_f32 v[6:7], v[0:1], v[126:127], v[4:5]
	v_add3_u32 v23, v128, v23, s84
	v_and_b32_e32 v138, 0xffff0000, v23
	v_and_b32_sdwa v23, v7, v216 dst_sel:DWORD dst_unused:UNUSED_PAD src0_sel:WORD_1 src1_sel:DWORD
	v_and_b32_sdwa v3, v129, v216 dst_sel:DWORD dst_unused:UNUSED_PAD src0_sel:WORD_1 src1_sel:DWORD
	v_and_b32_sdwa v126, v6, v216 dst_sel:DWORD dst_unused:UNUSED_PAD src0_sel:WORD_1 src1_sel:DWORD
	v_add3_u32 v23, v7, v23, s84
	v_or_b32_e32 v2, 32, v154
	v_add3_u32 v3, v129, v3, s84
	v_add3_u32 v139, v6, v126, s84
	v_and_b32_e32 v140, 0xffff0000, v23
	v_or_b32_sdwa v127, v140, v3 dst_sel:DWORD dst_unused:UNUSED_PAD src0_sel:DWORD src1_sel:WORD_1
	v_or_b32_sdwa v126, v139, v138 dst_sel:DWORD dst_unused:UNUSED_PAD src0_sel:WORD_1 src1_sel:DWORD
	v_add_u32_e32 v23, v2, v152
	ds_write_b64 v23, v[126:127]
	v_and_b32_e32 v126, 0xffff0000, v139
	v_sub_u32_e32 v6, v6, v126
	v_sub_u32_e32 v126, v128, v138
	v_and_b32_e32 v3, 0xffff0000, v3
	v_add_u32_e32 v126, 0x80, v126
	v_sub_u32_e32 v3, v129, v3
	v_sub_u32_e32 v7, v7, v140
	v_add_u32_e32 v6, 0x80, v6
	v_ashrrev_i32_e32 v126, 8, v126
	v_add_u32_e32 v3, 0x80, v3
	v_add_u32_e32 v7, 0x80, v7
	v_ashrrev_i32_e32 v6, 8, v6
	v_min_i32_e32 v126, 0x7f, v126
	v_ashrrev_i32_e32 v3, 8, v3
	v_ashrrev_i32_e32 v7, 8, v7
	v_min_i32_e32 v6, 0x7f, v6
	v_min_i32_sdwa v3, v3, s85 dst_sel:WORD_1 dst_unused:UNUSED_PAD src0_sel:DWORD src1_sel:DWORD
	v_min_i32_e32 v7, 0x7f, v7
	v_lshlrev_b32_e32 v126, 8, v126
	v_and_b32_e32 v126, 0xff00, v126
	v_and_b32_e32 v3, 0xff0000, v3
	v_perm_b32 v6, v7, v6, s92
	v_or3_b32 v3, v6, v126, v3
	ds_write_b32 v12, v3 offset:16
	v_mov_b32_e32 v6, v204
	v_mov_b32_e32 v7, v205
	v_pk_add_f32 v[108:109], v[108:109], v[6:7] op_sel_hi:[1,0] neg_lo:[0,1] neg_hi:[0,1]
	s_nop 0
	v_pk_mul_f32 v[108:109], v[6:7], v[108:109] op_sel:[1,0]
	s_nop 0
	v_pk_fma_f32 v[126:127], v[122:123], v[108:109], v[130:131]
	v_pk_add_f32 v[108:109], v[110:111], v[6:7] op_sel_hi:[1,0] neg_lo:[0,1] neg_hi:[0,1]
	v_and_b32_sdwa v3, v127, v216 dst_sel:DWORD dst_unused:UNUSED_PAD src0_sel:WORD_1 src1_sel:DWORD
	v_pk_mul_f32 v[6:7], v[6:7], v[108:109] op_sel:[1,0]
	v_and_b32_sdwa v108, v126, v216 dst_sel:DWORD dst_unused:UNUSED_PAD src0_sel:WORD_1 src1_sel:DWORD
	v_pk_fma_f32 v[6:7], v[0:1], v[6:7], v[4:5]
	v_add3_u32 v108, v126, v108, s84
	v_and_b32_e32 v109, 0xffff0000, v108
	v_and_b32_sdwa v108, v7, v216 dst_sel:DWORD dst_unused:UNUSED_PAD src0_sel:WORD_1 src1_sel:DWORD
	v_and_b32_sdwa v110, v6, v216 dst_sel:DWORD dst_unused:UNUSED_PAD src0_sel:WORD_1 src1_sel:DWORD
	v_add3_u32 v108, v7, v108, s84
	v_add3_u32 v3, v127, v3, s84
	v_add3_u32 v128, v6, v110, s84
;     ...
;           _Pragma("unroll") for (int bj = 0; bj < 2; ++bj) _Pragma("unroll") for (int n = 0; n < 2; ++n) {
;             const int cc = bj * HALF + wc3 * 32 + n * 16 + fq3 * 4;
;             const float4 gm = *reinterpret_cast<const float4*>(g.gam + pn * BM + cc), bt = *reinterpret_cast<const float4*>(g.bet + pn * BM + cc);
;             _Pragma("unroll") for (int m = 0; m < 4; ++m) {
;               const int rr = wr3 * 64 + m * 16 + fr3;
;               const float2 ms = *reinterpret_cast<const float2*>(mr + (ai * HALF + rr) * 2);
;               f32x4 y = acc[ai][bj][m][n];
;               const float o0 = (y[0] - ms.x) * ms.y * gm.x + bt.x, o1 = (y[1] - ms.x) * ms.y * gm.y + bt.y;
;               const float o2 = (y[2] - ms.x) * ms.y * gm.z + bt.z, o3 = (y[3] - ms.x) * ms.y * gm.w + bt.w;
;               const unsigned h0 = f2bf(o0), h1 = f2bf(o1), h2 = f2bf(o2), h3 = f2bf(o3);
;               u32x2 ob; ob[0] = h0 | (h1 << 16); ob[1] = h2 | (h3 << 16);
;               *reinterpret_cast<u32x2*>(smem + (rr >> 1) * PIECE + (rr & 1) * 512 + cc * 2) = ob;
;               const int l0 = min(((int)__float_as_uint(o0) - (int)(h0 << 16) + 128) >> 8, 127);
;               const int l1 = min(((int)__float_as_uint(o1) - (int)(h1 << 16) + 128) >> 8, 127);
;               const int l2 = min(((int)__float_as_uint(o2) - (int)(h2 << 16) + 128) >> 8, 127);
;               const int l3 = min(((int)__float_as_uint(o3) - (int)(h3 << 16) + 128) >> 8, 127);
;               *reinterpret_cast<unsigned*>(smem + LOBASE + (rr >> 2) * PIECE + (rr & 3) * 256 + cc) =
;                   (unsigned)(l0 & 255) | ((unsigned)(l1 & 255) << 8) | ((unsigned)(l2 & 255) << 16) | ((unsigned)l3 << 24);
;             }
	v_and_b32_e32 v129, 0xffff0000, v108
	v_or_b32_sdwa v111, v129, v3 dst_sel:DWORD dst_unused:UNUSED_PAD src0_sel:DWORD src1_sel:WORD_1
	v_or_b32_sdwa v110, v128, v109 dst_sel:DWORD dst_unused:UNUSED_PAD src0_sel:WORD_1 src1_sel:DWORD
	v_add_u32_e32 v108, v2, v153
	ds_write_b64 v108, v[110:111]
	v_and_b32_e32 v110, 0xffff0000, v128
	v_sub_u32_e32 v109, v126, v109
	v_and_b32_e32 v3, 0xffff0000, v3
	v_sub_u32_e32 v6, v6, v110
	v_add_u32_e32 v109, 0x80, v109
	v_sub_u32_e32 v3, v127, v3
	v_sub_u32_e32 v7, v7, v129
	v_add_u32_e32 v6, 0x80, v6
	v_ashrrev_i32_e32 v109, 8, v109
	v_add_u32_e32 v3, 0x80, v3
	v_add_u32_e32 v7, 0x80, v7
	v_ashrrev_i32_e32 v6, 8, v6
	v_min_i32_e32 v109, 0x7f, v109
	v_ashrrev_i32_e32 v3, 8, v3
	v_ashrrev_i32_e32 v7, 8, v7
	v_min_i32_e32 v6, 0x7f, v6
	v_min_i32_sdwa v3, v3, s85 dst_sel:WORD_1 dst_unused:UNUSED_PAD src0_sel:DWORD src1_sel:DWORD
	v_min_i32_e32 v7, 0x7f, v7
	v_lshlrev_b32_e32 v109, 8, v109
	v_and_b32_e32 v109, 0xff00, v109
	v_and_b32_e32 v3, 0xff0000, v3
	v_perm_b32 v6, v7, v6, s92
	v_or3_b32 v3, v6, v109, v3
	ds_write_b32 v14, v3 offset:16
	v_mov_b32_e32 v6, v206
	v_mov_b32_e32 v7, v207
	v_pk_add_f32 v[98:99], v[98:99], v[6:7] op_sel_hi:[1,0] neg_lo:[0,1] neg_hi:[0,1]
	s_nop 0
	v_pk_mul_f32 v[98:99], v[6:7], v[98:99] op_sel:[1,0]
	s_nop 0
	v_pk_fma_f32 v[110:111], v[122:123], v[98:99], v[130:131]
	v_pk_add_f32 v[98:99], v[106:107], v[6:7] op_sel_hi:[1,0] neg_lo:[0,1] neg_hi:[0,1]
	v_and_b32_sdwa v3, v111, v216 dst_sel:DWORD dst_unused:UNUSED_PAD src0_sel:WORD_1 src1_sel:DWORD
	v_pk_mul_f32 v[6:7], v[6:7], v[98:99] op_sel:[1,0]
	v_and_b32_sdwa v98, v110, v216 dst_sel:DWORD dst_unused:UNUSED_PAD src0_sel:WORD_1 src1_sel:DWORD
	v_pk_fma_f32 v[6:7], v[0:1], v[6:7], v[4:5]
	v_add3_u32 v98, v110, v98, s84
	v_and_b32_e32 v99, 0xffff0000, v98
	v_and_b32_sdwa v98, v7, v216 dst_sel:DWORD dst_unused:UNUSED_PAD src0_sel:WORD_1 src1_sel:DWORD
	v_and_b32_sdwa v106, v6, v216 dst_sel:DWORD dst_unused:UNUSED_PAD src0_sel:WORD_1 src1_sel:DWORD
	v_add3_u32 v98, v7, v98, s84
	v_add3_u32 v3, v111, v3, s84
	v_add3_u32 v109, v6, v106, s84
	v_and_b32_e32 v126, 0xffff0000, v98
	v_or_b32_sdwa v107, v126, v3 dst_sel:DWORD dst_unused:UNUSED_PAD src0_sel:DWORD src1_sel:WORD_1
	v_or_b32_sdwa v106, v109, v99 dst_sel:DWORD dst_unused:UNUSED_PAD src0_sel:WORD_1 src1_sel:DWORD
	v_add_u32_e32 v98, v2, v137
	ds_write_b64 v98, v[106:107]
	v_and_b32_e32 v106, 0xffff0000, v109
	v_sub_u32_e32 v99, v110, v99
	v_and_b32_e32 v3, 0xffff0000, v3
	v_sub_u32_e32 v6, v6, v106
	v_add_u32_e32 v99, 0x80, v99
	v_sub_u32_e32 v3, v111, v3
	v_sub_u32_e32 v7, v7, v126
	v_add_u32_e32 v6, 0x80, v6
	v_ashrrev_i32_e32 v99, 8, v99
	v_add_u32_e32 v3, 0x80, v3
	v_add_u32_e32 v7, 0x80, v7
	v_ashrrev_i32_e32 v6, 8, v6
	v_min_i32_e32 v99, 0x7f, v99
	v_ashrrev_i32_e32 v3, 8, v3
	v_ashrrev_i32_e32 v7, 8, v7
	v_min_i32_e32 v6, 0x7f, v6
	v_min_i32_sdwa v3, v3, s85 dst_sel:WORD_1 dst_unused:UNUSED_PAD src0_sel:DWORD src1_sel:DWORD
	v_min_i32_e32 v7, 0x7f, v7
	v_lshlrev_b32_e32 v99, 8, v99
	v_and_b32_e32 v99, 0xff00, v99
	v_and_b32_e32 v3, 0xff0000, v3
	v_perm_b32 v6, v7, v6, s92
	v_or3_b32 v3, v6, v99, v3
	ds_write_b32 v18, v3 offset:16
	v_mov_b32_e32 v6, v208
	v_mov_b32_e32 v7, v209
	v_add_u32_e32 v99, v2, v136
	v_pk_add_f32 v[106:107], v[114:115], v[6:7] op_sel_hi:[1,0] neg_lo:[0,1] neg_hi:[0,1]
	s_nop 0
	v_pk_mul_f32 v[106:107], v[6:7], v[106:107] op_sel:[1,0]
	v_pk_add_f32 v[110:111], v[120:121], v[6:7] op_sel_hi:[1,0] neg_lo:[0,1] neg_hi:[0,1]
	v_pk_fma_f32 v[106:107], v[122:123], v[106:107], v[130:131]
	v_pk_mul_f32 v[6:7], v[6:7], v[110:111] op_sel:[1,0]
	v_and_b32_sdwa v3, v107, v216 dst_sel:DWORD dst_unused:UNUSED_PAD src0_sel:WORD_1 src1_sel:DWORD
	v_pk_fma_f32 v[0:1], v[0:1], v[6:7], v[4:5]
	v_and_b32_sdwa v4, v106, v216 dst_sel:DWORD dst_unused:UNUSED_PAD src0_sel:WORD_1 src1_sel:DWORD
	v_add3_u32 v4, v106, v4, s84
	v_and_b32_e32 v6, 0xffff0000, v4
	v_and_b32_sdwa v4, v1, v216 dst_sel:DWORD dst_unused:UNUSED_PAD src0_sel:WORD_1 src1_sel:DWORD
	v_and_b32_sdwa v5, v0, v216 dst_sel:DWORD dst_unused:UNUSED_PAD src0_sel:WORD_1 src1_sel:DWORD
	v_add3_u32 v4, v1, v4, s84
	v_add3_u32 v7, v0, v5, s84
	v_add3_u32 v3, v107, v3, s84
	v_and_b32_e32 v109, 0xffff0000, v4
	v_and_b32_e32 v2, 0xffff0000, v7
	v_or_b32_sdwa v5, v109, v3 dst_sel:DWORD dst_unused:UNUSED_PAD src0_sel:DWORD src1_sel:WORD_1
	v_sub_u32_e32 v0, v0, v2
	v_sub_u32_e32 v2, v106, v6
	v_and_b32_e32 v3, 0xffff0000, v3
	v_add_u32_e32 v2, 0x80, v2
	v_sub_u32_e32 v3, v107, v3
	v_sub_u32_e32 v1, v1, v109
	v_add_u32_e32 v0, 0x80, v0
	v_ashrrev_i32_e32 v2, 8, v2
	v_add_u32_e32 v3, 0x80, v3
	v_add_u32_e32 v1, 0x80, v1
	v_ashrrev_i32_e32 v0, 8, v0
	v_min_i32_e32 v2, 0x7f, v2
	v_ashrrev_i32_e32 v3, 8, v3
	v_ashrrev_i32_e32 v1, 8, v1
	v_min_i32_e32 v0, 0x7f, v0
	v_min_i32_sdwa v3, v3, s85 dst_sel:WORD_1 dst_unused:UNUSED_PAD src0_sel:DWORD src1_sel:DWORD
	v_min_i32_e32 v1, 0x7f, v1
	v_lshlrev_b32_e32 v2, 8, v2
	v_and_b32_e32 v2, 0xff00, v2
	v_and_b32_e32 v3, 0xff0000, v3
	v_perm_b32 v0, v1, v0, s92
	v_or_b32_sdwa v4, v7, v6 dst_sel:DWORD dst_unused:UNUSED_PAD src0_sel:WORD_1 src1_sel:DWORD
	v_or3_b32 v0, v0, v2, v3
	ds_write_b64 v99, v[4:5]
	ds_write_b32 v22, v0 offset:16
	v_mov_b32_e32 v0, v228
	v_mov_b32_e32 v1, v229
	v_mov_b32_e32 v2, v230
	v_mov_b32_e32 v3, v231
	v_mov_b32_e32 v4, v244
	v_mov_b32_e32 v5, v245
	v_mov_b32_e32 v6, v246
	v_mov_b32_e32 v7, v247
	v_mov_b32_e32 v106, v202
	v_mov_b32_e32 v107, v203
	v_or_b32_e32 v109, 0x100, v154
	v_pk_add_f32 v[120:121], v[124:125], v[106:107] op_sel_hi:[1,0] neg_lo:[0,1] neg_hi:[0,1]
	s_nop 0
	v_pk_mul_f32 v[120:121], v[106:107], v[120:121] op_sel:[1,0]
;     ...
;             _Pragma("unroll") for (int m = 0; m < 4; ++m) {
;               const int rr = wr3 * 64 + m * 16 + fr3;
;               const float2 ms = *reinterpret_cast<const float2*>(mr + (ai * HALF + rr) * 2);
;               f32x4 y = acc[ai][bj][m][n];
;               const float o0 = (y[0] - ms.x) * ms.y * gm.x + bt.x, o1 = (y[1] - ms.x) * ms.y * gm.y + bt.y;
;               const float o2 = (y[2] - ms.x) * ms.y * gm.z + bt.z, o3 = (y[3] - ms.x) * ms.y * gm.w + bt.w;
;               const unsigned h0 = f2bf(o0), h1 = f2bf(o1), h2 = f2bf(o2), h3 = f2bf(o3);
;               u32x2 ob; ob[0] = h0 | (h1 << 16); ob[1] = h2 | (h3 << 16);
;               *reinterpret_cast<u32x2*>(smem + (rr >> 1) * PIECE + (rr & 1) * 512 + cc * 2) = ob;
;               const int l0 = min(((int)__float_as_uint(o0) - (int)(h0 << 16) + 128) >> 8, 127);
;               const int l1 = min(((int)__float_as_uint(o1) - (int)(h1 << 16) + 128) >> 8, 127);
;               const int l2 = min(((int)__float_as_uint(o2) - (int)(h2 << 16) + 128) >> 8, 127);
;               const int l3 = min(((int)__float_as_uint(o3) - (int)(h3 << 16) + 128) >> 8, 127);
;               *reinterpret_cast<unsigned*>(smem + LOBASE + (rr >> 2) * PIECE + (rr & 3) * 256 + cc) =
;                   (unsigned)(l0 & 255) | ((unsigned)(l1 & 255) << 8) | ((unsigned)(l2 & 255) << 16) | ((unsigned)l3 << 24);
;             }
	v_pk_add_f32 v[118:119], v[118:119], v[106:107] op_sel_hi:[1,0] neg_lo:[0,1] neg_hi:[0,1]
	v_mov_b32_e32 v110, v1
	v_mov_b32_e32 v111, v2
	v_mov_b32_e32 v114, v5
	v_mov_b32_e32 v115, v6
	v_pk_fma_f32 v[120:121], v[110:111], v[120:121], v[114:115]
	v_pk_mul_f32 v[106:107], v[106:107], v[118:119] op_sel:[1,0]
	v_mov_b32_e32 v1, v3
	v_mov_b32_e32 v5, v7
	v_and_b32_sdwa v6, v121, v216 dst_sel:DWORD dst_unused:UNUSED_PAD src0_sel:WORD_1 src1_sel:DWORD
	v_and_b32_sdwa v7, v120, v216 dst_sel:DWORD dst_unused:UNUSED_PAD src0_sel:WORD_1 src1_sel:DWORD
	v_pk_fma_f32 v[2:3], v[0:1], v[106:107], v[4:5]
	v_add3_u32 v107, v121, v6, s84
	v_add3_u32 v6, v120, v7, s84
	v_and_b32_e32 v118, 0xffff0000, v6
	v_and_b32_sdwa v6, v3, v216 dst_sel:DWORD dst_unused:UNUSED_PAD src0_sel:WORD_1 src1_sel:DWORD
	v_and_b32_sdwa v7, v2, v216 dst_sel:DWORD dst_unused:UNUSED_PAD src0_sel:WORD_1 src1_sel:DWORD
	v_add3_u32 v6, v3, v6, s84
	v_add3_u32 v119, v2, v7, s84
	v_and_b32_e32 v122, 0xffff0000, v6
	v_or_b32_sdwa v7, v122, v107 dst_sel:DWORD dst_unused:UNUSED_PAD src0_sel:DWORD src1_sel:WORD_1
	v_or_b32_sdwa v6, v119, v118 dst_sel:DWORD dst_unused:UNUSED_PAD src0_sel:WORD_1 src1_sel:DWORD
	v_add_u32_e32 v106, v109, v152
	ds_write_b64 v106, v[6:7]
	v_and_b32_e32 v6, 0xffff0000, v119
	v_sub_u32_e32 v2, v2, v6
	v_sub_u32_e32 v6, v120, v118
	v_and_b32_e32 v7, 0xffff0000, v107
	v_add_u32_e32 v6, 0x80, v6
	v_sub_u32_e32 v7, v121, v7
	v_sub_u32_e32 v3, v3, v122
	v_add_u32_e32 v2, 0x80, v2
	v_ashrrev_i32_e32 v6, 8, v6
	v_add_u32_e32 v7, 0x80, v7
	v_add_u32_e32 v3, 0x80, v3
	v_ashrrev_i32_e32 v2, 8, v2
	v_min_i32_e32 v6, 0x7f, v6
	v_ashrrev_i32_e32 v7, 8, v7
	v_ashrrev_i32_e32 v3, 8, v3
	v_min_i32_e32 v2, 0x7f, v2
	v_min_i32_sdwa v7, v7, s85 dst_sel:WORD_1 dst_unused:UNUSED_PAD src0_sel:DWORD src1_sel:DWORD
	v_min_i32_e32 v3, 0x7f, v3
	v_lshlrev_b32_e32 v6, 8, v6
	v_and_b32_e32 v6, 0xff00, v6
	v_and_b32_e32 v7, 0xff0000, v7
	v_perm_b32 v2, v3, v2, s92
	v_or3_b32 v2, v2, v6, v7
	ds_write_b32 v12, v2 offset:128
	v_mov_b32_e32 v2, v204
	v_mov_b32_e32 v3, v205
	v_pk_add_f32 v[6:7], v[102:103], v[2:3] op_sel_hi:[1,0] neg_lo:[0,1] neg_hi:[0,1]
	s_nop 0
	v_pk_mul_f32 v[6:7], v[2:3], v[6:7] op_sel:[1,0]
	v_pk_add_f32 v[102:103], v[104:105], v[2:3] op_sel_hi:[1,0] neg_lo:[0,1] neg_hi:[0,1]
	v_pk_fma_f32 v[6:7], v[110:111], v[6:7], v[114:115]
	v_pk_mul_f32 v[2:3], v[2:3], v[102:103] op_sel:[1,0]
	v_and_b32_sdwa v102, v7, v216 dst_sel:DWORD dst_unused:UNUSED_PAD src0_sel:WORD_1 src1_sel:DWORD
	v_and_b32_sdwa v103, v6, v216 dst_sel:DWORD dst_unused:UNUSED_PAD src0_sel:WORD_1 src1_sel:DWORD
	v_pk_fma_f32 v[2:3], v[0:1], v[2:3], v[4:5]
	v_add3_u32 v107, v7, v102, s84
	v_add3_u32 v102, v6, v103, s84
	v_and_b32_e32 v103, 0xffff0000, v102
	v_and_b32_sdwa v102, v3, v216 dst_sel:DWORD dst_unused:UNUSED_PAD src0_sel:WORD_1 src1_sel:DWORD
	v_and_b32_sdwa v104, v2, v216 dst_sel:DWORD dst_unused:UNUSED_PAD src0_sel:WORD_1 src1_sel:DWORD
	v_add3_u32 v102, v3, v102, s84
	v_add3_u32 v118, v2, v104, s84
	v_and_b32_e32 v119, 0xffff0000, v102
	v_or_b32_sdwa v105, v119, v107 dst_sel:DWORD dst_unused:UNUSED_PAD src0_sel:DWORD src1_sel:WORD_1
	v_or_b32_sdwa v104, v118, v103 dst_sel:DWORD dst_unused:UNUSED_PAD src0_sel:WORD_1 src1_sel:DWORD
	v_add_u32_e32 v102, v109, v153
	ds_write_b64 v102, v[104:105]
	v_and_b32_e32 v104, 0xffff0000, v118
	v_sub_u32_e32 v6, v6, v103
	v_and_b32_e32 v103, 0xffff0000, v107
	v_sub_u32_e32 v2, v2, v104
	v_add_u32_e32 v6, 0x80, v6
	v_sub_u32_e32 v7, v7, v103
	v_sub_u32_e32 v3, v3, v119
	v_add_u32_e32 v2, 0x80, v2
	v_ashrrev_i32_e32 v6, 8, v6
	v_add_u32_e32 v7, 0x80, v7
	v_add_u32_e32 v3, 0x80, v3
	v_ashrrev_i32_e32 v2, 8, v2
	v_min_i32_e32 v6, 0x7f, v6
	v_ashrrev_i32_e32 v7, 8, v7
	v_ashrrev_i32_e32 v3, 8, v3
	v_min_i32_e32 v2, 0x7f, v2
	v_min_i32_sdwa v7, v7, s85 dst_sel:WORD_1 dst_unused:UNUSED_PAD src0_sel:DWORD src1_sel:DWORD
	v_min_i32_e32 v3, 0x7f, v3
	v_lshlrev_b32_e32 v6, 8, v6
	v_and_b32_e32 v6, 0xff00, v6
	v_and_b32_e32 v7, 0xff0000, v7
	v_perm_b32 v2, v3, v2, s92
	v_or3_b32 v2, v2, v6, v7
	ds_write_b32 v14, v2 offset:128
	v_mov_b32_e32 v2, v206
	v_mov_b32_e32 v3, v207
	v_pk_add_f32 v[6:7], v[92:93], v[2:3] op_sel_hi:[1,0] neg_lo:[0,1] neg_hi:[0,1]
	s_nop 0
	v_pk_mul_f32 v[6:7], v[2:3], v[6:7] op_sel:[1,0]
	v_pk_add_f32 v[88:89], v[88:89], v[2:3] op_sel_hi:[1,0] neg_lo:[0,1] neg_hi:[0,1]
	v_pk_fma_f32 v[6:7], v[110:111], v[6:7], v[114:115]
	v_pk_mul_f32 v[2:3], v[2:3], v[88:89] op_sel:[1,0]
	v_and_b32_sdwa v88, v7, v216 dst_sel:DWORD dst_unused:UNUSED_PAD src0_sel:WORD_1 src1_sel:DWORD
	v_and_b32_sdwa v89, v6, v216 dst_sel:DWORD dst_unused:UNUSED_PAD src0_sel:WORD_1 src1_sel:DWORD
	v_pk_fma_f32 v[2:3], v[0:1], v[2:3], v[4:5]
	v_add3_u32 v93, v7, v88, s84
	v_add3_u32 v88, v6, v89, s84
	v_and_b32_e32 v103, 0xffff0000, v88
	v_and_b32_sdwa v88, v3, v216 dst_sel:DWORD dst_unused:UNUSED_PAD src0_sel:WORD_1 src1_sel:DWORD
	v_and_b32_sdwa v89, v2, v216 dst_sel:DWORD dst_unused:UNUSED_PAD src0_sel:WORD_1 src1_sel:DWORD
	v_add3_u32 v88, v3, v88, s84
	v_add3_u32 v104, v2, v89, s84
	v_and_b32_e32 v105, 0xffff0000, v88
	v_or_b32_sdwa v89, v105, v93 dst_sel:DWORD dst_unused:UNUSED_PAD src0_sel:DWORD src1_sel:WORD_1
	v_or_b32_sdwa v88, v104, v103 dst_sel:DWORD dst_unused:UNUSED_PAD src0_sel:WORD_1 src1_sel:DWORD
	v_add_u32_e32 v92, v109, v137
	ds_write_b64 v92, v[88:89]
	v_and_b32_e32 v88, 0xffff0000, v104
	v_sub_u32_e32 v2, v2, v88
	v_sub_u32_e32 v6, v6, v103
	v_and_b32_e32 v88, 0xffff0000, v93
	v_add_u32_e32 v6, 0x80, v6
	v_sub_u32_e32 v7, v7, v88
	v_sub_u32_e32 v3, v3, v105
	v_add_u32_e32 v2, 0x80, v2
	v_ashrrev_i32_e32 v6, 8, v6
	v_add_u32_e32 v7, 0x80, v7
	v_add_u32_e32 v3, 0x80, v3
;     ...
;           _Pragma("unroll") for (int bj = 0; bj < 2; ++bj) _Pragma("unroll") for (int n = 0; n < 2; ++n) {
;             const int cc = bj * HALF + wc3 * 32 + n * 16 + fq3 * 4;
;             const float4 gm = *reinterpret_cast<const float4*>(g.gam + pn * BM + cc), bt = *reinterpret_cast<const float4*>(g.bet + pn * BM + cc);
;             _Pragma("unroll") for (int m = 0; m < 4; ++m) {
;               const int rr = wr3 * 64 + m * 16 + fr3;
;               const float2 ms = *reinterpret_cast<const float2*>(mr + (ai * HALF + rr) * 2);
;               f32x4 y = acc[ai][bj][m][n];
;               const float o0 = (y[0] - ms.x) * ms.y * gm.x + bt.x, o1 = (y[1] - ms.x) * ms.y * gm.y + bt.y;
;               const float o2 = (y[2] - ms.x) * ms.y * gm.z + bt.z, o3 = (y[3] - ms.x) * ms.y * gm.w + bt.w;
;               const unsigned h0 = f2bf(o0), h1 = f2bf(o1), h2 = f2bf(o2), h3 = f2bf(o3);
;               u32x2 ob; ob[0] = h0 | (h1 << 16); ob[1] = h2 | (h3 << 16);
;               *reinterpret_cast<u32x2*>(smem + (rr >> 1) * PIECE + (rr & 1) * 512 + cc * 2) = ob;
;               const int l0 = min(((int)__float_as_uint(o0) - (int)(h0 << 16) + 128) >> 8, 127);
;               const int l1 = min(((int)__float_as_uint(o1) - (int)(h1 << 16) + 128) >> 8, 127);
;               const int l2 = min(((int)__float_as_uint(o2) - (int)(h2 << 16) + 128) >> 8, 127);
;               const int l3 = min(((int)__float_as_uint(o3) - (int)(h3 << 16) + 128) >> 8, 127);
;               *reinterpret_cast<unsigned*>(smem + LOBASE + (rr >> 2) * PIECE + (rr & 3) * 256 + cc) =
;                   (unsigned)(l0 & 255) | ((unsigned)(l1 & 255) << 8) | ((unsigned)(l2 & 255) << 16) | ((unsigned)l3 << 24);
;             }
	v_ashrrev_i32_e32 v2, 8, v2
	v_min_i32_e32 v6, 0x7f, v6
	v_ashrrev_i32_e32 v7, 8, v7
	v_ashrrev_i32_e32 v3, 8, v3
	v_min_i32_e32 v2, 0x7f, v2
	v_min_i32_sdwa v7, v7, s85 dst_sel:WORD_1 dst_unused:UNUSED_PAD src0_sel:DWORD src1_sel:DWORD
	v_min_i32_e32 v3, 0x7f, v3
	v_lshlrev_b32_e32 v6, 8, v6
	v_and_b32_e32 v6, 0xff00, v6
	v_and_b32_e32 v7, 0xff0000, v7
	v_perm_b32 v2, v3, v2, s92
	v_or3_b32 v2, v2, v6, v7
	ds_write_b32 v18, v2 offset:128
	v_mov_b32_e32 v2, v208
	v_mov_b32_e32 v3, v209
	v_add_u32_e32 v93, v109, v136
	v_pk_add_f32 v[6:7], v[90:91], v[2:3] op_sel_hi:[1,0] neg_lo:[0,1] neg_hi:[0,1]
	s_nop 0
	v_pk_mul_f32 v[6:7], v[2:3], v[6:7] op_sel:[1,0]
	v_pk_add_f32 v[88:89], v[94:95], v[2:3] op_sel_hi:[1,0] neg_lo:[0,1] neg_hi:[0,1]
	v_pk_fma_f32 v[6:7], v[110:111], v[6:7], v[114:115]
	v_pk_mul_f32 v[2:3], v[2:3], v[88:89] op_sel:[1,0]
	s_nop 0
	v_pk_fma_f32 v[0:1], v[0:1], v[2:3], v[4:5]
	v_and_b32_sdwa v2, v7, v216 dst_sel:DWORD dst_unused:UNUSED_PAD src0_sel:WORD_1 src1_sel:DWORD
	v_and_b32_sdwa v3, v6, v216 dst_sel:DWORD dst_unused:UNUSED_PAD src0_sel:WORD_1 src1_sel:DWORD
	v_add3_u32 v4, v7, v2, s84
	v_add3_u32 v2, v6, v3, s84
	v_and_b32_e32 v5, 0xffff0000, v2
	v_and_b32_sdwa v2, v1, v216 dst_sel:DWORD dst_unused:UNUSED_PAD src0_sel:WORD_1 src1_sel:DWORD
	v_and_b32_sdwa v3, v0, v216 dst_sel:DWORD dst_unused:UNUSED_PAD src0_sel:WORD_1 src1_sel:DWORD
	v_add3_u32 v2, v1, v2, s84
	v_add3_u32 v88, v0, v3, s84
	v_and_b32_e32 v89, 0xffff0000, v2
	v_or_b32_sdwa v3, v89, v4 dst_sel:DWORD dst_unused:UNUSED_PAD src0_sel:DWORD src1_sel:WORD_1
	v_or_b32_sdwa v2, v88, v5 dst_sel:DWORD dst_unused:UNUSED_PAD src0_sel:WORD_1 src1_sel:DWORD
	ds_write_b64 v93, v[2:3]
	v_and_b32_e32 v2, 0xffff0000, v88
	v_sub_u32_e32 v0, v0, v2
	v_sub_u32_e32 v2, v6, v5
	v_and_b32_e32 v3, 0xffff0000, v4
	v_add_u32_e32 v2, 0x80, v2
	v_sub_u32_e32 v3, v7, v3
	v_sub_u32_e32 v1, v1, v89
	v_add_u32_e32 v0, 0x80, v0
	v_ashrrev_i32_e32 v2, 8, v2
	v_add_u32_e32 v3, 0x80, v3
	v_add_u32_e32 v1, 0x80, v1
	v_ashrrev_i32_e32 v0, 8, v0
	v_min_i32_e32 v2, 0x7f, v2
	v_ashrrev_i32_e32 v3, 8, v3
	v_ashrrev_i32_e32 v1, 8, v1
	v_min_i32_e32 v0, 0x7f, v0
	v_min_i32_sdwa v3, v3, s85 dst_sel:WORD_1 dst_unused:UNUSED_PAD src0_sel:DWORD src1_sel:DWORD
	v_min_i32_e32 v1, 0x7f, v1
	v_lshlrev_b32_e32 v2, 8, v2
	v_and_b32_e32 v2, 0xff00, v2
	v_and_b32_e32 v3, 0xff0000, v3
	v_perm_b32 v0, v1, v0, s92
	v_or3_b32 v0, v0, v2, v3
	ds_write_b32 v22, v0 offset:128
	v_mov_b32_e32 v0, v232
	v_mov_b32_e32 v1, v233
	v_mov_b32_e32 v2, v234
	v_mov_b32_e32 v3, v235
	v_mov_b32_e32 v4, v248
	v_mov_b32_e32 v5, v249
	v_mov_b32_e32 v6, v250
	v_mov_b32_e32 v7, v251
	v_mov_b32_e32 v94, v202
	v_mov_b32_e32 v95, v203
	v_pk_add_f32 v[104:105], v[116:117], v[94:95] op_sel_hi:[1,0] neg_lo:[0,1] neg_hi:[0,1]
	s_nop 0
	v_pk_mul_f32 v[104:105], v[94:95], v[104:105] op_sel:[1,0]
	v_pk_add_f32 v[110:111], v[112:113], v[94:95] op_sel_hi:[1,0] neg_lo:[0,1] neg_hi:[0,1]
	v_mov_b32_e32 v88, v1
	v_mov_b32_e32 v89, v2
	v_mov_b32_e32 v90, v5
	v_mov_b32_e32 v91, v6
	v_pk_fma_f32 v[104:105], v[88:89], v[104:105], v[90:91]
	v_pk_mul_f32 v[94:95], v[94:95], v[110:111] op_sel:[1,0]
	v_mov_b32_e32 v1, v3
	v_mov_b32_e32 v5, v7
	v_pk_fma_f32 v[6:7], v[0:1], v[94:95], v[4:5]
	v_and_b32_sdwa v94, v104, v216 dst_sel:DWORD dst_unused:UNUSED_PAD src0_sel:WORD_1 src1_sel:DWORD
	v_add3_u32 v94, v104, v94, s84
	v_and_b32_e32 v95, 0xffff0000, v94
	v_and_b32_sdwa v94, v7, v216 dst_sel:DWORD dst_unused:UNUSED_PAD src0_sel:WORD_1 src1_sel:DWORD
	v_and_b32_sdwa v3, v105, v216 dst_sel:DWORD dst_unused:UNUSED_PAD src0_sel:WORD_1 src1_sel:DWORD
	v_and_b32_sdwa v103, v6, v216 dst_sel:DWORD dst_unused:UNUSED_PAD src0_sel:WORD_1 src1_sel:DWORD
	v_add3_u32 v94, v7, v94, s84
	v_add3_u32 v3, v105, v3, s84
	v_add3_u32 v103, v6, v103, s84
	v_and_b32_e32 v107, 0xffff0000, v94
	v_or_b32_sdwa v111, v107, v3 dst_sel:DWORD dst_unused:UNUSED_PAD src0_sel:DWORD src1_sel:WORD_1
	v_or_b32_sdwa v110, v103, v95 dst_sel:DWORD dst_unused:UNUSED_PAD src0_sel:WORD_1 src1_sel:DWORD
	v_and_b32_e32 v103, 0xffff0000, v103
	v_sub_u32_e32 v95, v104, v95
	v_and_b32_e32 v3, 0xffff0000, v3
	v_sub_u32_e32 v6, v6, v103
	v_add_u32_e32 v95, 0x80, v95
	v_sub_u32_e32 v3, v105, v3
	v_sub_u32_e32 v7, v7, v107
	v_add_u32_e32 v6, 0x80, v6
	v_ashrrev_i32_e32 v95, 8, v95
	v_add_u32_e32 v3, 0x80, v3
	v_add_u32_e32 v7, 0x80, v7
	v_ashrrev_i32_e32 v6, 8, v6
	v_min_i32_e32 v95, 0x7f, v95
	v_ashrrev_i32_e32 v3, 8, v3
	v_ashrrev_i32_e32 v7, 8, v7
	v_min_i32_e32 v6, 0x7f, v6
	v_min_i32_sdwa v3, v3, s85 dst_sel:WORD_1 dst_unused:UNUSED_PAD src0_sel:DWORD src1_sel:DWORD
	v_min_i32_e32 v7, 0x7f, v7
	v_lshlrev_b32_e32 v95, 8, v95
	v_or_b32_e32 v2, 0x120, v154
	v_and_b32_e32 v95, 0xff00, v95
	v_and_b32_e32 v3, 0xff0000, v3
	v_perm_b32 v6, v7, v6, s92
	v_add_u32_e32 v94, v2, v152
	v_or3_b32 v3, v6, v95, v3
	ds_write_b64 v94, v[110:111]
	ds_write_b32 v12, v3 offset:144
	v_mov_b32_e32 v6, v204
	v_mov_b32_e32 v7, v205
	v_pk_add_f32 v[100:101], v[100:101], v[6:7] op_sel_hi:[1,0] neg_lo:[0,1] neg_hi:[0,1]
	s_nop 0
	v_pk_mul_f32 v[100:101], v[6:7], v[100:101] op_sel:[1,0]
	v_pk_add_f32 v[96:97], v[96:97], v[6:7] op_sel_hi:[1,0] neg_lo:[0,1] neg_hi:[0,1]
	v_pk_fma_f32 v[100:101], v[88:89], v[100:101], v[90:91]
	v_pk_mul_f32 v[6:7], v[6:7], v[96:97] op_sel:[1,0]
	v_and_b32_sdwa v95, v100, v216 dst_sel:DWORD dst_unused:UNUSED_PAD src0_sel:WORD_1 src1_sel:DWORD
	v_pk_fma_f32 v[6:7], v[0:1], v[6:7], v[4:5]
	v_add3_u32 v95, v100, v95, s84
	v_and_b32_e32 v103, 0xffff0000, v95
	v_and_b32_sdwa v95, v7, v216 dst_sel:DWORD dst_unused:UNUSED_PAD src0_sel:WORD_1 src1_sel:DWORD
	v_and_b32_sdwa v3, v101, v216 dst_sel:DWORD dst_unused:UNUSED_PAD src0_sel:WORD_1 src1_sel:DWORD
; #define WAIT_L(n) asm volatile("s_waitcnt lgkmcnt(" #n ")" ::: "memory")
; #define BAR __builtin_amdgcn_s_barrier()
;     ...
;           _Pragma("unroll") for (int bj = 0; bj < 2; ++bj) _Pragma("unroll") for (int n = 0; n < 2; ++n) {
;             const int cc = bj * HALF + wc3 * 32 + n * 16 + fq3 * 4;
;             const float4 gm = *reinterpret_cast<const float4*>(g.gam + pn * BM + cc), bt = *reinterpret_cast<const float4*>(g.bet + pn * BM + cc);
;             _Pragma("unroll") for (int m = 0; m < 4; ++m) {
;               const int rr = wr3 * 64 + m * 16 + fr3;
;               const float2 ms = *reinterpret_cast<const float2*>(mr + (ai * HALF + rr) * 2);
;               f32x4 y = acc[ai][bj][m][n];
;               const float o0 = (y[0] - ms.x) * ms.y * gm.x + bt.x, o1 = (y[1] - ms.x) * ms.y * gm.y + bt.y;
;               const float o2 = (y[2] - ms.x) * ms.y * gm.z + bt.z, o3 = (y[3] - ms.x) * ms.y * gm.w + bt.w;
;               const unsigned h0 = f2bf(o0), h1 = f2bf(o1), h2 = f2bf(o2), h3 = f2bf(o3);
;               u32x2 ob; ob[0] = h0 | (h1 << 16); ob[1] = h2 | (h3 << 16);
;               *reinterpret_cast<u32x2*>(smem + (rr >> 1) * PIECE + (rr & 1) * 512 + cc * 2) = ob;
;               const int l0 = min(((int)__float_as_uint(o0) - (int)(h0 << 16) + 128) >> 8, 127);
;               const int l1 = min(((int)__float_as_uint(o1) - (int)(h1 << 16) + 128) >> 8, 127);
;               const int l2 = min(((int)__float_as_uint(o2) - (int)(h2 << 16) + 128) >> 8, 127);
;               const int l3 = min(((int)__float_as_uint(o3) - (int)(h3 << 16) + 128) >> 8, 127);
;               *reinterpret_cast<unsigned*>(smem + LOBASE + (rr >> 2) * PIECE + (rr & 3) * 256 + cc) =
;                   (unsigned)(l0 & 255) | ((unsigned)(l1 & 255) << 8) | ((unsigned)(l2 & 255) << 16) | ((unsigned)l3 << 24);
;             }
;           }
;           WAIT_L(0); BAR;
	v_and_b32_sdwa v96, v6, v216 dst_sel:DWORD dst_unused:UNUSED_PAD src0_sel:WORD_1 src1_sel:DWORD
	v_add3_u32 v95, v7, v95, s84
	v_add3_u32 v3, v101, v3, s84
	v_add3_u32 v104, v6, v96, s84
	v_and_b32_e32 v105, 0xffff0000, v95
	v_or_b32_sdwa v97, v105, v3 dst_sel:DWORD dst_unused:UNUSED_PAD src0_sel:DWORD src1_sel:WORD_1
	v_or_b32_sdwa v96, v104, v103 dst_sel:DWORD dst_unused:UNUSED_PAD src0_sel:WORD_1 src1_sel:DWORD
	v_add_u32_e32 v95, v2, v153
	ds_write_b64 v95, v[96:97]
	v_and_b32_e32 v96, 0xffff0000, v104
	v_sub_u32_e32 v6, v6, v96
	v_sub_u32_e32 v96, v100, v103
	v_and_b32_e32 v3, 0xffff0000, v3
	v_add_u32_e32 v96, 0x80, v96
	v_sub_u32_e32 v3, v101, v3
	v_sub_u32_e32 v7, v7, v105
	v_add_u32_e32 v6, 0x80, v6
	v_ashrrev_i32_e32 v96, 8, v96
	v_add_u32_e32 v3, 0x80, v3
	v_add_u32_e32 v7, 0x80, v7
	v_ashrrev_i32_e32 v6, 8, v6
	v_min_i32_e32 v96, 0x7f, v96
	v_ashrrev_i32_e32 v3, 8, v3
	v_ashrrev_i32_e32 v7, 8, v7
	v_min_i32_e32 v6, 0x7f, v6
	v_min_i32_sdwa v3, v3, s85 dst_sel:WORD_1 dst_unused:UNUSED_PAD src0_sel:DWORD src1_sel:DWORD
	v_min_i32_e32 v7, 0x7f, v7
	v_lshlrev_b32_e32 v96, 8, v96
	v_and_b32_e32 v96, 0xff00, v96
	v_and_b32_e32 v3, 0xff0000, v3
	v_perm_b32 v6, v7, v6, s92
	v_or3_b32 v3, v6, v96, v3
	ds_write_b32 v14, v3 offset:144
	v_mov_b32_e32 v6, v206
	v_mov_b32_e32 v7, v207
	v_pk_add_f32 v[84:85], v[84:85], v[6:7] op_sel_hi:[1,0] neg_lo:[0,1] neg_hi:[0,1]
	s_nop 0
	v_pk_mul_f32 v[84:85], v[6:7], v[84:85] op_sel:[1,0]
	v_pk_add_f32 v[80:81], v[80:81], v[6:7] op_sel_hi:[1,0] neg_lo:[0,1] neg_hi:[0,1]
	v_pk_fma_f32 v[84:85], v[88:89], v[84:85], v[90:91]
	v_pk_mul_f32 v[6:7], v[6:7], v[80:81] op_sel:[1,0]
	v_and_b32_sdwa v80, v84, v216 dst_sel:DWORD dst_unused:UNUSED_PAD src0_sel:WORD_1 src1_sel:DWORD
	v_pk_fma_f32 v[6:7], v[0:1], v[6:7], v[4:5]
	v_add3_u32 v80, v84, v80, s84
	v_and_b32_e32 v81, 0xffff0000, v80
	v_and_b32_sdwa v80, v7, v216 dst_sel:DWORD dst_unused:UNUSED_PAD src0_sel:WORD_1 src1_sel:DWORD
	v_and_b32_sdwa v3, v85, v216 dst_sel:DWORD dst_unused:UNUSED_PAD src0_sel:WORD_1 src1_sel:DWORD
	v_and_b32_sdwa v96, v6, v216 dst_sel:DWORD dst_unused:UNUSED_PAD src0_sel:WORD_1 src1_sel:DWORD
	v_add3_u32 v80, v7, v80, s84
	v_add3_u32 v3, v85, v3, s84
	v_add3_u32 v100, v6, v96, s84
	v_and_b32_e32 v101, 0xffff0000, v80
	v_or_b32_sdwa v97, v101, v3 dst_sel:DWORD dst_unused:UNUSED_PAD src0_sel:DWORD src1_sel:WORD_1
	v_or_b32_sdwa v96, v100, v81 dst_sel:DWORD dst_unused:UNUSED_PAD src0_sel:WORD_1 src1_sel:DWORD
	v_add_u32_e32 v80, v2, v137
	ds_write_b64 v80, v[96:97]
	v_and_b32_e32 v96, 0xffff0000, v100
	v_sub_u32_e32 v81, v84, v81
	v_and_b32_e32 v3, 0xffff0000, v3
	v_sub_u32_e32 v6, v6, v96
	v_add_u32_e32 v81, 0x80, v81
	v_sub_u32_e32 v3, v85, v3
	v_sub_u32_e32 v7, v7, v101
	v_add_u32_e32 v6, 0x80, v6
	v_ashrrev_i32_e32 v81, 8, v81
	v_add_u32_e32 v3, 0x80, v3
	v_add_u32_e32 v7, 0x80, v7
	v_ashrrev_i32_e32 v6, 8, v6
	v_min_i32_e32 v81, 0x7f, v81
	v_ashrrev_i32_e32 v3, 8, v3
	v_ashrrev_i32_e32 v7, 8, v7
	v_min_i32_e32 v6, 0x7f, v6
	v_min_i32_sdwa v3, v3, s85 dst_sel:WORD_1 dst_unused:UNUSED_PAD src0_sel:DWORD src1_sel:DWORD
	v_min_i32_e32 v7, 0x7f, v7
	v_lshlrev_b32_e32 v81, 8, v81
	v_and_b32_e32 v81, 0xff00, v81
	v_and_b32_e32 v3, 0xff0000, v3
	v_perm_b32 v6, v7, v6, s92
	v_or3_b32 v3, v6, v81, v3
	ds_write_b32 v18, v3 offset:144
	v_mov_b32_e32 v6, v208
	v_mov_b32_e32 v7, v209
	v_or_b32_e32 v81, 0x6000, v148
	v_or_b32_e32 v96, 0x6000, v146
	v_pk_add_f32 v[72:73], v[72:73], v[6:7] op_sel_hi:[1,0] neg_lo:[0,1] neg_hi:[0,1]
	s_nop 0
	v_pk_mul_f32 v[72:73], v[6:7], v[72:73] op_sel:[1,0]
	s_nop 0
	v_pk_fma_f32 v[84:85], v[88:89], v[72:73], v[90:91]
	v_pk_add_f32 v[72:73], v[74:75], v[6:7] op_sel_hi:[1,0] neg_lo:[0,1] neg_hi:[0,1]
	v_and_b32_sdwa v3, v85, v216 dst_sel:DWORD dst_unused:UNUSED_PAD src0_sel:WORD_1 src1_sel:DWORD
	v_pk_mul_f32 v[6:7], v[6:7], v[72:73] op_sel:[1,0]
	v_add3_u32 v3, v85, v3, s84
	v_pk_fma_f32 v[0:1], v[0:1], v[6:7], v[4:5]
	v_and_b32_sdwa v4, v84, v216 dst_sel:DWORD dst_unused:UNUSED_PAD src0_sel:WORD_1 src1_sel:DWORD
	v_add3_u32 v4, v84, v4, s84
	v_and_b32_e32 v6, 0xffff0000, v4
	v_and_b32_sdwa v4, v1, v216 dst_sel:DWORD dst_unused:UNUSED_PAD src0_sel:WORD_1 src1_sel:DWORD
	v_and_b32_sdwa v5, v0, v216 dst_sel:DWORD dst_unused:UNUSED_PAD src0_sel:WORD_1 src1_sel:DWORD
	v_add3_u32 v4, v1, v4, s84
	v_add3_u32 v7, v0, v5, s84
	v_and_b32_e32 v72, 0xffff0000, v4
	v_add_u32_e32 v73, v2, v136
	v_and_b32_e32 v2, 0xffff0000, v7
	v_or_b32_sdwa v5, v72, v3 dst_sel:DWORD dst_unused:UNUSED_PAD src0_sel:DWORD src1_sel:WORD_1
	v_sub_u32_e32 v0, v0, v2
	v_sub_u32_e32 v2, v84, v6
	v_and_b32_e32 v3, 0xffff0000, v3
	v_add_u32_e32 v2, 0x80, v2
	v_sub_u32_e32 v3, v85, v3
	v_sub_u32_e32 v1, v1, v72
	v_add_u32_e32 v0, 0x80, v0
	v_ashrrev_i32_e32 v2, 8, v2
	v_add_u32_e32 v3, 0x80, v3
	v_add_u32_e32 v1, 0x80, v1
	v_ashrrev_i32_e32 v0, 8, v0
	v_min_i32_e32 v2, 0x7f, v2
	v_ashrrev_i32_e32 v3, 8, v3
	v_ashrrev_i32_e32 v1, 8, v1
	v_min_i32_e32 v0, 0x7f, v0
	v_min_i32_sdwa v3, v3, s85 dst_sel:WORD_1 dst_unused:UNUSED_PAD src0_sel:DWORD src1_sel:DWORD
	v_min_i32_e32 v1, 0x7f, v1
	v_lshlrev_b32_e32 v2, 8, v2
	v_and_b32_e32 v2, 0xff00, v2
	v_and_b32_e32 v3, 0xff0000, v3
	v_perm_b32 v0, v1, v0, s92
	v_or_b32_sdwa v4, v7, v6 dst_sel:DWORD dst_unused:UNUSED_PAD src0_sel:WORD_1 src1_sel:DWORD
	v_or3_b32 v0, v0, v2, v3
	ds_write_b64 v73, v[4:5]
	ds_write_b32 v22, v0 offset:144
	v_add_u32_e32 v72, s2, v151
	s_waitcnt lgkmcnt(0)
	s_barrier
;     ...
;             _Pragma("unroll") for (int m = 0; m < 4; ++m) {
;               const int rr = wr3 * 64 + m * 16 + fr3;
;               const float2 ms = *reinterpret_cast<const float2*>(mr + (ai * HALF + rr) * 2);
;               f32x4 y = acc[ai][bj][m][n];
;               const float o0 = (y[0] - ms.x) * ms.y * gm.x + bt.x, o1 = (y[1] - ms.x) * ms.y * gm.y + bt.y;
;               const float o2 = (y[2] - ms.x) * ms.y * gm.z + bt.z, o3 = (y[3] - ms.x) * ms.y * gm.w + bt.w;
;               const unsigned h0 = f2bf(o0), h1 = f2bf(o1), h2 = f2bf(o2), h3 = f2bf(o3);
;               u32x2 ob; ob[0] = h0 | (h1 << 16); ob[1] = h2 | (h3 << 16);
;               *reinterpret_cast<u32x2*>(smem + (rr >> 1) * PIECE + (rr & 1) * 512 + cc * 2) = ob;
;               const int l0 = min(((int)__float_as_uint(o0) - (int)(h0 << 16) + 128) >> 8, 127);
;               const int l1 = min(((int)__float_as_uint(o1) - (int)(h1 << 16) + 128) >> 8, 127);
;               const int l2 = min(((int)__float_as_uint(o2) - (int)(h2 << 16) + 128) >> 8, 127);
;               const int l3 = min(((int)__float_as_uint(o3) - (int)(h3 << 16) + 128) >> 8, 127);
;               *reinterpret_cast<unsigned*>(smem + LOBASE + (rr >> 2) * PIECE + (rr & 3) * 256 + cc) =
;                   (unsigned)(l0 & 255) | ((unsigned)(l1 & 255) << 8) | ((unsigned)(l2 & 255) << 16) | ((unsigned)l3 << 24);
;             }
;     ...
;           const int hso = ((brow + ai * HALF + 16 * wave) * DM + pn * BM) * 2;
;           const int lso = (brow + ai * HALF + 16 * wave) * DM + pn * BM;
;           _Pragma("unroll") for (int i = 0; i < 8; ++i) {
;             const u32x4 v = *reinterpret_cast<const u32x4*>(smem + (wave * 8 + i) * PIECE + lane3 * 16);
;             __builtin_amdgcn_raw_buffer_store_b128(v, rsXB, hvo + i * (2 * DM * 2), hso, 0);
;           }
;           _Pragma("unroll") for (int i = 0; i < 4; ++i) {
;             const u32x4 v = *reinterpret_cast<const u32x4*>(smem + LOBASE + (wave * 4 + i) * PIECE + lane3 * 16);
;             __builtin_amdgcn_raw_buffer_store_b128(v, rsLO, lvo + i * (4 * DM), lso, 0);
;           }
	ds_read_b128 v[128:131], v72
	v_or_b32_e32 v74, 0x2000, v148
	v_or_b32_e32 v75, 0x4000, v148
	v_or_b32_e32 v84, 0x8000, v148
	v_or_b32_e32 v85, 0xa000, v148
	ds_read_b128 v[136:139], v72 offset:1040
	v_or_b32_e32 v88, 0xc000, v148
	v_or_b32_e32 v89, 0xe000, v148
	v_or_b32_e32 v90, 0x2000, v146
	v_or_b32_e32 v91, 0x4000, v146
	ds_read_b128 v[140:143], v72 offset:2080
	ds_read_b128 v[152:155], v72 offset:3120
	ds_read_b128 v[156:159], v72 offset:4160
	ds_read_b128 v[160:163], v72 offset:5200
	ds_read_b128 v[164:167], v72 offset:6240
	ds_read_b128 v[168:171], v72 offset:7280
	ds_read_b128 v[172:175], v147
	ds_read_b128 v[176:179], v147 offset:1040
	ds_read_b128 v[180:183], v147 offset:2080
	ds_read_b128 v[184:187], v147 offset:3120
	s_waitcnt lgkmcnt(0)
	s_barrier
	s_nop 1
	v_mov_b32_e32 v0, v220
	v_mov_b32_e32 v1, v221
	v_mov_b32_e32 v2, v222
	v_mov_b32_e32 v3, v223
	v_mov_b32_e32 v4, v236
	v_mov_b32_e32 v5, v237
	v_mov_b32_e32 v6, v238
	v_mov_b32_e32 v7, v239
	ds_read_b64 v[110:111], v149 offset:1024
	s_waitcnt lgkmcnt(0)
	v_mov_b32_e32 v210, v110
	v_mov_b32_e32 v211, v111
	v_pk_add_f32 v[64:65], v[64:65], v[110:111] op_sel_hi:[1,0] neg_lo:[0,1] neg_hi:[0,1]
	s_nop 0
	v_pk_mul_f32 v[64:65], v[110:111], v[64:65] op_sel:[1,0]
	v_pk_add_f32 v[66:67], v[66:67], v[110:111] op_sel_hi:[1,0] neg_lo:[0,1] neg_hi:[0,1]
	v_mov_b32_e32 v100, v1
	v_mov_b32_e32 v101, v2
	v_mov_b32_e32 v104, v5
	v_mov_b32_e32 v105, v6
	v_pk_fma_f32 v[64:65], v[100:101], v[64:65], v[104:105]
	v_pk_mul_f32 v[66:67], v[110:111], v[66:67] op_sel:[1,0]
	v_mov_b32_e32 v1, v3
	v_mov_b32_e32 v5, v7
	v_and_b32_sdwa v6, v65, v216 dst_sel:DWORD dst_unused:UNUSED_PAD src0_sel:WORD_1 src1_sel:DWORD
	v_and_b32_sdwa v7, v64, v216 dst_sel:DWORD dst_unused:UNUSED_PAD src0_sel:WORD_1 src1_sel:DWORD
	v_pk_fma_f32 v[2:3], v[0:1], v[66:67], v[4:5]
	v_add3_u32 v66, v65, v6, s84
	v_add3_u32 v6, v64, v7, s84
	v_and_b32_e32 v67, 0xffff0000, v6
	v_and_b32_sdwa v6, v3, v216 dst_sel:DWORD dst_unused:UNUSED_PAD src0_sel:WORD_1 src1_sel:DWORD
	v_and_b32_sdwa v7, v2, v216 dst_sel:DWORD dst_unused:UNUSED_PAD src0_sel:WORD_1 src1_sel:DWORD
	v_add3_u32 v6, v3, v6, s84
	v_add3_u32 v97, v2, v7, s84
	v_and_b32_e32 v103, 0xffff0000, v6
	v_or_b32_sdwa v7, v103, v66 dst_sel:DWORD dst_unused:UNUSED_PAD src0_sel:DWORD src1_sel:WORD_1
	v_or_b32_sdwa v6, v97, v67 dst_sel:DWORD dst_unused:UNUSED_PAD src0_sel:WORD_1 src1_sel:DWORD
	ds_write_b64 v132, v[6:7]
	v_and_b32_e32 v6, 0xffff0000, v97
	v_sub_u32_e32 v2, v2, v6
	v_sub_u32_e32 v6, v64, v67
	v_and_b32_e32 v7, 0xffff0000, v66
	v_add_u32_e32 v6, 0x80, v6
	v_sub_u32_e32 v7, v65, v7
	v_sub_u32_e32 v3, v3, v103
	v_add_u32_e32 v2, 0x80, v2
	v_ashrrev_i32_e32 v6, 8, v6
	v_add_u32_e32 v7, 0x80, v7
	v_add_u32_e32 v3, 0x80, v3
	v_ashrrev_i32_e32 v2, 8, v2
	v_min_i32_e32 v6, 0x7f, v6
	v_ashrrev_i32_e32 v7, 8, v7
	v_ashrrev_i32_e32 v3, 8, v3
	v_min_i32_e32 v2, 0x7f, v2
	v_min_i32_sdwa v7, v7, s85 dst_sel:WORD_1 dst_unused:UNUSED_PAD src0_sel:DWORD src1_sel:DWORD
	v_min_i32_e32 v3, 0x7f, v3
	v_lshlrev_b32_e32 v6, 8, v6
	v_and_b32_e32 v6, 0xff00, v6
	v_and_b32_e32 v7, 0xff0000, v7
	v_perm_b32 v2, v3, v2, s92
	v_or3_b32 v2, v2, v6, v7
	ds_write_b32 v12, v2
	buffer_store_dwordx4 v[128:131], v148, s[16:19], s41 offen
	ds_read_b64 v[2:3], v13 offset:1024
	s_waitcnt lgkmcnt(0)
	v_mov_b32_e32 v212, v2
	v_mov_b32_e32 v213, v3
	v_pk_add_f32 v[6:7], v[68:69], v[2:3] op_sel_hi:[1,0] neg_lo:[0,1] neg_hi:[0,1]
	s_nop 0
	v_pk_mul_f32 v[6:7], v[2:3], v[6:7] op_sel:[1,0]
	v_pk_add_f32 v[64:65], v[70:71], v[2:3] op_sel_hi:[1,0] neg_lo:[0,1] neg_hi:[0,1]
	v_pk_fma_f32 v[6:7], v[100:101], v[6:7], v[104:105]
	v_pk_mul_f32 v[2:3], v[2:3], v[64:65] op_sel:[1,0]
	v_and_b32_sdwa v64, v7, v216 dst_sel:DWORD dst_unused:UNUSED_PAD src0_sel:WORD_1 src1_sel:DWORD
	v_and_b32_sdwa v65, v6, v216 dst_sel:DWORD dst_unused:UNUSED_PAD src0_sel:WORD_1 src1_sel:DWORD
	v_pk_fma_f32 v[2:3], v[0:1], v[2:3], v[4:5]
	v_add3_u32 v66, v7, v64, s84
	v_add3_u32 v64, v6, v65, s84
	v_and_b32_e32 v67, 0xffff0000, v64
	v_and_b32_sdwa v64, v3, v216 dst_sel:DWORD dst_unused:UNUSED_PAD src0_sel:WORD_1 src1_sel:DWORD
	v_and_b32_sdwa v65, v2, v216 dst_sel:DWORD dst_unused:UNUSED_PAD src0_sel:WORD_1 src1_sel:DWORD
	v_add3_u32 v64, v3, v64, s84
	v_add3_u32 v68, v2, v65, s84
	v_and_b32_e32 v69, 0xffff0000, v64
	v_or_b32_sdwa v65, v69, v66 dst_sel:DWORD dst_unused:UNUSED_PAD src0_sel:DWORD src1_sel:WORD_1
	v_or_b32_sdwa v64, v68, v67 dst_sel:DWORD dst_unused:UNUSED_PAD src0_sel:WORD_1 src1_sel:DWORD
	ds_write_b64 v133, v[64:65]
	v_and_b32_e32 v64, 0xffff0000, v68
	v_sub_u32_e32 v2, v2, v64
	v_sub_u32_e32 v6, v6, v67
	v_and_b32_e32 v64, 0xffff0000, v66
	v_add_u32_e32 v6, 0x80, v6
	v_sub_u32_e32 v7, v7, v64
	v_sub_u32_e32 v3, v3, v69
	v_add_u32_e32 v2, 0x80, v2
	v_ashrrev_i32_e32 v6, 8, v6
	v_add_u32_e32 v7, 0x80, v7
	v_add_u32_e32 v3, 0x80, v3
	v_ashrrev_i32_e32 v2, 8, v2
	v_min_i32_e32 v6, 0x7f, v6
	v_ashrrev_i32_e32 v7, 8, v7
	v_ashrrev_i32_e32 v3, 8, v3
	v_min_i32_e32 v2, 0x7f, v2
	v_min_i32_sdwa v7, v7, s85 dst_sel:WORD_1 dst_unused:UNUSED_PAD src0_sel:DWORD src1_sel:DWORD
	v_min_i32_e32 v3, 0x7f, v3
	v_lshlrev_b32_e32 v6, 8, v6
	v_and_b32_e32 v6, 0xff00, v6
	v_and_b32_e32 v7, 0xff0000, v7
	v_perm_b32 v2, v3, v2, s92
	v_or3_b32 v2, v2, v6, v7
	ds_write_b32 v14, v2
	buffer_store_dwordx4 v[136:139], v74, s[16:19], s41 offen
	ds_read_b64 v[2:3], v15 offset:1024
	s_waitcnt lgkmcnt(0)
;     ...
;             _Pragma("unroll") for (int m = 0; m < 4; ++m) {
;               const int rr = wr3 * 64 + m * 16 + fr3;
;               const float2 ms = *reinterpret_cast<const float2*>(mr + (ai * HALF + rr) * 2);
;               f32x4 y = acc[ai][bj][m][n];
;               const float o0 = (y[0] - ms.x) * ms.y * gm.x + bt.x, o1 = (y[1] - ms.x) * ms.y * gm.y + bt.y;
;               const float o2 = (y[2] - ms.x) * ms.y * gm.z + bt.z, o3 = (y[3] - ms.x) * ms.y * gm.w + bt.w;
;               const unsigned h0 = f2bf(o0), h1 = f2bf(o1), h2 = f2bf(o2), h3 = f2bf(o3);
;               u32x2 ob; ob[0] = h0 | (h1 << 16); ob[1] = h2 | (h3 << 16);
;               *reinterpret_cast<u32x2*>(smem + (rr >> 1) * PIECE + (rr & 1) * 512 + cc * 2) = ob;
;               const int l0 = min(((int)__float_as_uint(o0) - (int)(h0 << 16) + 128) >> 8, 127);
;               const int l1 = min(((int)__float_as_uint(o1) - (int)(h1 << 16) + 128) >> 8, 127);
;               const int l2 = min(((int)__float_as_uint(o2) - (int)(h2 << 16) + 128) >> 8, 127);
;               const int l3 = min(((int)__float_as_uint(o3) - (int)(h3 << 16) + 128) >> 8, 127);
;               *reinterpret_cast<unsigned*>(smem + LOBASE + (rr >> 2) * PIECE + (rr & 3) * 256 + cc) =
;                   (unsigned)(l0 & 255) | ((unsigned)(l1 & 255) << 8) | ((unsigned)(l2 & 255) << 16) | ((unsigned)l3 << 24);
;             }
	v_mov_b32_e32 v214, v2
	v_mov_b32_e32 v215, v3
	v_pk_add_f32 v[6:7], v[76:77], v[2:3] op_sel_hi:[1,0] neg_lo:[0,1] neg_hi:[0,1]
	s_nop 0
	v_pk_mul_f32 v[6:7], v[2:3], v[6:7] op_sel:[1,0]
	v_pk_add_f32 v[64:65], v[78:79], v[2:3] op_sel_hi:[1,0] neg_lo:[0,1] neg_hi:[0,1]
	v_pk_fma_f32 v[6:7], v[100:101], v[6:7], v[104:105]
	v_pk_mul_f32 v[2:3], v[2:3], v[64:65] op_sel:[1,0]
	v_and_b32_sdwa v64, v7, v216 dst_sel:DWORD dst_unused:UNUSED_PAD src0_sel:WORD_1 src1_sel:DWORD
	v_and_b32_sdwa v65, v6, v216 dst_sel:DWORD dst_unused:UNUSED_PAD src0_sel:WORD_1 src1_sel:DWORD
	v_pk_fma_f32 v[2:3], v[0:1], v[2:3], v[4:5]
	v_add3_u32 v66, v7, v64, s84
	v_add3_u32 v64, v6, v65, s84
	v_and_b32_e32 v67, 0xffff0000, v64
	v_and_b32_sdwa v64, v3, v216 dst_sel:DWORD dst_unused:UNUSED_PAD src0_sel:WORD_1 src1_sel:DWORD
	v_and_b32_sdwa v65, v2, v216 dst_sel:DWORD dst_unused:UNUSED_PAD src0_sel:WORD_1 src1_sel:DWORD
	v_add3_u32 v64, v3, v64, s84
	v_add3_u32 v68, v2, v65, s84
	v_and_b32_e32 v69, 0xffff0000, v64
	v_or_b32_sdwa v65, v69, v66 dst_sel:DWORD dst_unused:UNUSED_PAD src0_sel:DWORD src1_sel:WORD_1
	v_or_b32_sdwa v64, v68, v67 dst_sel:DWORD dst_unused:UNUSED_PAD src0_sel:WORD_1 src1_sel:DWORD
	ds_write_b64 v134, v[64:65]
	v_and_b32_e32 v64, 0xffff0000, v68
	v_sub_u32_e32 v2, v2, v64
	v_sub_u32_e32 v6, v6, v67
	v_and_b32_e32 v64, 0xffff0000, v66
	v_add_u32_e32 v6, 0x80, v6
	v_sub_u32_e32 v7, v7, v64
	v_sub_u32_e32 v3, v3, v69
	v_add_u32_e32 v2, 0x80, v2
	v_ashrrev_i32_e32 v6, 8, v6
	v_add_u32_e32 v7, 0x80, v7
	v_add_u32_e32 v3, 0x80, v3
	v_ashrrev_i32_e32 v2, 8, v2
	v_min_i32_e32 v6, 0x7f, v6
	v_ashrrev_i32_e32 v7, 8, v7
	v_ashrrev_i32_e32 v3, 8, v3
	v_min_i32_e32 v2, 0x7f, v2
	v_min_i32_sdwa v7, v7, s85 dst_sel:WORD_1 dst_unused:UNUSED_PAD src0_sel:DWORD src1_sel:DWORD
	v_min_i32_e32 v3, 0x7f, v3
	v_lshlrev_b32_e32 v6, 8, v6
	v_and_b32_e32 v6, 0xff00, v6
	v_and_b32_e32 v7, 0xff0000, v7
	v_perm_b32 v2, v3, v2, s92
	v_or3_b32 v2, v2, v6, v7
	ds_write_b32 v18, v2
	buffer_store_dwordx4 v[140:143], v75, s[16:19], s41 offen
	ds_read_b64 v[2:3], v19 offset:1024
	s_waitcnt lgkmcnt(0)
	v_mov_b32_e32 v252, v2
	v_mov_b32_e32 v253, v3
	v_pk_add_f32 v[6:7], v[82:83], v[2:3] op_sel_hi:[1,0] neg_lo:[0,1] neg_hi:[0,1]
	s_nop 0
	v_pk_mul_f32 v[6:7], v[2:3], v[6:7] op_sel:[1,0]
	v_pk_add_f32 v[64:65], v[86:87], v[2:3] op_sel_hi:[1,0] neg_lo:[0,1] neg_hi:[0,1]
	v_pk_fma_f32 v[6:7], v[100:101], v[6:7], v[104:105]
	v_pk_mul_f32 v[2:3], v[2:3], v[64:65] op_sel:[1,0]
	s_nop 0
	v_pk_fma_f32 v[0:1], v[0:1], v[2:3], v[4:5]
	v_and_b32_sdwa v2, v7, v216 dst_sel:DWORD dst_unused:UNUSED_PAD src0_sel:WORD_1 src1_sel:DWORD
	v_and_b32_sdwa v3, v6, v216 dst_sel:DWORD dst_unused:UNUSED_PAD src0_sel:WORD_1 src1_sel:DWORD
	v_add3_u32 v4, v7, v2, s84
	v_add3_u32 v2, v6, v3, s84
	v_and_b32_e32 v5, 0xffff0000, v2
	v_and_b32_sdwa v2, v1, v216 dst_sel:DWORD dst_unused:UNUSED_PAD src0_sel:WORD_1 src1_sel:DWORD
	v_and_b32_sdwa v3, v0, v216 dst_sel:DWORD dst_unused:UNUSED_PAD src0_sel:WORD_1 src1_sel:DWORD
	v_add3_u32 v2, v1, v2, s84
	v_add3_u32 v64, v0, v3, s84
	v_and_b32_e32 v65, 0xffff0000, v2
	v_or_b32_sdwa v3, v65, v4 dst_sel:DWORD dst_unused:UNUSED_PAD src0_sel:DWORD src1_sel:WORD_1
	v_or_b32_sdwa v2, v64, v5 dst_sel:DWORD dst_unused:UNUSED_PAD src0_sel:WORD_1 src1_sel:DWORD
	ds_write_b64 v135, v[2:3]
	v_and_b32_e32 v2, 0xffff0000, v64
	v_sub_u32_e32 v0, v0, v2
	v_sub_u32_e32 v2, v6, v5
	v_and_b32_e32 v3, 0xffff0000, v4
	v_add_u32_e32 v2, 0x80, v2
	v_sub_u32_e32 v3, v7, v3
	v_sub_u32_e32 v1, v1, v65
	v_add_u32_e32 v0, 0x80, v0
	v_ashrrev_i32_e32 v2, 8, v2
	v_add_u32_e32 v3, 0x80, v3
	v_add_u32_e32 v1, 0x80, v1
	v_ashrrev_i32_e32 v0, 8, v0
	v_min_i32_e32 v2, 0x7f, v2
	v_ashrrev_i32_e32 v3, 8, v3
	v_ashrrev_i32_e32 v1, 8, v1
	v_min_i32_e32 v0, 0x7f, v0
	v_min_i32_sdwa v3, v3, s85 dst_sel:WORD_1 dst_unused:UNUSED_PAD src0_sel:DWORD src1_sel:DWORD
	v_min_i32_e32 v1, 0x7f, v1
	v_lshlrev_b32_e32 v2, 8, v2
	v_and_b32_e32 v2, 0xff00, v2
	v_and_b32_e32 v3, 0xff0000, v3
	v_perm_b32 v0, v1, v0, s92
	v_or3_b32 v0, v0, v2, v3
	ds_write_b32 v22, v0
	buffer_store_dwordx4 v[152:155], v81, s[16:19], s41 offen
	v_mov_b32_e32 v0, v224
	v_mov_b32_e32 v1, v225
	v_mov_b32_e32 v2, v226
	v_mov_b32_e32 v3, v227
	v_mov_b32_e32 v4, v240
	v_mov_b32_e32 v5, v241
	v_mov_b32_e32 v6, v242
	v_mov_b32_e32 v7, v243
	v_mov_b32_e32 v68, v210
	v_mov_b32_e32 v69, v211
	v_pk_add_f32 v[60:61], v[60:61], v[68:69] op_sel_hi:[1,0] neg_lo:[0,1] neg_hi:[0,1]
	s_nop 0
	v_pk_mul_f32 v[60:61], v[68:69], v[60:61] op_sel:[1,0]
	v_pk_add_f32 v[58:59], v[58:59], v[68:69] op_sel_hi:[1,0] neg_lo:[0,1] neg_hi:[0,1]
	v_mov_b32_e32 v64, v1
	v_mov_b32_e32 v65, v2
	v_mov_b32_e32 v66, v5
	v_mov_b32_e32 v67, v6
	v_pk_fma_f32 v[60:61], v[64:65], v[60:61], v[66:67]
	v_pk_mul_f32 v[58:59], v[68:69], v[58:59] op_sel:[1,0]
	v_mov_b32_e32 v1, v3
	v_mov_b32_e32 v5, v7
	v_and_b32_sdwa v6, v61, v216 dst_sel:DWORD dst_unused:UNUSED_PAD src0_sel:WORD_1 src1_sel:DWORD
	v_and_b32_sdwa v7, v60, v216 dst_sel:DWORD dst_unused:UNUSED_PAD src0_sel:WORD_1 src1_sel:DWORD
	v_pk_fma_f32 v[2:3], v[0:1], v[58:59], v[4:5]
	v_add3_u32 v58, v61, v6, s84
	v_add3_u32 v6, v60, v7, s84
	v_and_b32_e32 v59, 0xffff0000, v6
	v_and_b32_sdwa v6, v3, v216 dst_sel:DWORD dst_unused:UNUSED_PAD src0_sel:WORD_1 src1_sel:DWORD
	v_and_b32_sdwa v7, v2, v216 dst_sel:DWORD dst_unused:UNUSED_PAD src0_sel:WORD_1 src1_sel:DWORD
	v_add3_u32 v6, v3, v6, s84
	v_add3_u32 v68, v2, v7, s84
	v_and_b32_e32 v69, 0xffff0000, v6
	v_or_b32_sdwa v7, v69, v58 dst_sel:DWORD dst_unused:UNUSED_PAD src0_sel:DWORD src1_sel:WORD_1
	v_or_b32_sdwa v6, v68, v59 dst_sel:DWORD dst_unused:UNUSED_PAD src0_sel:WORD_1 src1_sel:DWORD
;     ...
;           _Pragma("unroll") for (int bj = 0; bj < 2; ++bj) _Pragma("unroll") for (int n = 0; n < 2; ++n) {
;             const int cc = bj * HALF + wc3 * 32 + n * 16 + fq3 * 4;
;             const float4 gm = *reinterpret_cast<const float4*>(g.gam + pn * BM + cc), bt = *reinterpret_cast<const float4*>(g.bet + pn * BM + cc);
;             _Pragma("unroll") for (int m = 0; m < 4; ++m) {
;               const int rr = wr3 * 64 + m * 16 + fr3;
;               const float2 ms = *reinterpret_cast<const float2*>(mr + (ai * HALF + rr) * 2);
;               f32x4 y = acc[ai][bj][m][n];
;               const float o0 = (y[0] - ms.x) * ms.y * gm.x + bt.x, o1 = (y[1] - ms.x) * ms.y * gm.y + bt.y;
;               const float o2 = (y[2] - ms.x) * ms.y * gm.z + bt.z, o3 = (y[3] - ms.x) * ms.y * gm.w + bt.w;
;               const unsigned h0 = f2bf(o0), h1 = f2bf(o1), h2 = f2bf(o2), h3 = f2bf(o3);
;               u32x2 ob; ob[0] = h0 | (h1 << 16); ob[1] = h2 | (h3 << 16);
;               *reinterpret_cast<u32x2*>(smem + (rr >> 1) * PIECE + (rr & 1) * 512 + cc * 2) = ob;
;               const int l0 = min(((int)__float_as_uint(o0) - (int)(h0 << 16) + 128) >> 8, 127);
;               const int l1 = min(((int)__float_as_uint(o1) - (int)(h1 << 16) + 128) >> 8, 127);
;               const int l2 = min(((int)__float_as_uint(o2) - (int)(h2 << 16) + 128) >> 8, 127);
;               const int l3 = min(((int)__float_as_uint(o3) - (int)(h3 << 16) + 128) >> 8, 127);
;               *reinterpret_cast<unsigned*>(smem + LOBASE + (rr >> 2) * PIECE + (rr & 3) * 256 + cc) =
;                   (unsigned)(l0 & 255) | ((unsigned)(l1 & 255) << 8) | ((unsigned)(l2 & 255) << 16) | ((unsigned)l3 << 24);
;             }
	ds_write_b64 v23, v[6:7]
	v_and_b32_e32 v6, 0xffff0000, v68
	v_sub_u32_e32 v2, v2, v6
	v_sub_u32_e32 v6, v60, v59
	v_and_b32_e32 v7, 0xffff0000, v58
	v_add_u32_e32 v6, 0x80, v6
	v_sub_u32_e32 v7, v61, v7
	v_sub_u32_e32 v3, v3, v69
	v_add_u32_e32 v2, 0x80, v2
	v_ashrrev_i32_e32 v6, 8, v6
	v_add_u32_e32 v7, 0x80, v7
	v_add_u32_e32 v3, 0x80, v3
	v_ashrrev_i32_e32 v2, 8, v2
	v_min_i32_e32 v6, 0x7f, v6
	v_ashrrev_i32_e32 v7, 8, v7
	v_ashrrev_i32_e32 v3, 8, v3
	v_min_i32_e32 v2, 0x7f, v2
	v_min_i32_sdwa v7, v7, s85 dst_sel:WORD_1 dst_unused:UNUSED_PAD src0_sel:DWORD src1_sel:DWORD
	v_min_i32_e32 v3, 0x7f, v3
	v_lshlrev_b32_e32 v6, 8, v6
	v_and_b32_e32 v6, 0xff00, v6
	v_and_b32_e32 v7, 0xff0000, v7
	v_perm_b32 v2, v3, v2, s92
	v_or3_b32 v2, v2, v6, v7
	ds_write_b32 v12, v2 offset:16
	buffer_store_dwordx4 v[156:159], v84, s[16:19], s41 offen
	v_mov_b32_e32 v2, v212
	v_mov_b32_e32 v3, v213
	v_pk_add_f32 v[6:7], v[44:45], v[2:3] op_sel_hi:[1,0] neg_lo:[0,1] neg_hi:[0,1]
	s_nop 0
	v_pk_mul_f32 v[6:7], v[2:3], v[6:7] op_sel:[1,0]
	v_pk_add_f32 v[42:43], v[42:43], v[2:3] op_sel_hi:[1,0] neg_lo:[0,1] neg_hi:[0,1]
	v_pk_fma_f32 v[6:7], v[64:65], v[6:7], v[66:67]
	v_pk_mul_f32 v[2:3], v[2:3], v[42:43] op_sel:[1,0]
	v_and_b32_sdwa v42, v6, v216 dst_sel:DWORD dst_unused:UNUSED_PAD src0_sel:WORD_1 src1_sel:DWORD
	v_pk_fma_f32 v[2:3], v[0:1], v[2:3], v[4:5]
	v_add3_u32 v42, v6, v42, s84
	v_and_b32_e32 v44, 0xffff0000, v42
	v_and_b32_sdwa v42, v3, v216 dst_sel:DWORD dst_unused:UNUSED_PAD src0_sel:WORD_1 src1_sel:DWORD
	v_and_b32_sdwa v23, v7, v216 dst_sel:DWORD dst_unused:UNUSED_PAD src0_sel:WORD_1 src1_sel:DWORD
	v_and_b32_sdwa v43, v2, v216 dst_sel:DWORD dst_unused:UNUSED_PAD src0_sel:WORD_1 src1_sel:DWORD
	v_add3_u32 v42, v3, v42, s84
	v_add3_u32 v23, v7, v23, s84
	v_add3_u32 v45, v2, v43, s84
	v_and_b32_e32 v58, 0xffff0000, v42
	v_or_b32_sdwa v43, v58, v23 dst_sel:DWORD dst_unused:UNUSED_PAD src0_sel:DWORD src1_sel:WORD_1
	v_or_b32_sdwa v42, v45, v44 dst_sel:DWORD dst_unused:UNUSED_PAD src0_sel:WORD_1 src1_sel:DWORD
	ds_write_b64 v108, v[42:43]
	v_and_b32_e32 v42, 0xffff0000, v45
	v_sub_u32_e32 v6, v6, v44
	v_and_b32_e32 v23, 0xffff0000, v23
	v_sub_u32_e32 v2, v2, v42
	v_add_u32_e32 v6, 0x80, v6
	v_sub_u32_e32 v7, v7, v23
	v_sub_u32_e32 v3, v3, v58
	v_add_u32_e32 v2, 0x80, v2
	v_ashrrev_i32_e32 v6, 8, v6
	v_add_u32_e32 v7, 0x80, v7
	v_add_u32_e32 v3, 0x80, v3
	v_ashrrev_i32_e32 v2, 8, v2
	v_min_i32_e32 v6, 0x7f, v6
	v_ashrrev_i32_e32 v7, 8, v7
	v_ashrrev_i32_e32 v3, 8, v3
	v_min_i32_e32 v2, 0x7f, v2
	v_min_i32_sdwa v7, v7, s85 dst_sel:WORD_1 dst_unused:UNUSED_PAD src0_sel:DWORD src1_sel:DWORD
	v_min_i32_e32 v3, 0x7f, v3
	v_lshlrev_b32_e32 v6, 8, v6
	v_and_b32_e32 v6, 0xff00, v6
	v_and_b32_e32 v7, 0xff0000, v7
	v_perm_b32 v2, v3, v2, s92
	v_or3_b32 v2, v2, v6, v7
	ds_write_b32 v14, v2 offset:16
	buffer_store_dwordx4 v[160:163], v85, s[16:19], s41 offen
	v_mov_b32_e32 v2, v214
	v_mov_b32_e32 v3, v215
	v_pk_add_f32 v[6:7], v[34:35], v[2:3] op_sel_hi:[1,0] neg_lo:[0,1] neg_hi:[0,1]
	s_nop 0
	v_pk_mul_f32 v[6:7], v[2:3], v[6:7] op_sel:[1,0]
	v_pk_add_f32 v[34:35], v[46:47], v[2:3] op_sel_hi:[1,0] neg_lo:[0,1] neg_hi:[0,1]
	v_pk_fma_f32 v[6:7], v[64:65], v[6:7], v[66:67]
	v_pk_mul_f32 v[2:3], v[2:3], v[34:35] op_sel:[1,0]
	v_and_b32_sdwa v34, v6, v216 dst_sel:DWORD dst_unused:UNUSED_PAD src0_sel:WORD_1 src1_sel:DWORD
	v_pk_fma_f32 v[2:3], v[0:1], v[2:3], v[4:5]
	v_add3_u32 v34, v6, v34, s84
	v_and_b32_e32 v42, 0xffff0000, v34
	v_and_b32_sdwa v34, v3, v216 dst_sel:DWORD dst_unused:UNUSED_PAD src0_sel:WORD_1 src1_sel:DWORD
	v_and_b32_sdwa v23, v7, v216 dst_sel:DWORD dst_unused:UNUSED_PAD src0_sel:WORD_1 src1_sel:DWORD
	v_and_b32_sdwa v35, v2, v216 dst_sel:DWORD dst_unused:UNUSED_PAD src0_sel:WORD_1 src1_sel:DWORD
	v_add3_u32 v34, v3, v34, s84
	v_add3_u32 v23, v7, v23, s84
	v_add3_u32 v43, v2, v35, s84
	v_and_b32_e32 v44, 0xffff0000, v34
	v_or_b32_sdwa v35, v44, v23 dst_sel:DWORD dst_unused:UNUSED_PAD src0_sel:DWORD src1_sel:WORD_1
	v_or_b32_sdwa v34, v43, v42 dst_sel:DWORD dst_unused:UNUSED_PAD src0_sel:WORD_1 src1_sel:DWORD
	ds_write_b64 v98, v[34:35]
	v_and_b32_e32 v34, 0xffff0000, v43
	v_sub_u32_e32 v6, v6, v42
	v_and_b32_e32 v23, 0xffff0000, v23
	v_sub_u32_e32 v2, v2, v34
	v_add_u32_e32 v6, 0x80, v6
	v_sub_u32_e32 v7, v7, v23
	v_sub_u32_e32 v3, v3, v44
	v_add_u32_e32 v2, 0x80, v2
	v_ashrrev_i32_e32 v6, 8, v6
	v_add_u32_e32 v7, 0x80, v7
	v_add_u32_e32 v3, 0x80, v3
	v_ashrrev_i32_e32 v2, 8, v2
	v_min_i32_e32 v6, 0x7f, v6
	v_ashrrev_i32_e32 v7, 8, v7
	v_ashrrev_i32_e32 v3, 8, v3
	v_min_i32_e32 v2, 0x7f, v2
	v_min_i32_sdwa v7, v7, s85 dst_sel:WORD_1 dst_unused:UNUSED_PAD src0_sel:DWORD src1_sel:DWORD
	v_min_i32_e32 v3, 0x7f, v3
	v_lshlrev_b32_e32 v6, 8, v6
	v_and_b32_e32 v6, 0xff00, v6
	v_and_b32_e32 v7, 0xff0000, v7
	v_perm_b32 v2, v3, v2, s92
	v_or3_b32 v2, v2, v6, v7
	ds_write_b32 v18, v2 offset:16
	buffer_store_dwordx4 v[164:167], v88, s[16:19], s41 offen
	v_mov_b32_e32 v2, v252
	v_mov_b32_e32 v3, v253
	v_pk_add_f32 v[6:7], v[50:51], v[2:3] op_sel_hi:[1,0] neg_lo:[0,1] neg_hi:[0,1]
	s_nop 0
	v_pk_mul_f32 v[6:7], v[2:3], v[6:7] op_sel:[1,0]
	v_pk_add_f32 v[34:35], v[62:63], v[2:3] op_sel_hi:[1,0] neg_lo:[0,1] neg_hi:[0,1]
	v_pk_fma_f32 v[6:7], v[64:65], v[6:7], v[66:67]
	v_pk_mul_f32 v[2:3], v[2:3], v[34:35] op_sel:[1,0]
	s_nop 0
	v_pk_fma_f32 v[0:1], v[0:1], v[2:3], v[4:5]
	v_and_b32_sdwa v2, v7, v216 dst_sel:DWORD dst_unused:UNUSED_PAD src0_sel:WORD_1 src1_sel:DWORD
	v_and_b32_sdwa v3, v6, v216 dst_sel:DWORD dst_unused:UNUSED_PAD src0_sel:WORD_1 src1_sel:DWORD
	v_add3_u32 v4, v7, v2, s84
	v_add3_u32 v2, v6, v3, s84
	v_and_b32_e32 v5, 0xffff0000, v2
;     ...
;           _Pragma("unroll") for (int bj = 0; bj < 2; ++bj) _Pragma("unroll") for (int n = 0; n < 2; ++n) {
;             const int cc = bj * HALF + wc3 * 32 + n * 16 + fq3 * 4;
;             const float4 gm = *reinterpret_cast<const float4*>(g.gam + pn * BM + cc), bt = *reinterpret_cast<const float4*>(g.bet + pn * BM + cc);
;             _Pragma("unroll") for (int m = 0; m < 4; ++m) {
;               const int rr = wr3 * 64 + m * 16 + fr3;
;               const float2 ms = *reinterpret_cast<const float2*>(mr + (ai * HALF + rr) * 2);
;               f32x4 y = acc[ai][bj][m][n];
;               const float o0 = (y[0] - ms.x) * ms.y * gm.x + bt.x, o1 = (y[1] - ms.x) * ms.y * gm.y + bt.y;
;               const float o2 = (y[2] - ms.x) * ms.y * gm.z + bt.z, o3 = (y[3] - ms.x) * ms.y * gm.w + bt.w;
;               const unsigned h0 = f2bf(o0), h1 = f2bf(o1), h2 = f2bf(o2), h3 = f2bf(o3);
;               u32x2 ob; ob[0] = h0 | (h1 << 16); ob[1] = h2 | (h3 << 16);
;               *reinterpret_cast<u32x2*>(smem + (rr >> 1) * PIECE + (rr & 1) * 512 + cc * 2) = ob;
;               const int l0 = min(((int)__float_as_uint(o0) - (int)(h0 << 16) + 128) >> 8, 127);
;               const int l1 = min(((int)__float_as_uint(o1) - (int)(h1 << 16) + 128) >> 8, 127);
;               const int l2 = min(((int)__float_as_uint(o2) - (int)(h2 << 16) + 128) >> 8, 127);
;               const int l3 = min(((int)__float_as_uint(o3) - (int)(h3 << 16) + 128) >> 8, 127);
;               *reinterpret_cast<unsigned*>(smem + LOBASE + (rr >> 2) * PIECE + (rr & 3) * 256 + cc) =
;                   (unsigned)(l0 & 255) | ((unsigned)(l1 & 255) << 8) | ((unsigned)(l2 & 255) << 16) | ((unsigned)l3 << 24);
;             }
	v_and_b32_sdwa v2, v1, v216 dst_sel:DWORD dst_unused:UNUSED_PAD src0_sel:WORD_1 src1_sel:DWORD
	v_and_b32_sdwa v3, v0, v216 dst_sel:DWORD dst_unused:UNUSED_PAD src0_sel:WORD_1 src1_sel:DWORD
	v_add3_u32 v2, v1, v2, s84
	v_add3_u32 v23, v0, v3, s84
	v_and_b32_e32 v34, 0xffff0000, v2
	v_or_b32_sdwa v3, v34, v4 dst_sel:DWORD dst_unused:UNUSED_PAD src0_sel:DWORD src1_sel:WORD_1
	v_or_b32_sdwa v2, v23, v5 dst_sel:DWORD dst_unused:UNUSED_PAD src0_sel:WORD_1 src1_sel:DWORD
	ds_write_b64 v99, v[2:3]
	v_and_b32_e32 v2, 0xffff0000, v23
	v_sub_u32_e32 v0, v0, v2
	v_sub_u32_e32 v2, v6, v5
	v_and_b32_e32 v3, 0xffff0000, v4
	v_add_u32_e32 v2, 0x80, v2
	v_sub_u32_e32 v3, v7, v3
	v_sub_u32_e32 v1, v1, v34
	v_add_u32_e32 v0, 0x80, v0
	v_ashrrev_i32_e32 v2, 8, v2
	v_add_u32_e32 v3, 0x80, v3
	v_add_u32_e32 v1, 0x80, v1
	v_ashrrev_i32_e32 v0, 8, v0
	v_min_i32_e32 v2, 0x7f, v2
	v_ashrrev_i32_e32 v3, 8, v3
	v_ashrrev_i32_e32 v1, 8, v1
	v_min_i32_e32 v0, 0x7f, v0
	v_min_i32_sdwa v3, v3, s85 dst_sel:WORD_1 dst_unused:UNUSED_PAD src0_sel:DWORD src1_sel:DWORD
	v_min_i32_e32 v1, 0x7f, v1
	v_lshlrev_b32_e32 v2, 8, v2
	v_and_b32_e32 v2, 0xff00, v2
	v_and_b32_e32 v3, 0xff0000, v3
	v_perm_b32 v0, v1, v0, s92
	v_or3_b32 v0, v0, v2, v3
	ds_write_b32 v22, v0 offset:16
	buffer_store_dwordx4 v[168:171], v89, s[16:19], s41 offen
	v_mov_b32_e32 v0, v228
	v_mov_b32_e32 v1, v229
	v_mov_b32_e32 v2, v230
	v_mov_b32_e32 v3, v231
	v_mov_b32_e32 v4, v244
	v_mov_b32_e32 v5, v245
	v_mov_b32_e32 v6, v246
	v_mov_b32_e32 v7, v247
	v_mov_b32_e32 v44, v210
	v_mov_b32_e32 v45, v211
	v_pk_add_f32 v[46:47], v[56:57], v[44:45] op_sel_hi:[1,0] neg_lo:[0,1] neg_hi:[0,1]
	s_nop 0
	v_pk_mul_f32 v[46:47], v[44:45], v[46:47] op_sel:[1,0]
	v_pk_add_f32 v[50:51], v[54:55], v[44:45] op_sel_hi:[1,0] neg_lo:[0,1] neg_hi:[0,1]
	v_mov_b32_e32 v34, v1
	v_mov_b32_e32 v35, v2
	v_mov_b32_e32 v42, v5
	v_mov_b32_e32 v43, v6
	v_pk_fma_f32 v[46:47], v[34:35], v[46:47], v[42:43]
	v_pk_mul_f32 v[44:45], v[44:45], v[50:51] op_sel:[1,0]
	v_mov_b32_e32 v1, v3
	v_mov_b32_e32 v5, v7
	v_and_b32_sdwa v6, v47, v216 dst_sel:DWORD dst_unused:UNUSED_PAD src0_sel:WORD_1 src1_sel:DWORD
	v_and_b32_sdwa v7, v46, v216 dst_sel:DWORD dst_unused:UNUSED_PAD src0_sel:WORD_1 src1_sel:DWORD
	v_pk_fma_f32 v[2:3], v[0:1], v[44:45], v[4:5]
	v_add3_u32 v23, v47, v6, s84
	v_add3_u32 v6, v46, v7, s84
	v_and_b32_e32 v44, 0xffff0000, v6
	v_and_b32_sdwa v6, v3, v216 dst_sel:DWORD dst_unused:UNUSED_PAD src0_sel:WORD_1 src1_sel:DWORD
	v_and_b32_sdwa v7, v2, v216 dst_sel:DWORD dst_unused:UNUSED_PAD src0_sel:WORD_1 src1_sel:DWORD
	v_add3_u32 v6, v3, v6, s84
	v_add3_u32 v45, v2, v7, s84
	v_and_b32_e32 v50, 0xffff0000, v6
	v_or_b32_sdwa v7, v50, v23 dst_sel:DWORD dst_unused:UNUSED_PAD src0_sel:DWORD src1_sel:WORD_1
	v_or_b32_sdwa v6, v45, v44 dst_sel:DWORD dst_unused:UNUSED_PAD src0_sel:WORD_1 src1_sel:DWORD
	ds_write_b64 v106, v[6:7]
	v_and_b32_e32 v6, 0xffff0000, v45
	v_sub_u32_e32 v2, v2, v6
	v_sub_u32_e32 v6, v46, v44
	v_and_b32_e32 v7, 0xffff0000, v23
	v_add_u32_e32 v6, 0x80, v6
	v_sub_u32_e32 v7, v47, v7
	v_sub_u32_e32 v3, v3, v50
	v_add_u32_e32 v2, 0x80, v2
	v_ashrrev_i32_e32 v6, 8, v6
	v_add_u32_e32 v7, 0x80, v7
	v_add_u32_e32 v3, 0x80, v3
	v_ashrrev_i32_e32 v2, 8, v2
	v_min_i32_e32 v6, 0x7f, v6
	v_ashrrev_i32_e32 v7, 8, v7
	v_ashrrev_i32_e32 v3, 8, v3
	v_min_i32_e32 v2, 0x7f, v2
	v_min_i32_sdwa v7, v7, s85 dst_sel:WORD_1 dst_unused:UNUSED_PAD src0_sel:DWORD src1_sel:DWORD
	v_min_i32_e32 v3, 0x7f, v3
	v_lshlrev_b32_e32 v6, 8, v6
	v_and_b32_e32 v6, 0xff00, v6
	v_and_b32_e32 v7, 0xff0000, v7
	v_perm_b32 v2, v3, v2, s92
	v_or3_b32 v2, v2, v6, v7
	ds_write_b32 v12, v2 offset:128
	buffer_store_dwordx4 v[172:175], v146, s[20:23], s1 offen
	v_mov_b32_e32 v2, v212
	v_mov_b32_e32 v3, v213
	v_pk_add_f32 v[6:7], v[40:41], v[2:3] op_sel_hi:[1,0] neg_lo:[0,1] neg_hi:[0,1]
	s_nop 0
	v_pk_mul_f32 v[6:7], v[2:3], v[6:7] op_sel:[1,0]
	v_pk_add_f32 v[38:39], v[38:39], v[2:3] op_sel_hi:[1,0] neg_lo:[0,1] neg_hi:[0,1]
	v_pk_fma_f32 v[6:7], v[34:35], v[6:7], v[42:43]
	v_pk_mul_f32 v[2:3], v[2:3], v[38:39] op_sel:[1,0]
	v_and_b32_sdwa v38, v6, v216 dst_sel:DWORD dst_unused:UNUSED_PAD src0_sel:WORD_1 src1_sel:DWORD
	v_pk_fma_f32 v[2:3], v[0:1], v[2:3], v[4:5]
	v_add3_u32 v38, v6, v38, s84
	v_and_b32_e32 v40, 0xffff0000, v38
	v_and_b32_sdwa v38, v3, v216 dst_sel:DWORD dst_unused:UNUSED_PAD src0_sel:WORD_1 src1_sel:DWORD
	v_and_b32_sdwa v23, v7, v216 dst_sel:DWORD dst_unused:UNUSED_PAD src0_sel:WORD_1 src1_sel:DWORD
	v_and_b32_sdwa v39, v2, v216 dst_sel:DWORD dst_unused:UNUSED_PAD src0_sel:WORD_1 src1_sel:DWORD
	v_add3_u32 v38, v3, v38, s84
	v_add3_u32 v23, v7, v23, s84
	v_add3_u32 v41, v2, v39, s84
	v_and_b32_e32 v44, 0xffff0000, v38
	v_or_b32_sdwa v39, v44, v23 dst_sel:DWORD dst_unused:UNUSED_PAD src0_sel:DWORD src1_sel:WORD_1
	v_or_b32_sdwa v38, v41, v40 dst_sel:DWORD dst_unused:UNUSED_PAD src0_sel:WORD_1 src1_sel:DWORD
	ds_write_b64 v102, v[38:39]
	v_and_b32_e32 v38, 0xffff0000, v41
	v_sub_u32_e32 v6, v6, v40
	v_and_b32_e32 v23, 0xffff0000, v23
	v_sub_u32_e32 v2, v2, v38
	v_add_u32_e32 v6, 0x80, v6
	v_sub_u32_e32 v7, v7, v23
	v_sub_u32_e32 v3, v3, v44
	v_add_u32_e32 v2, 0x80, v2
	v_ashrrev_i32_e32 v6, 8, v6
	v_add_u32_e32 v7, 0x80, v7
	v_add_u32_e32 v3, 0x80, v3
	v_ashrrev_i32_e32 v2, 8, v2
	v_min_i32_e32 v6, 0x7f, v6
	v_ashrrev_i32_e32 v7, 8, v7
	v_ashrrev_i32_e32 v3, 8, v3
	v_min_i32_e32 v2, 0x7f, v2
	v_min_i32_sdwa v7, v7, s85 dst_sel:WORD_1 dst_unused:UNUSED_PAD src0_sel:DWORD src1_sel:DWORD
	v_min_i32_e32 v3, 0x7f, v3
	v_lshlrev_b32_e32 v6, 8, v6
	v_and_b32_e32 v6, 0xff00, v6
	v_and_b32_e32 v7, 0xff0000, v7
	v_perm_b32 v2, v3, v2, s92
	v_or3_b32 v2, v2, v6, v7
;     ...
;           _Pragma("unroll") for (int bj = 0; bj < 2; ++bj) _Pragma("unroll") for (int n = 0; n < 2; ++n) {
;             const int cc = bj * HALF + wc3 * 32 + n * 16 + fq3 * 4;
;             const float4 gm = *reinterpret_cast<const float4*>(g.gam + pn * BM + cc), bt = *reinterpret_cast<const float4*>(g.bet + pn * BM + cc);
;             _Pragma("unroll") for (int m = 0; m < 4; ++m) {
;               const int rr = wr3 * 64 + m * 16 + fr3;
;               const float2 ms = *reinterpret_cast<const float2*>(mr + (ai * HALF + rr) * 2);
;               f32x4 y = acc[ai][bj][m][n];
;               const float o0 = (y[0] - ms.x) * ms.y * gm.x + bt.x, o1 = (y[1] - ms.x) * ms.y * gm.y + bt.y;
;               const float o2 = (y[2] - ms.x) * ms.y * gm.z + bt.z, o3 = (y[3] - ms.x) * ms.y * gm.w + bt.w;
;               const unsigned h0 = f2bf(o0), h1 = f2bf(o1), h2 = f2bf(o2), h3 = f2bf(o3);
;               u32x2 ob; ob[0] = h0 | (h1 << 16); ob[1] = h2 | (h3 << 16);
;               *reinterpret_cast<u32x2*>(smem + (rr >> 1) * PIECE + (rr & 1) * 512 + cc * 2) = ob;
;               const int l0 = min(((int)__float_as_uint(o0) - (int)(h0 << 16) + 128) >> 8, 127);
;               const int l1 = min(((int)__float_as_uint(o1) - (int)(h1 << 16) + 128) >> 8, 127);
;               const int l2 = min(((int)__float_as_uint(o2) - (int)(h2 << 16) + 128) >> 8, 127);
;               const int l3 = min(((int)__float_as_uint(o3) - (int)(h3 << 16) + 128) >> 8, 127);
;               *reinterpret_cast<unsigned*>(smem + LOBASE + (rr >> 2) * PIECE + (rr & 3) * 256 + cc) =
;                   (unsigned)(l0 & 255) | ((unsigned)(l1 & 255) << 8) | ((unsigned)(l2 & 255) << 16) | ((unsigned)l3 << 24);
;             }
	ds_write_b32 v14, v2 offset:128
	buffer_store_dwordx4 v[176:179], v90, s[20:23], s1 offen
	v_mov_b32_e32 v2, v214
	v_mov_b32_e32 v3, v215
	v_pk_add_f32 v[6:7], v[24:25], v[2:3] op_sel_hi:[1,0] neg_lo:[0,1] neg_hi:[0,1]
	s_nop 0
	v_pk_mul_f32 v[6:7], v[2:3], v[6:7] op_sel:[1,0]
	v_pk_add_f32 v[24:25], v[26:27], v[2:3] op_sel_hi:[1,0] neg_lo:[0,1] neg_hi:[0,1]
	v_pk_fma_f32 v[6:7], v[34:35], v[6:7], v[42:43]
	v_pk_mul_f32 v[2:3], v[2:3], v[24:25] op_sel:[1,0]
	v_and_b32_sdwa v24, v6, v216 dst_sel:DWORD dst_unused:UNUSED_PAD src0_sel:WORD_1 src1_sel:DWORD
	v_pk_fma_f32 v[2:3], v[0:1], v[2:3], v[4:5]
	v_add3_u32 v24, v6, v24, s84
	v_and_b32_e32 v26, 0xffff0000, v24
	v_and_b32_sdwa v24, v3, v216 dst_sel:DWORD dst_unused:UNUSED_PAD src0_sel:WORD_1 src1_sel:DWORD
	v_and_b32_sdwa v23, v7, v216 dst_sel:DWORD dst_unused:UNUSED_PAD src0_sel:WORD_1 src1_sel:DWORD
	v_and_b32_sdwa v25, v2, v216 dst_sel:DWORD dst_unused:UNUSED_PAD src0_sel:WORD_1 src1_sel:DWORD
	v_add3_u32 v24, v3, v24, s84
	v_add3_u32 v23, v7, v23, s84
	v_add3_u32 v27, v2, v25, s84
	v_and_b32_e32 v38, 0xffff0000, v24
	v_or_b32_sdwa v25, v38, v23 dst_sel:DWORD dst_unused:UNUSED_PAD src0_sel:DWORD src1_sel:WORD_1
	v_or_b32_sdwa v24, v27, v26 dst_sel:DWORD dst_unused:UNUSED_PAD src0_sel:WORD_1 src1_sel:DWORD
	ds_write_b64 v92, v[24:25]
	v_and_b32_e32 v24, 0xffff0000, v27
	v_sub_u32_e32 v6, v6, v26
	v_and_b32_e32 v23, 0xffff0000, v23
	v_sub_u32_e32 v2, v2, v24
	v_add_u32_e32 v6, 0x80, v6
	v_sub_u32_e32 v7, v7, v23
	v_sub_u32_e32 v3, v3, v38
	v_add_u32_e32 v2, 0x80, v2
	v_ashrrev_i32_e32 v6, 8, v6
	v_add_u32_e32 v7, 0x80, v7
	v_add_u32_e32 v3, 0x80, v3
	v_ashrrev_i32_e32 v2, 8, v2
	v_min_i32_e32 v6, 0x7f, v6
	v_ashrrev_i32_e32 v7, 8, v7
	v_ashrrev_i32_e32 v3, 8, v3
	v_min_i32_e32 v2, 0x7f, v2
	v_min_i32_sdwa v7, v7, s85 dst_sel:WORD_1 dst_unused:UNUSED_PAD src0_sel:DWORD src1_sel:DWORD
	v_min_i32_e32 v3, 0x7f, v3
	v_lshlrev_b32_e32 v6, 8, v6
	v_and_b32_e32 v6, 0xff00, v6
	v_and_b32_e32 v7, 0xff0000, v7
	v_perm_b32 v2, v3, v2, s92
	v_or3_b32 v2, v2, v6, v7
	ds_write_b32 v18, v2 offset:128
	buffer_store_dwordx4 v[180:183], v91, s[20:23], s1 offen
	v_mov_b32_e32 v2, v252
	v_mov_b32_e32 v3, v253
	v_pk_add_f32 v[6:7], v[28:29], v[2:3] op_sel_hi:[1,0] neg_lo:[0,1] neg_hi:[0,1]
	s_nop 0
	v_pk_mul_f32 v[6:7], v[2:3], v[6:7] op_sel:[1,0]
	v_pk_add_f32 v[24:25], v[30:31], v[2:3] op_sel_hi:[1,0] neg_lo:[0,1] neg_hi:[0,1]
	v_pk_fma_f32 v[6:7], v[34:35], v[6:7], v[42:43]
	v_pk_mul_f32 v[2:3], v[2:3], v[24:25] op_sel:[1,0]
	s_nop 0
	v_pk_fma_f32 v[0:1], v[0:1], v[2:3], v[4:5]
	v_and_b32_sdwa v2, v7, v216 dst_sel:DWORD dst_unused:UNUSED_PAD src0_sel:WORD_1 src1_sel:DWORD
	v_and_b32_sdwa v3, v6, v216 dst_sel:DWORD dst_unused:UNUSED_PAD src0_sel:WORD_1 src1_sel:DWORD
	v_add3_u32 v4, v7, v2, s84
	v_add3_u32 v2, v6, v3, s84
	v_and_b32_e32 v5, 0xffff0000, v2
	v_and_b32_sdwa v2, v1, v216 dst_sel:DWORD dst_unused:UNUSED_PAD src0_sel:WORD_1 src1_sel:DWORD
	v_and_b32_sdwa v3, v0, v216 dst_sel:DWORD dst_unused:UNUSED_PAD src0_sel:WORD_1 src1_sel:DWORD
	v_add3_u32 v2, v1, v2, s84
	v_add3_u32 v23, v0, v3, s84
	v_and_b32_e32 v24, 0xffff0000, v2
	v_or_b32_sdwa v3, v24, v4 dst_sel:DWORD dst_unused:UNUSED_PAD src0_sel:DWORD src1_sel:WORD_1
	v_or_b32_sdwa v2, v23, v5 dst_sel:DWORD dst_unused:UNUSED_PAD src0_sel:WORD_1 src1_sel:DWORD
	ds_write_b64 v93, v[2:3]
	v_and_b32_e32 v2, 0xffff0000, v23
	v_sub_u32_e32 v0, v0, v2
	v_sub_u32_e32 v2, v6, v5
	v_and_b32_e32 v3, 0xffff0000, v4
	v_add_u32_e32 v2, 0x80, v2
	v_sub_u32_e32 v3, v7, v3
	v_sub_u32_e32 v1, v1, v24
	v_add_u32_e32 v0, 0x80, v0
	v_ashrrev_i32_e32 v2, 8, v2
	v_add_u32_e32 v3, 0x80, v3
	v_add_u32_e32 v1, 0x80, v1
	v_ashrrev_i32_e32 v0, 8, v0
	v_min_i32_e32 v2, 0x7f, v2
	v_ashrrev_i32_e32 v3, 8, v3
	v_ashrrev_i32_e32 v1, 8, v1
	v_min_i32_e32 v0, 0x7f, v0
	v_min_i32_sdwa v3, v3, s85 dst_sel:WORD_1 dst_unused:UNUSED_PAD src0_sel:DWORD src1_sel:DWORD
	v_min_i32_e32 v1, 0x7f, v1
	v_lshlrev_b32_e32 v2, 8, v2
	v_and_b32_e32 v2, 0xff00, v2
	v_and_b32_e32 v3, 0xff0000, v3
	v_perm_b32 v0, v1, v0, s92
	v_or3_b32 v0, v0, v2, v3
	ds_write_b32 v22, v0 offset:128
	buffer_store_dwordx4 v[184:187], v96, s[20:23], s1 offen
	v_mov_b32_e32 v0, v232
	v_mov_b32_e32 v1, v233
	v_mov_b32_e32 v2, v234
	v_mov_b32_e32 v3, v235
	v_mov_b32_e32 v4, v248
	v_mov_b32_e32 v5, v249
	v_mov_b32_e32 v6, v250
	v_mov_b32_e32 v7, v251
	v_mov_b32_e32 v28, v210
	v_mov_b32_e32 v29, v211
	s_mov_b64 s[4:5], -1
	v_pk_add_f32 v[30:31], v[52:53], v[28:29] op_sel_hi:[1,0] neg_lo:[0,1] neg_hi:[0,1]
	s_nop 0
	v_pk_mul_f32 v[30:31], v[28:29], v[30:31] op_sel:[1,0]
	v_pk_add_f32 v[34:35], v[48:49], v[28:29] op_sel_hi:[1,0] neg_lo:[0,1] neg_hi:[0,1]
	v_mov_b32_e32 v24, v1
	v_mov_b32_e32 v25, v2
	v_mov_b32_e32 v26, v5
	v_mov_b32_e32 v27, v6
	v_pk_fma_f32 v[30:31], v[24:25], v[30:31], v[26:27]
	v_pk_mul_f32 v[28:29], v[28:29], v[34:35] op_sel:[1,0]
	v_mov_b32_e32 v1, v3
	v_mov_b32_e32 v5, v7
	v_and_b32_sdwa v6, v31, v216 dst_sel:DWORD dst_unused:UNUSED_PAD src0_sel:WORD_1 src1_sel:DWORD
	v_and_b32_sdwa v7, v30, v216 dst_sel:DWORD dst_unused:UNUSED_PAD src0_sel:WORD_1 src1_sel:DWORD
	v_pk_fma_f32 v[2:3], v[0:1], v[28:29], v[4:5]
	v_add3_u32 v23, v31, v6, s84
	v_add3_u32 v6, v30, v7, s84
	v_and_b32_e32 v28, 0xffff0000, v6
	v_and_b32_sdwa v6, v3, v216 dst_sel:DWORD dst_unused:UNUSED_PAD src0_sel:WORD_1 src1_sel:DWORD
	v_and_b32_sdwa v7, v2, v216 dst_sel:DWORD dst_unused:UNUSED_PAD src0_sel:WORD_1 src1_sel:DWORD
	v_add3_u32 v6, v3, v6, s84
	v_add3_u32 v29, v2, v7, s84
	v_and_b32_e32 v34, 0xffff0000, v6
	v_or_b32_sdwa v7, v34, v23 dst_sel:DWORD dst_unused:UNUSED_PAD src0_sel:DWORD src1_sel:WORD_1
; #define WAIT_L(n) asm volatile("s_waitcnt lgkmcnt(" #n ")" ::: "memory")
; #define BAR __builtin_amdgcn_s_barrier()
;     ...
;           _Pragma("unroll") for (int bj = 0; bj < 2; ++bj) _Pragma("unroll") for (int n = 0; n < 2; ++n) {
;             const int cc = bj * HALF + wc3 * 32 + n * 16 + fq3 * 4;
;             const float4 gm = *reinterpret_cast<const float4*>(g.gam + pn * BM + cc), bt = *reinterpret_cast<const float4*>(g.bet + pn * BM + cc);
;             _Pragma("unroll") for (int m = 0; m < 4; ++m) {
;               const int rr = wr3 * 64 + m * 16 + fr3;
;               const float2 ms = *reinterpret_cast<const float2*>(mr + (ai * HALF + rr) * 2);
;               f32x4 y = acc[ai][bj][m][n];
;               const float o0 = (y[0] - ms.x) * ms.y * gm.x + bt.x, o1 = (y[1] - ms.x) * ms.y * gm.y + bt.y;
;               const float o2 = (y[2] - ms.x) * ms.y * gm.z + bt.z, o3 = (y[3] - ms.x) * ms.y * gm.w + bt.w;
;               const unsigned h0 = f2bf(o0), h1 = f2bf(o1), h2 = f2bf(o2), h3 = f2bf(o3);
;               u32x2 ob; ob[0] = h0 | (h1 << 16); ob[1] = h2 | (h3 << 16);
;               *reinterpret_cast<u32x2*>(smem + (rr >> 1) * PIECE + (rr & 1) * 512 + cc * 2) = ob;
;               const int l0 = min(((int)__float_as_uint(o0) - (int)(h0 << 16) + 128) >> 8, 127);
;               const int l1 = min(((int)__float_as_uint(o1) - (int)(h1 << 16) + 128) >> 8, 127);
;               const int l2 = min(((int)__float_as_uint(o2) - (int)(h2 << 16) + 128) >> 8, 127);
;               const int l3 = min(((int)__float_as_uint(o3) - (int)(h3 << 16) + 128) >> 8, 127);
;               *reinterpret_cast<unsigned*>(smem + LOBASE + (rr >> 2) * PIECE + (rr & 3) * 256 + cc) =
;                   (unsigned)(l0 & 255) | ((unsigned)(l1 & 255) << 8) | ((unsigned)(l2 & 255) << 16) | ((unsigned)l3 << 24);
;             }
;           }
;           WAIT_L(0); BAR;
	v_or_b32_sdwa v6, v29, v28 dst_sel:DWORD dst_unused:UNUSED_PAD src0_sel:WORD_1 src1_sel:DWORD
	ds_write_b64 v94, v[6:7]
	v_and_b32_e32 v6, 0xffff0000, v29
	v_sub_u32_e32 v2, v2, v6
	v_sub_u32_e32 v6, v30, v28
	v_and_b32_e32 v7, 0xffff0000, v23
	v_add_u32_e32 v6, 0x80, v6
	v_sub_u32_e32 v7, v31, v7
	v_sub_u32_e32 v3, v3, v34
	v_add_u32_e32 v2, 0x80, v2
	v_ashrrev_i32_e32 v6, 8, v6
	v_add_u32_e32 v7, 0x80, v7
	v_add_u32_e32 v3, 0x80, v3
	v_ashrrev_i32_e32 v2, 8, v2
	v_min_i32_e32 v6, 0x7f, v6
	v_ashrrev_i32_e32 v7, 8, v7
	v_ashrrev_i32_e32 v3, 8, v3
	v_min_i32_e32 v2, 0x7f, v2
	v_min_i32_sdwa v7, v7, s85 dst_sel:WORD_1 dst_unused:UNUSED_PAD src0_sel:DWORD src1_sel:DWORD
	v_min_i32_e32 v3, 0x7f, v3
	v_lshlrev_b32_e32 v6, 8, v6
	v_and_b32_e32 v6, 0xff00, v6
	v_and_b32_e32 v7, 0xff0000, v7
	v_perm_b32 v2, v3, v2, s92
	v_or3_b32 v2, v2, v6, v7
	ds_write_b32 v12, v2 offset:144
	v_mov_b32_e32 v2, v212
	v_mov_b32_e32 v3, v213
	v_pk_add_f32 v[6:7], v[36:37], v[2:3] op_sel_hi:[1,0] neg_lo:[0,1] neg_hi:[0,1]
	s_nop 0
	v_pk_mul_f32 v[6:7], v[2:3], v[6:7] op_sel:[1,0]
	v_pk_add_f32 v[12:13], v[32:33], v[2:3] op_sel_hi:[1,0] neg_lo:[0,1] neg_hi:[0,1]
	v_pk_fma_f32 v[6:7], v[24:25], v[6:7], v[26:27]
	v_pk_mul_f32 v[2:3], v[2:3], v[12:13] op_sel:[1,0]
	v_and_b32_sdwa v12, v7, v216 dst_sel:DWORD dst_unused:UNUSED_PAD src0_sel:WORD_1 src1_sel:DWORD
	v_and_b32_sdwa v13, v6, v216 dst_sel:DWORD dst_unused:UNUSED_PAD src0_sel:WORD_1 src1_sel:DWORD
	v_pk_fma_f32 v[2:3], v[0:1], v[2:3], v[4:5]
	v_add3_u32 v23, v7, v12, s84
	v_add3_u32 v12, v6, v13, s84
	v_and_b32_e32 v28, 0xffff0000, v12
	v_and_b32_sdwa v12, v3, v216 dst_sel:DWORD dst_unused:UNUSED_PAD src0_sel:WORD_1 src1_sel:DWORD
	v_and_b32_sdwa v13, v2, v216 dst_sel:DWORD dst_unused:UNUSED_PAD src0_sel:WORD_1 src1_sel:DWORD
	v_add3_u32 v12, v3, v12, s84
	v_add3_u32 v29, v2, v13, s84
	v_and_b32_e32 v30, 0xffff0000, v12
	v_or_b32_sdwa v13, v30, v23 dst_sel:DWORD dst_unused:UNUSED_PAD src0_sel:DWORD src1_sel:WORD_1
	v_or_b32_sdwa v12, v29, v28 dst_sel:DWORD dst_unused:UNUSED_PAD src0_sel:WORD_1 src1_sel:DWORD
	ds_write_b64 v95, v[12:13]
	v_and_b32_e32 v12, 0xffff0000, v29
	v_sub_u32_e32 v2, v2, v12
	v_sub_u32_e32 v6, v6, v28
	v_and_b32_e32 v12, 0xffff0000, v23
	v_add_u32_e32 v6, 0x80, v6
	v_sub_u32_e32 v7, v7, v12
	v_sub_u32_e32 v3, v3, v30
	v_add_u32_e32 v2, 0x80, v2
	v_ashrrev_i32_e32 v6, 8, v6
	v_add_u32_e32 v7, 0x80, v7
	v_add_u32_e32 v3, 0x80, v3
	v_ashrrev_i32_e32 v2, 8, v2
	v_min_i32_e32 v6, 0x7f, v6
	v_ashrrev_i32_e32 v7, 8, v7
	v_ashrrev_i32_e32 v3, 8, v3
	v_min_i32_e32 v2, 0x7f, v2
	v_min_i32_sdwa v7, v7, s85 dst_sel:WORD_1 dst_unused:UNUSED_PAD src0_sel:DWORD src1_sel:DWORD
	v_min_i32_e32 v3, 0x7f, v3
	v_lshlrev_b32_e32 v6, 8, v6
	v_and_b32_e32 v6, 0xff00, v6
	v_and_b32_e32 v7, 0xff0000, v7
	v_perm_b32 v2, v3, v2, s92
	v_or3_b32 v2, v2, v6, v7
	ds_write_b32 v14, v2 offset:144
	v_mov_b32_e32 v2, v214
	v_mov_b32_e32 v3, v215
	v_pk_add_f32 v[6:7], v[20:21], v[2:3] op_sel_hi:[1,0] neg_lo:[0,1] neg_hi:[0,1]
	s_nop 0
	v_pk_mul_f32 v[6:7], v[2:3], v[6:7] op_sel:[1,0]
	v_pk_add_f32 v[12:13], v[16:17], v[2:3] op_sel_hi:[1,0] neg_lo:[0,1] neg_hi:[0,1]
	v_pk_fma_f32 v[6:7], v[24:25], v[6:7], v[26:27]
	v_pk_mul_f32 v[2:3], v[2:3], v[12:13] op_sel:[1,0]
	v_and_b32_sdwa v12, v7, v216 dst_sel:DWORD dst_unused:UNUSED_PAD src0_sel:WORD_1 src1_sel:DWORD
	v_and_b32_sdwa v13, v6, v216 dst_sel:DWORD dst_unused:UNUSED_PAD src0_sel:WORD_1 src1_sel:DWORD
	v_pk_fma_f32 v[2:3], v[0:1], v[2:3], v[4:5]
	v_add3_u32 v14, v7, v12, s84
	v_add3_u32 v12, v6, v13, s84
	v_and_b32_e32 v15, 0xffff0000, v12
	v_and_b32_sdwa v12, v3, v216 dst_sel:DWORD dst_unused:UNUSED_PAD src0_sel:WORD_1 src1_sel:DWORD
	v_and_b32_sdwa v13, v2, v216 dst_sel:DWORD dst_unused:UNUSED_PAD src0_sel:WORD_1 src1_sel:DWORD
	v_add3_u32 v12, v3, v12, s84
	v_add3_u32 v16, v2, v13, s84
	v_and_b32_e32 v17, 0xffff0000, v12
	v_or_b32_sdwa v13, v17, v14 dst_sel:DWORD dst_unused:UNUSED_PAD src0_sel:DWORD src1_sel:WORD_1
	v_or_b32_sdwa v12, v16, v15 dst_sel:DWORD dst_unused:UNUSED_PAD src0_sel:WORD_1 src1_sel:DWORD
	ds_write_b64 v80, v[12:13]
	v_and_b32_e32 v12, 0xffff0000, v16
	v_sub_u32_e32 v2, v2, v12
	v_sub_u32_e32 v6, v6, v15
	v_and_b32_e32 v12, 0xffff0000, v14
	v_add_u32_e32 v6, 0x80, v6
	v_sub_u32_e32 v7, v7, v12
	v_sub_u32_e32 v3, v3, v17
	v_add_u32_e32 v2, 0x80, v2
	v_ashrrev_i32_e32 v6, 8, v6
	v_add_u32_e32 v7, 0x80, v7
	v_add_u32_e32 v3, 0x80, v3
	v_ashrrev_i32_e32 v2, 8, v2
	v_min_i32_e32 v6, 0x7f, v6
	v_ashrrev_i32_e32 v7, 8, v7
	v_ashrrev_i32_e32 v3, 8, v3
	v_min_i32_e32 v2, 0x7f, v2
	v_min_i32_sdwa v7, v7, s85 dst_sel:WORD_1 dst_unused:UNUSED_PAD src0_sel:DWORD src1_sel:DWORD
	v_min_i32_e32 v3, 0x7f, v3
	v_lshlrev_b32_e32 v6, 8, v6
	v_and_b32_e32 v6, 0xff00, v6
	v_and_b32_e32 v7, 0xff0000, v7
	v_perm_b32 v2, v3, v2, s92
	v_or3_b32 v2, v2, v6, v7
	ds_write_b32 v18, v2 offset:144
	v_mov_b32_e32 v2, v252
	v_mov_b32_e32 v3, v253
	v_pk_add_f32 v[6:7], v[8:9], v[2:3] op_sel_hi:[1,0] neg_lo:[0,1] neg_hi:[0,1]
	s_nop 0
	v_pk_mul_f32 v[6:7], v[2:3], v[6:7] op_sel:[1,0]
	v_pk_add_f32 v[8:9], v[10:11], v[2:3] op_sel_hi:[1,0] neg_lo:[0,1] neg_hi:[0,1]
	v_pk_fma_f32 v[6:7], v[24:25], v[6:7], v[26:27]
	v_pk_mul_f32 v[2:3], v[2:3], v[8:9] op_sel:[1,0]
	s_nop 0
	v_pk_fma_f32 v[0:1], v[0:1], v[2:3], v[4:5]
	v_and_b32_sdwa v2, v7, v216 dst_sel:DWORD dst_unused:UNUSED_PAD src0_sel:WORD_1 src1_sel:DWORD
	v_and_b32_sdwa v3, v6, v216 dst_sel:DWORD dst_unused:UNUSED_PAD src0_sel:WORD_1 src1_sel:DWORD
	v_add3_u32 v4, v7, v2, s84
	v_add3_u32 v2, v6, v3, s84
	v_and_b32_e32 v5, 0xffff0000, v2
	v_and_b32_sdwa v2, v1, v216 dst_sel:DWORD dst_unused:UNUSED_PAD src0_sel:WORD_1 src1_sel:DWORD
	v_and_b32_sdwa v3, v0, v216 dst_sel:DWORD dst_unused:UNUSED_PAD src0_sel:WORD_1 src1_sel:DWORD
	v_add3_u32 v2, v1, v2, s84
	v_add3_u32 v8, v0, v3, s84
	v_and_b32_e32 v9, 0xffff0000, v2
	v_or_b32_sdwa v3, v9, v4 dst_sel:DWORD dst_unused:UNUSED_PAD src0_sel:DWORD src1_sel:WORD_1
	v_or_b32_sdwa v2, v8, v5 dst_sel:DWORD dst_unused:UNUSED_PAD src0_sel:WORD_1 src1_sel:DWORD
	ds_write_b64 v73, v[2:3]
	v_and_b32_e32 v2, 0xffff0000, v8
	v_sub_u32_e32 v0, v0, v2
	v_sub_u32_e32 v2, v6, v5
	v_and_b32_e32 v3, 0xffff0000, v4
	v_add_u32_e32 v2, 0x80, v2
	v_sub_u32_e32 v3, v7, v3
	v_sub_u32_e32 v1, v1, v9
	v_add_u32_e32 v0, 0x80, v0
	v_ashrrev_i32_e32 v2, 8, v2
	v_add_u32_e32 v3, 0x80, v3
	v_add_u32_e32 v1, 0x80, v1
	v_ashrrev_i32_e32 v0, 8, v0
	v_min_i32_e32 v2, 0x7f, v2
	v_ashrrev_i32_e32 v3, 8, v3
	v_ashrrev_i32_e32 v1, 8, v1
	v_min_i32_e32 v0, 0x7f, v0
	v_min_i32_sdwa v3, v3, s85 dst_sel:WORD_1 dst_unused:UNUSED_PAD src0_sel:DWORD src1_sel:DWORD
	v_min_i32_e32 v1, 0x7f, v1
	v_lshlrev_b32_e32 v2, 8, v2
	v_and_b32_e32 v2, 0xff00, v2
	v_and_b32_e32 v3, 0xff0000, v3
	v_perm_b32 v0, v1, v0, s92
	v_or3_b32 v0, v0, v2, v3
	ds_write_b32 v22, v0 offset:144
	s_waitcnt lgkmcnt(0)
	s_barrier
; #define STAGE(P, RS, SOFF, OFF, kt) do { const int _so = (SOFF) + (kt) * (BK * 2); \
;     _Pragma("unroll") for (int _i = 0; _i < 2; ++_i) { \
;       __builtin_amdgcn_raw_ptr_buffer_load_lds(RS, (__attribute__((address_space(3))) void*)((P) + wave * 1024 + _i * 8192), 16, OFF[_i], _so, 0, 0); } } while (0)
; #define WAIT_L(n) asm volatile("s_waitcnt lgkmcnt(" #n ")" ::: "memory")
; #define BAR __builtin_amdgcn_s_barrier()
;     ...
;   auto issue_prologue = [&](int sA0, int sA1, int sB0, int sB1) {
;     const int tid = opaque_tid(wave);
;     int offA[2], offB[2];
;     _Pragma("unroll") for (int i = 0; i < 2; ++i) {
;       int r, c; stage_rc(tid * 16 + i * 8192, r, c);
;       offA[i] = (r * lda + c) * 2; offB[i] = (r * ldb + c) * 2;
;     }
;     STAGE(SB(0, 0), rsB, sB0, offB, 0); STAGE(SA(0, 0), rsA, sA0, offA, 0);
;     STAGE(SB(0, 1), rsB, sB1, offB, 0); STAGE(SA(0, 1), rsA, sA1, offA, 0);
;     STAGE(SB(1, 0), rsB, sB0, offB, 1); STAGE(SA(1, 0), rsA, sA0, offA, 1); STAGE(SB(1, 1), rsB, sB1, offB, 1);
;   };
;     ...
;           const int hso = ((brow + ai * HALF + 16 * wave) * DM + pn * BM) * 2;
;           const int lso = (brow + ai * HALF + 16 * wave) * DM + pn * BM;
;           _Pragma("unroll") for (int i = 0; i < 8; ++i) {
;             const u32x4 v = *reinterpret_cast<const u32x4*>(smem + (wave * 8 + i) * PIECE + lane3 * 16);
;             __builtin_amdgcn_raw_buffer_store_b128(v, rsXB, hvo + i * (2 * DM * 2), hso, 0);
;           }
;           _Pragma("unroll") for (int i = 0; i < 4; ++i) {
;             const u32x4 v = *reinterpret_cast<const u32x4*>(smem + LOBASE + (wave * 4 + i) * PIECE + lane3 * 16);
;             __builtin_amdgcn_raw_buffer_store_b128(v, rsLO, lvo + i * (4 * DM), lso, 0);
;           }
;           WAIT_L(0); BAR;
;         }
;       }
;       if (has_next) issue_prologue(nA0, nA1, nB0, nB1);
	ds_read_b128 v[128:131], v72
	ds_read_b128 v[132:135], v72 offset:1040
	ds_read_b128 v[136:139], v72 offset:2080
	ds_read_b128 v[140:143], v72 offset:3120
	ds_read_b128 v[152:155], v72 offset:4160
	ds_read_b128 v[156:159], v72 offset:5200
	ds_read_b128 v[160:163], v72 offset:6240
	ds_read_b128 v[164:167], v72 offset:7280
	ds_read_b128 v[168:171], v147
	ds_read_b128 v[172:175], v147 offset:1040
	ds_read_b128 v[176:179], v147 offset:2080
	ds_read_b128 v[180:183], v147 offset:3120
	s_waitcnt lgkmcnt(0)
	s_barrier
	s_mov_b32 s98, s0
	s_cbranch_vccnz .Lmy_s1n_278
	v_mbcnt_lo_u32_b32 v0, -1, 0
	v_mbcnt_hi_u32_b32 v0, -1, v0
	s_mov_b32 m0, s37
	v_lshl_add_u32 v0, v0, 4, s35
	v_ashrrev_i32_e32 v1, 31, v0
	v_lshrrev_b32_e32 v1, 22, v1
	v_add_u32_e32 v1, v0, v1
	v_ashrrev_i32_e32 v1, 10, v1
	v_mul_i32_i24_e32 v2, 0x400, v1
	v_sub_u32_e32 v2, v0, v2
	v_lshrrev_b32_e32 v3, 4, v2
	v_bitop3_b32 v2, v3, v2, 32 bitop3:0x6c
	v_ashrrev_i32_e32 v4, 31, v2
	v_lshrrev_b32_e32 v4, 26, v4
	v_add_u32_e32 v4, v2, v4
	v_lshrrev_b32_e32 v5, 6, v4
	v_and_b32_e32 v4, 0xc0, v4
	v_lshlrev_b32_e32 v3, 3, v1
	v_lshlrev_b32_e32 v1, 5, v1
	v_sub_u32_e32 v2, v2, v4
	v_and_b32_e32 v3, 0x1ffff0, v3
	v_and_b32_e32 v1, 32, v1
	v_ashrrev_i16_sdwa v2, v216, sext(v2) dst_sel:DWORD dst_unused:UNUSED_PAD src0_sel:DWORD src1_sel:BYTE_0
	v_add_u32_sdwa v1, v1, sext(v2) dst_sel:DWORD dst_unused:UNUSED_PAD src0_sel:DWORD src1_sel:WORD_0
	v_add_lshl_u32 v2, v5, v3, 11
	v_add_u32_e32 v0, 0x2000, v0
	v_lshl_add_u32 v1, v1, 1, v2
	v_ashrrev_i32_e32 v2, 31, v0
	v_lshrrev_b32_e32 v2, 22, v2
	v_add_u32_e32 v2, v0, v2
	v_ashrrev_i32_e32 v2, 10, v2
	v_mul_i32_i24_e32 v3, 0x400, v2
	v_sub_u32_e32 v0, v0, v3
	v_lshrrev_b32_e32 v3, 4, v0
	v_bitop3_b32 v0, v3, v0, 32 bitop3:0x6c
	v_ashrrev_i32_e32 v4, 31, v0
	v_lshrrev_b32_e32 v4, 26, v4
	v_add_u32_e32 v4, v0, v4
	v_lshrrev_b32_e32 v5, 6, v4
	v_and_b32_e32 v4, 0xffc0, v4
	v_sub_u32_e32 v0, v0, v4
	v_lshrrev_b16_e32 v4, 7, v0
	v_and_b32_e32 v4, 1, v4
	v_lshlrev_b32_e32 v3, 3, v2
	v_lshlrev_b32_e32 v2, 5, v2
	v_add_u16_e32 v0, v0, v4
	v_and_b32_e32 v3, 0x1ffff0, v3
	v_and_b32_e32 v2, 32, v2
	v_ashrrev_i16_sdwa v0, v216, sext(v0) dst_sel:DWORD dst_unused:UNUSED_PAD src0_sel:DWORD src1_sel:BYTE_0
	v_add_u32_sdwa v0, v2, sext(v0) dst_sel:DWORD dst_unused:UNUSED_PAD src0_sel:DWORD src1_sel:WORD_0
	v_add_lshl_u32 v2, v5, v3, 11
	s_mov_b32 s14, s10
	s_mov_b32 s15, s11
	v_lshl_add_u32 v0, v0, 1, v2
	buffer_load_dwordx4 v1, s[12:15], s96 offen lds
	s_mov_b32 m0, s48
	s_or_b32 s0, s96, 0x80
	buffer_load_dwordx4 v0, s[12:15], s96 offen lds
	s_mov_b32 m0, s35
	s_mov_b64 s[4:5], 0
	buffer_load_dwordx4 v1, s[8:11], s95 offen lds
	s_mov_b32 m0, s49
	s_nop 0
	buffer_load_dwordx4 v0, s[8:11], s95 offen lds
	s_mov_b32 m0, s38
	s_nop 0
	buffer_load_dwordx4 v1, s[12:15], s97 offen lds
	s_mov_b32 m0, s54
	s_nop 0
	buffer_load_dwordx4 v0, s[12:15], s97 offen lds
	s_mov_b32 m0, s39
	s_nop 0
	buffer_load_dwordx4 v1, s[8:11], s94 offen lds
	s_mov_b32 m0, s55
	s_nop 0
	buffer_load_dwordx4 v0, s[8:11], s94 offen lds
	s_mov_b32 m0, s42
	s_nop 0
	buffer_load_dwordx4 v1, s[12:15], s0 offen lds
	s_mov_b32 m0, s58
	s_nop 0
	buffer_load_dwordx4 v0, s[12:15], s0 offen lds
	s_or_b32 s0, s95, 0x80
	s_mov_b32 m0, s43
	s_nop 0
	buffer_load_dwordx4 v1, s[8:11], s0 offen lds
	s_mov_b32 m0, s59
	s_nop 0
	buffer_load_dwordx4 v0, s[8:11], s0 offen lds
	s_add_i32 s0, s97, 0x80
	s_mov_b32 m0, s44
	s_nop 0
	buffer_load_dwordx4 v1, s[12:15], s0 offen lds
	s_mov_b32 m0, s60
	s_nop 0
	buffer_load_dwordx4 v0, s[12:15], s0 offen lds
	buffer_store_dwordx4 v[128:131], v148, s[16:19], s98 offen
	buffer_store_dwordx4 v[132:135], v74, s[16:19], s98 offen
	buffer_store_dwordx4 v[136:139], v75, s[16:19], s98 offen
	buffer_store_dwordx4 v[140:143], v81, s[16:19], s98 offen
	buffer_store_dwordx4 v[152:155], v84, s[16:19], s98 offen
	buffer_store_dwordx4 v[156:159], v85, s[16:19], s98 offen
	buffer_store_dwordx4 v[160:163], v88, s[16:19], s98 offen
	buffer_store_dwordx4 v[164:167], v89, s[16:19], s98 offen
	buffer_store_dwordx4 v[168:171], v146, s[20:23], s40 offen
	buffer_store_dwordx4 v[172:175], v90, s[20:23], s40 offen
	buffer_store_dwordx4 v[176:179], v91, s[20:23], s40 offen
	buffer_store_dwordx4 v[180:183], v96, s[20:23], s40 offen
	s_branch .LBB0_283

;     ...
;       const int tid3 = opaque_tid(wave);
;       const int wr3 = tid3 >> 8, wc3 = (tid3 >> 6) & 3, fr3 = tid3 & 15, fq3 = (tid3 & 63) >> 4;
;       const int ebase3 = (brow + wr3 * 64 + fr3) * DM + pn * BM + wc3 * 32 + fq3 * 4;
;       const int vo4b = ebase3 * 4, vo2 = ebase3 * 2, vo1 = ebase3;
;       (void)vo4b; (void)vo2; (void)vo1;
;       if constexpr (OUTF) {
;         _Pragma("unroll") for (int bj = 0; bj < 2; ++bj) _Pragma("unroll") for (int n = 0; n < 2; ++n) {
;           const int col = pn * BM + bj * HALF + wc3 * 32 + n * 16 + fq3 * 4;
;           const float4 gm = *reinterpret_cast<const float4*>(g.gam + col), bt = *reinterpret_cast<const float4*>(g.bet + col);
;           _Pragma("unroll") for (int ai = 0; ai < 2; ++ai) _Pragma("unroll") for (int m = 0; m < 4; ++m) {
;             const int rl = ai * HALF + wr3 * 64 + m * 16 + fr3;
;             const float2 ms = *reinterpret_cast<const float2*>(mr + rl * 2);
;             f32x4 y = acc[ai][bj][m][n];
;             u32x4 o;
;             o[0] = __float_as_uint((y[0] - ms.x) * ms.y * gm.x + bt.x); o[1] = __float_as_uint((y[1] - ms.x) * ms.y * gm.y + bt.y);
;             o[2] = __float_as_uint((y[2] - ms.x) * ms.y * gm.z + bt.z); o[3] = __float_as_uint((y[3] - ms.x) * ms.y * gm.w + bt.w);
;             __builtin_amdgcn_raw_buffer_store_b128(o, rsO, vo4b + ((ai * HALF + m * 16) * DM + bj * HALF + n * 16) * 4, 0, 0);
;           }
;         }
;       } else {
;         constexpr int PIECE = 1024 + 16, LOBASE = 64 * PIECE;
;         const int lane3 = tid3 & 63;
;         const int hvo = (lane3 >> 5) * (DM * 2) + (lane3 & 31) * 16;
;         const int lvo = (lane3 >> 4) * DM + (lane3 & 15) * 16;
;         _Pragma("unroll") for (int ai = 0; ai < 2; ++ai) {
;           _Pragma("unroll") for (int bj = 0; bj < 2; ++bj) _Pragma("unroll") for (int n = 0; n < 2; ++n) {
;             const int cc = bj * HALF + wc3 * 32 + n * 16 + fq3 * 4;
;             const float4 gm = *reinterpret_cast<const float4*>(g.gam + pn * BM + cc), bt = *reinterpret_cast<const float4*>(g.bet + pn * BM + cc);
;             _Pragma("unroll") for (int m = 0; m < 4; ++m) {
;               const int rr = wr3 * 64 + m * 16 + fr3;
;               const float2 ms = *reinterpret_cast<const float2*>(mr + (ai * HALF + rr) * 2);
;               f32x4 y = acc[ai][bj][m][n];
.LBB0_421:
	s_or_b64 exec, exec, s[6:7]
	s_waitcnt lgkmcnt(0)
	s_barrier
	v_mbcnt_lo_u32_b32 v0, -1, 0
	v_mbcnt_hi_u32_b32 v0, -1, v0
	s_movk_i32 s4, 0x60
	v_add_u32_e32 v1, s34, v0
	v_ashrrev_i32_e32 v5, 2, v1
	v_lshrrev_b32_e32 v6, 1, v1
	v_lshlrev_b32_e32 v1, 4, v1
	v_bfe_u32 v4, v0, 4, 2
	v_lshlrev_b32_e32 v12, 7, v0
	v_and_b32_e32 v13, 0x1f0, v1
	v_lshlrev_b32_e32 v7, 2, v4
	v_and_or_b32 v148, v12, s29, v13
	s_ashr_i32 s29, s28, 31
	v_readlane_b32 s60, v255, 0
	v_and_or_b32 v12, v6, s4, v7
	s_lshl_b64 s[4:5], s[28:29], 2
	v_readlane_b32 s66, v255, 6
	v_readlane_b32 s67, v255, 7
	s_add_u32 s6, s66, s4
	v_and_b32_e32 v2, 15, v0
	v_and_b32_e32 v3, 63, v0
	v_and_b32_e32 v1, 0xf0, v1
	v_lshlrev_b32_e32 v13, 9, v0
	v_lshlrev_b32_e32 v0, 8, v0
	s_addc_u32 s7, s67, s5
	v_lshlrev_b32_e32 v150, 2, v12
	v_lshl_or_b32 v146, v4, 11, v1
	v_and_or_b32 v156, v5, s2, v2
	v_and_b32_e32 v14, 0x300, v0
	v_lshlrev_b32_e32 v152, 4, v3
	global_load_dwordx4 v[220:223], v150, s[6:7]
	global_load_dwordx4 v[224:227], v150, s[6:7] offset:64
	global_load_dwordx4 v[228:231], v150, s[6:7] offset:512
	global_load_dwordx4 v[232:235], v150, s[6:7] offset:576
	v_readlane_b32 s68, v255, 8
	v_readlane_b32 s69, v255, 9
	s_add_u32 s4, s68, s4
	s_addc_u32 s5, s69, s5
	global_load_dwordx4 v[236:239], v150, s[4:5]
	global_load_dwordx4 v[240:243], v150, s[4:5] offset:64
	global_load_dwordx4 v[244:247], v150, s[4:5] offset:512
	global_load_dwordx4 v[248:251], v150, s[4:5] offset:576
	s_movk_i32 s22, 0x200
	v_lshl_add_u32 v149, v156, 3, v219
	v_add_u32_e32 v147, s46, v152
	s_andn2_b64 vcc, exec, s[14:15]
	s_movk_i32 s40, 0x100
	v_readlane_b32 s61, v255, 1
	v_readlane_b32 s62, v255, 2
	v_readlane_b32 s63, v255, 3
	v_readlane_b32 s64, v255, 4
	v_readlane_b32 s65, v255, 5
	v_readlane_b32 s70, v255, 10
	v_readlane_b32 s71, v255, 11
	v_readlane_b32 s72, v255, 12
	v_readlane_b32 s73, v255, 13
	v_readlane_b32 s74, v255, 14
	v_readlane_b32 s75, v255, 15
	s_waitcnt vmcnt(0)
	v_mov_b32_e32 v0, v220
	v_mov_b32_e32 v1, v221
	v_mov_b32_e32 v2, v222
	v_mov_b32_e32 v3, v223
	v_mov_b32_e32 v4, v236
	v_mov_b32_e32 v5, v237
	v_mov_b32_e32 v6, v238
	v_mov_b32_e32 v7, v239
	v_mov_b32_e32 v22, v1
	v_lshlrev_b32_e32 v1, 1, v12
	v_and_or_b32 v155, v13, s22, v1
	s_mov_b32 s22, 0x10400
	v_mov_b32_e32 v23, v2
	v_or3_b32 v2, v14, v12, s22
	ds_read_b64 v[12:13], v149
	v_mov_b32_e32 v144, v5
	v_mov_b32_e32 v145, v6
	v_mov_b32_e32 v1, v3
	v_mov_b32_e32 v5, v7
	s_waitcnt lgkmcnt(0)
	v_mov_b32_e32 v202, v12
	v_mov_b32_e32 v203, v13
	v_pk_add_f32 v[14:15], v[128:129], v[12:13] op_sel_hi:[1,0] neg_lo:[0,1] neg_hi:[0,1]
	v_pk_add_f32 v[20:21], v[130:131], v[12:13] op_sel_hi:[1,0] neg_lo:[0,1] neg_hi:[0,1]
	v_pk_mul_f32 v[14:15], v[12:13], v[14:15] op_sel:[1,0]
	v_pk_mul_f32 v[12:13], v[12:13], v[20:21] op_sel:[1,0]
	v_pk_fma_f32 v[14:15], v[22:23], v[14:15], v[144:145]
	v_pk_fma_f32 v[6:7], v[0:1], v[12:13], v[4:5]
	v_and_b32_sdwa v12, v14, v216 dst_sel:DWORD dst_unused:UNUSED_PAD src0_sel:WORD_1 src1_sel:DWORD
	v_add3_u32 v12, v14, v12, s82
	v_and_b32_e32 v20, 0xffff0000, v12
	v_and_b32_sdwa v12, v7, v216 dst_sel:DWORD dst_unused:UNUSED_PAD src0_sel:WORD_1 src1_sel:DWORD
	v_and_b32_sdwa v3, v15, v216 dst_sel:DWORD dst_unused:UNUSED_PAD src0_sel:WORD_1 src1_sel:DWORD
	v_and_b32_sdwa v13, v6, v216 dst_sel:DWORD dst_unused:UNUSED_PAD src0_sel:WORD_1 src1_sel:DWORD
	v_add3_u32 v12, v7, v12, s82
	v_lshrrev_b32_e32 v129, 1, v156
	v_add3_u32 v3, v15, v3, s82
	v_add3_u32 v21, v6, v13, s82
	v_and_b32_e32 v128, 0xffff0000, v12
	v_mul_lo_u32 v153, v129, s50
	v_or_b32_sdwa v13, v128, v3 dst_sel:DWORD dst_unused:UNUSED_PAD src0_sel:DWORD src1_sel:WORD_1
	v_or_b32_sdwa v12, v21, v20 dst_sel:DWORD dst_unused:UNUSED_PAD src0_sel:WORD_1 src1_sel:DWORD
	v_add_u32_e32 v151, v155, v153
	ds_write_b64 v151, v[12:13]
	v_and_b32_e32 v12, 0xffff0000, v21
	v_sub_u32_e32 v6, v6, v12
	v_sub_u32_e32 v12, v14, v20
	v_and_b32_e32 v3, 0xffff0000, v3
	v_add_u32_e32 v12, 0x80, v12
	v_sub_u32_e32 v3, v15, v3
	v_sub_u32_e32 v7, v7, v128
	v_add_u32_e32 v6, 0x80, v6
	v_ashrrev_i32_e32 v12, 8, v12
	v_add_u32_e32 v3, 0x80, v3
	v_add_u32_e32 v7, 0x80, v7
	v_ashrrev_i32_e32 v6, 8, v6
	v_min_i32_e32 v12, 0x7f, v12
	v_ashrrev_i32_e32 v3, 8, v3
	v_ashrrev_i32_e32 v7, 8, v7
	v_min_i32_e32 v6, 0x7f, v6
	v_min_i32_sdwa v3, v3, s83 dst_sel:WORD_1 dst_unused:UNUSED_PAD src0_sel:DWORD src1_sel:DWORD
	v_min_i32_e32 v7, 0x7f, v7
	v_lshlrev_b32_e32 v12, 8, v12
	v_and_b32_e32 v12, 0xff00, v12
	v_and_b32_e32 v3, 0xff0000, v3
	v_perm_b32 v6, v7, v6, s84
	v_or3_b32 v3, v6, v12, v3
	v_lshrrev_b32_e32 v6, 2, v156
	v_mad_u64_u32 v[12:13], s[22:23], v6, s50, v[2:3]
	ds_write_b32 v12, v3
	v_or_b32_e32 v3, 16, v156
	v_lshl_add_u32 v13, v3, 3, v219
	ds_read_b64 v[6:7], v13
	s_waitcnt lgkmcnt(0)
;     ...
;             _Pragma("unroll") for (int m = 0; m < 4; ++m) {
;               const int rr = wr3 * 64 + m * 16 + fr3;
;               const float2 ms = *reinterpret_cast<const float2*>(mr + (ai * HALF + rr) * 2);
;               f32x4 y = acc[ai][bj][m][n];
;               const float o0 = (y[0] - ms.x) * ms.y * gm.x + bt.x, o1 = (y[1] - ms.x) * ms.y * gm.y + bt.y;
;               const float o2 = (y[2] - ms.x) * ms.y * gm.z + bt.z, o3 = (y[3] - ms.x) * ms.y * gm.w + bt.w;
;               const unsigned h0 = f2bf(o0), h1 = f2bf(o1), h2 = f2bf(o2), h3 = f2bf(o3);
;               u32x2 ob; ob[0] = h0 | (h1 << 16); ob[1] = h2 | (h3 << 16);
;               *reinterpret_cast<u32x2*>(smem + (rr >> 1) * PIECE + (rr & 1) * 512 + cc * 2) = ob;
;               const int l0 = min(((int)__float_as_uint(o0) - (int)(h0 << 16) + 128) >> 8, 127);
;               const int l1 = min(((int)__float_as_uint(o1) - (int)(h1 << 16) + 128) >> 8, 127);
;               const int l2 = min(((int)__float_as_uint(o2) - (int)(h2 << 16) + 128) >> 8, 127);
;               const int l3 = min(((int)__float_as_uint(o3) - (int)(h3 << 16) + 128) >> 8, 127);
;               *reinterpret_cast<unsigned*>(smem + LOBASE + (rr >> 2) * PIECE + (rr & 3) * 256 + cc) =
;                   (unsigned)(l0 & 255) | ((unsigned)(l1 & 255) << 8) | ((unsigned)(l2 & 255) << 16) | ((unsigned)l3 << 24);
;             }
	v_mov_b32_e32 v204, v6
	v_mov_b32_e32 v205, v7
	v_pk_add_f32 v[14:15], v[134:135], v[6:7] op_sel_hi:[1,0] neg_lo:[0,1] neg_hi:[0,1]
	s_nop 0
	v_pk_mul_f32 v[14:15], v[6:7], v[14:15] op_sel:[1,0]
	v_pk_add_f32 v[20:21], v[132:133], v[6:7] op_sel_hi:[1,0] neg_lo:[0,1] neg_hi:[0,1]
	v_pk_fma_f32 v[14:15], v[22:23], v[14:15], v[144:145]
	v_pk_mul_f32 v[6:7], v[6:7], v[20:21] op_sel:[1,0]
	v_and_b32_sdwa v20, v15, v216 dst_sel:DWORD dst_unused:UNUSED_PAD src0_sel:WORD_1 src1_sel:DWORD
	v_and_b32_sdwa v21, v14, v216 dst_sel:DWORD dst_unused:UNUSED_PAD src0_sel:WORD_1 src1_sel:DWORD
	v_pk_fma_f32 v[6:7], v[0:1], v[6:7], v[4:5]
	v_add3_u32 v128, v15, v20, s82
	v_add3_u32 v20, v14, v21, s82
	v_and_b32_e32 v129, 0xffff0000, v20
	v_and_b32_sdwa v20, v7, v216 dst_sel:DWORD dst_unused:UNUSED_PAD src0_sel:WORD_1 src1_sel:DWORD
	v_and_b32_sdwa v21, v6, v216 dst_sel:DWORD dst_unused:UNUSED_PAD src0_sel:WORD_1 src1_sel:DWORD
	v_add3_u32 v20, v7, v20, s82
	v_lshrrev_b32_e32 v132, 1, v3
	v_add3_u32 v130, v6, v21, s82
	v_and_b32_e32 v131, 0xffff0000, v20
	v_mul_lo_u32 v154, v132, s50
	v_or_b32_sdwa v21, v131, v128 dst_sel:DWORD dst_unused:UNUSED_PAD src0_sel:DWORD src1_sel:WORD_1
	v_or_b32_sdwa v20, v130, v129 dst_sel:DWORD dst_unused:UNUSED_PAD src0_sel:WORD_1 src1_sel:DWORD
	v_add_u32_e32 v132, v155, v154
	ds_write_b64 v132, v[20:21]
	v_and_b32_e32 v20, 0xffff0000, v130
	v_sub_u32_e32 v6, v6, v20
	v_sub_u32_e32 v14, v14, v129
	v_and_b32_e32 v20, 0xffff0000, v128
	v_add_u32_e32 v14, 0x80, v14
	v_sub_u32_e32 v15, v15, v20
	v_sub_u32_e32 v7, v7, v131
	v_add_u32_e32 v6, 0x80, v6
	v_ashrrev_i32_e32 v14, 8, v14
	v_add_u32_e32 v15, 0x80, v15
	v_add_u32_e32 v7, 0x80, v7
	v_ashrrev_i32_e32 v6, 8, v6
	v_min_i32_e32 v14, 0x7f, v14
	v_ashrrev_i32_e32 v15, 8, v15
	v_ashrrev_i32_e32 v7, 8, v7
	v_min_i32_e32 v6, 0x7f, v6
	v_min_i32_sdwa v15, v15, s83 dst_sel:WORD_1 dst_unused:UNUSED_PAD src0_sel:DWORD src1_sel:DWORD
	v_min_i32_e32 v7, 0x7f, v7
	v_lshlrev_b32_e32 v14, 8, v14
	v_and_b32_e32 v14, 0xff00, v14
	v_and_b32_e32 v15, 0xff0000, v15
	v_perm_b32 v6, v7, v6, s84
	v_lshrrev_b32_e32 v3, 2, v3
	v_or3_b32 v6, v6, v14, v15
	v_mad_u64_u32 v[14:15], s[22:23], v3, s50, v[2:3]
	v_or_b32_e32 v3, 32, v156
	ds_write_b32 v14, v6
	v_lshl_add_u32 v15, v3, 3, v219
	ds_read_b64 v[6:7], v15
	v_lshrrev_b32_e32 v133, 1, v3
	v_lshrrev_b32_e32 v3, 2, v3
	s_waitcnt lgkmcnt(0)
	v_mov_b32_e32 v206, v6
	v_mov_b32_e32 v207, v7
	v_pk_add_f32 v[20:21], v[138:139], v[6:7] op_sel_hi:[1,0] neg_lo:[0,1] neg_hi:[0,1]
	s_nop 0
	v_pk_mul_f32 v[20:21], v[6:7], v[20:21] op_sel:[1,0]
	v_pk_add_f32 v[128:129], v[136:137], v[6:7] op_sel_hi:[1,0] neg_lo:[0,1] neg_hi:[0,1]
	v_pk_fma_f32 v[20:21], v[22:23], v[20:21], v[144:145]
	v_pk_mul_f32 v[6:7], v[6:7], v[128:129] op_sel:[1,0]
	v_and_b32_sdwa v128, v21, v216 dst_sel:DWORD dst_unused:UNUSED_PAD src0_sel:WORD_1 src1_sel:DWORD
	v_and_b32_sdwa v129, v20, v216 dst_sel:DWORD dst_unused:UNUSED_PAD src0_sel:WORD_1 src1_sel:DWORD
	v_pk_fma_f32 v[6:7], v[0:1], v[6:7], v[4:5]
	v_add3_u32 v130, v21, v128, s82
	v_add3_u32 v128, v20, v129, s82
	v_and_b32_e32 v131, 0xffff0000, v128
	v_and_b32_sdwa v128, v7, v216 dst_sel:DWORD dst_unused:UNUSED_PAD src0_sel:WORD_1 src1_sel:DWORD
	v_and_b32_sdwa v129, v6, v216 dst_sel:DWORD dst_unused:UNUSED_PAD src0_sel:WORD_1 src1_sel:DWORD
	v_add3_u32 v128, v7, v128, s82
	v_add3_u32 v134, v6, v129, s82
	v_and_b32_e32 v135, 0xffff0000, v128
	v_mul_lo_u32 v136, v133, s50
	v_or_b32_sdwa v129, v135, v130 dst_sel:DWORD dst_unused:UNUSED_PAD src0_sel:DWORD src1_sel:WORD_1
	v_or_b32_sdwa v128, v134, v131 dst_sel:DWORD dst_unused:UNUSED_PAD src0_sel:WORD_1 src1_sel:DWORD
	v_add_u32_e32 v133, v155, v136
	ds_write_b64 v133, v[128:129]
	v_and_b32_e32 v128, 0xffff0000, v134
	v_sub_u32_e32 v6, v6, v128
	v_sub_u32_e32 v20, v20, v131
	v_and_b32_e32 v128, 0xffff0000, v130
	v_add_u32_e32 v20, 0x80, v20
	v_sub_u32_e32 v21, v21, v128
	v_sub_u32_e32 v7, v7, v135
	v_add_u32_e32 v6, 0x80, v6
	v_ashrrev_i32_e32 v20, 8, v20
	v_add_u32_e32 v21, 0x80, v21
	v_add_u32_e32 v7, 0x80, v7
	v_ashrrev_i32_e32 v6, 8, v6
	v_min_i32_e32 v20, 0x7f, v20
	v_ashrrev_i32_e32 v21, 8, v21
	v_ashrrev_i32_e32 v7, 8, v7
	v_min_i32_e32 v6, 0x7f, v6
	v_min_i32_sdwa v21, v21, s83 dst_sel:WORD_1 dst_unused:UNUSED_PAD src0_sel:DWORD src1_sel:DWORD
	v_min_i32_e32 v7, 0x7f, v7
	v_lshlrev_b32_e32 v20, 8, v20
	v_and_b32_e32 v20, 0xff00, v20
	v_and_b32_e32 v21, 0xff0000, v21
	v_perm_b32 v6, v7, v6, s84
	v_or3_b32 v6, v6, v20, v21
	v_mad_u64_u32 v[20:21], s[22:23], v3, s50, v[2:3]
	v_or_b32_e32 v3, 48, v156
	ds_write_b32 v20, v6
	v_lshl_add_u32 v21, v3, 3, v219
	ds_read_b64 v[6:7], v21
	v_lshrrev_b32_e32 v130, 1, v3
	v_mul_lo_u32 v135, v130, s50
	v_add_u32_e32 v134, v155, v135
	s_waitcnt lgkmcnt(0)
;     ...
;           _Pragma("unroll") for (int bj = 0; bj < 2; ++bj) _Pragma("unroll") for (int n = 0; n < 2; ++n) {
;             const int cc = bj * HALF + wc3 * 32 + n * 16 + fq3 * 4;
;             const float4 gm = *reinterpret_cast<const float4*>(g.gam + pn * BM + cc), bt = *reinterpret_cast<const float4*>(g.bet + pn * BM + cc);
;             _Pragma("unroll") for (int m = 0; m < 4; ++m) {
;               const int rr = wr3 * 64 + m * 16 + fr3;
;               const float2 ms = *reinterpret_cast<const float2*>(mr + (ai * HALF + rr) * 2);
;               f32x4 y = acc[ai][bj][m][n];
;               const float o0 = (y[0] - ms.x) * ms.y * gm.x + bt.x, o1 = (y[1] - ms.x) * ms.y * gm.y + bt.y;
;               const float o2 = (y[2] - ms.x) * ms.y * gm.z + bt.z, o3 = (y[3] - ms.x) * ms.y * gm.w + bt.w;
;               const unsigned h0 = f2bf(o0), h1 = f2bf(o1), h2 = f2bf(o2), h3 = f2bf(o3);
;               u32x2 ob; ob[0] = h0 | (h1 << 16); ob[1] = h2 | (h3 << 16);
;               *reinterpret_cast<u32x2*>(smem + (rr >> 1) * PIECE + (rr & 1) * 512 + cc * 2) = ob;
;               const int l0 = min(((int)__float_as_uint(o0) - (int)(h0 << 16) + 128) >> 8, 127);
;               const int l1 = min(((int)__float_as_uint(o1) - (int)(h1 << 16) + 128) >> 8, 127);
;               const int l2 = min(((int)__float_as_uint(o2) - (int)(h2 << 16) + 128) >> 8, 127);
;               const int l3 = min(((int)__float_as_uint(o3) - (int)(h3 << 16) + 128) >> 8, 127);
;               *reinterpret_cast<unsigned*>(smem + LOBASE + (rr >> 2) * PIECE + (rr & 3) * 256 + cc) =
;                   (unsigned)(l0 & 255) | ((unsigned)(l1 & 255) << 8) | ((unsigned)(l2 & 255) << 16) | ((unsigned)l3 << 24);
;             }
	v_mov_b32_e32 v208, v6
	v_mov_b32_e32 v209, v7
	v_pk_add_f32 v[128:129], v[142:143], v[6:7] op_sel_hi:[1,0] neg_lo:[0,1] neg_hi:[0,1]
	s_nop 0
	v_pk_mul_f32 v[128:129], v[6:7], v[128:129] op_sel:[1,0]
	s_nop 0
	v_pk_fma_f32 v[22:23], v[22:23], v[128:129], v[144:145]
	v_pk_add_f32 v[128:129], v[140:141], v[6:7] op_sel_hi:[1,0] neg_lo:[0,1] neg_hi:[0,1]
	s_nop 0
	v_pk_mul_f32 v[6:7], v[6:7], v[128:129] op_sel:[1,0]
	s_nop 0
	v_pk_fma_f32 v[0:1], v[0:1], v[6:7], v[4:5]
	v_and_b32_sdwa v4, v23, v216 dst_sel:DWORD dst_unused:UNUSED_PAD src0_sel:WORD_1 src1_sel:DWORD
	v_and_b32_sdwa v5, v22, v216 dst_sel:DWORD dst_unused:UNUSED_PAD src0_sel:WORD_1 src1_sel:DWORD
	v_add3_u32 v6, v23, v4, s82
	v_add3_u32 v4, v22, v5, s82
	v_and_b32_e32 v7, 0xffff0000, v4
	v_and_b32_sdwa v4, v1, v216 dst_sel:DWORD dst_unused:UNUSED_PAD src0_sel:WORD_1 src1_sel:DWORD
	v_and_b32_sdwa v5, v0, v216 dst_sel:DWORD dst_unused:UNUSED_PAD src0_sel:WORD_1 src1_sel:DWORD
	v_add3_u32 v4, v1, v4, s82
	v_add3_u32 v128, v0, v5, s82
	v_and_b32_e32 v129, 0xffff0000, v4
	v_or_b32_sdwa v5, v129, v6 dst_sel:DWORD dst_unused:UNUSED_PAD src0_sel:DWORD src1_sel:WORD_1
	v_or_b32_sdwa v4, v128, v7 dst_sel:DWORD dst_unused:UNUSED_PAD src0_sel:WORD_1 src1_sel:DWORD
	ds_write_b64 v134, v[4:5]
	v_and_b32_e32 v4, 0xffff0000, v128
	v_sub_u32_e32 v0, v0, v4
	v_sub_u32_e32 v4, v22, v7
	v_and_b32_e32 v5, 0xffff0000, v6
	v_add_u32_e32 v4, 0x80, v4
	v_sub_u32_e32 v5, v23, v5
	v_sub_u32_e32 v1, v1, v129
	v_add_u32_e32 v0, 0x80, v0
	v_ashrrev_i32_e32 v4, 8, v4
	v_add_u32_e32 v5, 0x80, v5
	v_add_u32_e32 v1, 0x80, v1
	v_ashrrev_i32_e32 v0, 8, v0
	v_min_i32_e32 v4, 0x7f, v4
	v_ashrrev_i32_e32 v5, 8, v5
	v_ashrrev_i32_e32 v1, 8, v1
	v_min_i32_e32 v0, 0x7f, v0
	v_min_i32_sdwa v5, v5, s83 dst_sel:WORD_1 dst_unused:UNUSED_PAD src0_sel:DWORD src1_sel:DWORD
	v_min_i32_e32 v1, 0x7f, v1
	v_lshlrev_b32_e32 v4, 8, v4
	v_and_b32_e32 v4, 0xff00, v4
	v_and_b32_e32 v5, 0xff0000, v5
	v_perm_b32 v0, v1, v0, s84
	v_lshrrev_b32_e32 v1, 2, v3
	v_or3_b32 v0, v0, v4, v5
	v_mad_u64_u32 v[22:23], s[22:23], v1, s50, v[2:3]
	ds_write_b32 v22, v0
	v_mov_b32_e32 v0, v224
	v_mov_b32_e32 v1, v225
	v_mov_b32_e32 v2, v226
	v_mov_b32_e32 v3, v227
	v_mov_b32_e32 v4, v240
	v_mov_b32_e32 v5, v241
	v_mov_b32_e32 v6, v242
	v_mov_b32_e32 v7, v243
	v_mov_b32_e32 v138, v202
	v_mov_b32_e32 v139, v203
	s_mov_b32 s22, s18
	s_mov_b32 s23, s19
	v_pk_add_f32 v[124:125], v[124:125], v[138:139] op_sel_hi:[1,0] neg_lo:[0,1] neg_hi:[0,1]
	s_nop 0
	v_pk_mul_f32 v[124:125], v[138:139], v[124:125] op_sel:[1,0]
	v_pk_add_f32 v[126:127], v[126:127], v[138:139] op_sel_hi:[1,0] neg_lo:[0,1] neg_hi:[0,1]
	v_mov_b32_e32 v128, v1
	v_mov_b32_e32 v129, v2
	v_mov_b32_e32 v130, v5
	v_mov_b32_e32 v131, v6
	v_pk_fma_f32 v[124:125], v[128:129], v[124:125], v[130:131]
	v_pk_mul_f32 v[126:127], v[138:139], v[126:127] op_sel:[1,0]
	v_mov_b32_e32 v1, v3
	v_mov_b32_e32 v5, v7
	v_and_b32_sdwa v23, v124, v216 dst_sel:DWORD dst_unused:UNUSED_PAD src0_sel:WORD_1 src1_sel:DWORD
	v_pk_fma_f32 v[6:7], v[0:1], v[126:127], v[4:5]
	v_add3_u32 v23, v124, v23, s82
	v_and_b32_e32 v137, 0xffff0000, v23
	v_and_b32_sdwa v23, v7, v216 dst_sel:DWORD dst_unused:UNUSED_PAD src0_sel:WORD_1 src1_sel:DWORD
	v_and_b32_sdwa v3, v125, v216 dst_sel:DWORD dst_unused:UNUSED_PAD src0_sel:WORD_1 src1_sel:DWORD
	v_and_b32_sdwa v126, v6, v216 dst_sel:DWORD dst_unused:UNUSED_PAD src0_sel:WORD_1 src1_sel:DWORD
	v_add3_u32 v23, v7, v23, s82
	v_or_b32_e32 v2, 32, v155
	v_add3_u32 v3, v125, v3, s82
	v_add3_u32 v138, v6, v126, s82
	v_and_b32_e32 v139, 0xffff0000, v23
	v_or_b32_sdwa v127, v139, v3 dst_sel:DWORD dst_unused:UNUSED_PAD src0_sel:DWORD src1_sel:WORD_1
	v_or_b32_sdwa v126, v138, v137 dst_sel:DWORD dst_unused:UNUSED_PAD src0_sel:WORD_1 src1_sel:DWORD
	v_add_u32_e32 v23, v2, v153
	ds_write_b64 v23, v[126:127]
	v_and_b32_e32 v126, 0xffff0000, v138
	v_sub_u32_e32 v124, v124, v137
	v_and_b32_e32 v3, 0xffff0000, v3
	v_sub_u32_e32 v6, v6, v126
	v_add_u32_e32 v124, 0x80, v124
	v_sub_u32_e32 v3, v125, v3
	v_sub_u32_e32 v7, v7, v139
	v_add_u32_e32 v6, 0x80, v6
	v_ashrrev_i32_e32 v124, 8, v124
	v_add_u32_e32 v3, 0x80, v3
	v_add_u32_e32 v7, 0x80, v7
	v_ashrrev_i32_e32 v6, 8, v6
	v_min_i32_e32 v124, 0x7f, v124
	v_ashrrev_i32_e32 v3, 8, v3
	v_ashrrev_i32_e32 v7, 8, v7
	v_min_i32_e32 v6, 0x7f, v6
	v_min_i32_sdwa v3, v3, s83 dst_sel:WORD_1 dst_unused:UNUSED_PAD src0_sel:DWORD src1_sel:DWORD
	v_min_i32_e32 v7, 0x7f, v7
	v_lshlrev_b32_e32 v124, 8, v124
	v_and_b32_e32 v124, 0xff00, v124
	v_and_b32_e32 v3, 0xff0000, v3
	v_perm_b32 v6, v7, v6, s84
	v_or3_b32 v3, v6, v124, v3
	ds_write_b32 v12, v3 offset:16
	v_mov_b32_e32 v6, v204
	v_mov_b32_e32 v7, v205
	v_pk_add_f32 v[106:107], v[106:107], v[6:7] op_sel_hi:[1,0] neg_lo:[0,1] neg_hi:[0,1]
	s_nop 0
	v_pk_mul_f32 v[106:107], v[6:7], v[106:107] op_sel:[1,0]
	v_pk_add_f32 v[104:105], v[104:105], v[6:7] op_sel_hi:[1,0] neg_lo:[0,1] neg_hi:[0,1]
	v_pk_fma_f32 v[106:107], v[128:129], v[106:107], v[130:131]
	v_pk_mul_f32 v[6:7], v[6:7], v[104:105] op_sel:[1,0]
	v_and_b32_sdwa v104, v106, v216 dst_sel:DWORD dst_unused:UNUSED_PAD src0_sel:WORD_1 src1_sel:DWORD
	v_pk_fma_f32 v[6:7], v[0:1], v[6:7], v[4:5]
	v_add3_u32 v104, v106, v104, s82
	v_and_b32_e32 v105, 0xffff0000, v104
	v_and_b32_sdwa v104, v7, v216 dst_sel:DWORD dst_unused:UNUSED_PAD src0_sel:WORD_1 src1_sel:DWORD
	v_and_b32_sdwa v3, v107, v216 dst_sel:DWORD dst_unused:UNUSED_PAD src0_sel:WORD_1 src1_sel:DWORD
	v_and_b32_sdwa v124, v6, v216 dst_sel:DWORD dst_unused:UNUSED_PAD src0_sel:WORD_1 src1_sel:DWORD
	v_add3_u32 v104, v7, v104, s82
	v_add3_u32 v3, v107, v3, s82
	v_add3_u32 v126, v6, v124, s82
	v_and_b32_e32 v127, 0xffff0000, v104
;     ...
;           _Pragma("unroll") for (int bj = 0; bj < 2; ++bj) _Pragma("unroll") for (int n = 0; n < 2; ++n) {
;             const int cc = bj * HALF + wc3 * 32 + n * 16 + fq3 * 4;
;             const float4 gm = *reinterpret_cast<const float4*>(g.gam + pn * BM + cc), bt = *reinterpret_cast<const float4*>(g.bet + pn * BM + cc);
;             _Pragma("unroll") for (int m = 0; m < 4; ++m) {
;               const int rr = wr3 * 64 + m * 16 + fr3;
;               const float2 ms = *reinterpret_cast<const float2*>(mr + (ai * HALF + rr) * 2);
;               f32x4 y = acc[ai][bj][m][n];
;               const float o0 = (y[0] - ms.x) * ms.y * gm.x + bt.x, o1 = (y[1] - ms.x) * ms.y * gm.y + bt.y;
;               const float o2 = (y[2] - ms.x) * ms.y * gm.z + bt.z, o3 = (y[3] - ms.x) * ms.y * gm.w + bt.w;
;               const unsigned h0 = f2bf(o0), h1 = f2bf(o1), h2 = f2bf(o2), h3 = f2bf(o3);
;               u32x2 ob; ob[0] = h0 | (h1 << 16); ob[1] = h2 | (h3 << 16);
;               *reinterpret_cast<u32x2*>(smem + (rr >> 1) * PIECE + (rr & 1) * 512 + cc * 2) = ob;
;               const int l0 = min(((int)__float_as_uint(o0) - (int)(h0 << 16) + 128) >> 8, 127);
;               const int l1 = min(((int)__float_as_uint(o1) - (int)(h1 << 16) + 128) >> 8, 127);
;               const int l2 = min(((int)__float_as_uint(o2) - (int)(h2 << 16) + 128) >> 8, 127);
;               const int l3 = min(((int)__float_as_uint(o3) - (int)(h3 << 16) + 128) >> 8, 127);
;               *reinterpret_cast<unsigned*>(smem + LOBASE + (rr >> 2) * PIECE + (rr & 3) * 256 + cc) =
;                   (unsigned)(l0 & 255) | ((unsigned)(l1 & 255) << 8) | ((unsigned)(l2 & 255) << 16) | ((unsigned)l3 << 24);
;             }
	v_or_b32_sdwa v125, v127, v3 dst_sel:DWORD dst_unused:UNUSED_PAD src0_sel:DWORD src1_sel:WORD_1
	v_or_b32_sdwa v124, v126, v105 dst_sel:DWORD dst_unused:UNUSED_PAD src0_sel:WORD_1 src1_sel:DWORD
	v_add_u32_e32 v104, v2, v154
	ds_write_b64 v104, v[124:125]
	v_and_b32_e32 v124, 0xffff0000, v126
	v_sub_u32_e32 v105, v106, v105
	v_and_b32_e32 v3, 0xffff0000, v3
	v_sub_u32_e32 v6, v6, v124
	v_add_u32_e32 v105, 0x80, v105
	v_sub_u32_e32 v3, v107, v3
	v_sub_u32_e32 v7, v7, v127
	v_add_u32_e32 v6, 0x80, v6
	v_ashrrev_i32_e32 v105, 8, v105
	v_add_u32_e32 v3, 0x80, v3
	v_add_u32_e32 v7, 0x80, v7
	v_ashrrev_i32_e32 v6, 8, v6
	v_min_i32_e32 v105, 0x7f, v105
	v_ashrrev_i32_e32 v3, 8, v3
	v_ashrrev_i32_e32 v7, 8, v7
	v_min_i32_e32 v6, 0x7f, v6
	v_min_i32_sdwa v3, v3, s83 dst_sel:WORD_1 dst_unused:UNUSED_PAD src0_sel:DWORD src1_sel:DWORD
	v_min_i32_e32 v7, 0x7f, v7
	v_lshlrev_b32_e32 v105, 8, v105
	v_and_b32_e32 v105, 0xff00, v105
	v_and_b32_e32 v3, 0xff0000, v3
	v_perm_b32 v6, v7, v6, s84
	v_or3_b32 v3, v6, v105, v3
	ds_write_b32 v14, v3 offset:16
	v_mov_b32_e32 v6, v206
	v_mov_b32_e32 v7, v207
	v_pk_add_f32 v[106:107], v[110:111], v[6:7] op_sel_hi:[1,0] neg_lo:[0,1] neg_hi:[0,1]
	s_nop 0
	v_pk_mul_f32 v[106:107], v[6:7], v[106:107] op_sel:[1,0]
	v_pk_add_f32 v[108:109], v[108:109], v[6:7] op_sel_hi:[1,0] neg_lo:[0,1] neg_hi:[0,1]
	v_pk_fma_f32 v[106:107], v[128:129], v[106:107], v[130:131]
	v_pk_mul_f32 v[6:7], v[6:7], v[108:109] op_sel:[1,0]
	v_and_b32_sdwa v105, v106, v216 dst_sel:DWORD dst_unused:UNUSED_PAD src0_sel:WORD_1 src1_sel:DWORD
	v_pk_fma_f32 v[6:7], v[0:1], v[6:7], v[4:5]
	v_add3_u32 v105, v106, v105, s82
	v_and_b32_e32 v110, 0xffff0000, v105
	v_and_b32_sdwa v105, v7, v216 dst_sel:DWORD dst_unused:UNUSED_PAD src0_sel:WORD_1 src1_sel:DWORD
	v_and_b32_sdwa v3, v107, v216 dst_sel:DWORD dst_unused:UNUSED_PAD src0_sel:WORD_1 src1_sel:DWORD
	v_and_b32_sdwa v108, v6, v216 dst_sel:DWORD dst_unused:UNUSED_PAD src0_sel:WORD_1 src1_sel:DWORD
	v_add3_u32 v105, v7, v105, s82
	v_add3_u32 v3, v107, v3, s82
	v_add3_u32 v111, v6, v108, s82
	v_and_b32_e32 v124, 0xffff0000, v105
	v_or_b32_sdwa v109, v124, v3 dst_sel:DWORD dst_unused:UNUSED_PAD src0_sel:DWORD src1_sel:WORD_1
	v_or_b32_sdwa v108, v111, v110 dst_sel:DWORD dst_unused:UNUSED_PAD src0_sel:WORD_1 src1_sel:DWORD
	v_add_u32_e32 v105, v2, v136
	ds_write_b64 v105, v[108:109]
	v_and_b32_e32 v108, 0xffff0000, v111
	v_sub_u32_e32 v106, v106, v110
	v_and_b32_e32 v3, 0xffff0000, v3
	v_sub_u32_e32 v6, v6, v108
	v_add_u32_e32 v106, 0x80, v106
	v_sub_u32_e32 v3, v107, v3
	v_sub_u32_e32 v7, v7, v124
	v_add_u32_e32 v6, 0x80, v6
	v_ashrrev_i32_e32 v106, 8, v106
	v_add_u32_e32 v3, 0x80, v3
	v_add_u32_e32 v7, 0x80, v7
	v_ashrrev_i32_e32 v6, 8, v6
	v_min_i32_e32 v106, 0x7f, v106
	v_ashrrev_i32_e32 v3, 8, v3
	v_ashrrev_i32_e32 v7, 8, v7
	v_min_i32_e32 v6, 0x7f, v6
	v_min_i32_sdwa v3, v3, s83 dst_sel:WORD_1 dst_unused:UNUSED_PAD src0_sel:DWORD src1_sel:DWORD
	v_min_i32_e32 v7, 0x7f, v7
	v_lshlrev_b32_e32 v106, 8, v106
	v_and_b32_e32 v106, 0xff00, v106
	v_and_b32_e32 v3, 0xff0000, v3
	v_perm_b32 v6, v7, v6, s84
	v_or3_b32 v3, v6, v106, v3
	ds_write_b32 v20, v3 offset:16
	v_mov_b32_e32 v6, v208
	v_mov_b32_e32 v7, v209
	v_pk_add_f32 v[106:107], v[122:123], v[6:7] op_sel_hi:[1,0] neg_lo:[0,1] neg_hi:[0,1]
	s_nop 0
	v_pk_mul_f32 v[106:107], v[6:7], v[106:107] op_sel:[1,0]
	v_or_b32_e32 v122, 0x100, v155
	v_pk_fma_f32 v[108:109], v[128:129], v[106:107], v[130:131]
	v_pk_add_f32 v[106:107], v[114:115], v[6:7] op_sel_hi:[1,0] neg_lo:[0,1] neg_hi:[0,1]
	v_and_b32_sdwa v3, v109, v216 dst_sel:DWORD dst_unused:UNUSED_PAD src0_sel:WORD_1 src1_sel:DWORD
	v_pk_mul_f32 v[6:7], v[6:7], v[106:107] op_sel:[1,0]
	v_add3_u32 v3, v109, v3, s82
	v_pk_fma_f32 v[0:1], v[0:1], v[6:7], v[4:5]
	v_and_b32_sdwa v4, v108, v216 dst_sel:DWORD dst_unused:UNUSED_PAD src0_sel:WORD_1 src1_sel:DWORD
	v_add3_u32 v4, v108, v4, s82
	v_and_b32_e32 v6, 0xffff0000, v4
	v_and_b32_sdwa v4, v1, v216 dst_sel:DWORD dst_unused:UNUSED_PAD src0_sel:WORD_1 src1_sel:DWORD
	v_and_b32_sdwa v5, v0, v216 dst_sel:DWORD dst_unused:UNUSED_PAD src0_sel:WORD_1 src1_sel:DWORD
	v_add3_u32 v4, v1, v4, s82
	v_add3_u32 v7, v0, v5, s82
	v_and_b32_e32 v107, 0xffff0000, v4
	v_add_u32_e32 v106, v2, v135
	v_and_b32_e32 v2, 0xffff0000, v7
	v_or_b32_sdwa v5, v107, v3 dst_sel:DWORD dst_unused:UNUSED_PAD src0_sel:DWORD src1_sel:WORD_1
	v_sub_u32_e32 v0, v0, v2
	v_sub_u32_e32 v2, v108, v6
	v_and_b32_e32 v3, 0xffff0000, v3
	v_add_u32_e32 v2, 0x80, v2
	v_sub_u32_e32 v3, v109, v3
	v_sub_u32_e32 v1, v1, v107
	v_add_u32_e32 v0, 0x80, v0
	v_ashrrev_i32_e32 v2, 8, v2
	v_add_u32_e32 v3, 0x80, v3
	v_add_u32_e32 v1, 0x80, v1
	v_ashrrev_i32_e32 v0, 8, v0
	v_min_i32_e32 v2, 0x7f, v2
	v_ashrrev_i32_e32 v3, 8, v3
	v_ashrrev_i32_e32 v1, 8, v1
	v_min_i32_e32 v0, 0x7f, v0
	v_min_i32_sdwa v3, v3, s83 dst_sel:WORD_1 dst_unused:UNUSED_PAD src0_sel:DWORD src1_sel:DWORD
	v_min_i32_e32 v1, 0x7f, v1
	v_lshlrev_b32_e32 v2, 8, v2
	v_and_b32_e32 v2, 0xff00, v2
	v_and_b32_e32 v3, 0xff0000, v3
	v_perm_b32 v0, v1, v0, s84
	v_or_b32_sdwa v4, v7, v6 dst_sel:DWORD dst_unused:UNUSED_PAD src0_sel:WORD_1 src1_sel:DWORD
	v_or3_b32 v0, v0, v2, v3
	ds_write_b64 v106, v[4:5]
	ds_write_b32 v22, v0 offset:16
	v_mov_b32_e32 v0, v228
	v_mov_b32_e32 v1, v229
	v_mov_b32_e32 v2, v230
	v_mov_b32_e32 v3, v231
	v_mov_b32_e32 v4, v244
	v_mov_b32_e32 v5, v245
	v_mov_b32_e32 v6, v246
	v_mov_b32_e32 v7, v247
	v_mov_b32_e32 v114, v202
	v_mov_b32_e32 v115, v203
	v_add_u32_e32 v107, v122, v153
	v_pk_add_f32 v[118:119], v[118:119], v[114:115] op_sel_hi:[1,0] neg_lo:[0,1] neg_hi:[0,1]
	s_nop 0
	v_pk_mul_f32 v[118:119], v[114:115], v[118:119] op_sel:[1,0]
;     ...
;             _Pragma("unroll") for (int m = 0; m < 4; ++m) {
;               const int rr = wr3 * 64 + m * 16 + fr3;
;               const float2 ms = *reinterpret_cast<const float2*>(mr + (ai * HALF + rr) * 2);
;               f32x4 y = acc[ai][bj][m][n];
;               const float o0 = (y[0] - ms.x) * ms.y * gm.x + bt.x, o1 = (y[1] - ms.x) * ms.y * gm.y + bt.y;
;               const float o2 = (y[2] - ms.x) * ms.y * gm.z + bt.z, o3 = (y[3] - ms.x) * ms.y * gm.w + bt.w;
;               const unsigned h0 = f2bf(o0), h1 = f2bf(o1), h2 = f2bf(o2), h3 = f2bf(o3);
;               u32x2 ob; ob[0] = h0 | (h1 << 16); ob[1] = h2 | (h3 << 16);
;               *reinterpret_cast<u32x2*>(smem + (rr >> 1) * PIECE + (rr & 1) * 512 + cc * 2) = ob;
;               const int l0 = min(((int)__float_as_uint(o0) - (int)(h0 << 16) + 128) >> 8, 127);
;               const int l1 = min(((int)__float_as_uint(o1) - (int)(h1 << 16) + 128) >> 8, 127);
;               const int l2 = min(((int)__float_as_uint(o2) - (int)(h2 << 16) + 128) >> 8, 127);
;               const int l3 = min(((int)__float_as_uint(o3) - (int)(h3 << 16) + 128) >> 8, 127);
;               *reinterpret_cast<unsigned*>(smem + LOBASE + (rr >> 2) * PIECE + (rr & 3) * 256 + cc) =
;                   (unsigned)(l0 & 255) | ((unsigned)(l1 & 255) << 8) | ((unsigned)(l2 & 255) << 16) | ((unsigned)l3 << 24);
;             }
	v_pk_add_f32 v[120:121], v[120:121], v[114:115] op_sel_hi:[1,0] neg_lo:[0,1] neg_hi:[0,1]
	v_mov_b32_e32 v108, v1
	v_mov_b32_e32 v109, v2
	v_mov_b32_e32 v110, v5
	v_mov_b32_e32 v111, v6
	v_pk_fma_f32 v[118:119], v[108:109], v[118:119], v[110:111]
	v_pk_mul_f32 v[114:115], v[114:115], v[120:121] op_sel:[1,0]
	v_mov_b32_e32 v1, v3
	v_mov_b32_e32 v5, v7
	v_and_b32_sdwa v6, v119, v216 dst_sel:DWORD dst_unused:UNUSED_PAD src0_sel:WORD_1 src1_sel:DWORD
	v_and_b32_sdwa v7, v118, v216 dst_sel:DWORD dst_unused:UNUSED_PAD src0_sel:WORD_1 src1_sel:DWORD
	v_pk_fma_f32 v[2:3], v[0:1], v[114:115], v[4:5]
	v_add3_u32 v114, v119, v6, s82
	v_add3_u32 v6, v118, v7, s82
	v_and_b32_e32 v115, 0xffff0000, v6
	v_and_b32_sdwa v6, v3, v216 dst_sel:DWORD dst_unused:UNUSED_PAD src0_sel:WORD_1 src1_sel:DWORD
	v_and_b32_sdwa v7, v2, v216 dst_sel:DWORD dst_unused:UNUSED_PAD src0_sel:WORD_1 src1_sel:DWORD
	v_add3_u32 v6, v3, v6, s82
	v_add3_u32 v120, v2, v7, s82
	v_and_b32_e32 v121, 0xffff0000, v6
	v_or_b32_sdwa v7, v121, v114 dst_sel:DWORD dst_unused:UNUSED_PAD src0_sel:DWORD src1_sel:WORD_1
	v_or_b32_sdwa v6, v120, v115 dst_sel:DWORD dst_unused:UNUSED_PAD src0_sel:WORD_1 src1_sel:DWORD
	ds_write_b64 v107, v[6:7]
	v_and_b32_e32 v6, 0xffff0000, v120
	v_sub_u32_e32 v2, v2, v6
	v_sub_u32_e32 v6, v118, v115
	v_and_b32_e32 v7, 0xffff0000, v114
	v_add_u32_e32 v6, 0x80, v6
	v_sub_u32_e32 v7, v119, v7
	v_sub_u32_e32 v3, v3, v121
	v_add_u32_e32 v2, 0x80, v2
	v_ashrrev_i32_e32 v6, 8, v6
	v_add_u32_e32 v7, 0x80, v7
	v_add_u32_e32 v3, 0x80, v3
	v_ashrrev_i32_e32 v2, 8, v2
	v_min_i32_e32 v6, 0x7f, v6
	v_ashrrev_i32_e32 v7, 8, v7
	v_ashrrev_i32_e32 v3, 8, v3
	v_min_i32_e32 v2, 0x7f, v2
	v_min_i32_sdwa v7, v7, s83 dst_sel:WORD_1 dst_unused:UNUSED_PAD src0_sel:DWORD src1_sel:DWORD
	v_min_i32_e32 v3, 0x7f, v3
	v_lshlrev_b32_e32 v6, 8, v6
	v_and_b32_e32 v6, 0xff00, v6
	v_and_b32_e32 v7, 0xff0000, v7
	v_perm_b32 v2, v3, v2, s84
	v_or3_b32 v2, v2, v6, v7
	ds_write_b32 v12, v2 offset:128
	v_mov_b32_e32 v2, v204
	v_mov_b32_e32 v3, v205
	v_pk_add_f32 v[6:7], v[102:103], v[2:3] op_sel_hi:[1,0] neg_lo:[0,1] neg_hi:[0,1]
	s_nop 0
	v_pk_mul_f32 v[6:7], v[2:3], v[6:7] op_sel:[1,0]
	v_pk_add_f32 v[100:101], v[100:101], v[2:3] op_sel_hi:[1,0] neg_lo:[0,1] neg_hi:[0,1]
	v_pk_fma_f32 v[6:7], v[108:109], v[6:7], v[110:111]
	v_pk_mul_f32 v[2:3], v[2:3], v[100:101] op_sel:[1,0]
	v_and_b32_sdwa v100, v7, v216 dst_sel:DWORD dst_unused:UNUSED_PAD src0_sel:WORD_1 src1_sel:DWORD
	v_and_b32_sdwa v101, v6, v216 dst_sel:DWORD dst_unused:UNUSED_PAD src0_sel:WORD_1 src1_sel:DWORD
	v_pk_fma_f32 v[2:3], v[0:1], v[2:3], v[4:5]
	v_add3_u32 v114, v7, v100, s82
	v_add3_u32 v100, v6, v101, s82
	v_and_b32_e32 v101, 0xffff0000, v100
	v_and_b32_sdwa v100, v3, v216 dst_sel:DWORD dst_unused:UNUSED_PAD src0_sel:WORD_1 src1_sel:DWORD
	v_and_b32_sdwa v102, v2, v216 dst_sel:DWORD dst_unused:UNUSED_PAD src0_sel:WORD_1 src1_sel:DWORD
	v_add3_u32 v100, v3, v100, s82
	v_add3_u32 v115, v2, v102, s82
	v_and_b32_e32 v118, 0xffff0000, v100
	v_or_b32_sdwa v103, v118, v114 dst_sel:DWORD dst_unused:UNUSED_PAD src0_sel:DWORD src1_sel:WORD_1
	v_or_b32_sdwa v102, v115, v101 dst_sel:DWORD dst_unused:UNUSED_PAD src0_sel:WORD_1 src1_sel:DWORD
	v_add_u32_e32 v100, v122, v154
	ds_write_b64 v100, v[102:103]
	v_and_b32_e32 v102, 0xffff0000, v115
	v_sub_u32_e32 v6, v6, v101
	v_and_b32_e32 v101, 0xffff0000, v114
	v_sub_u32_e32 v2, v2, v102
	v_add_u32_e32 v6, 0x80, v6
	v_sub_u32_e32 v7, v7, v101
	v_sub_u32_e32 v3, v3, v118
	v_add_u32_e32 v2, 0x80, v2
	v_ashrrev_i32_e32 v6, 8, v6
	v_add_u32_e32 v7, 0x80, v7
	v_add_u32_e32 v3, 0x80, v3
	v_ashrrev_i32_e32 v2, 8, v2
	v_min_i32_e32 v6, 0x7f, v6
	v_ashrrev_i32_e32 v7, 8, v7
	v_ashrrev_i32_e32 v3, 8, v3
	v_min_i32_e32 v2, 0x7f, v2
	v_min_i32_sdwa v7, v7, s83 dst_sel:WORD_1 dst_unused:UNUSED_PAD src0_sel:DWORD src1_sel:DWORD
	v_min_i32_e32 v3, 0x7f, v3
	v_lshlrev_b32_e32 v6, 8, v6
	v_and_b32_e32 v6, 0xff00, v6
	v_and_b32_e32 v7, 0xff0000, v7
	v_perm_b32 v2, v3, v2, s84
	v_or3_b32 v2, v2, v6, v7
	ds_write_b32 v14, v2 offset:128
	v_mov_b32_e32 v2, v206
	v_mov_b32_e32 v3, v207
	v_add_u32_e32 v101, v122, v136
	v_pk_add_f32 v[6:7], v[90:91], v[2:3] op_sel_hi:[1,0] neg_lo:[0,1] neg_hi:[0,1]
	s_nop 0
	v_pk_mul_f32 v[6:7], v[2:3], v[6:7] op_sel:[1,0]
	v_pk_add_f32 v[88:89], v[88:89], v[2:3] op_sel_hi:[1,0] neg_lo:[0,1] neg_hi:[0,1]
	v_pk_fma_f32 v[6:7], v[108:109], v[6:7], v[110:111]
	v_pk_mul_f32 v[2:3], v[2:3], v[88:89] op_sel:[1,0]
	v_and_b32_sdwa v88, v7, v216 dst_sel:DWORD dst_unused:UNUSED_PAD src0_sel:WORD_1 src1_sel:DWORD
	v_and_b32_sdwa v89, v6, v216 dst_sel:DWORD dst_unused:UNUSED_PAD src0_sel:WORD_1 src1_sel:DWORD
	v_pk_fma_f32 v[2:3], v[0:1], v[2:3], v[4:5]
	v_add3_u32 v90, v7, v88, s82
	v_add3_u32 v88, v6, v89, s82
	v_and_b32_e32 v91, 0xffff0000, v88
	v_and_b32_sdwa v88, v3, v216 dst_sel:DWORD dst_unused:UNUSED_PAD src0_sel:WORD_1 src1_sel:DWORD
	v_and_b32_sdwa v89, v2, v216 dst_sel:DWORD dst_unused:UNUSED_PAD src0_sel:WORD_1 src1_sel:DWORD
	v_add3_u32 v88, v3, v88, s82
	v_add3_u32 v102, v2, v89, s82
	v_and_b32_e32 v103, 0xffff0000, v88
	v_or_b32_sdwa v89, v103, v90 dst_sel:DWORD dst_unused:UNUSED_PAD src0_sel:DWORD src1_sel:WORD_1
	v_or_b32_sdwa v88, v102, v91 dst_sel:DWORD dst_unused:UNUSED_PAD src0_sel:WORD_1 src1_sel:DWORD
	ds_write_b64 v101, v[88:89]
	v_and_b32_e32 v88, 0xffff0000, v102
	v_sub_u32_e32 v2, v2, v88
	v_sub_u32_e32 v6, v6, v91
	v_and_b32_e32 v88, 0xffff0000, v90
	v_add_u32_e32 v6, 0x80, v6
	v_sub_u32_e32 v7, v7, v88
	v_sub_u32_e32 v3, v3, v103
	v_add_u32_e32 v2, 0x80, v2
	v_ashrrev_i32_e32 v6, 8, v6
	v_add_u32_e32 v7, 0x80, v7
	v_add_u32_e32 v3, 0x80, v3
	v_ashrrev_i32_e32 v2, 8, v2
;     ...
;           _Pragma("unroll") for (int bj = 0; bj < 2; ++bj) _Pragma("unroll") for (int n = 0; n < 2; ++n) {
;             const int cc = bj * HALF + wc3 * 32 + n * 16 + fq3 * 4;
;             const float4 gm = *reinterpret_cast<const float4*>(g.gam + pn * BM + cc), bt = *reinterpret_cast<const float4*>(g.bet + pn * BM + cc);
;             _Pragma("unroll") for (int m = 0; m < 4; ++m) {
;               const int rr = wr3 * 64 + m * 16 + fr3;
;               const float2 ms = *reinterpret_cast<const float2*>(mr + (ai * HALF + rr) * 2);
;               f32x4 y = acc[ai][bj][m][n];
;               const float o0 = (y[0] - ms.x) * ms.y * gm.x + bt.x, o1 = (y[1] - ms.x) * ms.y * gm.y + bt.y;
;               const float o2 = (y[2] - ms.x) * ms.y * gm.z + bt.z, o3 = (y[3] - ms.x) * ms.y * gm.w + bt.w;
;               const unsigned h0 = f2bf(o0), h1 = f2bf(o1), h2 = f2bf(o2), h3 = f2bf(o3);
;               u32x2 ob; ob[0] = h0 | (h1 << 16); ob[1] = h2 | (h3 << 16);
;               *reinterpret_cast<u32x2*>(smem + (rr >> 1) * PIECE + (rr & 1) * 512 + cc * 2) = ob;
;               const int l0 = min(((int)__float_as_uint(o0) - (int)(h0 << 16) + 128) >> 8, 127);
;               const int l1 = min(((int)__float_as_uint(o1) - (int)(h1 << 16) + 128) >> 8, 127);
;               const int l2 = min(((int)__float_as_uint(o2) - (int)(h2 << 16) + 128) >> 8, 127);
;               const int l3 = min(((int)__float_as_uint(o3) - (int)(h3 << 16) + 128) >> 8, 127);
;               *reinterpret_cast<unsigned*>(smem + LOBASE + (rr >> 2) * PIECE + (rr & 3) * 256 + cc) =
;                   (unsigned)(l0 & 255) | ((unsigned)(l1 & 255) << 8) | ((unsigned)(l2 & 255) << 16) | ((unsigned)l3 << 24);
;             }
	v_min_i32_e32 v6, 0x7f, v6
	v_ashrrev_i32_e32 v7, 8, v7
	v_ashrrev_i32_e32 v3, 8, v3
	v_min_i32_e32 v2, 0x7f, v2
	v_min_i32_sdwa v7, v7, s83 dst_sel:WORD_1 dst_unused:UNUSED_PAD src0_sel:DWORD src1_sel:DWORD
	v_min_i32_e32 v3, 0x7f, v3
	v_lshlrev_b32_e32 v6, 8, v6
	v_and_b32_e32 v6, 0xff00, v6
	v_and_b32_e32 v7, 0xff0000, v7
	v_perm_b32 v2, v3, v2, s84
	v_or3_b32 v2, v2, v6, v7
	ds_write_b32 v20, v2 offset:128
	v_mov_b32_e32 v2, v208
	v_mov_b32_e32 v3, v209
	v_pk_add_f32 v[6:7], v[94:95], v[2:3] op_sel_hi:[1,0] neg_lo:[0,1] neg_hi:[0,1]
	s_nop 0
	v_pk_mul_f32 v[6:7], v[2:3], v[6:7] op_sel:[1,0]
	v_pk_add_f32 v[88:89], v[92:93], v[2:3] op_sel_hi:[1,0] neg_lo:[0,1] neg_hi:[0,1]
	v_pk_fma_f32 v[6:7], v[108:109], v[6:7], v[110:111]
	v_pk_mul_f32 v[2:3], v[2:3], v[88:89] op_sel:[1,0]
	v_add_u32_e32 v92, v122, v135
	v_pk_fma_f32 v[0:1], v[0:1], v[2:3], v[4:5]
	v_and_b32_sdwa v2, v7, v216 dst_sel:DWORD dst_unused:UNUSED_PAD src0_sel:WORD_1 src1_sel:DWORD
	v_and_b32_sdwa v3, v6, v216 dst_sel:DWORD dst_unused:UNUSED_PAD src0_sel:WORD_1 src1_sel:DWORD
	v_add3_u32 v4, v7, v2, s82
	v_add3_u32 v2, v6, v3, s82
	v_and_b32_e32 v5, 0xffff0000, v2
	v_and_b32_sdwa v2, v1, v216 dst_sel:DWORD dst_unused:UNUSED_PAD src0_sel:WORD_1 src1_sel:DWORD
	v_and_b32_sdwa v3, v0, v216 dst_sel:DWORD dst_unused:UNUSED_PAD src0_sel:WORD_1 src1_sel:DWORD
	v_add3_u32 v2, v1, v2, s82
	v_add3_u32 v88, v0, v3, s82
	v_and_b32_e32 v89, 0xffff0000, v2
	v_or_b32_sdwa v3, v89, v4 dst_sel:DWORD dst_unused:UNUSED_PAD src0_sel:DWORD src1_sel:WORD_1
	v_or_b32_sdwa v2, v88, v5 dst_sel:DWORD dst_unused:UNUSED_PAD src0_sel:WORD_1 src1_sel:DWORD
	ds_write_b64 v92, v[2:3]
	v_and_b32_e32 v2, 0xffff0000, v88
	v_sub_u32_e32 v0, v0, v2
	v_sub_u32_e32 v2, v6, v5
	v_and_b32_e32 v3, 0xffff0000, v4
	v_add_u32_e32 v2, 0x80, v2
	v_sub_u32_e32 v3, v7, v3
	v_sub_u32_e32 v1, v1, v89
	v_add_u32_e32 v0, 0x80, v0
	v_ashrrev_i32_e32 v2, 8, v2
	v_add_u32_e32 v3, 0x80, v3
	v_add_u32_e32 v1, 0x80, v1
	v_ashrrev_i32_e32 v0, 8, v0
	v_min_i32_e32 v2, 0x7f, v2
	v_ashrrev_i32_e32 v3, 8, v3
	v_ashrrev_i32_e32 v1, 8, v1
	v_min_i32_e32 v0, 0x7f, v0
	v_min_i32_sdwa v3, v3, s83 dst_sel:WORD_1 dst_unused:UNUSED_PAD src0_sel:DWORD src1_sel:DWORD
	v_min_i32_e32 v1, 0x7f, v1
	v_lshlrev_b32_e32 v2, 8, v2
	v_and_b32_e32 v2, 0xff00, v2
	v_and_b32_e32 v3, 0xff0000, v3
	v_perm_b32 v0, v1, v0, s84
	v_or3_b32 v0, v0, v2, v3
	ds_write_b32 v22, v0 offset:128
	v_mov_b32_e32 v0, v232
	v_mov_b32_e32 v1, v233
	v_mov_b32_e32 v2, v234
	v_mov_b32_e32 v3, v235
	v_mov_b32_e32 v4, v248
	v_mov_b32_e32 v5, v249
	v_mov_b32_e32 v6, v250
	v_mov_b32_e32 v7, v251
	v_mov_b32_e32 v94, v202
	v_mov_b32_e32 v95, v203
	v_pk_add_f32 v[102:103], v[116:117], v[94:95] op_sel_hi:[1,0] neg_lo:[0,1] neg_hi:[0,1]
	s_nop 0
	v_pk_mul_f32 v[102:103], v[94:95], v[102:103] op_sel:[1,0]
	v_pk_add_f32 v[108:109], v[112:113], v[94:95] op_sel_hi:[1,0] neg_lo:[0,1] neg_hi:[0,1]
	v_mov_b32_e32 v88, v1
	v_mov_b32_e32 v89, v2
	v_mov_b32_e32 v90, v5
	v_mov_b32_e32 v91, v6
	v_pk_fma_f32 v[102:103], v[88:89], v[102:103], v[90:91]
	v_pk_mul_f32 v[94:95], v[94:95], v[108:109] op_sel:[1,0]
	v_mov_b32_e32 v1, v3
	v_mov_b32_e32 v5, v7
	v_and_b32_sdwa v93, v102, v216 dst_sel:DWORD dst_unused:UNUSED_PAD src0_sel:WORD_1 src1_sel:DWORD
	v_pk_fma_f32 v[6:7], v[0:1], v[94:95], v[4:5]
	v_add3_u32 v93, v102, v93, s82
	v_and_b32_e32 v108, 0xffff0000, v93
	v_and_b32_sdwa v93, v7, v216 dst_sel:DWORD dst_unused:UNUSED_PAD src0_sel:WORD_1 src1_sel:DWORD
	v_and_b32_sdwa v3, v103, v216 dst_sel:DWORD dst_unused:UNUSED_PAD src0_sel:WORD_1 src1_sel:DWORD
	v_and_b32_sdwa v94, v6, v216 dst_sel:DWORD dst_unused:UNUSED_PAD src0_sel:WORD_1 src1_sel:DWORD
	v_add3_u32 v93, v7, v93, s82
	v_or_b32_e32 v2, 0x120, v155
	v_add3_u32 v3, v103, v3, s82
	v_add3_u32 v109, v6, v94, s82
	v_and_b32_e32 v110, 0xffff0000, v93
	v_or_b32_sdwa v95, v110, v3 dst_sel:DWORD dst_unused:UNUSED_PAD src0_sel:DWORD src1_sel:WORD_1
	v_or_b32_sdwa v94, v109, v108 dst_sel:DWORD dst_unused:UNUSED_PAD src0_sel:WORD_1 src1_sel:DWORD
	v_add_u32_e32 v93, v2, v153
	ds_write_b64 v93, v[94:95]
	v_and_b32_e32 v94, 0xffff0000, v109
	v_sub_u32_e32 v6, v6, v94
	v_sub_u32_e32 v94, v102, v108
	v_and_b32_e32 v3, 0xffff0000, v3
	v_add_u32_e32 v94, 0x80, v94
	v_sub_u32_e32 v3, v103, v3
	v_sub_u32_e32 v7, v7, v110
	v_add_u32_e32 v6, 0x80, v6
	v_ashrrev_i32_e32 v94, 8, v94
	v_add_u32_e32 v3, 0x80, v3
	v_add_u32_e32 v7, 0x80, v7
	v_ashrrev_i32_e32 v6, 8, v6
	v_min_i32_e32 v94, 0x7f, v94
	v_ashrrev_i32_e32 v3, 8, v3
	v_ashrrev_i32_e32 v7, 8, v7
	v_min_i32_e32 v6, 0x7f, v6
	v_min_i32_sdwa v3, v3, s83 dst_sel:WORD_1 dst_unused:UNUSED_PAD src0_sel:DWORD src1_sel:DWORD
	v_min_i32_e32 v7, 0x7f, v7
	v_lshlrev_b32_e32 v94, 8, v94
	v_and_b32_e32 v94, 0xff00, v94
	v_and_b32_e32 v3, 0xff0000, v3
	v_perm_b32 v6, v7, v6, s84
	v_or3_b32 v3, v6, v94, v3
	ds_write_b32 v12, v3 offset:144
	v_mov_b32_e32 v6, v204
	v_mov_b32_e32 v7, v205
	v_pk_add_f32 v[94:95], v[98:99], v[6:7] op_sel_hi:[1,0] neg_lo:[0,1] neg_hi:[0,1]
	s_nop 0
	v_pk_mul_f32 v[94:95], v[6:7], v[94:95] op_sel:[1,0]
	s_nop 0
	v_pk_fma_f32 v[98:99], v[88:89], v[94:95], v[90:91]
	v_pk_add_f32 v[94:95], v[96:97], v[6:7] op_sel_hi:[1,0] neg_lo:[0,1] neg_hi:[0,1]
	v_and_b32_sdwa v3, v99, v216 dst_sel:DWORD dst_unused:UNUSED_PAD src0_sel:WORD_1 src1_sel:DWORD
	v_pk_mul_f32 v[6:7], v[6:7], v[94:95] op_sel:[1,0]
	v_and_b32_sdwa v94, v98, v216 dst_sel:DWORD dst_unused:UNUSED_PAD src0_sel:WORD_1 src1_sel:DWORD
	v_pk_fma_f32 v[6:7], v[0:1], v[6:7], v[4:5]
	v_add3_u32 v94, v98, v94, s82
	v_and_b32_e32 v95, 0xffff0000, v94
	v_and_b32_sdwa v94, v7, v216 dst_sel:DWORD dst_unused:UNUSED_PAD src0_sel:WORD_1 src1_sel:DWORD
; #define WAIT_L(n) asm volatile("s_waitcnt lgkmcnt(" #n ")" ::: "memory")
; #define BAR __builtin_amdgcn_s_barrier()
;     ...
;           _Pragma("unroll") for (int bj = 0; bj < 2; ++bj) _Pragma("unroll") for (int n = 0; n < 2; ++n) {
;             const int cc = bj * HALF + wc3 * 32 + n * 16 + fq3 * 4;
;             const float4 gm = *reinterpret_cast<const float4*>(g.gam + pn * BM + cc), bt = *reinterpret_cast<const float4*>(g.bet + pn * BM + cc);
;             _Pragma("unroll") for (int m = 0; m < 4; ++m) {
;               const int rr = wr3 * 64 + m * 16 + fr3;
;               const float2 ms = *reinterpret_cast<const float2*>(mr + (ai * HALF + rr) * 2);
;               f32x4 y = acc[ai][bj][m][n];
;               const float o0 = (y[0] - ms.x) * ms.y * gm.x + bt.x, o1 = (y[1] - ms.x) * ms.y * gm.y + bt.y;
;               const float o2 = (y[2] - ms.x) * ms.y * gm.z + bt.z, o3 = (y[3] - ms.x) * ms.y * gm.w + bt.w;
;               const unsigned h0 = f2bf(o0), h1 = f2bf(o1), h2 = f2bf(o2), h3 = f2bf(o3);
;               u32x2 ob; ob[0] = h0 | (h1 << 16); ob[1] = h2 | (h3 << 16);
;               *reinterpret_cast<u32x2*>(smem + (rr >> 1) * PIECE + (rr & 1) * 512 + cc * 2) = ob;
;               const int l0 = min(((int)__float_as_uint(o0) - (int)(h0 << 16) + 128) >> 8, 127);
;               const int l1 = min(((int)__float_as_uint(o1) - (int)(h1 << 16) + 128) >> 8, 127);
;               const int l2 = min(((int)__float_as_uint(o2) - (int)(h2 << 16) + 128) >> 8, 127);
;               const int l3 = min(((int)__float_as_uint(o3) - (int)(h3 << 16) + 128) >> 8, 127);
;               *reinterpret_cast<unsigned*>(smem + LOBASE + (rr >> 2) * PIECE + (rr & 3) * 256 + cc) =
;                   (unsigned)(l0 & 255) | ((unsigned)(l1 & 255) << 8) | ((unsigned)(l2 & 255) << 16) | ((unsigned)l3 << 24);
;             }
;           }
;           WAIT_L(0); BAR;
	v_and_b32_sdwa v96, v6, v216 dst_sel:DWORD dst_unused:UNUSED_PAD src0_sel:WORD_1 src1_sel:DWORD
	v_add3_u32 v94, v7, v94, s82
	v_add3_u32 v3, v99, v3, s82
	v_add3_u32 v102, v6, v96, s82
	v_and_b32_e32 v103, 0xffff0000, v94
	v_or_b32_sdwa v97, v103, v3 dst_sel:DWORD dst_unused:UNUSED_PAD src0_sel:DWORD src1_sel:WORD_1
	v_or_b32_sdwa v96, v102, v95 dst_sel:DWORD dst_unused:UNUSED_PAD src0_sel:WORD_1 src1_sel:DWORD
	v_add_u32_e32 v94, v2, v154
	ds_write_b64 v94, v[96:97]
	v_and_b32_e32 v96, 0xffff0000, v102
	v_sub_u32_e32 v95, v98, v95
	v_and_b32_e32 v3, 0xffff0000, v3
	v_sub_u32_e32 v6, v6, v96
	v_add_u32_e32 v95, 0x80, v95
	v_sub_u32_e32 v3, v99, v3
	v_sub_u32_e32 v7, v7, v103
	v_add_u32_e32 v6, 0x80, v6
	v_ashrrev_i32_e32 v95, 8, v95
	v_add_u32_e32 v3, 0x80, v3
	v_add_u32_e32 v7, 0x80, v7
	v_ashrrev_i32_e32 v6, 8, v6
	v_min_i32_e32 v95, 0x7f, v95
	v_ashrrev_i32_e32 v3, 8, v3
	v_ashrrev_i32_e32 v7, 8, v7
	v_min_i32_e32 v6, 0x7f, v6
	v_min_i32_sdwa v3, v3, s83 dst_sel:WORD_1 dst_unused:UNUSED_PAD src0_sel:DWORD src1_sel:DWORD
	v_min_i32_e32 v7, 0x7f, v7
	v_lshlrev_b32_e32 v95, 8, v95
	v_and_b32_e32 v95, 0xff00, v95
	v_and_b32_e32 v3, 0xff0000, v3
	v_perm_b32 v6, v7, v6, s84
	v_or3_b32 v3, v6, v95, v3
	ds_write_b32 v14, v3 offset:144
	v_mov_b32_e32 v6, v206
	v_mov_b32_e32 v7, v207
	v_pk_add_f32 v[82:83], v[82:83], v[6:7] op_sel_hi:[1,0] neg_lo:[0,1] neg_hi:[0,1]
	s_nop 0
	v_pk_mul_f32 v[82:83], v[6:7], v[82:83] op_sel:[1,0]
	v_pk_add_f32 v[80:81], v[80:81], v[6:7] op_sel_hi:[1,0] neg_lo:[0,1] neg_hi:[0,1]
	v_pk_fma_f32 v[82:83], v[88:89], v[82:83], v[90:91]
	v_pk_mul_f32 v[6:7], v[6:7], v[80:81] op_sel:[1,0]
	v_and_b32_sdwa v80, v82, v216 dst_sel:DWORD dst_unused:UNUSED_PAD src0_sel:WORD_1 src1_sel:DWORD
	v_pk_fma_f32 v[6:7], v[0:1], v[6:7], v[4:5]
	v_add3_u32 v80, v82, v80, s82
	v_and_b32_e32 v81, 0xffff0000, v80
	v_and_b32_sdwa v80, v7, v216 dst_sel:DWORD dst_unused:UNUSED_PAD src0_sel:WORD_1 src1_sel:DWORD
	v_and_b32_sdwa v3, v83, v216 dst_sel:DWORD dst_unused:UNUSED_PAD src0_sel:WORD_1 src1_sel:DWORD
	v_and_b32_sdwa v95, v6, v216 dst_sel:DWORD dst_unused:UNUSED_PAD src0_sel:WORD_1 src1_sel:DWORD
	v_add3_u32 v80, v7, v80, s82
	v_add3_u32 v3, v83, v3, s82
	v_add3_u32 v95, v6, v95, s82
	v_and_b32_e32 v98, 0xffff0000, v80
	v_or_b32_sdwa v97, v98, v3 dst_sel:DWORD dst_unused:UNUSED_PAD src0_sel:DWORD src1_sel:WORD_1
	v_or_b32_sdwa v96, v95, v81 dst_sel:DWORD dst_unused:UNUSED_PAD src0_sel:WORD_1 src1_sel:DWORD
	v_and_b32_e32 v95, 0xffff0000, v95
	v_sub_u32_e32 v81, v82, v81
	v_and_b32_e32 v3, 0xffff0000, v3
	v_sub_u32_e32 v6, v6, v95
	v_add_u32_e32 v81, 0x80, v81
	v_sub_u32_e32 v3, v83, v3
	v_sub_u32_e32 v7, v7, v98
	v_add_u32_e32 v6, 0x80, v6
	v_ashrrev_i32_e32 v81, 8, v81
	v_add_u32_e32 v3, 0x80, v3
	v_add_u32_e32 v7, 0x80, v7
	v_ashrrev_i32_e32 v6, 8, v6
	v_min_i32_e32 v81, 0x7f, v81
	v_ashrrev_i32_e32 v3, 8, v3
	v_ashrrev_i32_e32 v7, 8, v7
	v_min_i32_e32 v6, 0x7f, v6
	v_min_i32_sdwa v3, v3, s83 dst_sel:WORD_1 dst_unused:UNUSED_PAD src0_sel:DWORD src1_sel:DWORD
	v_min_i32_e32 v7, 0x7f, v7
	v_lshlrev_b32_e32 v81, 8, v81
	v_and_b32_e32 v81, 0xff00, v81
	v_and_b32_e32 v3, 0xff0000, v3
	v_perm_b32 v6, v7, v6, s84
	v_add_u32_e32 v80, v2, v136
	v_or3_b32 v3, v6, v81, v3
	ds_write_b64 v80, v[96:97]
	ds_write_b32 v20, v3 offset:144
	v_mov_b32_e32 v6, v208
	v_mov_b32_e32 v7, v209
	v_or_b32_e32 v81, 0x6000, v148
	v_or_b32_e32 v82, 0x8000, v148
	v_or_b32_e32 v83, 0xa000, v148
	v_or_b32_e32 v95, 0x6000, v146
	v_pk_add_f32 v[74:75], v[74:75], v[6:7] op_sel_hi:[1,0] neg_lo:[0,1] neg_hi:[0,1]
	v_pk_add_f32 v[72:73], v[72:73], v[6:7] op_sel_hi:[1,0] neg_lo:[0,1] neg_hi:[0,1]
	v_pk_mul_f32 v[74:75], v[6:7], v[74:75] op_sel:[1,0]
	v_pk_mul_f32 v[6:7], v[6:7], v[72:73] op_sel:[1,0]
	v_pk_fma_f32 v[74:75], v[88:89], v[74:75], v[90:91]
	v_pk_fma_f32 v[0:1], v[0:1], v[6:7], v[4:5]
	v_and_b32_sdwa v4, v74, v216 dst_sel:DWORD dst_unused:UNUSED_PAD src0_sel:WORD_1 src1_sel:DWORD
	v_add3_u32 v4, v74, v4, s82
	v_and_b32_e32 v6, 0xffff0000, v4
	v_and_b32_sdwa v4, v1, v216 dst_sel:DWORD dst_unused:UNUSED_PAD src0_sel:WORD_1 src1_sel:DWORD
	v_and_b32_sdwa v5, v0, v216 dst_sel:DWORD dst_unused:UNUSED_PAD src0_sel:WORD_1 src1_sel:DWORD
	v_and_b32_sdwa v3, v75, v216 dst_sel:DWORD dst_unused:UNUSED_PAD src0_sel:WORD_1 src1_sel:DWORD
	v_add3_u32 v4, v1, v4, s82
	v_add3_u32 v7, v0, v5, s82
	v_add3_u32 v3, v75, v3, s82
	v_and_b32_e32 v72, 0xffff0000, v4
	v_add_u32_e32 v73, v2, v135
	v_and_b32_e32 v2, 0xffff0000, v7
	v_or_b32_sdwa v5, v72, v3 dst_sel:DWORD dst_unused:UNUSED_PAD src0_sel:DWORD src1_sel:WORD_1
	v_sub_u32_e32 v0, v0, v2
	v_sub_u32_e32 v2, v74, v6
	v_and_b32_e32 v3, 0xffff0000, v3
	v_add_u32_e32 v2, 0x80, v2
	v_sub_u32_e32 v3, v75, v3
	v_sub_u32_e32 v1, v1, v72
	v_add_u32_e32 v0, 0x80, v0
	v_ashrrev_i32_e32 v2, 8, v2
	v_add_u32_e32 v3, 0x80, v3
	v_add_u32_e32 v1, 0x80, v1
	v_ashrrev_i32_e32 v0, 8, v0
	v_min_i32_e32 v2, 0x7f, v2
	v_ashrrev_i32_e32 v3, 8, v3
	v_ashrrev_i32_e32 v1, 8, v1
	v_min_i32_e32 v0, 0x7f, v0
	v_min_i32_sdwa v3, v3, s83 dst_sel:WORD_1 dst_unused:UNUSED_PAD src0_sel:DWORD src1_sel:DWORD
	v_min_i32_e32 v1, 0x7f, v1
	v_lshlrev_b32_e32 v2, 8, v2
	v_and_b32_e32 v2, 0xff00, v2
	v_and_b32_e32 v3, 0xff0000, v3
	v_perm_b32 v0, v1, v0, s84
	v_or_b32_sdwa v4, v7, v6 dst_sel:DWORD dst_unused:UNUSED_PAD src0_sel:WORD_1 src1_sel:DWORD
	v_or3_b32 v0, v0, v2, v3
	ds_write_b64 v73, v[4:5]
	ds_write_b32 v22, v0 offset:144
	v_add_u32_e32 v72, s47, v152
	s_waitcnt lgkmcnt(0)
	s_barrier
;     ...
;           _Pragma("unroll") for (int bj = 0; bj < 2; ++bj) _Pragma("unroll") for (int n = 0; n < 2; ++n) {
;             const int cc = bj * HALF + wc3 * 32 + n * 16 + fq3 * 4;
;             const float4 gm = *reinterpret_cast<const float4*>(g.gam + pn * BM + cc), bt = *reinterpret_cast<const float4*>(g.bet + pn * BM + cc);
;             _Pragma("unroll") for (int m = 0; m < 4; ++m) {
;               const int rr = wr3 * 64 + m * 16 + fr3;
;               const float2 ms = *reinterpret_cast<const float2*>(mr + (ai * HALF + rr) * 2);
;               f32x4 y = acc[ai][bj][m][n];
;               const float o0 = (y[0] - ms.x) * ms.y * gm.x + bt.x, o1 = (y[1] - ms.x) * ms.y * gm.y + bt.y;
;               const float o2 = (y[2] - ms.x) * ms.y * gm.z + bt.z, o3 = (y[3] - ms.x) * ms.y * gm.w + bt.w;
;               const unsigned h0 = f2bf(o0), h1 = f2bf(o1), h2 = f2bf(o2), h3 = f2bf(o3);
;               u32x2 ob; ob[0] = h0 | (h1 << 16); ob[1] = h2 | (h3 << 16);
;               *reinterpret_cast<u32x2*>(smem + (rr >> 1) * PIECE + (rr & 1) * 512 + cc * 2) = ob;
;               const int l0 = min(((int)__float_as_uint(o0) - (int)(h0 << 16) + 128) >> 8, 127);
;               const int l1 = min(((int)__float_as_uint(o1) - (int)(h1 << 16) + 128) >> 8, 127);
;               const int l2 = min(((int)__float_as_uint(o2) - (int)(h2 << 16) + 128) >> 8, 127);
;               const int l3 = min(((int)__float_as_uint(o3) - (int)(h3 << 16) + 128) >> 8, 127);
;               *reinterpret_cast<unsigned*>(smem + LOBASE + (rr >> 2) * PIECE + (rr & 3) * 256 + cc) =
;                   (unsigned)(l0 & 255) | ((unsigned)(l1 & 255) << 8) | ((unsigned)(l2 & 255) << 16) | ((unsigned)l3 << 24);
;             }
;           }
;           WAIT_L(0); BAR;
;           const int hso = ((brow + ai * HALF + 16 * wave) * DM + pn * BM) * 2;
;           const int lso = (brow + ai * HALF + 16 * wave) * DM + pn * BM;
;           _Pragma("unroll") for (int i = 0; i < 8; ++i) {
;             const u32x4 v = *reinterpret_cast<const u32x4*>(smem + (wave * 8 + i) * PIECE + lane3 * 16);
;             __builtin_amdgcn_raw_buffer_store_b128(v, rsXB, hvo + i * (2 * DM * 2), hso, 0);
;           }
;           _Pragma("unroll") for (int i = 0; i < 4; ++i) {
;             const u32x4 v = *reinterpret_cast<const u32x4*>(smem + LOBASE + (wave * 4 + i) * PIECE + lane3 * 16);
	ds_read_b128 v[128:131], v72
	v_or_b32_e32 v74, 0x2000, v148
	v_or_b32_e32 v75, 0x4000, v148
	v_or_b32_e32 v88, 0xc000, v148
	v_or_b32_e32 v89, 0xe000, v148
	ds_read_b128 v[136:139], v72 offset:1040
	v_or_b32_e32 v90, 0x2000, v146
	v_or_b32_e32 v91, 0x4000, v146
	ds_read_b128 v[140:143], v72 offset:2080
	ds_read_b128 v[152:155], v72 offset:3120
	ds_read_b128 v[156:159], v72 offset:4160
	ds_read_b128 v[160:163], v72 offset:5200
	ds_read_b128 v[164:167], v72 offset:6240
	ds_read_b128 v[168:171], v72 offset:7280
	ds_read_b128 v[172:175], v147
	ds_read_b128 v[176:179], v147 offset:1040
	ds_read_b128 v[180:183], v147 offset:2080
	ds_read_b128 v[184:187], v147 offset:3120
	s_waitcnt lgkmcnt(0)
	s_barrier
	s_nop 1
	v_mov_b32_e32 v0, v220
	v_mov_b32_e32 v1, v221
	v_mov_b32_e32 v2, v222
	v_mov_b32_e32 v3, v223
	v_mov_b32_e32 v4, v236
	v_mov_b32_e32 v5, v237
	v_mov_b32_e32 v6, v238
	v_mov_b32_e32 v7, v239
	ds_read_b64 v[102:103], v149 offset:1024
	s_waitcnt lgkmcnt(0)
	v_mov_b32_e32 v210, v102
	v_mov_b32_e32 v211, v103
	v_pk_add_f32 v[66:67], v[66:67], v[102:103] op_sel_hi:[1,0] neg_lo:[0,1] neg_hi:[0,1]
	s_nop 0
	v_pk_mul_f32 v[66:67], v[102:103], v[66:67] op_sel:[1,0]
	v_pk_add_f32 v[64:65], v[64:65], v[102:103] op_sel_hi:[1,0] neg_lo:[0,1] neg_hi:[0,1]
	v_mov_b32_e32 v96, v1
	v_mov_b32_e32 v97, v2
	v_mov_b32_e32 v98, v5
	v_mov_b32_e32 v99, v6
	v_pk_fma_f32 v[66:67], v[96:97], v[66:67], v[98:99]
	v_pk_mul_f32 v[64:65], v[102:103], v[64:65] op_sel:[1,0]
	v_mov_b32_e32 v1, v3
	v_mov_b32_e32 v5, v7
	v_and_b32_sdwa v6, v67, v216 dst_sel:DWORD dst_unused:UNUSED_PAD src0_sel:WORD_1 src1_sel:DWORD
	v_and_b32_sdwa v7, v66, v216 dst_sel:DWORD dst_unused:UNUSED_PAD src0_sel:WORD_1 src1_sel:DWORD
	v_pk_fma_f32 v[2:3], v[0:1], v[64:65], v[4:5]
	v_add3_u32 v64, v67, v6, s82
	v_add3_u32 v6, v66, v7, s82
	v_and_b32_e32 v65, 0xffff0000, v6
	v_and_b32_sdwa v6, v3, v216 dst_sel:DWORD dst_unused:UNUSED_PAD src0_sel:WORD_1 src1_sel:DWORD
	v_and_b32_sdwa v7, v2, v216 dst_sel:DWORD dst_unused:UNUSED_PAD src0_sel:WORD_1 src1_sel:DWORD
	v_add3_u32 v6, v3, v6, s82
	v_add3_u32 v102, v2, v7, s82
	v_and_b32_e32 v103, 0xffff0000, v6
	v_or_b32_sdwa v7, v103, v64 dst_sel:DWORD dst_unused:UNUSED_PAD src0_sel:DWORD src1_sel:WORD_1
	v_or_b32_sdwa v6, v102, v65 dst_sel:DWORD dst_unused:UNUSED_PAD src0_sel:WORD_1 src1_sel:DWORD
	ds_write_b64 v151, v[6:7]
	v_and_b32_e32 v6, 0xffff0000, v102
	v_sub_u32_e32 v2, v2, v6
	v_sub_u32_e32 v6, v66, v65
	v_and_b32_e32 v7, 0xffff0000, v64
	v_add_u32_e32 v6, 0x80, v6
	v_sub_u32_e32 v7, v67, v7
	v_sub_u32_e32 v3, v3, v103
	v_add_u32_e32 v2, 0x80, v2
	v_ashrrev_i32_e32 v6, 8, v6
	v_add_u32_e32 v7, 0x80, v7
	v_add_u32_e32 v3, 0x80, v3
	v_ashrrev_i32_e32 v2, 8, v2
	v_min_i32_e32 v6, 0x7f, v6
	v_ashrrev_i32_e32 v7, 8, v7
	v_ashrrev_i32_e32 v3, 8, v3
	v_min_i32_e32 v2, 0x7f, v2
	v_min_i32_sdwa v7, v7, s83 dst_sel:WORD_1 dst_unused:UNUSED_PAD src0_sel:DWORD src1_sel:DWORD
	v_min_i32_e32 v3, 0x7f, v3
	v_lshlrev_b32_e32 v6, 8, v6
	v_and_b32_e32 v6, 0xff00, v6
	v_and_b32_e32 v7, 0xff0000, v7
	v_perm_b32 v2, v3, v2, s84
	v_or3_b32 v2, v2, v6, v7
	ds_write_b32 v12, v2
	buffer_store_dwordx4 v[128:131], v148, s[16:19], s33 offen
	ds_read_b64 v[2:3], v13 offset:1024
	s_waitcnt lgkmcnt(0)
	v_mov_b32_e32 v212, v2
	v_mov_b32_e32 v213, v3
	v_pk_add_f32 v[6:7], v[70:71], v[2:3] op_sel_hi:[1,0] neg_lo:[0,1] neg_hi:[0,1]
	s_nop 0
	v_pk_mul_f32 v[6:7], v[2:3], v[6:7] op_sel:[1,0]
	v_pk_add_f32 v[64:65], v[68:69], v[2:3] op_sel_hi:[1,0] neg_lo:[0,1] neg_hi:[0,1]
	v_pk_fma_f32 v[6:7], v[96:97], v[6:7], v[98:99]
	v_pk_mul_f32 v[2:3], v[2:3], v[64:65] op_sel:[1,0]
	v_and_b32_sdwa v64, v7, v216 dst_sel:DWORD dst_unused:UNUSED_PAD src0_sel:WORD_1 src1_sel:DWORD
	v_and_b32_sdwa v65, v6, v216 dst_sel:DWORD dst_unused:UNUSED_PAD src0_sel:WORD_1 src1_sel:DWORD
	v_pk_fma_f32 v[2:3], v[0:1], v[2:3], v[4:5]
	v_add3_u32 v66, v7, v64, s82
	v_add3_u32 v64, v6, v65, s82
	v_and_b32_e32 v67, 0xffff0000, v64
	v_and_b32_sdwa v64, v3, v216 dst_sel:DWORD dst_unused:UNUSED_PAD src0_sel:WORD_1 src1_sel:DWORD
	v_and_b32_sdwa v65, v2, v216 dst_sel:DWORD dst_unused:UNUSED_PAD src0_sel:WORD_1 src1_sel:DWORD
	v_add3_u32 v64, v3, v64, s82
	v_add3_u32 v68, v2, v65, s82
	v_and_b32_e32 v69, 0xffff0000, v64
	v_or_b32_sdwa v65, v69, v66 dst_sel:DWORD dst_unused:UNUSED_PAD src0_sel:DWORD src1_sel:WORD_1
	v_or_b32_sdwa v64, v68, v67 dst_sel:DWORD dst_unused:UNUSED_PAD src0_sel:WORD_1 src1_sel:DWORD
	ds_write_b64 v132, v[64:65]
	v_and_b32_e32 v64, 0xffff0000, v68
	v_sub_u32_e32 v2, v2, v64
	v_sub_u32_e32 v6, v6, v67
	v_and_b32_e32 v64, 0xffff0000, v66
	v_add_u32_e32 v6, 0x80, v6
	v_sub_u32_e32 v7, v7, v64
	v_sub_u32_e32 v3, v3, v69
	v_add_u32_e32 v2, 0x80, v2
	v_ashrrev_i32_e32 v6, 8, v6
	v_add_u32_e32 v7, 0x80, v7
	v_add_u32_e32 v3, 0x80, v3
	v_ashrrev_i32_e32 v2, 8, v2
	v_min_i32_e32 v6, 0x7f, v6
	v_ashrrev_i32_e32 v7, 8, v7
	v_ashrrev_i32_e32 v3, 8, v3
	v_min_i32_e32 v2, 0x7f, v2
	v_min_i32_sdwa v7, v7, s83 dst_sel:WORD_1 dst_unused:UNUSED_PAD src0_sel:DWORD src1_sel:DWORD
	v_min_i32_e32 v3, 0x7f, v3
	v_lshlrev_b32_e32 v6, 8, v6
	v_and_b32_e32 v6, 0xff00, v6
	v_and_b32_e32 v7, 0xff0000, v7
	v_perm_b32 v2, v3, v2, s84
	v_or3_b32 v2, v2, v6, v7
	ds_write_b32 v14, v2
	buffer_store_dwordx4 v[136:139], v74, s[16:19], s33 offen
	ds_read_b64 v[2:3], v15 offset:1024
	s_waitcnt lgkmcnt(0)
;     ...
;           _Pragma("unroll") for (int bj = 0; bj < 2; ++bj) _Pragma("unroll") for (int n = 0; n < 2; ++n) {
;             const int cc = bj * HALF + wc3 * 32 + n * 16 + fq3 * 4;
;             const float4 gm = *reinterpret_cast<const float4*>(g.gam + pn * BM + cc), bt = *reinterpret_cast<const float4*>(g.bet + pn * BM + cc);
;             _Pragma("unroll") for (int m = 0; m < 4; ++m) {
;               const int rr = wr3 * 64 + m * 16 + fr3;
;               const float2 ms = *reinterpret_cast<const float2*>(mr + (ai * HALF + rr) * 2);
;               f32x4 y = acc[ai][bj][m][n];
;               const float o0 = (y[0] - ms.x) * ms.y * gm.x + bt.x, o1 = (y[1] - ms.x) * ms.y * gm.y + bt.y;
;               const float o2 = (y[2] - ms.x) * ms.y * gm.z + bt.z, o3 = (y[3] - ms.x) * ms.y * gm.w + bt.w;
;               const unsigned h0 = f2bf(o0), h1 = f2bf(o1), h2 = f2bf(o2), h3 = f2bf(o3);
;               u32x2 ob; ob[0] = h0 | (h1 << 16); ob[1] = h2 | (h3 << 16);
;               *reinterpret_cast<u32x2*>(smem + (rr >> 1) * PIECE + (rr & 1) * 512 + cc * 2) = ob;
;               const int l0 = min(((int)__float_as_uint(o0) - (int)(h0 << 16) + 128) >> 8, 127);
;               const int l1 = min(((int)__float_as_uint(o1) - (int)(h1 << 16) + 128) >> 8, 127);
;               const int l2 = min(((int)__float_as_uint(o2) - (int)(h2 << 16) + 128) >> 8, 127);
;               const int l3 = min(((int)__float_as_uint(o3) - (int)(h3 << 16) + 128) >> 8, 127);
;               *reinterpret_cast<unsigned*>(smem + LOBASE + (rr >> 2) * PIECE + (rr & 3) * 256 + cc) =
;                   (unsigned)(l0 & 255) | ((unsigned)(l1 & 255) << 8) | ((unsigned)(l2 & 255) << 16) | ((unsigned)l3 << 24);
;             }
	v_mov_b32_e32 v214, v2
	v_mov_b32_e32 v215, v3
	v_pk_add_f32 v[6:7], v[78:79], v[2:3] op_sel_hi:[1,0] neg_lo:[0,1] neg_hi:[0,1]
	s_nop 0
	v_pk_mul_f32 v[6:7], v[2:3], v[6:7] op_sel:[1,0]
	v_pk_add_f32 v[64:65], v[76:77], v[2:3] op_sel_hi:[1,0] neg_lo:[0,1] neg_hi:[0,1]
	v_pk_fma_f32 v[6:7], v[96:97], v[6:7], v[98:99]
	v_pk_mul_f32 v[2:3], v[2:3], v[64:65] op_sel:[1,0]
	v_and_b32_sdwa v64, v7, v216 dst_sel:DWORD dst_unused:UNUSED_PAD src0_sel:WORD_1 src1_sel:DWORD
	v_and_b32_sdwa v65, v6, v216 dst_sel:DWORD dst_unused:UNUSED_PAD src0_sel:WORD_1 src1_sel:DWORD
	v_pk_fma_f32 v[2:3], v[0:1], v[2:3], v[4:5]
	v_add3_u32 v66, v7, v64, s82
	v_add3_u32 v64, v6, v65, s82
	v_and_b32_e32 v67, 0xffff0000, v64
	v_and_b32_sdwa v64, v3, v216 dst_sel:DWORD dst_unused:UNUSED_PAD src0_sel:WORD_1 src1_sel:DWORD
	v_and_b32_sdwa v65, v2, v216 dst_sel:DWORD dst_unused:UNUSED_PAD src0_sel:WORD_1 src1_sel:DWORD
	v_add3_u32 v64, v3, v64, s82
	v_add3_u32 v68, v2, v65, s82
	v_and_b32_e32 v69, 0xffff0000, v64
	v_or_b32_sdwa v65, v69, v66 dst_sel:DWORD dst_unused:UNUSED_PAD src0_sel:DWORD src1_sel:WORD_1
	v_or_b32_sdwa v64, v68, v67 dst_sel:DWORD dst_unused:UNUSED_PAD src0_sel:WORD_1 src1_sel:DWORD
	ds_write_b64 v133, v[64:65]
	v_and_b32_e32 v64, 0xffff0000, v68
	v_sub_u32_e32 v2, v2, v64
	v_sub_u32_e32 v6, v6, v67
	v_and_b32_e32 v64, 0xffff0000, v66
	v_add_u32_e32 v6, 0x80, v6
	v_sub_u32_e32 v7, v7, v64
	v_sub_u32_e32 v3, v3, v69
	v_add_u32_e32 v2, 0x80, v2
	v_ashrrev_i32_e32 v6, 8, v6
	v_add_u32_e32 v7, 0x80, v7
	v_add_u32_e32 v3, 0x80, v3
	v_ashrrev_i32_e32 v2, 8, v2
	v_min_i32_e32 v6, 0x7f, v6
	v_ashrrev_i32_e32 v7, 8, v7
	v_ashrrev_i32_e32 v3, 8, v3
	v_min_i32_e32 v2, 0x7f, v2
	v_min_i32_sdwa v7, v7, s83 dst_sel:WORD_1 dst_unused:UNUSED_PAD src0_sel:DWORD src1_sel:DWORD
	v_min_i32_e32 v3, 0x7f, v3
	v_lshlrev_b32_e32 v6, 8, v6
	v_and_b32_e32 v6, 0xff00, v6
	v_and_b32_e32 v7, 0xff0000, v7
	v_perm_b32 v2, v3, v2, s84
	v_or3_b32 v2, v2, v6, v7
	ds_write_b32 v20, v2
	buffer_store_dwordx4 v[140:143], v75, s[16:19], s33 offen
	ds_read_b64 v[2:3], v21 offset:1024
	s_waitcnt lgkmcnt(0)
	v_mov_b32_e32 v252, v2
	v_mov_b32_e32 v253, v3
	v_pk_add_f32 v[6:7], v[86:87], v[2:3] op_sel_hi:[1,0] neg_lo:[0,1] neg_hi:[0,1]
	s_nop 0
	v_pk_mul_f32 v[6:7], v[2:3], v[6:7] op_sel:[1,0]
	v_pk_add_f32 v[64:65], v[84:85], v[2:3] op_sel_hi:[1,0] neg_lo:[0,1] neg_hi:[0,1]
	v_pk_fma_f32 v[6:7], v[96:97], v[6:7], v[98:99]
	v_pk_mul_f32 v[2:3], v[2:3], v[64:65] op_sel:[1,0]
	s_nop 0
	v_pk_fma_f32 v[0:1], v[0:1], v[2:3], v[4:5]
	v_and_b32_sdwa v2, v7, v216 dst_sel:DWORD dst_unused:UNUSED_PAD src0_sel:WORD_1 src1_sel:DWORD
	v_and_b32_sdwa v3, v6, v216 dst_sel:DWORD dst_unused:UNUSED_PAD src0_sel:WORD_1 src1_sel:DWORD
	v_add3_u32 v4, v7, v2, s82
	v_add3_u32 v2, v6, v3, s82
	v_and_b32_e32 v5, 0xffff0000, v2
	v_and_b32_sdwa v2, v1, v216 dst_sel:DWORD dst_unused:UNUSED_PAD src0_sel:WORD_1 src1_sel:DWORD
	v_and_b32_sdwa v3, v0, v216 dst_sel:DWORD dst_unused:UNUSED_PAD src0_sel:WORD_1 src1_sel:DWORD
	v_add3_u32 v2, v1, v2, s82
	v_add3_u32 v64, v0, v3, s82
	v_and_b32_e32 v65, 0xffff0000, v2
	v_or_b32_sdwa v3, v65, v4 dst_sel:DWORD dst_unused:UNUSED_PAD src0_sel:DWORD src1_sel:WORD_1
	v_or_b32_sdwa v2, v64, v5 dst_sel:DWORD dst_unused:UNUSED_PAD src0_sel:WORD_1 src1_sel:DWORD
	ds_write_b64 v134, v[2:3]
	v_and_b32_e32 v2, 0xffff0000, v64
	v_sub_u32_e32 v0, v0, v2
	v_sub_u32_e32 v2, v6, v5
	v_and_b32_e32 v3, 0xffff0000, v4
	v_add_u32_e32 v2, 0x80, v2
	v_sub_u32_e32 v3, v7, v3
	v_sub_u32_e32 v1, v1, v65
	v_add_u32_e32 v0, 0x80, v0
	v_ashrrev_i32_e32 v2, 8, v2
	v_add_u32_e32 v3, 0x80, v3
	v_add_u32_e32 v1, 0x80, v1
	v_ashrrev_i32_e32 v0, 8, v0
	v_min_i32_e32 v2, 0x7f, v2
	v_ashrrev_i32_e32 v3, 8, v3
	v_ashrrev_i32_e32 v1, 8, v1
	v_min_i32_e32 v0, 0x7f, v0
	v_min_i32_sdwa v3, v3, s83 dst_sel:WORD_1 dst_unused:UNUSED_PAD src0_sel:DWORD src1_sel:DWORD
	v_min_i32_e32 v1, 0x7f, v1
	v_lshlrev_b32_e32 v2, 8, v2
	v_and_b32_e32 v2, 0xff00, v2
	v_and_b32_e32 v3, 0xff0000, v3
	v_perm_b32 v0, v1, v0, s84
	v_or3_b32 v0, v0, v2, v3
	ds_write_b32 v22, v0
	buffer_store_dwordx4 v[152:155], v81, s[16:19], s33 offen
	v_mov_b32_e32 v0, v224
	v_mov_b32_e32 v1, v225
	v_mov_b32_e32 v2, v226
	v_mov_b32_e32 v3, v227
	v_mov_b32_e32 v4, v240
	v_mov_b32_e32 v5, v241
	v_mov_b32_e32 v6, v242
	v_mov_b32_e32 v7, v243
	v_mov_b32_e32 v68, v210
	v_mov_b32_e32 v69, v211
	v_pk_add_f32 v[58:59], v[58:59], v[68:69] op_sel_hi:[1,0] neg_lo:[0,1] neg_hi:[0,1]
	s_nop 0
	v_pk_mul_f32 v[58:59], v[68:69], v[58:59] op_sel:[1,0]
	v_pk_add_f32 v[56:57], v[56:57], v[68:69] op_sel_hi:[1,0] neg_lo:[0,1] neg_hi:[0,1]
	v_mov_b32_e32 v64, v1
	v_mov_b32_e32 v65, v2
	v_mov_b32_e32 v66, v5
	v_mov_b32_e32 v67, v6
	v_pk_fma_f32 v[58:59], v[64:65], v[58:59], v[66:67]
	v_pk_mul_f32 v[56:57], v[68:69], v[56:57] op_sel:[1,0]
	v_mov_b32_e32 v1, v3
	v_mov_b32_e32 v5, v7
	v_and_b32_sdwa v6, v59, v216 dst_sel:DWORD dst_unused:UNUSED_PAD src0_sel:WORD_1 src1_sel:DWORD
	v_and_b32_sdwa v7, v58, v216 dst_sel:DWORD dst_unused:UNUSED_PAD src0_sel:WORD_1 src1_sel:DWORD
	v_pk_fma_f32 v[2:3], v[0:1], v[56:57], v[4:5]
	v_add3_u32 v56, v59, v6, s82
	v_add3_u32 v6, v58, v7, s82
	v_and_b32_e32 v57, 0xffff0000, v6
	v_and_b32_sdwa v6, v3, v216 dst_sel:DWORD dst_unused:UNUSED_PAD src0_sel:WORD_1 src1_sel:DWORD
	v_and_b32_sdwa v7, v2, v216 dst_sel:DWORD dst_unused:UNUSED_PAD src0_sel:WORD_1 src1_sel:DWORD
	v_add3_u32 v6, v3, v6, s82
	v_add3_u32 v68, v2, v7, s82
	v_and_b32_e32 v69, 0xffff0000, v6
	v_or_b32_sdwa v7, v69, v56 dst_sel:DWORD dst_unused:UNUSED_PAD src0_sel:DWORD src1_sel:WORD_1
	v_or_b32_sdwa v6, v68, v57 dst_sel:DWORD dst_unused:UNUSED_PAD src0_sel:WORD_1 src1_sel:DWORD
;     ...
;           _Pragma("unroll") for (int bj = 0; bj < 2; ++bj) _Pragma("unroll") for (int n = 0; n < 2; ++n) {
;             const int cc = bj * HALF + wc3 * 32 + n * 16 + fq3 * 4;
;             const float4 gm = *reinterpret_cast<const float4*>(g.gam + pn * BM + cc), bt = *reinterpret_cast<const float4*>(g.bet + pn * BM + cc);
;             _Pragma("unroll") for (int m = 0; m < 4; ++m) {
;               const int rr = wr3 * 64 + m * 16 + fr3;
;               const float2 ms = *reinterpret_cast<const float2*>(mr + (ai * HALF + rr) * 2);
;               f32x4 y = acc[ai][bj][m][n];
;               const float o0 = (y[0] - ms.x) * ms.y * gm.x + bt.x, o1 = (y[1] - ms.x) * ms.y * gm.y + bt.y;
;               const float o2 = (y[2] - ms.x) * ms.y * gm.z + bt.z, o3 = (y[3] - ms.x) * ms.y * gm.w + bt.w;
;               const unsigned h0 = f2bf(o0), h1 = f2bf(o1), h2 = f2bf(o2), h3 = f2bf(o3);
;               u32x2 ob; ob[0] = h0 | (h1 << 16); ob[1] = h2 | (h3 << 16);
;               *reinterpret_cast<u32x2*>(smem + (rr >> 1) * PIECE + (rr & 1) * 512 + cc * 2) = ob;
;               const int l0 = min(((int)__float_as_uint(o0) - (int)(h0 << 16) + 128) >> 8, 127);
;               const int l1 = min(((int)__float_as_uint(o1) - (int)(h1 << 16) + 128) >> 8, 127);
;               const int l2 = min(((int)__float_as_uint(o2) - (int)(h2 << 16) + 128) >> 8, 127);
;               const int l3 = min(((int)__float_as_uint(o3) - (int)(h3 << 16) + 128) >> 8, 127);
;               *reinterpret_cast<unsigned*>(smem + LOBASE + (rr >> 2) * PIECE + (rr & 3) * 256 + cc) =
;                   (unsigned)(l0 & 255) | ((unsigned)(l1 & 255) << 8) | ((unsigned)(l2 & 255) << 16) | ((unsigned)l3 << 24);
;             }
	ds_write_b64 v23, v[6:7]
	v_and_b32_e32 v6, 0xffff0000, v68
	v_sub_u32_e32 v2, v2, v6
	v_sub_u32_e32 v6, v58, v57
	v_and_b32_e32 v7, 0xffff0000, v56
	v_add_u32_e32 v6, 0x80, v6
	v_sub_u32_e32 v7, v59, v7
	v_sub_u32_e32 v3, v3, v69
	v_add_u32_e32 v2, 0x80, v2
	v_ashrrev_i32_e32 v6, 8, v6
	v_add_u32_e32 v7, 0x80, v7
	v_add_u32_e32 v3, 0x80, v3
	v_ashrrev_i32_e32 v2, 8, v2
	v_min_i32_e32 v6, 0x7f, v6
	v_ashrrev_i32_e32 v7, 8, v7
	v_ashrrev_i32_e32 v3, 8, v3
	v_min_i32_e32 v2, 0x7f, v2
	v_min_i32_sdwa v7, v7, s83 dst_sel:WORD_1 dst_unused:UNUSED_PAD src0_sel:DWORD src1_sel:DWORD
	v_min_i32_e32 v3, 0x7f, v3
	v_lshlrev_b32_e32 v6, 8, v6
	v_and_b32_e32 v6, 0xff00, v6
	v_and_b32_e32 v7, 0xff0000, v7
	v_perm_b32 v2, v3, v2, s84
	v_or3_b32 v2, v2, v6, v7
	ds_write_b32 v12, v2 offset:16
	buffer_store_dwordx4 v[156:159], v82, s[16:19], s33 offen
	v_mov_b32_e32 v2, v212
	v_mov_b32_e32 v3, v213
	v_pk_add_f32 v[6:7], v[42:43], v[2:3] op_sel_hi:[1,0] neg_lo:[0,1] neg_hi:[0,1]
	s_nop 0
	v_pk_mul_f32 v[6:7], v[2:3], v[6:7] op_sel:[1,0]
	v_pk_add_f32 v[40:41], v[40:41], v[2:3] op_sel_hi:[1,0] neg_lo:[0,1] neg_hi:[0,1]
	v_pk_fma_f32 v[6:7], v[64:65], v[6:7], v[66:67]
	v_pk_mul_f32 v[2:3], v[2:3], v[40:41] op_sel:[1,0]
	v_and_b32_sdwa v40, v6, v216 dst_sel:DWORD dst_unused:UNUSED_PAD src0_sel:WORD_1 src1_sel:DWORD
	v_pk_fma_f32 v[2:3], v[0:1], v[2:3], v[4:5]
	v_add3_u32 v40, v6, v40, s82
	v_and_b32_e32 v42, 0xffff0000, v40
	v_and_b32_sdwa v40, v3, v216 dst_sel:DWORD dst_unused:UNUSED_PAD src0_sel:WORD_1 src1_sel:DWORD
	v_and_b32_sdwa v23, v7, v216 dst_sel:DWORD dst_unused:UNUSED_PAD src0_sel:WORD_1 src1_sel:DWORD
	v_and_b32_sdwa v41, v2, v216 dst_sel:DWORD dst_unused:UNUSED_PAD src0_sel:WORD_1 src1_sel:DWORD
	v_add3_u32 v40, v3, v40, s82
	v_add3_u32 v23, v7, v23, s82
	v_add3_u32 v43, v2, v41, s82
	v_and_b32_e32 v56, 0xffff0000, v40
	v_or_b32_sdwa v41, v56, v23 dst_sel:DWORD dst_unused:UNUSED_PAD src0_sel:DWORD src1_sel:WORD_1
	v_or_b32_sdwa v40, v43, v42 dst_sel:DWORD dst_unused:UNUSED_PAD src0_sel:WORD_1 src1_sel:DWORD
	ds_write_b64 v104, v[40:41]
	v_and_b32_e32 v40, 0xffff0000, v43
	v_sub_u32_e32 v6, v6, v42
	v_and_b32_e32 v23, 0xffff0000, v23
	v_sub_u32_e32 v2, v2, v40
	v_add_u32_e32 v6, 0x80, v6
	v_sub_u32_e32 v7, v7, v23
	v_sub_u32_e32 v3, v3, v56
	v_add_u32_e32 v2, 0x80, v2
	v_ashrrev_i32_e32 v6, 8, v6
	v_add_u32_e32 v7, 0x80, v7
	v_add_u32_e32 v3, 0x80, v3
	v_ashrrev_i32_e32 v2, 8, v2
	v_min_i32_e32 v6, 0x7f, v6
	v_ashrrev_i32_e32 v7, 8, v7
	v_ashrrev_i32_e32 v3, 8, v3
	v_min_i32_e32 v2, 0x7f, v2
	v_min_i32_sdwa v7, v7, s83 dst_sel:WORD_1 dst_unused:UNUSED_PAD src0_sel:DWORD src1_sel:DWORD
	v_min_i32_e32 v3, 0x7f, v3
	v_lshlrev_b32_e32 v6, 8, v6
	v_and_b32_e32 v6, 0xff00, v6
	v_and_b32_e32 v7, 0xff0000, v7
	v_perm_b32 v2, v3, v2, s84
	v_or3_b32 v2, v2, v6, v7
	ds_write_b32 v14, v2 offset:16
	buffer_store_dwordx4 v[160:163], v83, s[16:19], s33 offen
	v_mov_b32_e32 v2, v214
	v_mov_b32_e32 v3, v215
	v_pk_add_f32 v[6:7], v[46:47], v[2:3] op_sel_hi:[1,0] neg_lo:[0,1] neg_hi:[0,1]
	s_nop 0
	v_pk_mul_f32 v[6:7], v[2:3], v[6:7] op_sel:[1,0]
	v_pk_add_f32 v[40:41], v[44:45], v[2:3] op_sel_hi:[1,0] neg_lo:[0,1] neg_hi:[0,1]
	v_pk_fma_f32 v[6:7], v[64:65], v[6:7], v[66:67]
	v_pk_mul_f32 v[2:3], v[2:3], v[40:41] op_sel:[1,0]
	v_and_b32_sdwa v40, v6, v216 dst_sel:DWORD dst_unused:UNUSED_PAD src0_sel:WORD_1 src1_sel:DWORD
	v_pk_fma_f32 v[2:3], v[0:1], v[2:3], v[4:5]
	v_add3_u32 v40, v6, v40, s82
	v_and_b32_e32 v42, 0xffff0000, v40
	v_and_b32_sdwa v40, v3, v216 dst_sel:DWORD dst_unused:UNUSED_PAD src0_sel:WORD_1 src1_sel:DWORD
	v_and_b32_sdwa v23, v7, v216 dst_sel:DWORD dst_unused:UNUSED_PAD src0_sel:WORD_1 src1_sel:DWORD
	v_and_b32_sdwa v41, v2, v216 dst_sel:DWORD dst_unused:UNUSED_PAD src0_sel:WORD_1 src1_sel:DWORD
	v_add3_u32 v40, v3, v40, s82
	v_add3_u32 v23, v7, v23, s82
	v_add3_u32 v43, v2, v41, s82
	v_and_b32_e32 v44, 0xffff0000, v40
	v_or_b32_sdwa v41, v44, v23 dst_sel:DWORD dst_unused:UNUSED_PAD src0_sel:DWORD src1_sel:WORD_1
	v_or_b32_sdwa v40, v43, v42 dst_sel:DWORD dst_unused:UNUSED_PAD src0_sel:WORD_1 src1_sel:DWORD
	ds_write_b64 v105, v[40:41]
	v_and_b32_e32 v40, 0xffff0000, v43
	v_sub_u32_e32 v6, v6, v42
	v_and_b32_e32 v23, 0xffff0000, v23
	v_sub_u32_e32 v2, v2, v40
	v_add_u32_e32 v6, 0x80, v6
	v_sub_u32_e32 v7, v7, v23
	v_sub_u32_e32 v3, v3, v44
	v_add_u32_e32 v2, 0x80, v2
	v_ashrrev_i32_e32 v6, 8, v6
	v_add_u32_e32 v7, 0x80, v7
	v_add_u32_e32 v3, 0x80, v3
	v_ashrrev_i32_e32 v2, 8, v2
	v_min_i32_e32 v6, 0x7f, v6
	v_ashrrev_i32_e32 v7, 8, v7
	v_ashrrev_i32_e32 v3, 8, v3
	v_min_i32_e32 v2, 0x7f, v2
	v_min_i32_sdwa v7, v7, s83 dst_sel:WORD_1 dst_unused:UNUSED_PAD src0_sel:DWORD src1_sel:DWORD
	v_min_i32_e32 v3, 0x7f, v3
	v_lshlrev_b32_e32 v6, 8, v6
	v_and_b32_e32 v6, 0xff00, v6
	v_and_b32_e32 v7, 0xff0000, v7
	v_perm_b32 v2, v3, v2, s84
	v_or3_b32 v2, v2, v6, v7
	ds_write_b32 v20, v2 offset:16
	buffer_store_dwordx4 v[164:167], v88, s[16:19], s33 offen
	v_mov_b32_e32 v2, v252
	v_mov_b32_e32 v3, v253
	v_pk_add_f32 v[6:7], v[62:63], v[2:3] op_sel_hi:[1,0] neg_lo:[0,1] neg_hi:[0,1]
	s_nop 0
	v_pk_mul_f32 v[6:7], v[2:3], v[6:7] op_sel:[1,0]
	v_pk_add_f32 v[40:41], v[60:61], v[2:3] op_sel_hi:[1,0] neg_lo:[0,1] neg_hi:[0,1]
	v_pk_fma_f32 v[6:7], v[64:65], v[6:7], v[66:67]
	v_pk_mul_f32 v[2:3], v[2:3], v[40:41] op_sel:[1,0]
	s_nop 0
	v_pk_fma_f32 v[0:1], v[0:1], v[2:3], v[4:5]
	v_and_b32_sdwa v2, v7, v216 dst_sel:DWORD dst_unused:UNUSED_PAD src0_sel:WORD_1 src1_sel:DWORD
	v_and_b32_sdwa v3, v6, v216 dst_sel:DWORD dst_unused:UNUSED_PAD src0_sel:WORD_1 src1_sel:DWORD
	v_add3_u32 v4, v7, v2, s82
	v_add3_u32 v2, v6, v3, s82
	v_and_b32_e32 v5, 0xffff0000, v2
;     ...
;           _Pragma("unroll") for (int bj = 0; bj < 2; ++bj) _Pragma("unroll") for (int n = 0; n < 2; ++n) {
;             const int cc = bj * HALF + wc3 * 32 + n * 16 + fq3 * 4;
;             const float4 gm = *reinterpret_cast<const float4*>(g.gam + pn * BM + cc), bt = *reinterpret_cast<const float4*>(g.bet + pn * BM + cc);
;             _Pragma("unroll") for (int m = 0; m < 4; ++m) {
;               const int rr = wr3 * 64 + m * 16 + fr3;
;               const float2 ms = *reinterpret_cast<const float2*>(mr + (ai * HALF + rr) * 2);
;               f32x4 y = acc[ai][bj][m][n];
;               const float o0 = (y[0] - ms.x) * ms.y * gm.x + bt.x, o1 = (y[1] - ms.x) * ms.y * gm.y + bt.y;
;               const float o2 = (y[2] - ms.x) * ms.y * gm.z + bt.z, o3 = (y[3] - ms.x) * ms.y * gm.w + bt.w;
;               const unsigned h0 = f2bf(o0), h1 = f2bf(o1), h2 = f2bf(o2), h3 = f2bf(o3);
;               u32x2 ob; ob[0] = h0 | (h1 << 16); ob[1] = h2 | (h3 << 16);
;               *reinterpret_cast<u32x2*>(smem + (rr >> 1) * PIECE + (rr & 1) * 512 + cc * 2) = ob;
;               const int l0 = min(((int)__float_as_uint(o0) - (int)(h0 << 16) + 128) >> 8, 127);
;               const int l1 = min(((int)__float_as_uint(o1) - (int)(h1 << 16) + 128) >> 8, 127);
;               const int l2 = min(((int)__float_as_uint(o2) - (int)(h2 << 16) + 128) >> 8, 127);
;               const int l3 = min(((int)__float_as_uint(o3) - (int)(h3 << 16) + 128) >> 8, 127);
;               *reinterpret_cast<unsigned*>(smem + LOBASE + (rr >> 2) * PIECE + (rr & 3) * 256 + cc) =
;                   (unsigned)(l0 & 255) | ((unsigned)(l1 & 255) << 8) | ((unsigned)(l2 & 255) << 16) | ((unsigned)l3 << 24);
;             }
	v_and_b32_sdwa v2, v1, v216 dst_sel:DWORD dst_unused:UNUSED_PAD src0_sel:WORD_1 src1_sel:DWORD
	v_and_b32_sdwa v3, v0, v216 dst_sel:DWORD dst_unused:UNUSED_PAD src0_sel:WORD_1 src1_sel:DWORD
	v_add3_u32 v2, v1, v2, s82
	v_add3_u32 v23, v0, v3, s82
	v_and_b32_e32 v40, 0xffff0000, v2
	v_or_b32_sdwa v3, v40, v4 dst_sel:DWORD dst_unused:UNUSED_PAD src0_sel:DWORD src1_sel:WORD_1
	v_or_b32_sdwa v2, v23, v5 dst_sel:DWORD dst_unused:UNUSED_PAD src0_sel:WORD_1 src1_sel:DWORD
	ds_write_b64 v106, v[2:3]
	v_and_b32_e32 v2, 0xffff0000, v23
	v_sub_u32_e32 v0, v0, v2
	v_sub_u32_e32 v2, v6, v5
	v_and_b32_e32 v3, 0xffff0000, v4
	v_add_u32_e32 v2, 0x80, v2
	v_sub_u32_e32 v3, v7, v3
	v_sub_u32_e32 v1, v1, v40
	v_add_u32_e32 v0, 0x80, v0
	v_ashrrev_i32_e32 v2, 8, v2
	v_add_u32_e32 v3, 0x80, v3
	v_add_u32_e32 v1, 0x80, v1
	v_ashrrev_i32_e32 v0, 8, v0
	v_min_i32_e32 v2, 0x7f, v2
	v_ashrrev_i32_e32 v3, 8, v3
	v_ashrrev_i32_e32 v1, 8, v1
	v_min_i32_e32 v0, 0x7f, v0
	v_min_i32_sdwa v3, v3, s83 dst_sel:WORD_1 dst_unused:UNUSED_PAD src0_sel:DWORD src1_sel:DWORD
	v_min_i32_e32 v1, 0x7f, v1
	v_lshlrev_b32_e32 v2, 8, v2
	v_and_b32_e32 v2, 0xff00, v2
	v_and_b32_e32 v3, 0xff0000, v3
	v_perm_b32 v0, v1, v0, s84
	v_or3_b32 v0, v0, v2, v3
	ds_write_b32 v22, v0 offset:16
	buffer_store_dwordx4 v[168:171], v89, s[16:19], s33 offen
	v_mov_b32_e32 v0, v228
	v_mov_b32_e32 v1, v229
	v_mov_b32_e32 v2, v230
	v_mov_b32_e32 v3, v231
	v_mov_b32_e32 v4, v244
	v_mov_b32_e32 v5, v245
	v_mov_b32_e32 v6, v246
	v_mov_b32_e32 v7, v247
	v_mov_b32_e32 v44, v210
	v_mov_b32_e32 v45, v211
	v_pk_add_f32 v[46:47], v[54:55], v[44:45] op_sel_hi:[1,0] neg_lo:[0,1] neg_hi:[0,1]
	s_nop 0
	v_pk_mul_f32 v[46:47], v[44:45], v[46:47] op_sel:[1,0]
	v_pk_add_f32 v[52:53], v[52:53], v[44:45] op_sel_hi:[1,0] neg_lo:[0,1] neg_hi:[0,1]
	v_mov_b32_e32 v40, v1
	v_mov_b32_e32 v41, v2
	v_mov_b32_e32 v42, v5
	v_mov_b32_e32 v43, v6
	v_pk_fma_f32 v[46:47], v[40:41], v[46:47], v[42:43]
	v_pk_mul_f32 v[44:45], v[44:45], v[52:53] op_sel:[1,0]
	v_mov_b32_e32 v1, v3
	v_mov_b32_e32 v5, v7
	v_and_b32_sdwa v6, v47, v216 dst_sel:DWORD dst_unused:UNUSED_PAD src0_sel:WORD_1 src1_sel:DWORD
	v_and_b32_sdwa v7, v46, v216 dst_sel:DWORD dst_unused:UNUSED_PAD src0_sel:WORD_1 src1_sel:DWORD
	v_pk_fma_f32 v[2:3], v[0:1], v[44:45], v[4:5]
	v_add3_u32 v23, v47, v6, s82
	v_add3_u32 v6, v46, v7, s82
	v_and_b32_e32 v44, 0xffff0000, v6
	v_and_b32_sdwa v6, v3, v216 dst_sel:DWORD dst_unused:UNUSED_PAD src0_sel:WORD_1 src1_sel:DWORD
	v_and_b32_sdwa v7, v2, v216 dst_sel:DWORD dst_unused:UNUSED_PAD src0_sel:WORD_1 src1_sel:DWORD
	v_add3_u32 v6, v3, v6, s82
	v_add3_u32 v45, v2, v7, s82
	v_and_b32_e32 v52, 0xffff0000, v6
	v_or_b32_sdwa v7, v52, v23 dst_sel:DWORD dst_unused:UNUSED_PAD src0_sel:DWORD src1_sel:WORD_1
	v_or_b32_sdwa v6, v45, v44 dst_sel:DWORD dst_unused:UNUSED_PAD src0_sel:WORD_1 src1_sel:DWORD
	ds_write_b64 v107, v[6:7]
	v_and_b32_e32 v6, 0xffff0000, v45
	v_sub_u32_e32 v2, v2, v6
	v_sub_u32_e32 v6, v46, v44
	v_and_b32_e32 v7, 0xffff0000, v23
	v_add_u32_e32 v6, 0x80, v6
	v_sub_u32_e32 v7, v47, v7
	v_sub_u32_e32 v3, v3, v52
	v_add_u32_e32 v2, 0x80, v2
	v_ashrrev_i32_e32 v6, 8, v6
	v_add_u32_e32 v7, 0x80, v7
	v_add_u32_e32 v3, 0x80, v3
	v_ashrrev_i32_e32 v2, 8, v2
	v_min_i32_e32 v6, 0x7f, v6
	v_ashrrev_i32_e32 v7, 8, v7
	v_ashrrev_i32_e32 v3, 8, v3
	v_min_i32_e32 v2, 0x7f, v2
	v_min_i32_sdwa v7, v7, s83 dst_sel:WORD_1 dst_unused:UNUSED_PAD src0_sel:DWORD src1_sel:DWORD
	v_min_i32_e32 v3, 0x7f, v3
	v_lshlrev_b32_e32 v6, 8, v6
	v_and_b32_e32 v6, 0xff00, v6
	v_and_b32_e32 v7, 0xff0000, v7
	v_perm_b32 v2, v3, v2, s84
	v_or3_b32 v2, v2, v6, v7
	ds_write_b32 v12, v2 offset:128
	buffer_store_dwordx4 v[172:175], v146, s[20:23], s0 offen
	v_mov_b32_e32 v2, v212
	v_mov_b32_e32 v3, v213
	v_pk_add_f32 v[6:7], v[38:39], v[2:3] op_sel_hi:[1,0] neg_lo:[0,1] neg_hi:[0,1]
	s_nop 0
	v_pk_mul_f32 v[6:7], v[2:3], v[6:7] op_sel:[1,0]
	v_pk_add_f32 v[36:37], v[36:37], v[2:3] op_sel_hi:[1,0] neg_lo:[0,1] neg_hi:[0,1]
	v_pk_fma_f32 v[6:7], v[40:41], v[6:7], v[42:43]
	v_pk_mul_f32 v[2:3], v[2:3], v[36:37] op_sel:[1,0]
	v_and_b32_sdwa v36, v6, v216 dst_sel:DWORD dst_unused:UNUSED_PAD src0_sel:WORD_1 src1_sel:DWORD
	v_pk_fma_f32 v[2:3], v[0:1], v[2:3], v[4:5]
	v_add3_u32 v36, v6, v36, s82
	v_and_b32_e32 v38, 0xffff0000, v36
	v_and_b32_sdwa v36, v3, v216 dst_sel:DWORD dst_unused:UNUSED_PAD src0_sel:WORD_1 src1_sel:DWORD
	v_and_b32_sdwa v23, v7, v216 dst_sel:DWORD dst_unused:UNUSED_PAD src0_sel:WORD_1 src1_sel:DWORD
	v_and_b32_sdwa v37, v2, v216 dst_sel:DWORD dst_unused:UNUSED_PAD src0_sel:WORD_1 src1_sel:DWORD
	v_add3_u32 v36, v3, v36, s82
	v_add3_u32 v23, v7, v23, s82
	v_add3_u32 v39, v2, v37, s82
	v_and_b32_e32 v44, 0xffff0000, v36
	v_or_b32_sdwa v37, v44, v23 dst_sel:DWORD dst_unused:UNUSED_PAD src0_sel:DWORD src1_sel:WORD_1
	v_or_b32_sdwa v36, v39, v38 dst_sel:DWORD dst_unused:UNUSED_PAD src0_sel:WORD_1 src1_sel:DWORD
	ds_write_b64 v100, v[36:37]
	v_and_b32_e32 v36, 0xffff0000, v39
	v_sub_u32_e32 v6, v6, v38
	v_and_b32_e32 v23, 0xffff0000, v23
	v_sub_u32_e32 v2, v2, v36
	v_add_u32_e32 v6, 0x80, v6
	v_sub_u32_e32 v7, v7, v23
	v_sub_u32_e32 v3, v3, v44
	v_add_u32_e32 v2, 0x80, v2
	v_ashrrev_i32_e32 v6, 8, v6
	v_add_u32_e32 v7, 0x80, v7
	v_add_u32_e32 v3, 0x80, v3
	v_ashrrev_i32_e32 v2, 8, v2
	v_min_i32_e32 v6, 0x7f, v6
	v_ashrrev_i32_e32 v7, 8, v7
	v_ashrrev_i32_e32 v3, 8, v3
	v_min_i32_e32 v2, 0x7f, v2
	v_min_i32_sdwa v7, v7, s83 dst_sel:WORD_1 dst_unused:UNUSED_PAD src0_sel:DWORD src1_sel:DWORD
	v_min_i32_e32 v3, 0x7f, v3
	v_lshlrev_b32_e32 v6, 8, v6
	v_and_b32_e32 v6, 0xff00, v6
	v_and_b32_e32 v7, 0xff0000, v7
	v_perm_b32 v2, v3, v2, s84
	v_or3_b32 v2, v2, v6, v7
;     ...
;           _Pragma("unroll") for (int bj = 0; bj < 2; ++bj) _Pragma("unroll") for (int n = 0; n < 2; ++n) {
;             const int cc = bj * HALF + wc3 * 32 + n * 16 + fq3 * 4;
;             const float4 gm = *reinterpret_cast<const float4*>(g.gam + pn * BM + cc), bt = *reinterpret_cast<const float4*>(g.bet + pn * BM + cc);
;             _Pragma("unroll") for (int m = 0; m < 4; ++m) {
;               const int rr = wr3 * 64 + m * 16 + fr3;
;               const float2 ms = *reinterpret_cast<const float2*>(mr + (ai * HALF + rr) * 2);
;               f32x4 y = acc[ai][bj][m][n];
;               const float o0 = (y[0] - ms.x) * ms.y * gm.x + bt.x, o1 = (y[1] - ms.x) * ms.y * gm.y + bt.y;
;               const float o2 = (y[2] - ms.x) * ms.y * gm.z + bt.z, o3 = (y[3] - ms.x) * ms.y * gm.w + bt.w;
;               const unsigned h0 = f2bf(o0), h1 = f2bf(o1), h2 = f2bf(o2), h3 = f2bf(o3);
;               u32x2 ob; ob[0] = h0 | (h1 << 16); ob[1] = h2 | (h3 << 16);
;               *reinterpret_cast<u32x2*>(smem + (rr >> 1) * PIECE + (rr & 1) * 512 + cc * 2) = ob;
;               const int l0 = min(((int)__float_as_uint(o0) - (int)(h0 << 16) + 128) >> 8, 127);
;               const int l1 = min(((int)__float_as_uint(o1) - (int)(h1 << 16) + 128) >> 8, 127);
;               const int l2 = min(((int)__float_as_uint(o2) - (int)(h2 << 16) + 128) >> 8, 127);
;               const int l3 = min(((int)__float_as_uint(o3) - (int)(h3 << 16) + 128) >> 8, 127);
;               *reinterpret_cast<unsigned*>(smem + LOBASE + (rr >> 2) * PIECE + (rr & 3) * 256 + cc) =
;                   (unsigned)(l0 & 255) | ((unsigned)(l1 & 255) << 8) | ((unsigned)(l2 & 255) << 16) | ((unsigned)l3 << 24);
;             }
	ds_write_b32 v14, v2 offset:128
	buffer_store_dwordx4 v[176:179], v90, s[20:23], s0 offen
	v_mov_b32_e32 v2, v214
	v_mov_b32_e32 v3, v215
	v_pk_add_f32 v[6:7], v[26:27], v[2:3] op_sel_hi:[1,0] neg_lo:[0,1] neg_hi:[0,1]
	s_nop 0
	v_pk_mul_f32 v[6:7], v[2:3], v[6:7] op_sel:[1,0]
	v_pk_add_f32 v[24:25], v[24:25], v[2:3] op_sel_hi:[1,0] neg_lo:[0,1] neg_hi:[0,1]
	v_pk_fma_f32 v[6:7], v[40:41], v[6:7], v[42:43]
	v_pk_mul_f32 v[2:3], v[2:3], v[24:25] op_sel:[1,0]
	v_and_b32_sdwa v24, v6, v216 dst_sel:DWORD dst_unused:UNUSED_PAD src0_sel:WORD_1 src1_sel:DWORD
	v_pk_fma_f32 v[2:3], v[0:1], v[2:3], v[4:5]
	v_add3_u32 v24, v6, v24, s82
	v_and_b32_e32 v26, 0xffff0000, v24
	v_and_b32_sdwa v24, v3, v216 dst_sel:DWORD dst_unused:UNUSED_PAD src0_sel:WORD_1 src1_sel:DWORD
	v_and_b32_sdwa v23, v7, v216 dst_sel:DWORD dst_unused:UNUSED_PAD src0_sel:WORD_1 src1_sel:DWORD
	v_and_b32_sdwa v25, v2, v216 dst_sel:DWORD dst_unused:UNUSED_PAD src0_sel:WORD_1 src1_sel:DWORD
	v_add3_u32 v24, v3, v24, s82
	v_add3_u32 v23, v7, v23, s82
	v_add3_u32 v27, v2, v25, s82
	v_and_b32_e32 v36, 0xffff0000, v24
	v_or_b32_sdwa v25, v36, v23 dst_sel:DWORD dst_unused:UNUSED_PAD src0_sel:DWORD src1_sel:WORD_1
	v_or_b32_sdwa v24, v27, v26 dst_sel:DWORD dst_unused:UNUSED_PAD src0_sel:WORD_1 src1_sel:DWORD
	ds_write_b64 v101, v[24:25]
	v_and_b32_e32 v24, 0xffff0000, v27
	v_sub_u32_e32 v6, v6, v26
	v_and_b32_e32 v23, 0xffff0000, v23
	v_sub_u32_e32 v2, v2, v24
	v_add_u32_e32 v6, 0x80, v6
	v_sub_u32_e32 v7, v7, v23
	v_sub_u32_e32 v3, v3, v36
	v_add_u32_e32 v2, 0x80, v2
	v_ashrrev_i32_e32 v6, 8, v6
	v_add_u32_e32 v7, 0x80, v7
	v_add_u32_e32 v3, 0x80, v3
	v_ashrrev_i32_e32 v2, 8, v2
	v_min_i32_e32 v6, 0x7f, v6
	v_ashrrev_i32_e32 v7, 8, v7
	v_ashrrev_i32_e32 v3, 8, v3
	v_min_i32_e32 v2, 0x7f, v2
	v_min_i32_sdwa v7, v7, s83 dst_sel:WORD_1 dst_unused:UNUSED_PAD src0_sel:DWORD src1_sel:DWORD
	v_min_i32_e32 v3, 0x7f, v3
	v_lshlrev_b32_e32 v6, 8, v6
	v_and_b32_e32 v6, 0xff00, v6
	v_and_b32_e32 v7, 0xff0000, v7
	v_perm_b32 v2, v3, v2, s84
	v_or3_b32 v2, v2, v6, v7
	ds_write_b32 v20, v2 offset:128
	buffer_store_dwordx4 v[180:183], v91, s[20:23], s0 offen
	v_mov_b32_e32 v2, v252
	v_mov_b32_e32 v3, v253
	v_pk_add_f32 v[6:7], v[30:31], v[2:3] op_sel_hi:[1,0] neg_lo:[0,1] neg_hi:[0,1]
	s_nop 0
	v_pk_mul_f32 v[6:7], v[2:3], v[6:7] op_sel:[1,0]
	v_pk_add_f32 v[24:25], v[28:29], v[2:3] op_sel_hi:[1,0] neg_lo:[0,1] neg_hi:[0,1]
	v_pk_fma_f32 v[6:7], v[40:41], v[6:7], v[42:43]
	v_pk_mul_f32 v[2:3], v[2:3], v[24:25] op_sel:[1,0]
	s_nop 0
	v_pk_fma_f32 v[0:1], v[0:1], v[2:3], v[4:5]
	v_and_b32_sdwa v2, v7, v216 dst_sel:DWORD dst_unused:UNUSED_PAD src0_sel:WORD_1 src1_sel:DWORD
	v_and_b32_sdwa v3, v6, v216 dst_sel:DWORD dst_unused:UNUSED_PAD src0_sel:WORD_1 src1_sel:DWORD
	v_add3_u32 v4, v7, v2, s82
	v_add3_u32 v2, v6, v3, s82
	v_and_b32_e32 v5, 0xffff0000, v2
	v_and_b32_sdwa v2, v1, v216 dst_sel:DWORD dst_unused:UNUSED_PAD src0_sel:WORD_1 src1_sel:DWORD
	v_and_b32_sdwa v3, v0, v216 dst_sel:DWORD dst_unused:UNUSED_PAD src0_sel:WORD_1 src1_sel:DWORD
	v_add3_u32 v2, v1, v2, s82
	v_add3_u32 v23, v0, v3, s82
	v_and_b32_e32 v24, 0xffff0000, v2
	v_or_b32_sdwa v3, v24, v4 dst_sel:DWORD dst_unused:UNUSED_PAD src0_sel:DWORD src1_sel:WORD_1
	v_or_b32_sdwa v2, v23, v5 dst_sel:DWORD dst_unused:UNUSED_PAD src0_sel:WORD_1 src1_sel:DWORD
	ds_write_b64 v92, v[2:3]
	v_and_b32_e32 v2, 0xffff0000, v23
	v_sub_u32_e32 v0, v0, v2
	v_sub_u32_e32 v2, v6, v5
	v_and_b32_e32 v3, 0xffff0000, v4
	v_add_u32_e32 v2, 0x80, v2
	v_sub_u32_e32 v3, v7, v3
	v_sub_u32_e32 v1, v1, v24
	v_add_u32_e32 v0, 0x80, v0
	v_ashrrev_i32_e32 v2, 8, v2
	v_add_u32_e32 v3, 0x80, v3
	v_add_u32_e32 v1, 0x80, v1
	v_ashrrev_i32_e32 v0, 8, v0
	v_min_i32_e32 v2, 0x7f, v2
	v_ashrrev_i32_e32 v3, 8, v3
	v_ashrrev_i32_e32 v1, 8, v1
	v_min_i32_e32 v0, 0x7f, v0
	v_min_i32_sdwa v3, v3, s83 dst_sel:WORD_1 dst_unused:UNUSED_PAD src0_sel:DWORD src1_sel:DWORD
	v_min_i32_e32 v1, 0x7f, v1
	v_lshlrev_b32_e32 v2, 8, v2
	v_and_b32_e32 v2, 0xff00, v2
	v_and_b32_e32 v3, 0xff0000, v3
	v_perm_b32 v0, v1, v0, s84
	v_or3_b32 v0, v0, v2, v3
	ds_write_b32 v22, v0 offset:128
	buffer_store_dwordx4 v[184:187], v95, s[20:23], s0 offen
	v_mov_b32_e32 v0, v232
	v_mov_b32_e32 v1, v233
	v_mov_b32_e32 v2, v234
	v_mov_b32_e32 v3, v235
	v_mov_b32_e32 v4, v248
	v_mov_b32_e32 v5, v249
	v_mov_b32_e32 v6, v250
	v_mov_b32_e32 v7, v251
	v_mov_b32_e32 v28, v210
	v_mov_b32_e32 v29, v211
	s_mov_b64 s[4:5], -1
	v_pk_add_f32 v[30:31], v[50:51], v[28:29] op_sel_hi:[1,0] neg_lo:[0,1] neg_hi:[0,1]
	s_nop 0
	v_pk_mul_f32 v[30:31], v[28:29], v[30:31] op_sel:[1,0]
	v_pk_add_f32 v[36:37], v[48:49], v[28:29] op_sel_hi:[1,0] neg_lo:[0,1] neg_hi:[0,1]
	v_mov_b32_e32 v24, v1
	v_mov_b32_e32 v25, v2
	v_mov_b32_e32 v26, v5
	v_mov_b32_e32 v27, v6
	v_pk_fma_f32 v[30:31], v[24:25], v[30:31], v[26:27]
	v_pk_mul_f32 v[28:29], v[28:29], v[36:37] op_sel:[1,0]
	v_mov_b32_e32 v1, v3
	v_mov_b32_e32 v5, v7
	v_and_b32_sdwa v6, v31, v216 dst_sel:DWORD dst_unused:UNUSED_PAD src0_sel:WORD_1 src1_sel:DWORD
	v_and_b32_sdwa v7, v30, v216 dst_sel:DWORD dst_unused:UNUSED_PAD src0_sel:WORD_1 src1_sel:DWORD
	v_pk_fma_f32 v[2:3], v[0:1], v[28:29], v[4:5]
	v_add3_u32 v23, v31, v6, s82
	v_add3_u32 v6, v30, v7, s82
	v_and_b32_e32 v28, 0xffff0000, v6
	v_and_b32_sdwa v6, v3, v216 dst_sel:DWORD dst_unused:UNUSED_PAD src0_sel:WORD_1 src1_sel:DWORD
	v_and_b32_sdwa v7, v2, v216 dst_sel:DWORD dst_unused:UNUSED_PAD src0_sel:WORD_1 src1_sel:DWORD
	v_add3_u32 v6, v3, v6, s82
	v_add3_u32 v29, v2, v7, s82
	v_and_b32_e32 v36, 0xffff0000, v6
	v_or_b32_sdwa v7, v36, v23 dst_sel:DWORD dst_unused:UNUSED_PAD src0_sel:DWORD src1_sel:WORD_1
; #define WAIT_L(n) asm volatile("s_waitcnt lgkmcnt(" #n ")" ::: "memory")
; #define BAR __builtin_amdgcn_s_barrier()
;     ...
;           _Pragma("unroll") for (int bj = 0; bj < 2; ++bj) _Pragma("unroll") for (int n = 0; n < 2; ++n) {
;             const int cc = bj * HALF + wc3 * 32 + n * 16 + fq3 * 4;
;             const float4 gm = *reinterpret_cast<const float4*>(g.gam + pn * BM + cc), bt = *reinterpret_cast<const float4*>(g.bet + pn * BM + cc);
;             _Pragma("unroll") for (int m = 0; m < 4; ++m) {
;               const int rr = wr3 * 64 + m * 16 + fr3;
;               const float2 ms = *reinterpret_cast<const float2*>(mr + (ai * HALF + rr) * 2);
;               f32x4 y = acc[ai][bj][m][n];
;               const float o0 = (y[0] - ms.x) * ms.y * gm.x + bt.x, o1 = (y[1] - ms.x) * ms.y * gm.y + bt.y;
;               const float o2 = (y[2] - ms.x) * ms.y * gm.z + bt.z, o3 = (y[3] - ms.x) * ms.y * gm.w + bt.w;
;               const unsigned h0 = f2bf(o0), h1 = f2bf(o1), h2 = f2bf(o2), h3 = f2bf(o3);
;               u32x2 ob; ob[0] = h0 | (h1 << 16); ob[1] = h2 | (h3 << 16);
;               *reinterpret_cast<u32x2*>(smem + (rr >> 1) * PIECE + (rr & 1) * 512 + cc * 2) = ob;
;               const int l0 = min(((int)__float_as_uint(o0) - (int)(h0 << 16) + 128) >> 8, 127);
;               const int l1 = min(((int)__float_as_uint(o1) - (int)(h1 << 16) + 128) >> 8, 127);
;               const int l2 = min(((int)__float_as_uint(o2) - (int)(h2 << 16) + 128) >> 8, 127);
;               const int l3 = min(((int)__float_as_uint(o3) - (int)(h3 << 16) + 128) >> 8, 127);
;               *reinterpret_cast<unsigned*>(smem + LOBASE + (rr >> 2) * PIECE + (rr & 3) * 256 + cc) =
;                   (unsigned)(l0 & 255) | ((unsigned)(l1 & 255) << 8) | ((unsigned)(l2 & 255) << 16) | ((unsigned)l3 << 24);
;             }
;           }
;           WAIT_L(0); BAR;
	v_or_b32_sdwa v6, v29, v28 dst_sel:DWORD dst_unused:UNUSED_PAD src0_sel:WORD_1 src1_sel:DWORD
	ds_write_b64 v93, v[6:7]
	v_and_b32_e32 v6, 0xffff0000, v29
	v_sub_u32_e32 v2, v2, v6
	v_sub_u32_e32 v6, v30, v28
	v_and_b32_e32 v7, 0xffff0000, v23
	v_add_u32_e32 v6, 0x80, v6
	v_sub_u32_e32 v7, v31, v7
	v_sub_u32_e32 v3, v3, v36
	v_add_u32_e32 v2, 0x80, v2
	v_ashrrev_i32_e32 v6, 8, v6
	v_add_u32_e32 v7, 0x80, v7
	v_add_u32_e32 v3, 0x80, v3
	v_ashrrev_i32_e32 v2, 8, v2
	v_min_i32_e32 v6, 0x7f, v6
	v_ashrrev_i32_e32 v7, 8, v7
	v_ashrrev_i32_e32 v3, 8, v3
	v_min_i32_e32 v2, 0x7f, v2
	v_min_i32_sdwa v7, v7, s83 dst_sel:WORD_1 dst_unused:UNUSED_PAD src0_sel:DWORD src1_sel:DWORD
	v_min_i32_e32 v3, 0x7f, v3
	v_lshlrev_b32_e32 v6, 8, v6
	v_and_b32_e32 v6, 0xff00, v6
	v_and_b32_e32 v7, 0xff0000, v7
	v_perm_b32 v2, v3, v2, s84
	v_or3_b32 v2, v2, v6, v7
	ds_write_b32 v12, v2 offset:144
	v_mov_b32_e32 v2, v212
	v_mov_b32_e32 v3, v213
	v_pk_add_f32 v[6:7], v[34:35], v[2:3] op_sel_hi:[1,0] neg_lo:[0,1] neg_hi:[0,1]
	s_nop 0
	v_pk_mul_f32 v[6:7], v[2:3], v[6:7] op_sel:[1,0]
	v_pk_add_f32 v[12:13], v[32:33], v[2:3] op_sel_hi:[1,0] neg_lo:[0,1] neg_hi:[0,1]
	v_pk_fma_f32 v[6:7], v[24:25], v[6:7], v[26:27]
	v_pk_mul_f32 v[2:3], v[2:3], v[12:13] op_sel:[1,0]
	v_and_b32_sdwa v12, v7, v216 dst_sel:DWORD dst_unused:UNUSED_PAD src0_sel:WORD_1 src1_sel:DWORD
	v_and_b32_sdwa v13, v6, v216 dst_sel:DWORD dst_unused:UNUSED_PAD src0_sel:WORD_1 src1_sel:DWORD
	v_pk_fma_f32 v[2:3], v[0:1], v[2:3], v[4:5]
	v_add3_u32 v23, v7, v12, s82
	v_add3_u32 v12, v6, v13, s82
	v_and_b32_e32 v28, 0xffff0000, v12
	v_and_b32_sdwa v12, v3, v216 dst_sel:DWORD dst_unused:UNUSED_PAD src0_sel:WORD_1 src1_sel:DWORD
	v_and_b32_sdwa v13, v2, v216 dst_sel:DWORD dst_unused:UNUSED_PAD src0_sel:WORD_1 src1_sel:DWORD
	v_add3_u32 v12, v3, v12, s82
	v_add3_u32 v29, v2, v13, s82
	v_and_b32_e32 v30, 0xffff0000, v12
	v_or_b32_sdwa v13, v30, v23 dst_sel:DWORD dst_unused:UNUSED_PAD src0_sel:DWORD src1_sel:WORD_1
	v_or_b32_sdwa v12, v29, v28 dst_sel:DWORD dst_unused:UNUSED_PAD src0_sel:WORD_1 src1_sel:DWORD
	ds_write_b64 v94, v[12:13]
	v_and_b32_e32 v12, 0xffff0000, v29
	v_sub_u32_e32 v2, v2, v12
	v_sub_u32_e32 v6, v6, v28
	v_and_b32_e32 v12, 0xffff0000, v23
	v_add_u32_e32 v6, 0x80, v6
	v_sub_u32_e32 v7, v7, v12
	v_sub_u32_e32 v3, v3, v30
	v_add_u32_e32 v2, 0x80, v2
	v_ashrrev_i32_e32 v6, 8, v6
	v_add_u32_e32 v7, 0x80, v7
	v_add_u32_e32 v3, 0x80, v3
	v_ashrrev_i32_e32 v2, 8, v2
	v_min_i32_e32 v6, 0x7f, v6
	v_ashrrev_i32_e32 v7, 8, v7
	v_ashrrev_i32_e32 v3, 8, v3
	v_min_i32_e32 v2, 0x7f, v2
	v_min_i32_sdwa v7, v7, s83 dst_sel:WORD_1 dst_unused:UNUSED_PAD src0_sel:DWORD src1_sel:DWORD
	v_min_i32_e32 v3, 0x7f, v3
	v_lshlrev_b32_e32 v6, 8, v6
	v_and_b32_e32 v6, 0xff00, v6
	v_and_b32_e32 v7, 0xff0000, v7
	v_perm_b32 v2, v3, v2, s84
	v_or3_b32 v2, v2, v6, v7
	ds_write_b32 v14, v2 offset:144
	v_mov_b32_e32 v2, v214
	v_mov_b32_e32 v3, v215
	v_pk_add_f32 v[6:7], v[18:19], v[2:3] op_sel_hi:[1,0] neg_lo:[0,1] neg_hi:[0,1]
	s_nop 0
	v_pk_mul_f32 v[6:7], v[2:3], v[6:7] op_sel:[1,0]
	v_pk_add_f32 v[12:13], v[16:17], v[2:3] op_sel_hi:[1,0] neg_lo:[0,1] neg_hi:[0,1]
	v_pk_fma_f32 v[6:7], v[24:25], v[6:7], v[26:27]
	v_pk_mul_f32 v[2:3], v[2:3], v[12:13] op_sel:[1,0]
	v_and_b32_sdwa v12, v7, v216 dst_sel:DWORD dst_unused:UNUSED_PAD src0_sel:WORD_1 src1_sel:DWORD
	v_and_b32_sdwa v13, v6, v216 dst_sel:DWORD dst_unused:UNUSED_PAD src0_sel:WORD_1 src1_sel:DWORD
	v_pk_fma_f32 v[2:3], v[0:1], v[2:3], v[4:5]
	v_add3_u32 v14, v7, v12, s82
	v_add3_u32 v12, v6, v13, s82
	v_and_b32_e32 v15, 0xffff0000, v12
	v_and_b32_sdwa v12, v3, v216 dst_sel:DWORD dst_unused:UNUSED_PAD src0_sel:WORD_1 src1_sel:DWORD
	v_and_b32_sdwa v13, v2, v216 dst_sel:DWORD dst_unused:UNUSED_PAD src0_sel:WORD_1 src1_sel:DWORD
	v_add3_u32 v12, v3, v12, s82
	v_add3_u32 v16, v2, v13, s82
	v_and_b32_e32 v17, 0xffff0000, v12
	v_or_b32_sdwa v13, v17, v14 dst_sel:DWORD dst_unused:UNUSED_PAD src0_sel:DWORD src1_sel:WORD_1
	v_or_b32_sdwa v12, v16, v15 dst_sel:DWORD dst_unused:UNUSED_PAD src0_sel:WORD_1 src1_sel:DWORD
	ds_write_b64 v80, v[12:13]
	v_and_b32_e32 v12, 0xffff0000, v16
	v_sub_u32_e32 v2, v2, v12
	v_sub_u32_e32 v6, v6, v15
	v_and_b32_e32 v12, 0xffff0000, v14
	v_add_u32_e32 v6, 0x80, v6
	v_sub_u32_e32 v7, v7, v12
	v_sub_u32_e32 v3, v3, v17
	v_add_u32_e32 v2, 0x80, v2
	v_ashrrev_i32_e32 v6, 8, v6
	v_add_u32_e32 v7, 0x80, v7
	v_add_u32_e32 v3, 0x80, v3
	v_ashrrev_i32_e32 v2, 8, v2
	v_min_i32_e32 v6, 0x7f, v6
	v_ashrrev_i32_e32 v7, 8, v7
	v_ashrrev_i32_e32 v3, 8, v3
	v_min_i32_e32 v2, 0x7f, v2
	v_min_i32_sdwa v7, v7, s83 dst_sel:WORD_1 dst_unused:UNUSED_PAD src0_sel:DWORD src1_sel:DWORD
	v_min_i32_e32 v3, 0x7f, v3
	v_lshlrev_b32_e32 v6, 8, v6
	v_and_b32_e32 v6, 0xff00, v6
	v_and_b32_e32 v7, 0xff0000, v7
	v_perm_b32 v2, v3, v2, s84
	v_or3_b32 v2, v2, v6, v7
	ds_write_b32 v20, v2 offset:144
	v_mov_b32_e32 v2, v252
	v_mov_b32_e32 v3, v253
	v_pk_add_f32 v[6:7], v[10:11], v[2:3] op_sel_hi:[1,0] neg_lo:[0,1] neg_hi:[0,1]
	s_nop 0
	v_pk_mul_f32 v[6:7], v[2:3], v[6:7] op_sel:[1,0]
	v_pk_add_f32 v[8:9], v[8:9], v[2:3] op_sel_hi:[1,0] neg_lo:[0,1] neg_hi:[0,1]
	v_pk_fma_f32 v[6:7], v[24:25], v[6:7], v[26:27]
	v_pk_mul_f32 v[2:3], v[2:3], v[8:9] op_sel:[1,0]
	s_nop 0
	v_pk_fma_f32 v[0:1], v[0:1], v[2:3], v[4:5]
	v_and_b32_sdwa v2, v7, v216 dst_sel:DWORD dst_unused:UNUSED_PAD src0_sel:WORD_1 src1_sel:DWORD
	v_and_b32_sdwa v3, v6, v216 dst_sel:DWORD dst_unused:UNUSED_PAD src0_sel:WORD_1 src1_sel:DWORD
	v_add3_u32 v4, v7, v2, s82
	v_add3_u32 v2, v6, v3, s82
	v_and_b32_e32 v5, 0xffff0000, v2
	v_and_b32_sdwa v2, v1, v216 dst_sel:DWORD dst_unused:UNUSED_PAD src0_sel:WORD_1 src1_sel:DWORD
	v_and_b32_sdwa v3, v0, v216 dst_sel:DWORD dst_unused:UNUSED_PAD src0_sel:WORD_1 src1_sel:DWORD
	v_add3_u32 v2, v1, v2, s82
	v_add3_u32 v8, v0, v3, s82
	v_and_b32_e32 v9, 0xffff0000, v2
	v_or_b32_sdwa v3, v9, v4 dst_sel:DWORD dst_unused:UNUSED_PAD src0_sel:DWORD src1_sel:WORD_1
	v_or_b32_sdwa v2, v8, v5 dst_sel:DWORD dst_unused:UNUSED_PAD src0_sel:WORD_1 src1_sel:DWORD
	ds_write_b64 v73, v[2:3]
	v_and_b32_e32 v2, 0xffff0000, v8
	v_sub_u32_e32 v0, v0, v2
	v_sub_u32_e32 v2, v6, v5
	v_and_b32_e32 v3, 0xffff0000, v4
	v_add_u32_e32 v2, 0x80, v2
	v_sub_u32_e32 v3, v7, v3
	v_sub_u32_e32 v1, v1, v9
	v_add_u32_e32 v0, 0x80, v0
	v_ashrrev_i32_e32 v2, 8, v2
	v_add_u32_e32 v3, 0x80, v3
	v_add_u32_e32 v1, 0x80, v1
	v_ashrrev_i32_e32 v0, 8, v0
	v_min_i32_e32 v2, 0x7f, v2
	v_ashrrev_i32_e32 v3, 8, v3
	v_ashrrev_i32_e32 v1, 8, v1
	v_min_i32_e32 v0, 0x7f, v0
	v_min_i32_sdwa v3, v3, s83 dst_sel:WORD_1 dst_unused:UNUSED_PAD src0_sel:DWORD src1_sel:DWORD
	v_min_i32_e32 v1, 0x7f, v1
	v_lshlrev_b32_e32 v2, 8, v2
	v_and_b32_e32 v2, 0xff00, v2
	v_and_b32_e32 v3, 0xff0000, v3
	v_perm_b32 v0, v1, v0, s84
	v_or3_b32 v0, v0, v2, v3
	ds_write_b32 v22, v0 offset:144
	s_waitcnt lgkmcnt(0)
	s_barrier
; #define STAGE(P, RS, SOFF, OFF, kt) do { const int _so = (SOFF) + (kt) * (BK * 2); \
;     _Pragma("unroll") for (int _i = 0; _i < 2; ++_i) { \
;       __builtin_amdgcn_raw_ptr_buffer_load_lds(RS, (__attribute__((address_space(3))) void*)((P) + wave * 1024 + _i * 8192), 16, OFF[_i], _so, 0, 0); } } while (0)
; #define WAIT_L(n) asm volatile("s_waitcnt lgkmcnt(" #n ")" ::: "memory")
; #define BAR __builtin_amdgcn_s_barrier()
;     ...
;   auto issue_prologue = [&](int sA0, int sA1, int sB0, int sB1) {
;     const int tid = opaque_tid(wave);
;     int offA[2], offB[2];
;     _Pragma("unroll") for (int i = 0; i < 2; ++i) {
;       int r, c; stage_rc(tid * 16 + i * 8192, r, c);
;       offA[i] = (r * lda + c) * 2; offB[i] = (r * ldb + c) * 2;
;     }
;     STAGE(SB(0, 0), rsB, sB0, offB, 0); STAGE(SA(0, 0), rsA, sA0, offA, 0);
;     STAGE(SB(0, 1), rsB, sB1, offB, 0); STAGE(SA(0, 1), rsA, sA1, offA, 0);
;     STAGE(SB(1, 0), rsB, sB0, offB, 1); STAGE(SA(1, 0), rsA, sA0, offA, 1); STAGE(SB(1, 1), rsB, sB1, offB, 1);
;   };
;     ...
;           WAIT_L(0); BAR;
;           const int hso = ((brow + ai * HALF + 16 * wave) * DM + pn * BM) * 2;
;           const int lso = (brow + ai * HALF + 16 * wave) * DM + pn * BM;
;           _Pragma("unroll") for (int i = 0; i < 8; ++i) {
;             const u32x4 v = *reinterpret_cast<const u32x4*>(smem + (wave * 8 + i) * PIECE + lane3 * 16);
;             __builtin_amdgcn_raw_buffer_store_b128(v, rsXB, hvo + i * (2 * DM * 2), hso, 0);
;           }
;           _Pragma("unroll") for (int i = 0; i < 4; ++i) {
;             const u32x4 v = *reinterpret_cast<const u32x4*>(smem + LOBASE + (wave * 4 + i) * PIECE + lane3 * 16);
;             __builtin_amdgcn_raw_buffer_store_b128(v, rsLO, lvo + i * (4 * DM), lso, 0);
;           }
;           WAIT_L(0); BAR;
;         }
;       }
;       if (has_next) issue_prologue(nA0, nA1, nB0, nB1);
	ds_read_b128 v[128:131], v72
	ds_read_b128 v[132:135], v72 offset:1040
	ds_read_b128 v[136:139], v72 offset:2080
	ds_read_b128 v[140:143], v72 offset:3120
	ds_read_b128 v[152:155], v72 offset:4160
	ds_read_b128 v[156:159], v72 offset:5200
	ds_read_b128 v[160:163], v72 offset:6240
	ds_read_b128 v[164:167], v72 offset:7280
	ds_read_b128 v[168:171], v147
	ds_read_b128 v[172:175], v147 offset:1040
	ds_read_b128 v[176:179], v147 offset:2080
	ds_read_b128 v[180:183], v147 offset:3120
	s_waitcnt lgkmcnt(0)
	s_barrier
	s_cbranch_vccnz .Lmy_s1n_379
	v_mbcnt_lo_u32_b32 v0, -1, 0
	v_mbcnt_hi_u32_b32 v0, -1, v0
	s_mov_b32 m0, s37
	v_lshl_add_u32 v0, v0, 4, s35
	v_ashrrev_i32_e32 v1, 31, v0
	v_lshrrev_b32_e32 v1, 22, v1
	v_add_u32_e32 v1, v0, v1
	v_ashrrev_i32_e32 v1, 10, v1
	v_mul_i32_i24_e32 v2, 0x400, v1
	v_sub_u32_e32 v2, v0, v2
	v_lshrrev_b32_e32 v3, 4, v2
	v_bitop3_b32 v2, v3, v2, 32 bitop3:0x6c
	v_ashrrev_i32_e32 v4, 31, v2
	v_lshrrev_b32_e32 v4, 26, v4
	v_add_u32_e32 v4, v2, v4
	v_lshrrev_b32_e32 v5, 6, v4
	v_and_b32_e32 v4, 0xc0, v4
	v_lshlrev_b32_e32 v3, 3, v1
	v_lshlrev_b32_e32 v1, 5, v1
	v_sub_u32_e32 v2, v2, v4
	v_and_b32_e32 v3, 0x7fff0, v3
	v_and_b32_e32 v1, 32, v1
	v_ashrrev_i16_sdwa v2, v216, sext(v2) dst_sel:DWORD dst_unused:UNUSED_PAD src0_sel:DWORD src1_sel:BYTE_0
	v_add_u32_sdwa v1, v1, sext(v2) dst_sel:DWORD dst_unused:UNUSED_PAD src0_sel:DWORD src1_sel:WORD_0
	v_add_lshl_u32 v2, v5, v3, 13
	v_add_u32_e32 v0, 0x2000, v0
	v_lshl_add_u32 v1, v1, 1, v2
	v_ashrrev_i32_e32 v2, 31, v0
	v_lshrrev_b32_e32 v2, 22, v2
	v_add_u32_e32 v2, v0, v2
	v_ashrrev_i32_e32 v2, 10, v2
	v_mul_i32_i24_e32 v3, 0x400, v2
	v_sub_u32_e32 v0, v0, v3
	v_lshrrev_b32_e32 v3, 4, v0
	v_bitop3_b32 v0, v3, v0, 32 bitop3:0x6c
	v_ashrrev_i32_e32 v4, 31, v0
	v_lshrrev_b32_e32 v4, 26, v4
	v_add_u32_e32 v4, v0, v4
	v_lshrrev_b32_e32 v5, 6, v4
	v_and_b32_e32 v4, 0xffc0, v4
	v_sub_u32_e32 v0, v0, v4
	v_lshrrev_b16_e32 v4, 7, v0
	v_and_b32_e32 v4, 1, v4
	v_lshlrev_b32_e32 v3, 3, v2
	v_lshlrev_b32_e32 v2, 5, v2
	v_add_u16_e32 v0, v0, v4
	v_and_b32_e32 v3, 0x7fff0, v3
	v_and_b32_e32 v2, 32, v2
	v_ashrrev_i16_sdwa v0, v216, sext(v0) dst_sel:DWORD dst_unused:UNUSED_PAD src0_sel:DWORD src1_sel:BYTE_0
	v_add_u32_sdwa v0, v2, sext(v0) dst_sel:DWORD dst_unused:UNUSED_PAD src0_sel:DWORD src1_sel:WORD_0
	v_add_lshl_u32 v2, v5, v3, 13
	s_mov_b32 s14, s10
	s_mov_b32 s15, s11
	v_lshl_add_u32 v0, v0, 1, v2
	buffer_load_dwordx4 v1, s[12:15], s92 offen lds
	s_mov_b32 m0, s48
	s_or_b32 s0, s92, 0x80
	buffer_load_dwordx4 v0, s[12:15], s92 offen lds
	s_mov_b32 m0, s35
	s_mov_b64 s[4:5], 0
	buffer_load_dwordx4 v1, s[8:11], s87 offen lds
	s_mov_b32 m0, s49
	s_nop 0
	buffer_load_dwordx4 v0, s[8:11], s87 offen lds
	s_mov_b32 m0, s38
	s_nop 0
	buffer_load_dwordx4 v1, s[12:15], s93 offen lds
	s_mov_b32 m0, s54
	s_nop 0
	buffer_load_dwordx4 v0, s[12:15], s93 offen lds
	s_mov_b32 m0, s39
	s_nop 0
	buffer_load_dwordx4 v1, s[8:11], s86 offen lds
	s_mov_b32 m0, s55
	s_nop 0
	buffer_load_dwordx4 v0, s[8:11], s86 offen lds
	s_mov_b32 m0, s42
	s_nop 0
	buffer_load_dwordx4 v1, s[12:15], s0 offen lds
	s_mov_b32 m0, s56
	s_nop 0
	buffer_load_dwordx4 v0, s[12:15], s0 offen lds
	s_or_b32 s0, s87, 0x80
	s_mov_b32 m0, s43
	s_nop 0
	buffer_load_dwordx4 v1, s[8:11], s0 offen lds
	s_mov_b32 m0, s57
	s_nop 0
	buffer_load_dwordx4 v0, s[8:11], s0 offen lds
	s_add_i32 s0, s93, 0x80
	s_mov_b32 m0, s44
	s_nop 0
	buffer_load_dwordx4 v1, s[12:15], s0 offen lds
	s_mov_b32 m0, s58
	s_nop 0
	buffer_load_dwordx4 v0, s[12:15], s0 offen lds
	buffer_store_dwordx4 v[128:131], v148, s[16:19], s3 offen
	buffer_store_dwordx4 v[132:135], v74, s[16:19], s3 offen
	buffer_store_dwordx4 v[136:139], v75, s[16:19], s3 offen
	buffer_store_dwordx4 v[140:143], v81, s[16:19], s3 offen
	buffer_store_dwordx4 v[152:155], v82, s[16:19], s3 offen
	buffer_store_dwordx4 v[156:159], v83, s[16:19], s3 offen
	buffer_store_dwordx4 v[160:163], v88, s[16:19], s3 offen
	buffer_store_dwordx4 v[164:167], v89, s[16:19], s3 offen
	buffer_store_dwordx4 v[168:171], v146, s[20:23], s1 offen
	buffer_store_dwordx4 v[172:175], v90, s[20:23], s1 offen
	buffer_store_dwordx4 v[176:179], v91, s[20:23], s1 offen
	buffer_store_dwordx4 v[180:183], v95, s[20:23], s1 offen
	s_branch .LBB0_384

;     ...
;       const int tid3 = opaque_tid(wave);
;       const int wr3 = tid3 >> 8, wc3 = (tid3 >> 6) & 3, fr3 = tid3 & 15, fq3 = (tid3 & 63) >> 4;
;       const int ebase3 = (brow + wr3 * 64 + fr3) * DM + pn * BM + wc3 * 32 + fq3 * 4;
;       const int vo4b = ebase3 * 4, vo2 = ebase3 * 2, vo1 = ebase3;
;       (void)vo4b; (void)vo2; (void)vo1;
;       if constexpr (OUTF) {
;         _Pragma("unroll") for (int bj = 0; bj < 2; ++bj) _Pragma("unroll") for (int n = 0; n < 2; ++n) {
;           const int col = pn * BM + bj * HALF + wc3 * 32 + n * 16 + fq3 * 4;
;           const float4 gm = *reinterpret_cast<const float4*>(g.gam + col), bt = *reinterpret_cast<const float4*>(g.bet + col);
;           _Pragma("unroll") for (int ai = 0; ai < 2; ++ai) _Pragma("unroll") for (int m = 0; m < 4; ++m) {
;             const int rl = ai * HALF + wr3 * 64 + m * 16 + fr3;
;             const float2 ms = *reinterpret_cast<const float2*>(mr + rl * 2);
;             f32x4 y = acc[ai][bj][m][n];
;             u32x4 o;
;             o[0] = __float_as_uint((y[0] - ms.x) * ms.y * gm.x + bt.x); o[1] = __float_as_uint((y[1] - ms.x) * ms.y * gm.y + bt.y);
;             o[2] = __float_as_uint((y[2] - ms.x) * ms.y * gm.z + bt.z); o[3] = __float_as_uint((y[3] - ms.x) * ms.y * gm.w + bt.w);
;             __builtin_amdgcn_raw_buffer_store_b128(o, rsO, vo4b + ((ai * HALF + m * 16) * DM + bj * HALF + n * 16) * 4, 0, 0);
;           }
;         }
;       } else {
;         constexpr int PIECE = 1024 + 16, LOBASE = 64 * PIECE;
;         const int lane3 = tid3 & 63;
;         const int hvo = (lane3 >> 5) * (DM * 2) + (lane3 & 31) * 16;
;         const int lvo = (lane3 >> 4) * DM + (lane3 & 15) * 16;
;         _Pragma("unroll") for (int ai = 0; ai < 2; ++ai) {
;           _Pragma("unroll") for (int bj = 0; bj < 2; ++bj) _Pragma("unroll") for (int n = 0; n < 2; ++n) {
;             const int cc = bj * HALF + wc3 * 32 + n * 16 + fq3 * 4;
;             const float4 gm = *reinterpret_cast<const float4*>(g.gam + pn * BM + cc), bt = *reinterpret_cast<const float4*>(g.bet + pn * BM + cc);
;             _Pragma("unroll") for (int m = 0; m < 4; ++m) {
;               const int rr = wr3 * 64 + m * 16 + fr3;
;               const float2 ms = *reinterpret_cast<const float2*>(mr + (ai * HALF + rr) * 2);
;               f32x4 y = acc[ai][bj][m][n];
.LBB0_523:
	s_or_b64 exec, exec, s[6:7]
	s_waitcnt lgkmcnt(0)
	s_barrier
	v_mbcnt_lo_u32_b32 v0, -1, 0
	v_mbcnt_hi_u32_b32 v0, -1, v0
	v_readlane_b32 s40, v255, 0
	v_add_u32_e32 v1, s34, v0
	v_bfe_u32 v4, v0, 4, 2
	v_ashrrev_i32_e32 v5, 2, v1
	v_lshrrev_b32_e32 v6, 1, v1
	v_lshlrev_b32_e32 v1, 4, v1
	v_lshlrev_b32_e32 v7, 2, v4
	v_lshlrev_b32_e32 v12, 7, v0
	v_and_b32_e32 v13, 0x1f0, v1
	s_movk_i32 s4, 0x60
	s_ashr_i32 s29, s28, 31
	v_readlane_b32 s54, v255, 14
	v_readlane_b32 s55, v255, 15
	v_and_or_b32 v148, v12, s75, v13
	v_and_or_b32 v12, v6, s4, v7
	s_lshl_b64 s[4:5], s[28:29], 2
	s_mov_b64 s[22:23], s[54:55]
	s_add_u32 s6, s22, s4
	v_and_b32_e32 v2, 15, v0
	v_and_b32_e32 v3, 63, v0
	v_and_b32_e32 v1, 0xf0, v1
	v_lshlrev_b32_e32 v13, 9, v0
	v_lshlrev_b32_e32 v0, 8, v0
	s_addc_u32 s7, s23, s5
	v_lshlrev_b32_e32 v150, 2, v12
	v_lshl_or_b32 v146, v4, 11, v1
	v_and_or_b32 v156, v5, s31, v2
	v_and_b32_e32 v14, 0x300, v0
	v_lshlrev_b32_e32 v151, 4, v3
	global_load_dwordx4 v[220:223], v150, s[6:7]
	global_load_dwordx4 v[224:227], v150, s[6:7] offset:64
	global_load_dwordx4 v[228:231], v150, s[6:7] offset:512
	global_load_dwordx4 v[232:235], v150, s[6:7] offset:576
	v_readlane_b32 s41, v255, 1
	v_readlane_b32 s42, v255, 2
	v_readlane_b32 s43, v255, 3
	v_readlane_b32 s44, v255, 4
	v_readlane_b32 s45, v255, 5
	v_readlane_b32 s46, v255, 6
	v_readlane_b32 s47, v255, 7
	v_readlane_b32 s48, v255, 8
	v_readlane_b32 s49, v255, 9
	v_readlane_b32 s50, v255, 10
	v_readlane_b32 s51, v255, 11
	v_readlane_b32 s52, v255, 12
	v_readlane_b32 s53, v255, 13
	v_readlane_b32 s40, v255, 16
	v_readlane_b32 s41, v255, 17
	s_add_u32 s4, s40, s4
	s_addc_u32 s5, s41, s5
	global_load_dwordx4 v[236:239], v150, s[4:5]
	global_load_dwordx4 v[240:243], v150, s[4:5] offset:64
	global_load_dwordx4 v[244:247], v150, s[4:5] offset:512
	global_load_dwordx4 v[248:251], v150, s[4:5] offset:576
	s_movk_i32 s22, 0x200
	v_lshl_add_u32 v149, v156, 3, v219
	v_add_u32_e32 v147, s69, v151
	s_andn2_b64 vcc, exec, s[14:15]
	v_readlane_b32 s42, v255, 18
	v_readlane_b32 s43, v255, 19
	v_readlane_b32 s44, v255, 20
	v_readlane_b32 s45, v255, 21
	v_readlane_b32 s46, v255, 22
	v_readlane_b32 s47, v255, 23
	v_readlane_b32 s48, v255, 24
	v_readlane_b32 s49, v255, 25
	v_readlane_b32 s50, v255, 26
	v_readlane_b32 s51, v255, 27
	v_readlane_b32 s52, v255, 28
	v_readlane_b32 s53, v255, 29
	v_readlane_b32 s54, v255, 30
	v_readlane_b32 s55, v255, 31
	s_waitcnt vmcnt(0)
	v_mov_b32_e32 v0, v220
	v_mov_b32_e32 v1, v221
	v_mov_b32_e32 v2, v222
	v_mov_b32_e32 v3, v223
	v_mov_b32_e32 v4, v236
	v_mov_b32_e32 v5, v237
	v_mov_b32_e32 v6, v238
	v_mov_b32_e32 v7, v239
	v_mov_b32_e32 v22, v1
	v_lshlrev_b32_e32 v1, 1, v12
	v_and_or_b32 v155, v13, s22, v1
	s_mov_b32 s22, 0x10400
	v_mov_b32_e32 v23, v2
	v_or3_b32 v2, v14, v12, s22
	ds_read_b64 v[12:13], v149
	v_mov_b32_e32 v1, v3
	s_waitcnt lgkmcnt(0)
	v_mov_b32_e32 v202, v12
	v_mov_b32_e32 v203, v13
	v_pk_add_f32 v[14:15], v[128:129], v[12:13] op_sel_hi:[1,0] neg_lo:[0,1] neg_hi:[0,1]
	s_nop 0
	v_pk_mul_f32 v[14:15], v[12:13], v[14:15] op_sel:[1,0]
	v_pk_add_f32 v[20:21], v[130:131], v[12:13] op_sel_hi:[1,0] neg_lo:[0,1] neg_hi:[0,1]
	v_lshrrev_b32_e32 v129, 1, v156
	v_pk_mul_f32 v[12:13], v[12:13], v[20:21] op_sel:[1,0]
	v_mul_lo_u32 v153, v129, s61
	v_add_u32_e32 v152, v155, v153
	v_mov_b32_e32 v144, v5
	v_mov_b32_e32 v145, v6
	v_pk_fma_f32 v[14:15], v[22:23], v[14:15], v[144:145]
	v_mov_b32_e32 v5, v7
	v_pk_fma_f32 v[6:7], v[0:1], v[12:13], v[4:5]
	v_and_b32_sdwa v12, v14, v216 dst_sel:DWORD dst_unused:UNUSED_PAD src0_sel:WORD_1 src1_sel:DWORD
	v_add3_u32 v12, v14, v12, s78
	v_and_b32_e32 v20, 0xffff0000, v12
	v_and_b32_sdwa v12, v7, v216 dst_sel:DWORD dst_unused:UNUSED_PAD src0_sel:WORD_1 src1_sel:DWORD
	v_and_b32_sdwa v3, v15, v216 dst_sel:DWORD dst_unused:UNUSED_PAD src0_sel:WORD_1 src1_sel:DWORD
	v_and_b32_sdwa v13, v6, v216 dst_sel:DWORD dst_unused:UNUSED_PAD src0_sel:WORD_1 src1_sel:DWORD
	v_add3_u32 v12, v7, v12, s78
	v_add3_u32 v3, v15, v3, s78
	v_add3_u32 v21, v6, v13, s78
	v_and_b32_e32 v128, 0xffff0000, v12
	v_or_b32_sdwa v13, v128, v3 dst_sel:DWORD dst_unused:UNUSED_PAD src0_sel:DWORD src1_sel:WORD_1
	v_or_b32_sdwa v12, v21, v20 dst_sel:DWORD dst_unused:UNUSED_PAD src0_sel:WORD_1 src1_sel:DWORD
	ds_write_b64 v152, v[12:13]
	v_and_b32_e32 v12, 0xffff0000, v21
	v_sub_u32_e32 v6, v6, v12
	v_sub_u32_e32 v12, v14, v20
	v_and_b32_e32 v3, 0xffff0000, v3
	v_add_u32_e32 v12, 0x80, v12
	v_sub_u32_e32 v3, v15, v3
	v_sub_u32_e32 v7, v7, v128
	v_add_u32_e32 v6, 0x80, v6
	v_ashrrev_i32_e32 v12, 8, v12
	v_add_u32_e32 v3, 0x80, v3
	v_add_u32_e32 v7, 0x80, v7
	v_ashrrev_i32_e32 v6, 8, v6
	v_min_i32_e32 v12, 0x7f, v12
	v_ashrrev_i32_e32 v3, 8, v3
	v_ashrrev_i32_e32 v7, 8, v7
	v_min_i32_e32 v6, 0x7f, v6
	v_min_i32_sdwa v3, v3, s79 dst_sel:WORD_1 dst_unused:UNUSED_PAD src0_sel:DWORD src1_sel:DWORD
	v_min_i32_e32 v7, 0x7f, v7
	v_lshlrev_b32_e32 v12, 8, v12
	v_and_b32_e32 v12, 0xff00, v12
	v_and_b32_e32 v3, 0xff0000, v3
	v_perm_b32 v6, v7, v6, s80
	v_or3_b32 v3, v6, v12, v3
	v_lshrrev_b32_e32 v6, 2, v156
	v_mad_u64_u32 v[12:13], s[22:23], v6, s61, v[2:3]
	ds_write_b32 v12, v3
	v_or_b32_e32 v3, 16, v156
	v_lshl_add_u32 v13, v3, 3, v219
	ds_read_b64 v[6:7], v13
	s_waitcnt lgkmcnt(0)
;     ...
;           _Pragma("unroll") for (int bj = 0; bj < 2; ++bj) _Pragma("unroll") for (int n = 0; n < 2; ++n) {
;             const int cc = bj * HALF + wc3 * 32 + n * 16 + fq3 * 4;
;             const float4 gm = *reinterpret_cast<const float4*>(g.gam + pn * BM + cc), bt = *reinterpret_cast<const float4*>(g.bet + pn * BM + cc);
;             _Pragma("unroll") for (int m = 0; m < 4; ++m) {
;               const int rr = wr3 * 64 + m * 16 + fr3;
;               const float2 ms = *reinterpret_cast<const float2*>(mr + (ai * HALF + rr) * 2);
;               f32x4 y = acc[ai][bj][m][n];
;               const float o0 = (y[0] - ms.x) * ms.y * gm.x + bt.x, o1 = (y[1] - ms.x) * ms.y * gm.y + bt.y;
;               const float o2 = (y[2] - ms.x) * ms.y * gm.z + bt.z, o3 = (y[3] - ms.x) * ms.y * gm.w + bt.w;
;               const unsigned h0 = f2bf(o0), h1 = f2bf(o1), h2 = f2bf(o2), h3 = f2bf(o3);
;               u32x2 ob; ob[0] = h0 | (h1 << 16); ob[1] = h2 | (h3 << 16);
;               *reinterpret_cast<u32x2*>(smem + (rr >> 1) * PIECE + (rr & 1) * 512 + cc * 2) = ob;
;               const int l0 = min(((int)__float_as_uint(o0) - (int)(h0 << 16) + 128) >> 8, 127);
;               const int l1 = min(((int)__float_as_uint(o1) - (int)(h1 << 16) + 128) >> 8, 127);
;               const int l2 = min(((int)__float_as_uint(o2) - (int)(h2 << 16) + 128) >> 8, 127);
;               const int l3 = min(((int)__float_as_uint(o3) - (int)(h3 << 16) + 128) >> 8, 127);
;               *reinterpret_cast<unsigned*>(smem + LOBASE + (rr >> 2) * PIECE + (rr & 3) * 256 + cc) =
;                   (unsigned)(l0 & 255) | ((unsigned)(l1 & 255) << 8) | ((unsigned)(l2 & 255) << 16) | ((unsigned)l3 << 24);
;             }
	v_mov_b32_e32 v204, v6
	v_mov_b32_e32 v205, v7
	v_pk_add_f32 v[14:15], v[134:135], v[6:7] op_sel_hi:[1,0] neg_lo:[0,1] neg_hi:[0,1]
	s_nop 0
	v_pk_mul_f32 v[14:15], v[6:7], v[14:15] op_sel:[1,0]
	v_pk_add_f32 v[20:21], v[132:133], v[6:7] op_sel_hi:[1,0] neg_lo:[0,1] neg_hi:[0,1]
	v_pk_fma_f32 v[14:15], v[22:23], v[14:15], v[144:145]
	v_pk_mul_f32 v[6:7], v[6:7], v[20:21] op_sel:[1,0]
	v_and_b32_sdwa v20, v15, v216 dst_sel:DWORD dst_unused:UNUSED_PAD src0_sel:WORD_1 src1_sel:DWORD
	v_and_b32_sdwa v21, v14, v216 dst_sel:DWORD dst_unused:UNUSED_PAD src0_sel:WORD_1 src1_sel:DWORD
	v_pk_fma_f32 v[6:7], v[0:1], v[6:7], v[4:5]
	v_add3_u32 v128, v15, v20, s78
	v_add3_u32 v20, v14, v21, s78
	v_and_b32_e32 v129, 0xffff0000, v20
	v_and_b32_sdwa v20, v7, v216 dst_sel:DWORD dst_unused:UNUSED_PAD src0_sel:WORD_1 src1_sel:DWORD
	v_and_b32_sdwa v21, v6, v216 dst_sel:DWORD dst_unused:UNUSED_PAD src0_sel:WORD_1 src1_sel:DWORD
	v_add3_u32 v20, v7, v20, s78
	v_lshrrev_b32_e32 v132, 1, v3
	v_add3_u32 v130, v6, v21, s78
	v_and_b32_e32 v131, 0xffff0000, v20
	v_mul_lo_u32 v154, v132, s61
	v_or_b32_sdwa v21, v131, v128 dst_sel:DWORD dst_unused:UNUSED_PAD src0_sel:DWORD src1_sel:WORD_1
	v_or_b32_sdwa v20, v130, v129 dst_sel:DWORD dst_unused:UNUSED_PAD src0_sel:WORD_1 src1_sel:DWORD
	v_add_u32_e32 v132, v155, v154
	ds_write_b64 v132, v[20:21]
	v_and_b32_e32 v20, 0xffff0000, v130
	v_sub_u32_e32 v6, v6, v20
	v_sub_u32_e32 v14, v14, v129
	v_and_b32_e32 v20, 0xffff0000, v128
	v_add_u32_e32 v14, 0x80, v14
	v_sub_u32_e32 v15, v15, v20
	v_sub_u32_e32 v7, v7, v131
	v_add_u32_e32 v6, 0x80, v6
	v_ashrrev_i32_e32 v14, 8, v14
	v_add_u32_e32 v15, 0x80, v15
	v_add_u32_e32 v7, 0x80, v7
	v_ashrrev_i32_e32 v6, 8, v6
	v_min_i32_e32 v14, 0x7f, v14
	v_ashrrev_i32_e32 v15, 8, v15
	v_ashrrev_i32_e32 v7, 8, v7
	v_min_i32_e32 v6, 0x7f, v6
	v_min_i32_sdwa v15, v15, s79 dst_sel:WORD_1 dst_unused:UNUSED_PAD src0_sel:DWORD src1_sel:DWORD
	v_min_i32_e32 v7, 0x7f, v7
	v_lshlrev_b32_e32 v14, 8, v14
	v_and_b32_e32 v14, 0xff00, v14
	v_and_b32_e32 v15, 0xff0000, v15
	v_perm_b32 v6, v7, v6, s80
	v_lshrrev_b32_e32 v3, 2, v3
	v_or3_b32 v6, v6, v14, v15
	v_mad_u64_u32 v[14:15], s[22:23], v3, s61, v[2:3]
	v_or_b32_e32 v3, 32, v156
	ds_write_b32 v14, v6
	v_lshl_add_u32 v15, v3, 3, v219
	ds_read_b64 v[6:7], v15
	v_lshrrev_b32_e32 v133, 1, v3
	v_lshrrev_b32_e32 v3, 2, v3
	s_waitcnt lgkmcnt(0)
	v_mov_b32_e32 v206, v6
	v_mov_b32_e32 v207, v7
	v_pk_add_f32 v[20:21], v[138:139], v[6:7] op_sel_hi:[1,0] neg_lo:[0,1] neg_hi:[0,1]
	s_nop 0
	v_pk_mul_f32 v[20:21], v[6:7], v[20:21] op_sel:[1,0]
	v_pk_add_f32 v[128:129], v[136:137], v[6:7] op_sel_hi:[1,0] neg_lo:[0,1] neg_hi:[0,1]
	v_pk_fma_f32 v[20:21], v[22:23], v[20:21], v[144:145]
	v_pk_mul_f32 v[6:7], v[6:7], v[128:129] op_sel:[1,0]
	v_and_b32_sdwa v128, v21, v216 dst_sel:DWORD dst_unused:UNUSED_PAD src0_sel:WORD_1 src1_sel:DWORD
	v_and_b32_sdwa v129, v20, v216 dst_sel:DWORD dst_unused:UNUSED_PAD src0_sel:WORD_1 src1_sel:DWORD
	v_pk_fma_f32 v[6:7], v[0:1], v[6:7], v[4:5]
	v_add3_u32 v130, v21, v128, s78
	v_add3_u32 v128, v20, v129, s78
	v_and_b32_e32 v131, 0xffff0000, v128
	v_and_b32_sdwa v128, v7, v216 dst_sel:DWORD dst_unused:UNUSED_PAD src0_sel:WORD_1 src1_sel:DWORD
	v_and_b32_sdwa v129, v6, v216 dst_sel:DWORD dst_unused:UNUSED_PAD src0_sel:WORD_1 src1_sel:DWORD
	v_add3_u32 v128, v7, v128, s78
	v_add3_u32 v134, v6, v129, s78
	v_and_b32_e32 v135, 0xffff0000, v128
	v_mul_lo_u32 v136, v133, s61
	v_or_b32_sdwa v129, v135, v130 dst_sel:DWORD dst_unused:UNUSED_PAD src0_sel:DWORD src1_sel:WORD_1
	v_or_b32_sdwa v128, v134, v131 dst_sel:DWORD dst_unused:UNUSED_PAD src0_sel:WORD_1 src1_sel:DWORD
	v_add_u32_e32 v133, v155, v136
	ds_write_b64 v133, v[128:129]
	v_and_b32_e32 v128, 0xffff0000, v134
	v_sub_u32_e32 v6, v6, v128
	v_sub_u32_e32 v20, v20, v131
	v_and_b32_e32 v128, 0xffff0000, v130
	v_add_u32_e32 v20, 0x80, v20
	v_sub_u32_e32 v21, v21, v128
	v_sub_u32_e32 v7, v7, v135
	v_add_u32_e32 v6, 0x80, v6
	v_ashrrev_i32_e32 v20, 8, v20
	v_add_u32_e32 v21, 0x80, v21
	v_add_u32_e32 v7, 0x80, v7
	v_ashrrev_i32_e32 v6, 8, v6
	v_min_i32_e32 v20, 0x7f, v20
	v_ashrrev_i32_e32 v21, 8, v21
	v_ashrrev_i32_e32 v7, 8, v7
	v_min_i32_e32 v6, 0x7f, v6
	v_min_i32_sdwa v21, v21, s79 dst_sel:WORD_1 dst_unused:UNUSED_PAD src0_sel:DWORD src1_sel:DWORD
	v_min_i32_e32 v7, 0x7f, v7
	v_lshlrev_b32_e32 v20, 8, v20
	v_and_b32_e32 v20, 0xff00, v20
	v_and_b32_e32 v21, 0xff0000, v21
	v_perm_b32 v6, v7, v6, s80
	v_or3_b32 v6, v6, v20, v21
	v_mad_u64_u32 v[20:21], s[22:23], v3, s61, v[2:3]
	v_or_b32_e32 v3, 48, v156
	ds_write_b32 v20, v6
	v_lshl_add_u32 v21, v3, 3, v219
	ds_read_b64 v[6:7], v21
	v_lshrrev_b32_e32 v130, 1, v3
	v_mul_lo_u32 v135, v130, s61
	v_add_u32_e32 v134, v155, v135
	s_waitcnt lgkmcnt(0)
;     ...
;           _Pragma("unroll") for (int bj = 0; bj < 2; ++bj) _Pragma("unroll") for (int n = 0; n < 2; ++n) {
;             const int cc = bj * HALF + wc3 * 32 + n * 16 + fq3 * 4;
;             const float4 gm = *reinterpret_cast<const float4*>(g.gam + pn * BM + cc), bt = *reinterpret_cast<const float4*>(g.bet + pn * BM + cc);
;             _Pragma("unroll") for (int m = 0; m < 4; ++m) {
;               const int rr = wr3 * 64 + m * 16 + fr3;
;               const float2 ms = *reinterpret_cast<const float2*>(mr + (ai * HALF + rr) * 2);
;               f32x4 y = acc[ai][bj][m][n];
;               const float o0 = (y[0] - ms.x) * ms.y * gm.x + bt.x, o1 = (y[1] - ms.x) * ms.y * gm.y + bt.y;
;               const float o2 = (y[2] - ms.x) * ms.y * gm.z + bt.z, o3 = (y[3] - ms.x) * ms.y * gm.w + bt.w;
;               const unsigned h0 = f2bf(o0), h1 = f2bf(o1), h2 = f2bf(o2), h3 = f2bf(o3);
;               u32x2 ob; ob[0] = h0 | (h1 << 16); ob[1] = h2 | (h3 << 16);
;               *reinterpret_cast<u32x2*>(smem + (rr >> 1) * PIECE + (rr & 1) * 512 + cc * 2) = ob;
;               const int l0 = min(((int)__float_as_uint(o0) - (int)(h0 << 16) + 128) >> 8, 127);
;               const int l1 = min(((int)__float_as_uint(o1) - (int)(h1 << 16) + 128) >> 8, 127);
;               const int l2 = min(((int)__float_as_uint(o2) - (int)(h2 << 16) + 128) >> 8, 127);
;               const int l3 = min(((int)__float_as_uint(o3) - (int)(h3 << 16) + 128) >> 8, 127);
;               *reinterpret_cast<unsigned*>(smem + LOBASE + (rr >> 2) * PIECE + (rr & 3) * 256 + cc) =
;                   (unsigned)(l0 & 255) | ((unsigned)(l1 & 255) << 8) | ((unsigned)(l2 & 255) << 16) | ((unsigned)l3 << 24);
;             }
	v_mov_b32_e32 v208, v6
	v_mov_b32_e32 v209, v7
	v_pk_add_f32 v[128:129], v[142:143], v[6:7] op_sel_hi:[1,0] neg_lo:[0,1] neg_hi:[0,1]
	s_nop 0
	v_pk_mul_f32 v[128:129], v[6:7], v[128:129] op_sel:[1,0]
	s_nop 0
	v_pk_fma_f32 v[22:23], v[22:23], v[128:129], v[144:145]
	v_pk_add_f32 v[128:129], v[140:141], v[6:7] op_sel_hi:[1,0] neg_lo:[0,1] neg_hi:[0,1]
	s_nop 0
	v_pk_mul_f32 v[6:7], v[6:7], v[128:129] op_sel:[1,0]
	s_nop 0
	v_pk_fma_f32 v[0:1], v[0:1], v[6:7], v[4:5]
	v_and_b32_sdwa v4, v23, v216 dst_sel:DWORD dst_unused:UNUSED_PAD src0_sel:WORD_1 src1_sel:DWORD
	v_and_b32_sdwa v5, v22, v216 dst_sel:DWORD dst_unused:UNUSED_PAD src0_sel:WORD_1 src1_sel:DWORD
	v_add3_u32 v6, v23, v4, s78
	v_add3_u32 v4, v22, v5, s78
	v_and_b32_e32 v7, 0xffff0000, v4
	v_and_b32_sdwa v4, v1, v216 dst_sel:DWORD dst_unused:UNUSED_PAD src0_sel:WORD_1 src1_sel:DWORD
	v_and_b32_sdwa v5, v0, v216 dst_sel:DWORD dst_unused:UNUSED_PAD src0_sel:WORD_1 src1_sel:DWORD
	v_add3_u32 v4, v1, v4, s78
	v_add3_u32 v128, v0, v5, s78
	v_and_b32_e32 v129, 0xffff0000, v4
	v_or_b32_sdwa v5, v129, v6 dst_sel:DWORD dst_unused:UNUSED_PAD src0_sel:DWORD src1_sel:WORD_1
	v_or_b32_sdwa v4, v128, v7 dst_sel:DWORD dst_unused:UNUSED_PAD src0_sel:WORD_1 src1_sel:DWORD
	ds_write_b64 v134, v[4:5]
	v_and_b32_e32 v4, 0xffff0000, v128
	v_sub_u32_e32 v0, v0, v4
	v_sub_u32_e32 v4, v22, v7
	v_and_b32_e32 v5, 0xffff0000, v6
	v_add_u32_e32 v4, 0x80, v4
	v_sub_u32_e32 v5, v23, v5
	v_sub_u32_e32 v1, v1, v129
	v_add_u32_e32 v0, 0x80, v0
	v_ashrrev_i32_e32 v4, 8, v4
	v_add_u32_e32 v5, 0x80, v5
	v_add_u32_e32 v1, 0x80, v1
	v_ashrrev_i32_e32 v0, 8, v0
	v_min_i32_e32 v4, 0x7f, v4
	v_ashrrev_i32_e32 v5, 8, v5
	v_ashrrev_i32_e32 v1, 8, v1
	v_min_i32_e32 v0, 0x7f, v0
	v_min_i32_sdwa v5, v5, s79 dst_sel:WORD_1 dst_unused:UNUSED_PAD src0_sel:DWORD src1_sel:DWORD
	v_min_i32_e32 v1, 0x7f, v1
	v_lshlrev_b32_e32 v4, 8, v4
	v_and_b32_e32 v4, 0xff00, v4
	v_and_b32_e32 v5, 0xff0000, v5
	v_perm_b32 v0, v1, v0, s80
	v_lshrrev_b32_e32 v1, 2, v3
	v_or3_b32 v0, v0, v4, v5
	v_mad_u64_u32 v[22:23], s[22:23], v1, s61, v[2:3]
	ds_write_b32 v22, v0
	v_mov_b32_e32 v0, v224
	v_mov_b32_e32 v1, v225
	v_mov_b32_e32 v2, v226
	v_mov_b32_e32 v3, v227
	v_mov_b32_e32 v4, v240
	v_mov_b32_e32 v5, v241
	v_mov_b32_e32 v6, v242
	v_mov_b32_e32 v7, v243
	v_mov_b32_e32 v138, v202
	v_mov_b32_e32 v139, v203
	s_mov_b32 s22, s18
	s_mov_b32 s23, s19
	v_pk_add_f32 v[124:125], v[124:125], v[138:139] op_sel_hi:[1,0] neg_lo:[0,1] neg_hi:[0,1]
	s_nop 0
	v_pk_mul_f32 v[124:125], v[138:139], v[124:125] op_sel:[1,0]
	v_pk_add_f32 v[126:127], v[126:127], v[138:139] op_sel_hi:[1,0] neg_lo:[0,1] neg_hi:[0,1]
	v_mov_b32_e32 v128, v1
	v_mov_b32_e32 v129, v2
	v_mov_b32_e32 v130, v5
	v_mov_b32_e32 v131, v6
	v_pk_fma_f32 v[124:125], v[128:129], v[124:125], v[130:131]
	v_pk_mul_f32 v[126:127], v[138:139], v[126:127] op_sel:[1,0]
	v_mov_b32_e32 v1, v3
	v_mov_b32_e32 v5, v7
	v_and_b32_sdwa v23, v124, v216 dst_sel:DWORD dst_unused:UNUSED_PAD src0_sel:WORD_1 src1_sel:DWORD
	v_pk_fma_f32 v[6:7], v[0:1], v[126:127], v[4:5]
	v_add3_u32 v23, v124, v23, s78
	v_and_b32_e32 v137, 0xffff0000, v23
	v_and_b32_sdwa v23, v7, v216 dst_sel:DWORD dst_unused:UNUSED_PAD src0_sel:WORD_1 src1_sel:DWORD
	v_and_b32_sdwa v3, v125, v216 dst_sel:DWORD dst_unused:UNUSED_PAD src0_sel:WORD_1 src1_sel:DWORD
	v_and_b32_sdwa v126, v6, v216 dst_sel:DWORD dst_unused:UNUSED_PAD src0_sel:WORD_1 src1_sel:DWORD
	v_add3_u32 v23, v7, v23, s78
	v_or_b32_e32 v2, 32, v155
	v_add3_u32 v3, v125, v3, s78
	v_add3_u32 v138, v6, v126, s78
	v_and_b32_e32 v139, 0xffff0000, v23
	v_or_b32_sdwa v127, v139, v3 dst_sel:DWORD dst_unused:UNUSED_PAD src0_sel:DWORD src1_sel:WORD_1
	v_or_b32_sdwa v126, v138, v137 dst_sel:DWORD dst_unused:UNUSED_PAD src0_sel:WORD_1 src1_sel:DWORD
	v_add_u32_e32 v23, v2, v153
	ds_write_b64 v23, v[126:127]
	v_and_b32_e32 v126, 0xffff0000, v138
	v_sub_u32_e32 v124, v124, v137
	v_and_b32_e32 v3, 0xffff0000, v3
	v_sub_u32_e32 v6, v6, v126
	v_add_u32_e32 v124, 0x80, v124
	v_sub_u32_e32 v3, v125, v3
	v_sub_u32_e32 v7, v7, v139
	v_add_u32_e32 v6, 0x80, v6
	v_ashrrev_i32_e32 v124, 8, v124
	v_add_u32_e32 v3, 0x80, v3
	v_add_u32_e32 v7, 0x80, v7
	v_ashrrev_i32_e32 v6, 8, v6
	v_min_i32_e32 v124, 0x7f, v124
	v_ashrrev_i32_e32 v3, 8, v3
	v_ashrrev_i32_e32 v7, 8, v7
	v_min_i32_e32 v6, 0x7f, v6
	v_min_i32_sdwa v3, v3, s79 dst_sel:WORD_1 dst_unused:UNUSED_PAD src0_sel:DWORD src1_sel:DWORD
	v_min_i32_e32 v7, 0x7f, v7
	v_lshlrev_b32_e32 v124, 8, v124
	v_and_b32_e32 v124, 0xff00, v124
	v_and_b32_e32 v3, 0xff0000, v3
	v_perm_b32 v6, v7, v6, s80
	v_or3_b32 v3, v6, v124, v3
	ds_write_b32 v12, v3 offset:16
	v_mov_b32_e32 v6, v204
	v_mov_b32_e32 v7, v205
	v_pk_add_f32 v[106:107], v[106:107], v[6:7] op_sel_hi:[1,0] neg_lo:[0,1] neg_hi:[0,1]
	s_nop 0
	v_pk_mul_f32 v[106:107], v[6:7], v[106:107] op_sel:[1,0]
	v_pk_add_f32 v[104:105], v[104:105], v[6:7] op_sel_hi:[1,0] neg_lo:[0,1] neg_hi:[0,1]
	v_pk_fma_f32 v[106:107], v[128:129], v[106:107], v[130:131]
	v_pk_mul_f32 v[6:7], v[6:7], v[104:105] op_sel:[1,0]
	v_and_b32_sdwa v104, v106, v216 dst_sel:DWORD dst_unused:UNUSED_PAD src0_sel:WORD_1 src1_sel:DWORD
	v_pk_fma_f32 v[6:7], v[0:1], v[6:7], v[4:5]
	v_add3_u32 v104, v106, v104, s78
	v_and_b32_e32 v105, 0xffff0000, v104
	v_and_b32_sdwa v104, v7, v216 dst_sel:DWORD dst_unused:UNUSED_PAD src0_sel:WORD_1 src1_sel:DWORD
	v_and_b32_sdwa v3, v107, v216 dst_sel:DWORD dst_unused:UNUSED_PAD src0_sel:WORD_1 src1_sel:DWORD
	v_and_b32_sdwa v124, v6, v216 dst_sel:DWORD dst_unused:UNUSED_PAD src0_sel:WORD_1 src1_sel:DWORD
	v_add3_u32 v104, v7, v104, s78
	v_add3_u32 v3, v107, v3, s78
	v_add3_u32 v126, v6, v124, s78
	v_and_b32_e32 v127, 0xffff0000, v104
;     ...
;           _Pragma("unroll") for (int bj = 0; bj < 2; ++bj) _Pragma("unroll") for (int n = 0; n < 2; ++n) {
;             const int cc = bj * HALF + wc3 * 32 + n * 16 + fq3 * 4;
;             const float4 gm = *reinterpret_cast<const float4*>(g.gam + pn * BM + cc), bt = *reinterpret_cast<const float4*>(g.bet + pn * BM + cc);
;             _Pragma("unroll") for (int m = 0; m < 4; ++m) {
;               const int rr = wr3 * 64 + m * 16 + fr3;
;               const float2 ms = *reinterpret_cast<const float2*>(mr + (ai * HALF + rr) * 2);
;               f32x4 y = acc[ai][bj][m][n];
;               const float o0 = (y[0] - ms.x) * ms.y * gm.x + bt.x, o1 = (y[1] - ms.x) * ms.y * gm.y + bt.y;
;               const float o2 = (y[2] - ms.x) * ms.y * gm.z + bt.z, o3 = (y[3] - ms.x) * ms.y * gm.w + bt.w;
;               const unsigned h0 = f2bf(o0), h1 = f2bf(o1), h2 = f2bf(o2), h3 = f2bf(o3);
;               u32x2 ob; ob[0] = h0 | (h1 << 16); ob[1] = h2 | (h3 << 16);
;               *reinterpret_cast<u32x2*>(smem + (rr >> 1) * PIECE + (rr & 1) * 512 + cc * 2) = ob;
;               const int l0 = min(((int)__float_as_uint(o0) - (int)(h0 << 16) + 128) >> 8, 127);
;               const int l1 = min(((int)__float_as_uint(o1) - (int)(h1 << 16) + 128) >> 8, 127);
;               const int l2 = min(((int)__float_as_uint(o2) - (int)(h2 << 16) + 128) >> 8, 127);
;               const int l3 = min(((int)__float_as_uint(o3) - (int)(h3 << 16) + 128) >> 8, 127);
;               *reinterpret_cast<unsigned*>(smem + LOBASE + (rr >> 2) * PIECE + (rr & 3) * 256 + cc) =
;                   (unsigned)(l0 & 255) | ((unsigned)(l1 & 255) << 8) | ((unsigned)(l2 & 255) << 16) | ((unsigned)l3 << 24);
;             }
	v_or_b32_sdwa v125, v127, v3 dst_sel:DWORD dst_unused:UNUSED_PAD src0_sel:DWORD src1_sel:WORD_1
	v_or_b32_sdwa v124, v126, v105 dst_sel:DWORD dst_unused:UNUSED_PAD src0_sel:WORD_1 src1_sel:DWORD
	v_add_u32_e32 v104, v2, v154
	ds_write_b64 v104, v[124:125]
	v_and_b32_e32 v124, 0xffff0000, v126
	v_sub_u32_e32 v105, v106, v105
	v_and_b32_e32 v3, 0xffff0000, v3
	v_sub_u32_e32 v6, v6, v124
	v_add_u32_e32 v105, 0x80, v105
	v_sub_u32_e32 v3, v107, v3
	v_sub_u32_e32 v7, v7, v127
	v_add_u32_e32 v6, 0x80, v6
	v_ashrrev_i32_e32 v105, 8, v105
	v_add_u32_e32 v3, 0x80, v3
	v_add_u32_e32 v7, 0x80, v7
	v_ashrrev_i32_e32 v6, 8, v6
	v_min_i32_e32 v105, 0x7f, v105
	v_ashrrev_i32_e32 v3, 8, v3
	v_ashrrev_i32_e32 v7, 8, v7
	v_min_i32_e32 v6, 0x7f, v6
	v_min_i32_sdwa v3, v3, s79 dst_sel:WORD_1 dst_unused:UNUSED_PAD src0_sel:DWORD src1_sel:DWORD
	v_min_i32_e32 v7, 0x7f, v7
	v_lshlrev_b32_e32 v105, 8, v105
	v_and_b32_e32 v105, 0xff00, v105
	v_and_b32_e32 v3, 0xff0000, v3
	v_perm_b32 v6, v7, v6, s80
	v_or3_b32 v3, v6, v105, v3
	ds_write_b32 v14, v3 offset:16
	v_mov_b32_e32 v6, v206
	v_mov_b32_e32 v7, v207
	v_pk_add_f32 v[106:107], v[110:111], v[6:7] op_sel_hi:[1,0] neg_lo:[0,1] neg_hi:[0,1]
	s_nop 0
	v_pk_mul_f32 v[106:107], v[6:7], v[106:107] op_sel:[1,0]
	v_pk_add_f32 v[108:109], v[108:109], v[6:7] op_sel_hi:[1,0] neg_lo:[0,1] neg_hi:[0,1]
	v_pk_fma_f32 v[106:107], v[128:129], v[106:107], v[130:131]
	v_pk_mul_f32 v[6:7], v[6:7], v[108:109] op_sel:[1,0]
	v_and_b32_sdwa v105, v106, v216 dst_sel:DWORD dst_unused:UNUSED_PAD src0_sel:WORD_1 src1_sel:DWORD
	v_pk_fma_f32 v[6:7], v[0:1], v[6:7], v[4:5]
	v_add3_u32 v105, v106, v105, s78
	v_and_b32_e32 v110, 0xffff0000, v105
	v_and_b32_sdwa v105, v7, v216 dst_sel:DWORD dst_unused:UNUSED_PAD src0_sel:WORD_1 src1_sel:DWORD
	v_and_b32_sdwa v3, v107, v216 dst_sel:DWORD dst_unused:UNUSED_PAD src0_sel:WORD_1 src1_sel:DWORD
	v_and_b32_sdwa v108, v6, v216 dst_sel:DWORD dst_unused:UNUSED_PAD src0_sel:WORD_1 src1_sel:DWORD
	v_add3_u32 v105, v7, v105, s78
	v_add3_u32 v3, v107, v3, s78
	v_add3_u32 v111, v6, v108, s78
	v_and_b32_e32 v124, 0xffff0000, v105
	v_or_b32_sdwa v109, v124, v3 dst_sel:DWORD dst_unused:UNUSED_PAD src0_sel:DWORD src1_sel:WORD_1
	v_or_b32_sdwa v108, v111, v110 dst_sel:DWORD dst_unused:UNUSED_PAD src0_sel:WORD_1 src1_sel:DWORD
	v_add_u32_e32 v105, v2, v136
	ds_write_b64 v105, v[108:109]
	v_and_b32_e32 v108, 0xffff0000, v111
	v_sub_u32_e32 v106, v106, v110
	v_and_b32_e32 v3, 0xffff0000, v3
	v_sub_u32_e32 v6, v6, v108
	v_add_u32_e32 v106, 0x80, v106
	v_sub_u32_e32 v3, v107, v3
	v_sub_u32_e32 v7, v7, v124
	v_add_u32_e32 v6, 0x80, v6
	v_ashrrev_i32_e32 v106, 8, v106
	v_add_u32_e32 v3, 0x80, v3
	v_add_u32_e32 v7, 0x80, v7
	v_ashrrev_i32_e32 v6, 8, v6
	v_min_i32_e32 v106, 0x7f, v106
	v_ashrrev_i32_e32 v3, 8, v3
	v_ashrrev_i32_e32 v7, 8, v7
	v_min_i32_e32 v6, 0x7f, v6
	v_min_i32_sdwa v3, v3, s79 dst_sel:WORD_1 dst_unused:UNUSED_PAD src0_sel:DWORD src1_sel:DWORD
	v_min_i32_e32 v7, 0x7f, v7
	v_lshlrev_b32_e32 v106, 8, v106
	v_and_b32_e32 v106, 0xff00, v106
	v_and_b32_e32 v3, 0xff0000, v3
	v_perm_b32 v6, v7, v6, s80
	v_or3_b32 v3, v6, v106, v3
	ds_write_b32 v20, v3 offset:16
	v_mov_b32_e32 v6, v208
	v_mov_b32_e32 v7, v209
	v_pk_add_f32 v[106:107], v[122:123], v[6:7] op_sel_hi:[1,0] neg_lo:[0,1] neg_hi:[0,1]
	s_nop 0
	v_pk_mul_f32 v[106:107], v[6:7], v[106:107] op_sel:[1,0]
	v_or_b32_e32 v122, 0x100, v155
	v_pk_fma_f32 v[108:109], v[128:129], v[106:107], v[130:131]
	v_pk_add_f32 v[106:107], v[114:115], v[6:7] op_sel_hi:[1,0] neg_lo:[0,1] neg_hi:[0,1]
	v_and_b32_sdwa v3, v109, v216 dst_sel:DWORD dst_unused:UNUSED_PAD src0_sel:WORD_1 src1_sel:DWORD
	v_pk_mul_f32 v[6:7], v[6:7], v[106:107] op_sel:[1,0]
	v_add3_u32 v3, v109, v3, s78
	v_pk_fma_f32 v[0:1], v[0:1], v[6:7], v[4:5]
	v_and_b32_sdwa v4, v108, v216 dst_sel:DWORD dst_unused:UNUSED_PAD src0_sel:WORD_1 src1_sel:DWORD
	v_add3_u32 v4, v108, v4, s78
	v_and_b32_e32 v6, 0xffff0000, v4
	v_and_b32_sdwa v4, v1, v216 dst_sel:DWORD dst_unused:UNUSED_PAD src0_sel:WORD_1 src1_sel:DWORD
	v_and_b32_sdwa v5, v0, v216 dst_sel:DWORD dst_unused:UNUSED_PAD src0_sel:WORD_1 src1_sel:DWORD
	v_add3_u32 v4, v1, v4, s78
	v_add3_u32 v7, v0, v5, s78
	v_and_b32_e32 v107, 0xffff0000, v4
	v_add_u32_e32 v106, v2, v135
	v_and_b32_e32 v2, 0xffff0000, v7
	v_or_b32_sdwa v5, v107, v3 dst_sel:DWORD dst_unused:UNUSED_PAD src0_sel:DWORD src1_sel:WORD_1
	v_sub_u32_e32 v0, v0, v2
	v_sub_u32_e32 v2, v108, v6
	v_and_b32_e32 v3, 0xffff0000, v3
	v_add_u32_e32 v2, 0x80, v2
	v_sub_u32_e32 v3, v109, v3
	v_sub_u32_e32 v1, v1, v107
	v_add_u32_e32 v0, 0x80, v0
	v_ashrrev_i32_e32 v2, 8, v2
	v_add_u32_e32 v3, 0x80, v3
	v_add_u32_e32 v1, 0x80, v1
	v_ashrrev_i32_e32 v0, 8, v0
	v_min_i32_e32 v2, 0x7f, v2
	v_ashrrev_i32_e32 v3, 8, v3
	v_ashrrev_i32_e32 v1, 8, v1
	v_min_i32_e32 v0, 0x7f, v0
	v_min_i32_sdwa v3, v3, s79 dst_sel:WORD_1 dst_unused:UNUSED_PAD src0_sel:DWORD src1_sel:DWORD
	v_min_i32_e32 v1, 0x7f, v1
	v_lshlrev_b32_e32 v2, 8, v2
	v_and_b32_e32 v2, 0xff00, v2
	v_and_b32_e32 v3, 0xff0000, v3
	v_perm_b32 v0, v1, v0, s80
	v_or_b32_sdwa v4, v7, v6 dst_sel:DWORD dst_unused:UNUSED_PAD src0_sel:WORD_1 src1_sel:DWORD
	v_or3_b32 v0, v0, v2, v3
	ds_write_b64 v106, v[4:5]
	ds_write_b32 v22, v0 offset:16
	v_mov_b32_e32 v0, v228
	v_mov_b32_e32 v1, v229
	v_mov_b32_e32 v2, v230
	v_mov_b32_e32 v3, v231
	v_mov_b32_e32 v4, v244
	v_mov_b32_e32 v5, v245
	v_mov_b32_e32 v6, v246
	v_mov_b32_e32 v7, v247
	v_mov_b32_e32 v114, v202
	v_mov_b32_e32 v115, v203
	v_add_u32_e32 v107, v122, v153
	v_pk_add_f32 v[118:119], v[118:119], v[114:115] op_sel_hi:[1,0] neg_lo:[0,1] neg_hi:[0,1]
	s_nop 0
	v_pk_mul_f32 v[118:119], v[114:115], v[118:119] op_sel:[1,0]
;     ...
;           _Pragma("unroll") for (int bj = 0; bj < 2; ++bj) _Pragma("unroll") for (int n = 0; n < 2; ++n) {
;             const int cc = bj * HALF + wc3 * 32 + n * 16 + fq3 * 4;
;             const float4 gm = *reinterpret_cast<const float4*>(g.gam + pn * BM + cc), bt = *reinterpret_cast<const float4*>(g.bet + pn * BM + cc);
;             _Pragma("unroll") for (int m = 0; m < 4; ++m) {
;               const int rr = wr3 * 64 + m * 16 + fr3;
;               const float2 ms = *reinterpret_cast<const float2*>(mr + (ai * HALF + rr) * 2);
;               f32x4 y = acc[ai][bj][m][n];
;               const float o0 = (y[0] - ms.x) * ms.y * gm.x + bt.x, o1 = (y[1] - ms.x) * ms.y * gm.y + bt.y;
;               const float o2 = (y[2] - ms.x) * ms.y * gm.z + bt.z, o3 = (y[3] - ms.x) * ms.y * gm.w + bt.w;
;               const unsigned h0 = f2bf(o0), h1 = f2bf(o1), h2 = f2bf(o2), h3 = f2bf(o3);
;               u32x2 ob; ob[0] = h0 | (h1 << 16); ob[1] = h2 | (h3 << 16);
;               *reinterpret_cast<u32x2*>(smem + (rr >> 1) * PIECE + (rr & 1) * 512 + cc * 2) = ob;
;               const int l0 = min(((int)__float_as_uint(o0) - (int)(h0 << 16) + 128) >> 8, 127);
;               const int l1 = min(((int)__float_as_uint(o1) - (int)(h1 << 16) + 128) >> 8, 127);
;               const int l2 = min(((int)__float_as_uint(o2) - (int)(h2 << 16) + 128) >> 8, 127);
;               const int l3 = min(((int)__float_as_uint(o3) - (int)(h3 << 16) + 128) >> 8, 127);
;               *reinterpret_cast<unsigned*>(smem + LOBASE + (rr >> 2) * PIECE + (rr & 3) * 256 + cc) =
;                   (unsigned)(l0 & 255) | ((unsigned)(l1 & 255) << 8) | ((unsigned)(l2 & 255) << 16) | ((unsigned)l3 << 24);
;             }
	v_pk_add_f32 v[120:121], v[120:121], v[114:115] op_sel_hi:[1,0] neg_lo:[0,1] neg_hi:[0,1]
	v_mov_b32_e32 v108, v1
	v_mov_b32_e32 v109, v2
	v_mov_b32_e32 v110, v5
	v_mov_b32_e32 v111, v6
	v_pk_fma_f32 v[118:119], v[108:109], v[118:119], v[110:111]
	v_pk_mul_f32 v[114:115], v[114:115], v[120:121] op_sel:[1,0]
	v_mov_b32_e32 v1, v3
	v_mov_b32_e32 v5, v7
	v_and_b32_sdwa v6, v119, v216 dst_sel:DWORD dst_unused:UNUSED_PAD src0_sel:WORD_1 src1_sel:DWORD
	v_and_b32_sdwa v7, v118, v216 dst_sel:DWORD dst_unused:UNUSED_PAD src0_sel:WORD_1 src1_sel:DWORD
	v_pk_fma_f32 v[2:3], v[0:1], v[114:115], v[4:5]
	v_add3_u32 v114, v119, v6, s78
	v_add3_u32 v6, v118, v7, s78
	v_and_b32_e32 v115, 0xffff0000, v6
	v_and_b32_sdwa v6, v3, v216 dst_sel:DWORD dst_unused:UNUSED_PAD src0_sel:WORD_1 src1_sel:DWORD
	v_and_b32_sdwa v7, v2, v216 dst_sel:DWORD dst_unused:UNUSED_PAD src0_sel:WORD_1 src1_sel:DWORD
	v_add3_u32 v6, v3, v6, s78
	v_add3_u32 v120, v2, v7, s78
	v_and_b32_e32 v121, 0xffff0000, v6
	v_or_b32_sdwa v7, v121, v114 dst_sel:DWORD dst_unused:UNUSED_PAD src0_sel:DWORD src1_sel:WORD_1
	v_or_b32_sdwa v6, v120, v115 dst_sel:DWORD dst_unused:UNUSED_PAD src0_sel:WORD_1 src1_sel:DWORD
	ds_write_b64 v107, v[6:7]
	v_and_b32_e32 v6, 0xffff0000, v120
	v_sub_u32_e32 v2, v2, v6
	v_sub_u32_e32 v6, v118, v115
	v_and_b32_e32 v7, 0xffff0000, v114
	v_add_u32_e32 v6, 0x80, v6
	v_sub_u32_e32 v7, v119, v7
	v_sub_u32_e32 v3, v3, v121
	v_add_u32_e32 v2, 0x80, v2
	v_ashrrev_i32_e32 v6, 8, v6
	v_add_u32_e32 v7, 0x80, v7
	v_add_u32_e32 v3, 0x80, v3
	v_ashrrev_i32_e32 v2, 8, v2
	v_min_i32_e32 v6, 0x7f, v6
	v_ashrrev_i32_e32 v7, 8, v7
	v_ashrrev_i32_e32 v3, 8, v3
	v_min_i32_e32 v2, 0x7f, v2
	v_min_i32_sdwa v7, v7, s79 dst_sel:WORD_1 dst_unused:UNUSED_PAD src0_sel:DWORD src1_sel:DWORD
	v_min_i32_e32 v3, 0x7f, v3
	v_lshlrev_b32_e32 v6, 8, v6
	v_and_b32_e32 v6, 0xff00, v6
	v_and_b32_e32 v7, 0xff0000, v7
	v_perm_b32 v2, v3, v2, s80
	v_or3_b32 v2, v2, v6, v7
	ds_write_b32 v12, v2 offset:128
	v_mov_b32_e32 v2, v204
	v_mov_b32_e32 v3, v205
	v_pk_add_f32 v[6:7], v[102:103], v[2:3] op_sel_hi:[1,0] neg_lo:[0,1] neg_hi:[0,1]
	s_nop 0
	v_pk_mul_f32 v[6:7], v[2:3], v[6:7] op_sel:[1,0]
	v_pk_add_f32 v[100:101], v[100:101], v[2:3] op_sel_hi:[1,0] neg_lo:[0,1] neg_hi:[0,1]
	v_pk_fma_f32 v[6:7], v[108:109], v[6:7], v[110:111]
	v_pk_mul_f32 v[2:3], v[2:3], v[100:101] op_sel:[1,0]
	v_and_b32_sdwa v100, v7, v216 dst_sel:DWORD dst_unused:UNUSED_PAD src0_sel:WORD_1 src1_sel:DWORD
	v_and_b32_sdwa v101, v6, v216 dst_sel:DWORD dst_unused:UNUSED_PAD src0_sel:WORD_1 src1_sel:DWORD
	v_pk_fma_f32 v[2:3], v[0:1], v[2:3], v[4:5]
	v_add3_u32 v114, v7, v100, s78
	v_add3_u32 v100, v6, v101, s78
	v_and_b32_e32 v101, 0xffff0000, v100
	v_and_b32_sdwa v100, v3, v216 dst_sel:DWORD dst_unused:UNUSED_PAD src0_sel:WORD_1 src1_sel:DWORD
	v_and_b32_sdwa v102, v2, v216 dst_sel:DWORD dst_unused:UNUSED_PAD src0_sel:WORD_1 src1_sel:DWORD
	v_add3_u32 v100, v3, v100, s78
	v_add3_u32 v115, v2, v102, s78
	v_and_b32_e32 v118, 0xffff0000, v100
	v_or_b32_sdwa v103, v118, v114 dst_sel:DWORD dst_unused:UNUSED_PAD src0_sel:DWORD src1_sel:WORD_1
	v_or_b32_sdwa v102, v115, v101 dst_sel:DWORD dst_unused:UNUSED_PAD src0_sel:WORD_1 src1_sel:DWORD
	v_add_u32_e32 v100, v122, v154
	ds_write_b64 v100, v[102:103]
	v_and_b32_e32 v102, 0xffff0000, v115
	v_sub_u32_e32 v6, v6, v101
	v_and_b32_e32 v101, 0xffff0000, v114
	v_sub_u32_e32 v2, v2, v102
	v_add_u32_e32 v6, 0x80, v6
	v_sub_u32_e32 v7, v7, v101
	v_sub_u32_e32 v3, v3, v118
	v_add_u32_e32 v2, 0x80, v2
	v_ashrrev_i32_e32 v6, 8, v6
	v_add_u32_e32 v7, 0x80, v7
	v_add_u32_e32 v3, 0x80, v3
	v_ashrrev_i32_e32 v2, 8, v2
	v_min_i32_e32 v6, 0x7f, v6
	v_ashrrev_i32_e32 v7, 8, v7
	v_ashrrev_i32_e32 v3, 8, v3
	v_min_i32_e32 v2, 0x7f, v2
	v_min_i32_sdwa v7, v7, s79 dst_sel:WORD_1 dst_unused:UNUSED_PAD src0_sel:DWORD src1_sel:DWORD
	v_min_i32_e32 v3, 0x7f, v3
	v_lshlrev_b32_e32 v6, 8, v6
	v_and_b32_e32 v6, 0xff00, v6
	v_and_b32_e32 v7, 0xff0000, v7
	v_perm_b32 v2, v3, v2, s80
	v_or3_b32 v2, v2, v6, v7
	ds_write_b32 v14, v2 offset:128
	v_mov_b32_e32 v2, v206
	v_mov_b32_e32 v3, v207
	v_add_u32_e32 v101, v122, v136
	v_pk_add_f32 v[6:7], v[90:91], v[2:3] op_sel_hi:[1,0] neg_lo:[0,1] neg_hi:[0,1]
	s_nop 0
	v_pk_mul_f32 v[6:7], v[2:3], v[6:7] op_sel:[1,0]
	v_pk_add_f32 v[88:89], v[88:89], v[2:3] op_sel_hi:[1,0] neg_lo:[0,1] neg_hi:[0,1]
	v_pk_fma_f32 v[6:7], v[108:109], v[6:7], v[110:111]
	v_pk_mul_f32 v[2:3], v[2:3], v[88:89] op_sel:[1,0]
	v_and_b32_sdwa v88, v7, v216 dst_sel:DWORD dst_unused:UNUSED_PAD src0_sel:WORD_1 src1_sel:DWORD
	v_and_b32_sdwa v89, v6, v216 dst_sel:DWORD dst_unused:UNUSED_PAD src0_sel:WORD_1 src1_sel:DWORD
	v_pk_fma_f32 v[2:3], v[0:1], v[2:3], v[4:5]
	v_add3_u32 v90, v7, v88, s78
	v_add3_u32 v88, v6, v89, s78
	v_and_b32_e32 v91, 0xffff0000, v88
	v_and_b32_sdwa v88, v3, v216 dst_sel:DWORD dst_unused:UNUSED_PAD src0_sel:WORD_1 src1_sel:DWORD
	v_and_b32_sdwa v89, v2, v216 dst_sel:DWORD dst_unused:UNUSED_PAD src0_sel:WORD_1 src1_sel:DWORD
	v_add3_u32 v88, v3, v88, s78
	v_add3_u32 v102, v2, v89, s78
	v_and_b32_e32 v103, 0xffff0000, v88
	v_or_b32_sdwa v89, v103, v90 dst_sel:DWORD dst_unused:UNUSED_PAD src0_sel:DWORD src1_sel:WORD_1
	v_or_b32_sdwa v88, v102, v91 dst_sel:DWORD dst_unused:UNUSED_PAD src0_sel:WORD_1 src1_sel:DWORD
	ds_write_b64 v101, v[88:89]
	v_and_b32_e32 v88, 0xffff0000, v102
	v_sub_u32_e32 v2, v2, v88
	v_sub_u32_e32 v6, v6, v91
	v_and_b32_e32 v88, 0xffff0000, v90
	v_add_u32_e32 v6, 0x80, v6
	v_sub_u32_e32 v7, v7, v88
	v_sub_u32_e32 v3, v3, v103
	v_add_u32_e32 v2, 0x80, v2
	v_ashrrev_i32_e32 v6, 8, v6
	v_add_u32_e32 v7, 0x80, v7
	v_add_u32_e32 v3, 0x80, v3
	v_ashrrev_i32_e32 v2, 8, v2
;     ...
;           _Pragma("unroll") for (int bj = 0; bj < 2; ++bj) _Pragma("unroll") for (int n = 0; n < 2; ++n) {
;             const int cc = bj * HALF + wc3 * 32 + n * 16 + fq3 * 4;
;             const float4 gm = *reinterpret_cast<const float4*>(g.gam + pn * BM + cc), bt = *reinterpret_cast<const float4*>(g.bet + pn * BM + cc);
;             _Pragma("unroll") for (int m = 0; m < 4; ++m) {
;               const int rr = wr3 * 64 + m * 16 + fr3;
;               const float2 ms = *reinterpret_cast<const float2*>(mr + (ai * HALF + rr) * 2);
;               f32x4 y = acc[ai][bj][m][n];
;               const float o0 = (y[0] - ms.x) * ms.y * gm.x + bt.x, o1 = (y[1] - ms.x) * ms.y * gm.y + bt.y;
;               const float o2 = (y[2] - ms.x) * ms.y * gm.z + bt.z, o3 = (y[3] - ms.x) * ms.y * gm.w + bt.w;
;               const unsigned h0 = f2bf(o0), h1 = f2bf(o1), h2 = f2bf(o2), h3 = f2bf(o3);
;               u32x2 ob; ob[0] = h0 | (h1 << 16); ob[1] = h2 | (h3 << 16);
;               *reinterpret_cast<u32x2*>(smem + (rr >> 1) * PIECE + (rr & 1) * 512 + cc * 2) = ob;
;               const int l0 = min(((int)__float_as_uint(o0) - (int)(h0 << 16) + 128) >> 8, 127);
;               const int l1 = min(((int)__float_as_uint(o1) - (int)(h1 << 16) + 128) >> 8, 127);
;               const int l2 = min(((int)__float_as_uint(o2) - (int)(h2 << 16) + 128) >> 8, 127);
;               const int l3 = min(((int)__float_as_uint(o3) - (int)(h3 << 16) + 128) >> 8, 127);
;               *reinterpret_cast<unsigned*>(smem + LOBASE + (rr >> 2) * PIECE + (rr & 3) * 256 + cc) =
;                   (unsigned)(l0 & 255) | ((unsigned)(l1 & 255) << 8) | ((unsigned)(l2 & 255) << 16) | ((unsigned)l3 << 24);
;             }
	v_min_i32_e32 v6, 0x7f, v6
	v_ashrrev_i32_e32 v7, 8, v7
	v_ashrrev_i32_e32 v3, 8, v3
	v_min_i32_e32 v2, 0x7f, v2
	v_min_i32_sdwa v7, v7, s79 dst_sel:WORD_1 dst_unused:UNUSED_PAD src0_sel:DWORD src1_sel:DWORD
	v_min_i32_e32 v3, 0x7f, v3
	v_lshlrev_b32_e32 v6, 8, v6
	v_and_b32_e32 v6, 0xff00, v6
	v_and_b32_e32 v7, 0xff0000, v7
	v_perm_b32 v2, v3, v2, s80
	v_or3_b32 v2, v2, v6, v7
	ds_write_b32 v20, v2 offset:128
	v_mov_b32_e32 v2, v208
	v_mov_b32_e32 v3, v209
	v_pk_add_f32 v[6:7], v[94:95], v[2:3] op_sel_hi:[1,0] neg_lo:[0,1] neg_hi:[0,1]
	s_nop 0
	v_pk_mul_f32 v[6:7], v[2:3], v[6:7] op_sel:[1,0]
	v_pk_add_f32 v[88:89], v[92:93], v[2:3] op_sel_hi:[1,0] neg_lo:[0,1] neg_hi:[0,1]
	v_pk_fma_f32 v[6:7], v[108:109], v[6:7], v[110:111]
	v_pk_mul_f32 v[2:3], v[2:3], v[88:89] op_sel:[1,0]
	v_add_u32_e32 v92, v122, v135
	v_pk_fma_f32 v[0:1], v[0:1], v[2:3], v[4:5]
	v_and_b32_sdwa v2, v7, v216 dst_sel:DWORD dst_unused:UNUSED_PAD src0_sel:WORD_1 src1_sel:DWORD
	v_and_b32_sdwa v3, v6, v216 dst_sel:DWORD dst_unused:UNUSED_PAD src0_sel:WORD_1 src1_sel:DWORD
	v_add3_u32 v4, v7, v2, s78
	v_add3_u32 v2, v6, v3, s78
	v_and_b32_e32 v5, 0xffff0000, v2
	v_and_b32_sdwa v2, v1, v216 dst_sel:DWORD dst_unused:UNUSED_PAD src0_sel:WORD_1 src1_sel:DWORD
	v_and_b32_sdwa v3, v0, v216 dst_sel:DWORD dst_unused:UNUSED_PAD src0_sel:WORD_1 src1_sel:DWORD
	v_add3_u32 v2, v1, v2, s78
	v_add3_u32 v88, v0, v3, s78
	v_and_b32_e32 v89, 0xffff0000, v2
	v_or_b32_sdwa v3, v89, v4 dst_sel:DWORD dst_unused:UNUSED_PAD src0_sel:DWORD src1_sel:WORD_1
	v_or_b32_sdwa v2, v88, v5 dst_sel:DWORD dst_unused:UNUSED_PAD src0_sel:WORD_1 src1_sel:DWORD
	ds_write_b64 v92, v[2:3]
	v_and_b32_e32 v2, 0xffff0000, v88
	v_sub_u32_e32 v0, v0, v2
	v_sub_u32_e32 v2, v6, v5
	v_and_b32_e32 v3, 0xffff0000, v4
	v_add_u32_e32 v2, 0x80, v2
	v_sub_u32_e32 v3, v7, v3
	v_sub_u32_e32 v1, v1, v89
	v_add_u32_e32 v0, 0x80, v0
	v_ashrrev_i32_e32 v2, 8, v2
	v_add_u32_e32 v3, 0x80, v3
	v_add_u32_e32 v1, 0x80, v1
	v_ashrrev_i32_e32 v0, 8, v0
	v_min_i32_e32 v2, 0x7f, v2
	v_ashrrev_i32_e32 v3, 8, v3
	v_ashrrev_i32_e32 v1, 8, v1
	v_min_i32_e32 v0, 0x7f, v0
	v_min_i32_sdwa v3, v3, s79 dst_sel:WORD_1 dst_unused:UNUSED_PAD src0_sel:DWORD src1_sel:DWORD
	v_min_i32_e32 v1, 0x7f, v1
	v_lshlrev_b32_e32 v2, 8, v2
	v_and_b32_e32 v2, 0xff00, v2
	v_and_b32_e32 v3, 0xff0000, v3
	v_perm_b32 v0, v1, v0, s80
	v_or3_b32 v0, v0, v2, v3
	ds_write_b32 v22, v0 offset:128
	v_mov_b32_e32 v0, v232
	v_mov_b32_e32 v1, v233
	v_mov_b32_e32 v2, v234
	v_mov_b32_e32 v3, v235
	v_mov_b32_e32 v4, v248
	v_mov_b32_e32 v5, v249
	v_mov_b32_e32 v6, v250
	v_mov_b32_e32 v7, v251
	v_mov_b32_e32 v94, v202
	v_mov_b32_e32 v95, v203
	v_pk_add_f32 v[102:103], v[116:117], v[94:95] op_sel_hi:[1,0] neg_lo:[0,1] neg_hi:[0,1]
	s_nop 0
	v_pk_mul_f32 v[102:103], v[94:95], v[102:103] op_sel:[1,0]
	v_pk_add_f32 v[108:109], v[112:113], v[94:95] op_sel_hi:[1,0] neg_lo:[0,1] neg_hi:[0,1]
	v_mov_b32_e32 v88, v1
	v_mov_b32_e32 v89, v2
	v_mov_b32_e32 v90, v5
	v_mov_b32_e32 v91, v6
	v_pk_fma_f32 v[102:103], v[88:89], v[102:103], v[90:91]
	v_pk_mul_f32 v[94:95], v[94:95], v[108:109] op_sel:[1,0]
	v_mov_b32_e32 v1, v3
	v_mov_b32_e32 v5, v7
	v_and_b32_sdwa v93, v102, v216 dst_sel:DWORD dst_unused:UNUSED_PAD src0_sel:WORD_1 src1_sel:DWORD
	v_pk_fma_f32 v[6:7], v[0:1], v[94:95], v[4:5]
	v_add3_u32 v93, v102, v93, s78
	v_and_b32_e32 v108, 0xffff0000, v93
	v_and_b32_sdwa v93, v7, v216 dst_sel:DWORD dst_unused:UNUSED_PAD src0_sel:WORD_1 src1_sel:DWORD
	v_and_b32_sdwa v3, v103, v216 dst_sel:DWORD dst_unused:UNUSED_PAD src0_sel:WORD_1 src1_sel:DWORD
	v_and_b32_sdwa v94, v6, v216 dst_sel:DWORD dst_unused:UNUSED_PAD src0_sel:WORD_1 src1_sel:DWORD
	v_add3_u32 v93, v7, v93, s78
	v_or_b32_e32 v2, 0x120, v155
	v_add3_u32 v3, v103, v3, s78
	v_add3_u32 v109, v6, v94, s78
	v_and_b32_e32 v110, 0xffff0000, v93
	v_or_b32_sdwa v95, v110, v3 dst_sel:DWORD dst_unused:UNUSED_PAD src0_sel:DWORD src1_sel:WORD_1
	v_or_b32_sdwa v94, v109, v108 dst_sel:DWORD dst_unused:UNUSED_PAD src0_sel:WORD_1 src1_sel:DWORD
	v_add_u32_e32 v93, v2, v153
	ds_write_b64 v93, v[94:95]
	v_and_b32_e32 v94, 0xffff0000, v109
	v_sub_u32_e32 v6, v6, v94
	v_sub_u32_e32 v94, v102, v108
	v_and_b32_e32 v3, 0xffff0000, v3
	v_add_u32_e32 v94, 0x80, v94
	v_sub_u32_e32 v3, v103, v3
	v_sub_u32_e32 v7, v7, v110
	v_add_u32_e32 v6, 0x80, v6
	v_ashrrev_i32_e32 v94, 8, v94
	v_add_u32_e32 v3, 0x80, v3
	v_add_u32_e32 v7, 0x80, v7
	v_ashrrev_i32_e32 v6, 8, v6
	v_min_i32_e32 v94, 0x7f, v94
	v_ashrrev_i32_e32 v3, 8, v3
	v_ashrrev_i32_e32 v7, 8, v7
	v_min_i32_e32 v6, 0x7f, v6
	v_min_i32_sdwa v3, v3, s79 dst_sel:WORD_1 dst_unused:UNUSED_PAD src0_sel:DWORD src1_sel:DWORD
	v_min_i32_e32 v7, 0x7f, v7
	v_lshlrev_b32_e32 v94, 8, v94
	v_and_b32_e32 v94, 0xff00, v94
	v_and_b32_e32 v3, 0xff0000, v3
	v_perm_b32 v6, v7, v6, s80
	v_or3_b32 v3, v6, v94, v3
	ds_write_b32 v12, v3 offset:144
	v_mov_b32_e32 v6, v204
	v_mov_b32_e32 v7, v205
	v_pk_add_f32 v[94:95], v[98:99], v[6:7] op_sel_hi:[1,0] neg_lo:[0,1] neg_hi:[0,1]
	s_nop 0
	v_pk_mul_f32 v[94:95], v[6:7], v[94:95] op_sel:[1,0]
	s_nop 0
	v_pk_fma_f32 v[98:99], v[88:89], v[94:95], v[90:91]
	v_pk_add_f32 v[94:95], v[96:97], v[6:7] op_sel_hi:[1,0] neg_lo:[0,1] neg_hi:[0,1]
	v_and_b32_sdwa v3, v99, v216 dst_sel:DWORD dst_unused:UNUSED_PAD src0_sel:WORD_1 src1_sel:DWORD
	v_pk_mul_f32 v[6:7], v[6:7], v[94:95] op_sel:[1,0]
	v_and_b32_sdwa v94, v98, v216 dst_sel:DWORD dst_unused:UNUSED_PAD src0_sel:WORD_1 src1_sel:DWORD
	v_pk_fma_f32 v[6:7], v[0:1], v[6:7], v[4:5]
	v_add3_u32 v94, v98, v94, s78
	v_and_b32_e32 v95, 0xffff0000, v94
	v_and_b32_sdwa v94, v7, v216 dst_sel:DWORD dst_unused:UNUSED_PAD src0_sel:WORD_1 src1_sel:DWORD
; #define WAIT_L(n) asm volatile("s_waitcnt lgkmcnt(" #n ")" ::: "memory")
; #define BAR __builtin_amdgcn_s_barrier()
;     ...
;           _Pragma("unroll") for (int bj = 0; bj < 2; ++bj) _Pragma("unroll") for (int n = 0; n < 2; ++n) {
;             const int cc = bj * HALF + wc3 * 32 + n * 16 + fq3 * 4;
;             const float4 gm = *reinterpret_cast<const float4*>(g.gam + pn * BM + cc), bt = *reinterpret_cast<const float4*>(g.bet + pn * BM + cc);
;             _Pragma("unroll") for (int m = 0; m < 4; ++m) {
;               const int rr = wr3 * 64 + m * 16 + fr3;
;               const float2 ms = *reinterpret_cast<const float2*>(mr + (ai * HALF + rr) * 2);
;               f32x4 y = acc[ai][bj][m][n];
;               const float o0 = (y[0] - ms.x) * ms.y * gm.x + bt.x, o1 = (y[1] - ms.x) * ms.y * gm.y + bt.y;
;               const float o2 = (y[2] - ms.x) * ms.y * gm.z + bt.z, o3 = (y[3] - ms.x) * ms.y * gm.w + bt.w;
;               const unsigned h0 = f2bf(o0), h1 = f2bf(o1), h2 = f2bf(o2), h3 = f2bf(o3);
;               u32x2 ob; ob[0] = h0 | (h1 << 16); ob[1] = h2 | (h3 << 16);
;               *reinterpret_cast<u32x2*>(smem + (rr >> 1) * PIECE + (rr & 1) * 512 + cc * 2) = ob;
;               const int l0 = min(((int)__float_as_uint(o0) - (int)(h0 << 16) + 128) >> 8, 127);
;               const int l1 = min(((int)__float_as_uint(o1) - (int)(h1 << 16) + 128) >> 8, 127);
;               const int l2 = min(((int)__float_as_uint(o2) - (int)(h2 << 16) + 128) >> 8, 127);
;               const int l3 = min(((int)__float_as_uint(o3) - (int)(h3 << 16) + 128) >> 8, 127);
;               *reinterpret_cast<unsigned*>(smem + LOBASE + (rr >> 2) * PIECE + (rr & 3) * 256 + cc) =
;                   (unsigned)(l0 & 255) | ((unsigned)(l1 & 255) << 8) | ((unsigned)(l2 & 255) << 16) | ((unsigned)l3 << 24);
;             }
;           }
;           WAIT_L(0); BAR;
	v_and_b32_sdwa v96, v6, v216 dst_sel:DWORD dst_unused:UNUSED_PAD src0_sel:WORD_1 src1_sel:DWORD
	v_add3_u32 v94, v7, v94, s78
	v_add3_u32 v3, v99, v3, s78
	v_add3_u32 v102, v6, v96, s78
	v_and_b32_e32 v103, 0xffff0000, v94
	v_or_b32_sdwa v97, v103, v3 dst_sel:DWORD dst_unused:UNUSED_PAD src0_sel:DWORD src1_sel:WORD_1
	v_or_b32_sdwa v96, v102, v95 dst_sel:DWORD dst_unused:UNUSED_PAD src0_sel:WORD_1 src1_sel:DWORD
	v_add_u32_e32 v94, v2, v154
	ds_write_b64 v94, v[96:97]
	v_and_b32_e32 v96, 0xffff0000, v102
	v_sub_u32_e32 v95, v98, v95
	v_and_b32_e32 v3, 0xffff0000, v3
	v_sub_u32_e32 v6, v6, v96
	v_add_u32_e32 v95, 0x80, v95
	v_sub_u32_e32 v3, v99, v3
	v_sub_u32_e32 v7, v7, v103
	v_add_u32_e32 v6, 0x80, v6
	v_ashrrev_i32_e32 v95, 8, v95
	v_add_u32_e32 v3, 0x80, v3
	v_add_u32_e32 v7, 0x80, v7
	v_ashrrev_i32_e32 v6, 8, v6
	v_min_i32_e32 v95, 0x7f, v95
	v_ashrrev_i32_e32 v3, 8, v3
	v_ashrrev_i32_e32 v7, 8, v7
	v_min_i32_e32 v6, 0x7f, v6
	v_min_i32_sdwa v3, v3, s79 dst_sel:WORD_1 dst_unused:UNUSED_PAD src0_sel:DWORD src1_sel:DWORD
	v_min_i32_e32 v7, 0x7f, v7
	v_lshlrev_b32_e32 v95, 8, v95
	v_and_b32_e32 v95, 0xff00, v95
	v_and_b32_e32 v3, 0xff0000, v3
	v_perm_b32 v6, v7, v6, s80
	v_or3_b32 v3, v6, v95, v3
	ds_write_b32 v14, v3 offset:144
	v_mov_b32_e32 v6, v206
	v_mov_b32_e32 v7, v207
	v_pk_add_f32 v[82:83], v[82:83], v[6:7] op_sel_hi:[1,0] neg_lo:[0,1] neg_hi:[0,1]
	s_nop 0
	v_pk_mul_f32 v[82:83], v[6:7], v[82:83] op_sel:[1,0]
	v_pk_add_f32 v[80:81], v[80:81], v[6:7] op_sel_hi:[1,0] neg_lo:[0,1] neg_hi:[0,1]
	v_pk_fma_f32 v[82:83], v[88:89], v[82:83], v[90:91]
	v_pk_mul_f32 v[6:7], v[6:7], v[80:81] op_sel:[1,0]
	v_and_b32_sdwa v80, v82, v216 dst_sel:DWORD dst_unused:UNUSED_PAD src0_sel:WORD_1 src1_sel:DWORD
	v_pk_fma_f32 v[6:7], v[0:1], v[6:7], v[4:5]
	v_add3_u32 v80, v82, v80, s78
	v_and_b32_e32 v81, 0xffff0000, v80
	v_and_b32_sdwa v80, v7, v216 dst_sel:DWORD dst_unused:UNUSED_PAD src0_sel:WORD_1 src1_sel:DWORD
	v_and_b32_sdwa v3, v83, v216 dst_sel:DWORD dst_unused:UNUSED_PAD src0_sel:WORD_1 src1_sel:DWORD
	v_and_b32_sdwa v95, v6, v216 dst_sel:DWORD dst_unused:UNUSED_PAD src0_sel:WORD_1 src1_sel:DWORD
	v_add3_u32 v80, v7, v80, s78
	v_add3_u32 v3, v83, v3, s78
	v_add3_u32 v95, v6, v95, s78
	v_and_b32_e32 v98, 0xffff0000, v80
	v_or_b32_sdwa v97, v98, v3 dst_sel:DWORD dst_unused:UNUSED_PAD src0_sel:DWORD src1_sel:WORD_1
	v_or_b32_sdwa v96, v95, v81 dst_sel:DWORD dst_unused:UNUSED_PAD src0_sel:WORD_1 src1_sel:DWORD
	v_and_b32_e32 v95, 0xffff0000, v95
	v_sub_u32_e32 v81, v82, v81
	v_and_b32_e32 v3, 0xffff0000, v3
	v_sub_u32_e32 v6, v6, v95
	v_add_u32_e32 v81, 0x80, v81
	v_sub_u32_e32 v3, v83, v3
	v_sub_u32_e32 v7, v7, v98
	v_add_u32_e32 v6, 0x80, v6
	v_ashrrev_i32_e32 v81, 8, v81
	v_add_u32_e32 v3, 0x80, v3
	v_add_u32_e32 v7, 0x80, v7
	v_ashrrev_i32_e32 v6, 8, v6
	v_min_i32_e32 v81, 0x7f, v81
	v_ashrrev_i32_e32 v3, 8, v3
	v_ashrrev_i32_e32 v7, 8, v7
	v_min_i32_e32 v6, 0x7f, v6
	v_min_i32_sdwa v3, v3, s79 dst_sel:WORD_1 dst_unused:UNUSED_PAD src0_sel:DWORD src1_sel:DWORD
	v_min_i32_e32 v7, 0x7f, v7
	v_lshlrev_b32_e32 v81, 8, v81
	v_and_b32_e32 v81, 0xff00, v81
	v_and_b32_e32 v3, 0xff0000, v3
	v_perm_b32 v6, v7, v6, s80
	v_add_u32_e32 v80, v2, v136
	v_or3_b32 v3, v6, v81, v3
	ds_write_b64 v80, v[96:97]
	ds_write_b32 v20, v3 offset:144
	v_mov_b32_e32 v6, v208
	v_mov_b32_e32 v7, v209
	v_or_b32_e32 v81, 0x6000, v148
	v_or_b32_e32 v82, 0x8000, v148
	v_or_b32_e32 v83, 0xa000, v148
	v_or_b32_e32 v95, 0x6000, v146
	v_pk_add_f32 v[74:75], v[74:75], v[6:7] op_sel_hi:[1,0] neg_lo:[0,1] neg_hi:[0,1]
	v_pk_add_f32 v[72:73], v[72:73], v[6:7] op_sel_hi:[1,0] neg_lo:[0,1] neg_hi:[0,1]
	v_pk_mul_f32 v[74:75], v[6:7], v[74:75] op_sel:[1,0]
	v_pk_mul_f32 v[6:7], v[6:7], v[72:73] op_sel:[1,0]
	v_pk_fma_f32 v[74:75], v[88:89], v[74:75], v[90:91]
	v_pk_fma_f32 v[0:1], v[0:1], v[6:7], v[4:5]
	v_and_b32_sdwa v4, v74, v216 dst_sel:DWORD dst_unused:UNUSED_PAD src0_sel:WORD_1 src1_sel:DWORD
	v_add3_u32 v4, v74, v4, s78
	v_and_b32_e32 v6, 0xffff0000, v4
	v_and_b32_sdwa v4, v1, v216 dst_sel:DWORD dst_unused:UNUSED_PAD src0_sel:WORD_1 src1_sel:DWORD
	v_and_b32_sdwa v5, v0, v216 dst_sel:DWORD dst_unused:UNUSED_PAD src0_sel:WORD_1 src1_sel:DWORD
	v_and_b32_sdwa v3, v75, v216 dst_sel:DWORD dst_unused:UNUSED_PAD src0_sel:WORD_1 src1_sel:DWORD
	v_add3_u32 v4, v1, v4, s78
	v_add3_u32 v7, v0, v5, s78
	v_add3_u32 v3, v75, v3, s78
	v_and_b32_e32 v72, 0xffff0000, v4
	v_add_u32_e32 v73, v2, v135
	v_and_b32_e32 v2, 0xffff0000, v7
	v_or_b32_sdwa v5, v72, v3 dst_sel:DWORD dst_unused:UNUSED_PAD src0_sel:DWORD src1_sel:WORD_1
	v_sub_u32_e32 v0, v0, v2
	v_sub_u32_e32 v2, v74, v6
	v_and_b32_e32 v3, 0xffff0000, v3
	v_add_u32_e32 v2, 0x80, v2
	v_sub_u32_e32 v3, v75, v3
	v_sub_u32_e32 v1, v1, v72
	v_add_u32_e32 v0, 0x80, v0
	v_ashrrev_i32_e32 v2, 8, v2
	v_add_u32_e32 v3, 0x80, v3
	v_add_u32_e32 v1, 0x80, v1
	v_ashrrev_i32_e32 v0, 8, v0
	v_min_i32_e32 v2, 0x7f, v2
	v_ashrrev_i32_e32 v3, 8, v3
	v_ashrrev_i32_e32 v1, 8, v1
	v_min_i32_e32 v0, 0x7f, v0
	v_min_i32_sdwa v3, v3, s79 dst_sel:WORD_1 dst_unused:UNUSED_PAD src0_sel:DWORD src1_sel:DWORD
	v_min_i32_e32 v1, 0x7f, v1
	v_lshlrev_b32_e32 v2, 8, v2
	v_and_b32_e32 v2, 0xff00, v2
	v_and_b32_e32 v3, 0xff0000, v3
	v_perm_b32 v0, v1, v0, s80
	v_or_b32_sdwa v4, v7, v6 dst_sel:DWORD dst_unused:UNUSED_PAD src0_sel:WORD_1 src1_sel:DWORD
	v_or3_b32 v0, v0, v2, v3
	ds_write_b64 v73, v[4:5]
	ds_write_b32 v22, v0 offset:144
	v_add_u32_e32 v72, s60, v151
	s_waitcnt lgkmcnt(0)
	s_barrier
;     ...
;           _Pragma("unroll") for (int bj = 0; bj < 2; ++bj) _Pragma("unroll") for (int n = 0; n < 2; ++n) {
;             const int cc = bj * HALF + wc3 * 32 + n * 16 + fq3 * 4;
;             const float4 gm = *reinterpret_cast<const float4*>(g.gam + pn * BM + cc), bt = *reinterpret_cast<const float4*>(g.bet + pn * BM + cc);
;             _Pragma("unroll") for (int m = 0; m < 4; ++m) {
;               const int rr = wr3 * 64 + m * 16 + fr3;
;               const float2 ms = *reinterpret_cast<const float2*>(mr + (ai * HALF + rr) * 2);
;               f32x4 y = acc[ai][bj][m][n];
;               const float o0 = (y[0] - ms.x) * ms.y * gm.x + bt.x, o1 = (y[1] - ms.x) * ms.y * gm.y + bt.y;
;               const float o2 = (y[2] - ms.x) * ms.y * gm.z + bt.z, o3 = (y[3] - ms.x) * ms.y * gm.w + bt.w;
;               const unsigned h0 = f2bf(o0), h1 = f2bf(o1), h2 = f2bf(o2), h3 = f2bf(o3);
;               u32x2 ob; ob[0] = h0 | (h1 << 16); ob[1] = h2 | (h3 << 16);
;               *reinterpret_cast<u32x2*>(smem + (rr >> 1) * PIECE + (rr & 1) * 512 + cc * 2) = ob;
;               const int l0 = min(((int)__float_as_uint(o0) - (int)(h0 << 16) + 128) >> 8, 127);
;               const int l1 = min(((int)__float_as_uint(o1) - (int)(h1 << 16) + 128) >> 8, 127);
;               const int l2 = min(((int)__float_as_uint(o2) - (int)(h2 << 16) + 128) >> 8, 127);
;               const int l3 = min(((int)__float_as_uint(o3) - (int)(h3 << 16) + 128) >> 8, 127);
;               *reinterpret_cast<unsigned*>(smem + LOBASE + (rr >> 2) * PIECE + (rr & 3) * 256 + cc) =
;                   (unsigned)(l0 & 255) | ((unsigned)(l1 & 255) << 8) | ((unsigned)(l2 & 255) << 16) | ((unsigned)l3 << 24);
;             }
;           }
;           WAIT_L(0); BAR;
;           const int hso = ((brow + ai * HALF + 16 * wave) * DM + pn * BM) * 2;
;           const int lso = (brow + ai * HALF + 16 * wave) * DM + pn * BM;
;           _Pragma("unroll") for (int i = 0; i < 8; ++i) {
;             const u32x4 v = *reinterpret_cast<const u32x4*>(smem + (wave * 8 + i) * PIECE + lane3 * 16);
;             __builtin_amdgcn_raw_buffer_store_b128(v, rsXB, hvo + i * (2 * DM * 2), hso, 0);
;           }
;           _Pragma("unroll") for (int i = 0; i < 4; ++i) {
;             const u32x4 v = *reinterpret_cast<const u32x4*>(smem + LOBASE + (wave * 4 + i) * PIECE + lane3 * 16);
	ds_read_b128 v[128:131], v72
	v_or_b32_e32 v74, 0x2000, v148
	v_or_b32_e32 v75, 0x4000, v148
	v_or_b32_e32 v88, 0xc000, v148
	v_or_b32_e32 v89, 0xe000, v148
	ds_read_b128 v[136:139], v72 offset:1040
	v_or_b32_e32 v90, 0x2000, v146
	v_or_b32_e32 v91, 0x4000, v146
	ds_read_b128 v[140:143], v72 offset:2080
	ds_read_b128 v[156:159], v72 offset:3120
	ds_read_b128 v[160:163], v72 offset:4160
	ds_read_b128 v[164:167], v72 offset:5200
	ds_read_b128 v[168:171], v72 offset:6240
	ds_read_b128 v[172:175], v72 offset:7280
	ds_read_b128 v[176:179], v147
	ds_read_b128 v[180:183], v147 offset:1040
	ds_read_b128 v[184:187], v147 offset:2080
	ds_read_b128 v[188:191], v147 offset:3120
	s_waitcnt lgkmcnt(0)
	s_barrier
	s_nop 1
	v_mov_b32_e32 v0, v220
	v_mov_b32_e32 v1, v221
	v_mov_b32_e32 v2, v222
	v_mov_b32_e32 v3, v223
	v_mov_b32_e32 v4, v236
	v_mov_b32_e32 v5, v237
	v_mov_b32_e32 v6, v238
	v_mov_b32_e32 v7, v239
	ds_read_b64 v[102:103], v149 offset:1024
	s_waitcnt lgkmcnt(0)
	v_mov_b32_e32 v210, v102
	v_mov_b32_e32 v211, v103
	v_pk_add_f32 v[66:67], v[66:67], v[102:103] op_sel_hi:[1,0] neg_lo:[0,1] neg_hi:[0,1]
	s_nop 0
	v_pk_mul_f32 v[66:67], v[102:103], v[66:67] op_sel:[1,0]
	v_pk_add_f32 v[64:65], v[64:65], v[102:103] op_sel_hi:[1,0] neg_lo:[0,1] neg_hi:[0,1]
	v_mov_b32_e32 v96, v1
	v_mov_b32_e32 v97, v2
	v_mov_b32_e32 v98, v5
	v_mov_b32_e32 v99, v6
	v_pk_fma_f32 v[66:67], v[96:97], v[66:67], v[98:99]
	v_pk_mul_f32 v[64:65], v[102:103], v[64:65] op_sel:[1,0]
	v_mov_b32_e32 v1, v3
	v_mov_b32_e32 v5, v7
	v_and_b32_sdwa v6, v67, v216 dst_sel:DWORD dst_unused:UNUSED_PAD src0_sel:WORD_1 src1_sel:DWORD
	v_and_b32_sdwa v7, v66, v216 dst_sel:DWORD dst_unused:UNUSED_PAD src0_sel:WORD_1 src1_sel:DWORD
	v_pk_fma_f32 v[2:3], v[0:1], v[64:65], v[4:5]
	v_add3_u32 v64, v67, v6, s78
	v_add3_u32 v6, v66, v7, s78
	v_and_b32_e32 v65, 0xffff0000, v6
	v_and_b32_sdwa v6, v3, v216 dst_sel:DWORD dst_unused:UNUSED_PAD src0_sel:WORD_1 src1_sel:DWORD
	v_and_b32_sdwa v7, v2, v216 dst_sel:DWORD dst_unused:UNUSED_PAD src0_sel:WORD_1 src1_sel:DWORD
	v_add3_u32 v6, v3, v6, s78
	v_add3_u32 v102, v2, v7, s78
	v_and_b32_e32 v103, 0xffff0000, v6
	v_or_b32_sdwa v7, v103, v64 dst_sel:DWORD dst_unused:UNUSED_PAD src0_sel:DWORD src1_sel:WORD_1
	v_or_b32_sdwa v6, v102, v65 dst_sel:DWORD dst_unused:UNUSED_PAD src0_sel:WORD_1 src1_sel:DWORD
	ds_write_b64 v152, v[6:7]
	v_and_b32_e32 v6, 0xffff0000, v102
	v_sub_u32_e32 v2, v2, v6
	v_sub_u32_e32 v6, v66, v65
	v_and_b32_e32 v7, 0xffff0000, v64
	v_add_u32_e32 v6, 0x80, v6
	v_sub_u32_e32 v7, v67, v7
	v_sub_u32_e32 v3, v3, v103
	v_add_u32_e32 v2, 0x80, v2
	v_ashrrev_i32_e32 v6, 8, v6
	v_add_u32_e32 v7, 0x80, v7
	v_add_u32_e32 v3, 0x80, v3
	v_ashrrev_i32_e32 v2, 8, v2
	v_min_i32_e32 v6, 0x7f, v6
	v_ashrrev_i32_e32 v7, 8, v7
	v_ashrrev_i32_e32 v3, 8, v3
	v_min_i32_e32 v2, 0x7f, v2
	v_min_i32_sdwa v7, v7, s79 dst_sel:WORD_1 dst_unused:UNUSED_PAD src0_sel:DWORD src1_sel:DWORD
	v_min_i32_e32 v3, 0x7f, v3
	v_lshlrev_b32_e32 v6, 8, v6
	v_and_b32_e32 v6, 0xff00, v6
	v_and_b32_e32 v7, 0xff0000, v7
	v_perm_b32 v2, v3, v2, s80
	v_or3_b32 v2, v2, v6, v7
	ds_write_b32 v12, v2
	buffer_store_dwordx4 v[128:131], v148, s[16:19], s33 offen
	ds_read_b64 v[2:3], v13 offset:1024
	s_waitcnt lgkmcnt(0)
	v_mov_b32_e32 v212, v2
	v_mov_b32_e32 v213, v3
	v_pk_add_f32 v[6:7], v[70:71], v[2:3] op_sel_hi:[1,0] neg_lo:[0,1] neg_hi:[0,1]
	s_nop 0
	v_pk_mul_f32 v[6:7], v[2:3], v[6:7] op_sel:[1,0]
	v_pk_add_f32 v[64:65], v[68:69], v[2:3] op_sel_hi:[1,0] neg_lo:[0,1] neg_hi:[0,1]
	v_pk_fma_f32 v[6:7], v[96:97], v[6:7], v[98:99]
	v_pk_mul_f32 v[2:3], v[2:3], v[64:65] op_sel:[1,0]
	v_and_b32_sdwa v64, v7, v216 dst_sel:DWORD dst_unused:UNUSED_PAD src0_sel:WORD_1 src1_sel:DWORD
	v_and_b32_sdwa v65, v6, v216 dst_sel:DWORD dst_unused:UNUSED_PAD src0_sel:WORD_1 src1_sel:DWORD
	v_pk_fma_f32 v[2:3], v[0:1], v[2:3], v[4:5]
	v_add3_u32 v66, v7, v64, s78
	v_add3_u32 v64, v6, v65, s78
	v_and_b32_e32 v67, 0xffff0000, v64
	v_and_b32_sdwa v64, v3, v216 dst_sel:DWORD dst_unused:UNUSED_PAD src0_sel:WORD_1 src1_sel:DWORD
	v_and_b32_sdwa v65, v2, v216 dst_sel:DWORD dst_unused:UNUSED_PAD src0_sel:WORD_1 src1_sel:DWORD
	v_add3_u32 v64, v3, v64, s78
	v_add3_u32 v68, v2, v65, s78
	v_and_b32_e32 v69, 0xffff0000, v64
	v_or_b32_sdwa v65, v69, v66 dst_sel:DWORD dst_unused:UNUSED_PAD src0_sel:DWORD src1_sel:WORD_1
	v_or_b32_sdwa v64, v68, v67 dst_sel:DWORD dst_unused:UNUSED_PAD src0_sel:WORD_1 src1_sel:DWORD
	ds_write_b64 v132, v[64:65]
	v_and_b32_e32 v64, 0xffff0000, v68
	v_sub_u32_e32 v2, v2, v64
	v_sub_u32_e32 v6, v6, v67
	v_and_b32_e32 v64, 0xffff0000, v66
	v_add_u32_e32 v6, 0x80, v6
	v_sub_u32_e32 v7, v7, v64
	v_sub_u32_e32 v3, v3, v69
	v_add_u32_e32 v2, 0x80, v2
	v_ashrrev_i32_e32 v6, 8, v6
	v_add_u32_e32 v7, 0x80, v7
	v_add_u32_e32 v3, 0x80, v3
	v_ashrrev_i32_e32 v2, 8, v2
	v_min_i32_e32 v6, 0x7f, v6
	v_ashrrev_i32_e32 v7, 8, v7
	v_ashrrev_i32_e32 v3, 8, v3
	v_min_i32_e32 v2, 0x7f, v2
	v_min_i32_sdwa v7, v7, s79 dst_sel:WORD_1 dst_unused:UNUSED_PAD src0_sel:DWORD src1_sel:DWORD
	v_min_i32_e32 v3, 0x7f, v3
	v_lshlrev_b32_e32 v6, 8, v6
	v_and_b32_e32 v6, 0xff00, v6
	v_and_b32_e32 v7, 0xff0000, v7
	v_perm_b32 v2, v3, v2, s80
	v_or3_b32 v2, v2, v6, v7
	ds_write_b32 v14, v2
	buffer_store_dwordx4 v[136:139], v74, s[16:19], s33 offen
	ds_read_b64 v[2:3], v15 offset:1024
	s_waitcnt lgkmcnt(0)
;     ...
;           _Pragma("unroll") for (int bj = 0; bj < 2; ++bj) _Pragma("unroll") for (int n = 0; n < 2; ++n) {
;             const int cc = bj * HALF + wc3 * 32 + n * 16 + fq3 * 4;
;             const float4 gm = *reinterpret_cast<const float4*>(g.gam + pn * BM + cc), bt = *reinterpret_cast<const float4*>(g.bet + pn * BM + cc);
;             _Pragma("unroll") for (int m = 0; m < 4; ++m) {
;               const int rr = wr3 * 64 + m * 16 + fr3;
;               const float2 ms = *reinterpret_cast<const float2*>(mr + (ai * HALF + rr) * 2);
;               f32x4 y = acc[ai][bj][m][n];
;               const float o0 = (y[0] - ms.x) * ms.y * gm.x + bt.x, o1 = (y[1] - ms.x) * ms.y * gm.y + bt.y;
;               const float o2 = (y[2] - ms.x) * ms.y * gm.z + bt.z, o3 = (y[3] - ms.x) * ms.y * gm.w + bt.w;
;               const unsigned h0 = f2bf(o0), h1 = f2bf(o1), h2 = f2bf(o2), h3 = f2bf(o3);
;               u32x2 ob; ob[0] = h0 | (h1 << 16); ob[1] = h2 | (h3 << 16);
;               *reinterpret_cast<u32x2*>(smem + (rr >> 1) * PIECE + (rr & 1) * 512 + cc * 2) = ob;
;               const int l0 = min(((int)__float_as_uint(o0) - (int)(h0 << 16) + 128) >> 8, 127);
;               const int l1 = min(((int)__float_as_uint(o1) - (int)(h1 << 16) + 128) >> 8, 127);
;               const int l2 = min(((int)__float_as_uint(o2) - (int)(h2 << 16) + 128) >> 8, 127);
;               const int l3 = min(((int)__float_as_uint(o3) - (int)(h3 << 16) + 128) >> 8, 127);
;               *reinterpret_cast<unsigned*>(smem + LOBASE + (rr >> 2) * PIECE + (rr & 3) * 256 + cc) =
;                   (unsigned)(l0 & 255) | ((unsigned)(l1 & 255) << 8) | ((unsigned)(l2 & 255) << 16) | ((unsigned)l3 << 24);
;             }
	v_mov_b32_e32 v214, v2
	v_mov_b32_e32 v215, v3
	v_pk_add_f32 v[6:7], v[78:79], v[2:3] op_sel_hi:[1,0] neg_lo:[0,1] neg_hi:[0,1]
	s_nop 0
	v_pk_mul_f32 v[6:7], v[2:3], v[6:7] op_sel:[1,0]
	v_pk_add_f32 v[64:65], v[76:77], v[2:3] op_sel_hi:[1,0] neg_lo:[0,1] neg_hi:[0,1]
	v_pk_fma_f32 v[6:7], v[96:97], v[6:7], v[98:99]
	v_pk_mul_f32 v[2:3], v[2:3], v[64:65] op_sel:[1,0]
	v_and_b32_sdwa v64, v7, v216 dst_sel:DWORD dst_unused:UNUSED_PAD src0_sel:WORD_1 src1_sel:DWORD
	v_and_b32_sdwa v65, v6, v216 dst_sel:DWORD dst_unused:UNUSED_PAD src0_sel:WORD_1 src1_sel:DWORD
	v_pk_fma_f32 v[2:3], v[0:1], v[2:3], v[4:5]
	v_add3_u32 v66, v7, v64, s78
	v_add3_u32 v64, v6, v65, s78
	v_and_b32_e32 v67, 0xffff0000, v64
	v_and_b32_sdwa v64, v3, v216 dst_sel:DWORD dst_unused:UNUSED_PAD src0_sel:WORD_1 src1_sel:DWORD
	v_and_b32_sdwa v65, v2, v216 dst_sel:DWORD dst_unused:UNUSED_PAD src0_sel:WORD_1 src1_sel:DWORD
	v_add3_u32 v64, v3, v64, s78
	v_add3_u32 v68, v2, v65, s78
	v_and_b32_e32 v69, 0xffff0000, v64
	v_or_b32_sdwa v65, v69, v66 dst_sel:DWORD dst_unused:UNUSED_PAD src0_sel:DWORD src1_sel:WORD_1
	v_or_b32_sdwa v64, v68, v67 dst_sel:DWORD dst_unused:UNUSED_PAD src0_sel:WORD_1 src1_sel:DWORD
	ds_write_b64 v133, v[64:65]
	v_and_b32_e32 v64, 0xffff0000, v68
	v_sub_u32_e32 v2, v2, v64
	v_sub_u32_e32 v6, v6, v67
	v_and_b32_e32 v64, 0xffff0000, v66
	v_add_u32_e32 v6, 0x80, v6
	v_sub_u32_e32 v7, v7, v64
	v_sub_u32_e32 v3, v3, v69
	v_add_u32_e32 v2, 0x80, v2
	v_ashrrev_i32_e32 v6, 8, v6
	v_add_u32_e32 v7, 0x80, v7
	v_add_u32_e32 v3, 0x80, v3
	v_ashrrev_i32_e32 v2, 8, v2
	v_min_i32_e32 v6, 0x7f, v6
	v_ashrrev_i32_e32 v7, 8, v7
	v_ashrrev_i32_e32 v3, 8, v3
	v_min_i32_e32 v2, 0x7f, v2
	v_min_i32_sdwa v7, v7, s79 dst_sel:WORD_1 dst_unused:UNUSED_PAD src0_sel:DWORD src1_sel:DWORD
	v_min_i32_e32 v3, 0x7f, v3
	v_lshlrev_b32_e32 v6, 8, v6
	v_and_b32_e32 v6, 0xff00, v6
	v_and_b32_e32 v7, 0xff0000, v7
	v_perm_b32 v2, v3, v2, s80
	v_or3_b32 v2, v2, v6, v7
	ds_write_b32 v20, v2
	buffer_store_dwordx4 v[140:143], v75, s[16:19], s33 offen
	ds_read_b64 v[2:3], v21 offset:1024
	s_waitcnt lgkmcnt(0)
	v_mov_b32_e32 v252, v2
	v_mov_b32_e32 v253, v3
	v_pk_add_f32 v[6:7], v[86:87], v[2:3] op_sel_hi:[1,0] neg_lo:[0,1] neg_hi:[0,1]
	s_nop 0
	v_pk_mul_f32 v[6:7], v[2:3], v[6:7] op_sel:[1,0]
	v_pk_add_f32 v[64:65], v[84:85], v[2:3] op_sel_hi:[1,0] neg_lo:[0,1] neg_hi:[0,1]
	v_pk_fma_f32 v[6:7], v[96:97], v[6:7], v[98:99]
	v_pk_mul_f32 v[2:3], v[2:3], v[64:65] op_sel:[1,0]
	s_nop 0
	v_pk_fma_f32 v[0:1], v[0:1], v[2:3], v[4:5]
	v_and_b32_sdwa v2, v7, v216 dst_sel:DWORD dst_unused:UNUSED_PAD src0_sel:WORD_1 src1_sel:DWORD
	v_and_b32_sdwa v3, v6, v216 dst_sel:DWORD dst_unused:UNUSED_PAD src0_sel:WORD_1 src1_sel:DWORD
	v_add3_u32 v4, v7, v2, s78
	v_add3_u32 v2, v6, v3, s78
	v_and_b32_e32 v5, 0xffff0000, v2
	v_and_b32_sdwa v2, v1, v216 dst_sel:DWORD dst_unused:UNUSED_PAD src0_sel:WORD_1 src1_sel:DWORD
	v_and_b32_sdwa v3, v0, v216 dst_sel:DWORD dst_unused:UNUSED_PAD src0_sel:WORD_1 src1_sel:DWORD
	v_add3_u32 v2, v1, v2, s78
	v_add3_u32 v64, v0, v3, s78
	v_and_b32_e32 v65, 0xffff0000, v2
	v_or_b32_sdwa v3, v65, v4 dst_sel:DWORD dst_unused:UNUSED_PAD src0_sel:DWORD src1_sel:WORD_1
	v_or_b32_sdwa v2, v64, v5 dst_sel:DWORD dst_unused:UNUSED_PAD src0_sel:WORD_1 src1_sel:DWORD
	ds_write_b64 v134, v[2:3]
	v_and_b32_e32 v2, 0xffff0000, v64
	v_sub_u32_e32 v0, v0, v2
	v_sub_u32_e32 v2, v6, v5
	v_and_b32_e32 v3, 0xffff0000, v4
	v_add_u32_e32 v2, 0x80, v2
	v_sub_u32_e32 v3, v7, v3
	v_sub_u32_e32 v1, v1, v65
	v_add_u32_e32 v0, 0x80, v0
	v_ashrrev_i32_e32 v2, 8, v2
	v_add_u32_e32 v3, 0x80, v3
	v_add_u32_e32 v1, 0x80, v1
	v_ashrrev_i32_e32 v0, 8, v0
	v_min_i32_e32 v2, 0x7f, v2
	v_ashrrev_i32_e32 v3, 8, v3
	v_ashrrev_i32_e32 v1, 8, v1
	v_min_i32_e32 v0, 0x7f, v0
	v_min_i32_sdwa v3, v3, s79 dst_sel:WORD_1 dst_unused:UNUSED_PAD src0_sel:DWORD src1_sel:DWORD
	v_min_i32_e32 v1, 0x7f, v1
	v_lshlrev_b32_e32 v2, 8, v2
	v_and_b32_e32 v2, 0xff00, v2
	v_and_b32_e32 v3, 0xff0000, v3
	v_perm_b32 v0, v1, v0, s80
	v_or3_b32 v0, v0, v2, v3
	ds_write_b32 v22, v0
	buffer_store_dwordx4 v[156:159], v81, s[16:19], s33 offen
	v_mov_b32_e32 v0, v224
	v_mov_b32_e32 v1, v225
	v_mov_b32_e32 v2, v226
	v_mov_b32_e32 v3, v227
	v_mov_b32_e32 v4, v240
	v_mov_b32_e32 v5, v241
	v_mov_b32_e32 v6, v242
	v_mov_b32_e32 v7, v243
	v_mov_b32_e32 v68, v210
	v_mov_b32_e32 v69, v211
	v_pk_add_f32 v[58:59], v[58:59], v[68:69] op_sel_hi:[1,0] neg_lo:[0,1] neg_hi:[0,1]
	s_nop 0
	v_pk_mul_f32 v[58:59], v[68:69], v[58:59] op_sel:[1,0]
	v_pk_add_f32 v[56:57], v[56:57], v[68:69] op_sel_hi:[1,0] neg_lo:[0,1] neg_hi:[0,1]
	v_mov_b32_e32 v64, v1
	v_mov_b32_e32 v65, v2
	v_mov_b32_e32 v66, v5
	v_mov_b32_e32 v67, v6
	v_pk_fma_f32 v[58:59], v[64:65], v[58:59], v[66:67]
	v_pk_mul_f32 v[56:57], v[68:69], v[56:57] op_sel:[1,0]
	v_mov_b32_e32 v1, v3
	v_mov_b32_e32 v5, v7
	v_and_b32_sdwa v6, v59, v216 dst_sel:DWORD dst_unused:UNUSED_PAD src0_sel:WORD_1 src1_sel:DWORD
	v_and_b32_sdwa v7, v58, v216 dst_sel:DWORD dst_unused:UNUSED_PAD src0_sel:WORD_1 src1_sel:DWORD
	v_pk_fma_f32 v[2:3], v[0:1], v[56:57], v[4:5]
	v_add3_u32 v56, v59, v6, s78
	v_add3_u32 v6, v58, v7, s78
	v_and_b32_e32 v57, 0xffff0000, v6
	v_and_b32_sdwa v6, v3, v216 dst_sel:DWORD dst_unused:UNUSED_PAD src0_sel:WORD_1 src1_sel:DWORD
	v_and_b32_sdwa v7, v2, v216 dst_sel:DWORD dst_unused:UNUSED_PAD src0_sel:WORD_1 src1_sel:DWORD
	v_add3_u32 v6, v3, v6, s78
	v_add3_u32 v68, v2, v7, s78
	v_and_b32_e32 v69, 0xffff0000, v6
	v_or_b32_sdwa v7, v69, v56 dst_sel:DWORD dst_unused:UNUSED_PAD src0_sel:DWORD src1_sel:WORD_1
	v_or_b32_sdwa v6, v68, v57 dst_sel:DWORD dst_unused:UNUSED_PAD src0_sel:WORD_1 src1_sel:DWORD
;     ...
;           _Pragma("unroll") for (int bj = 0; bj < 2; ++bj) _Pragma("unroll") for (int n = 0; n < 2; ++n) {
;             const int cc = bj * HALF + wc3 * 32 + n * 16 + fq3 * 4;
;             const float4 gm = *reinterpret_cast<const float4*>(g.gam + pn * BM + cc), bt = *reinterpret_cast<const float4*>(g.bet + pn * BM + cc);
;             _Pragma("unroll") for (int m = 0; m < 4; ++m) {
;               const int rr = wr3 * 64 + m * 16 + fr3;
;               const float2 ms = *reinterpret_cast<const float2*>(mr + (ai * HALF + rr) * 2);
;               f32x4 y = acc[ai][bj][m][n];
;               const float o0 = (y[0] - ms.x) * ms.y * gm.x + bt.x, o1 = (y[1] - ms.x) * ms.y * gm.y + bt.y;
;               const float o2 = (y[2] - ms.x) * ms.y * gm.z + bt.z, o3 = (y[3] - ms.x) * ms.y * gm.w + bt.w;
;               const unsigned h0 = f2bf(o0), h1 = f2bf(o1), h2 = f2bf(o2), h3 = f2bf(o3);
;               u32x2 ob; ob[0] = h0 | (h1 << 16); ob[1] = h2 | (h3 << 16);
;               *reinterpret_cast<u32x2*>(smem + (rr >> 1) * PIECE + (rr & 1) * 512 + cc * 2) = ob;
;               const int l0 = min(((int)__float_as_uint(o0) - (int)(h0 << 16) + 128) >> 8, 127);
;               const int l1 = min(((int)__float_as_uint(o1) - (int)(h1 << 16) + 128) >> 8, 127);
;               const int l2 = min(((int)__float_as_uint(o2) - (int)(h2 << 16) + 128) >> 8, 127);
;               const int l3 = min(((int)__float_as_uint(o3) - (int)(h3 << 16) + 128) >> 8, 127);
;               *reinterpret_cast<unsigned*>(smem + LOBASE + (rr >> 2) * PIECE + (rr & 3) * 256 + cc) =
;                   (unsigned)(l0 & 255) | ((unsigned)(l1 & 255) << 8) | ((unsigned)(l2 & 255) << 16) | ((unsigned)l3 << 24);
;             }
	ds_write_b64 v23, v[6:7]
	v_and_b32_e32 v6, 0xffff0000, v68
	v_sub_u32_e32 v2, v2, v6
	v_sub_u32_e32 v6, v58, v57
	v_and_b32_e32 v7, 0xffff0000, v56
	v_add_u32_e32 v6, 0x80, v6
	v_sub_u32_e32 v7, v59, v7
	v_sub_u32_e32 v3, v3, v69
	v_add_u32_e32 v2, 0x80, v2
	v_ashrrev_i32_e32 v6, 8, v6
	v_add_u32_e32 v7, 0x80, v7
	v_add_u32_e32 v3, 0x80, v3
	v_ashrrev_i32_e32 v2, 8, v2
	v_min_i32_e32 v6, 0x7f, v6
	v_ashrrev_i32_e32 v7, 8, v7
	v_ashrrev_i32_e32 v3, 8, v3
	v_min_i32_e32 v2, 0x7f, v2
	v_min_i32_sdwa v7, v7, s79 dst_sel:WORD_1 dst_unused:UNUSED_PAD src0_sel:DWORD src1_sel:DWORD
	v_min_i32_e32 v3, 0x7f, v3
	v_lshlrev_b32_e32 v6, 8, v6
	v_and_b32_e32 v6, 0xff00, v6
	v_and_b32_e32 v7, 0xff0000, v7
	v_perm_b32 v2, v3, v2, s80
	v_or3_b32 v2, v2, v6, v7
	ds_write_b32 v12, v2 offset:16
	buffer_store_dwordx4 v[160:163], v82, s[16:19], s33 offen
	v_mov_b32_e32 v2, v212
	v_mov_b32_e32 v3, v213
	v_pk_add_f32 v[6:7], v[42:43], v[2:3] op_sel_hi:[1,0] neg_lo:[0,1] neg_hi:[0,1]
	s_nop 0
	v_pk_mul_f32 v[6:7], v[2:3], v[6:7] op_sel:[1,0]
	v_pk_add_f32 v[40:41], v[40:41], v[2:3] op_sel_hi:[1,0] neg_lo:[0,1] neg_hi:[0,1]
	v_pk_fma_f32 v[6:7], v[64:65], v[6:7], v[66:67]
	v_pk_mul_f32 v[2:3], v[2:3], v[40:41] op_sel:[1,0]
	v_and_b32_sdwa v40, v6, v216 dst_sel:DWORD dst_unused:UNUSED_PAD src0_sel:WORD_1 src1_sel:DWORD
	v_pk_fma_f32 v[2:3], v[0:1], v[2:3], v[4:5]
	v_add3_u32 v40, v6, v40, s78
	v_and_b32_e32 v42, 0xffff0000, v40
	v_and_b32_sdwa v40, v3, v216 dst_sel:DWORD dst_unused:UNUSED_PAD src0_sel:WORD_1 src1_sel:DWORD
	v_and_b32_sdwa v23, v7, v216 dst_sel:DWORD dst_unused:UNUSED_PAD src0_sel:WORD_1 src1_sel:DWORD
	v_and_b32_sdwa v41, v2, v216 dst_sel:DWORD dst_unused:UNUSED_PAD src0_sel:WORD_1 src1_sel:DWORD
	v_add3_u32 v40, v3, v40, s78
	v_add3_u32 v23, v7, v23, s78
	v_add3_u32 v43, v2, v41, s78
	v_and_b32_e32 v56, 0xffff0000, v40
	v_or_b32_sdwa v41, v56, v23 dst_sel:DWORD dst_unused:UNUSED_PAD src0_sel:DWORD src1_sel:WORD_1
	v_or_b32_sdwa v40, v43, v42 dst_sel:DWORD dst_unused:UNUSED_PAD src0_sel:WORD_1 src1_sel:DWORD
	ds_write_b64 v104, v[40:41]
	v_and_b32_e32 v40, 0xffff0000, v43
	v_sub_u32_e32 v6, v6, v42
	v_and_b32_e32 v23, 0xffff0000, v23
	v_sub_u32_e32 v2, v2, v40
	v_add_u32_e32 v6, 0x80, v6
	v_sub_u32_e32 v7, v7, v23
	v_sub_u32_e32 v3, v3, v56
	v_add_u32_e32 v2, 0x80, v2
	v_ashrrev_i32_e32 v6, 8, v6
	v_add_u32_e32 v7, 0x80, v7
	v_add_u32_e32 v3, 0x80, v3
	v_ashrrev_i32_e32 v2, 8, v2
	v_min_i32_e32 v6, 0x7f, v6
	v_ashrrev_i32_e32 v7, 8, v7
	v_ashrrev_i32_e32 v3, 8, v3
	v_min_i32_e32 v2, 0x7f, v2
	v_min_i32_sdwa v7, v7, s79 dst_sel:WORD_1 dst_unused:UNUSED_PAD src0_sel:DWORD src1_sel:DWORD
	v_min_i32_e32 v3, 0x7f, v3
	v_lshlrev_b32_e32 v6, 8, v6
	v_and_b32_e32 v6, 0xff00, v6
	v_and_b32_e32 v7, 0xff0000, v7
	v_perm_b32 v2, v3, v2, s80
	v_or3_b32 v2, v2, v6, v7
	ds_write_b32 v14, v2 offset:16
	buffer_store_dwordx4 v[164:167], v83, s[16:19], s33 offen
	v_mov_b32_e32 v2, v214
	v_mov_b32_e32 v3, v215
	v_pk_add_f32 v[6:7], v[46:47], v[2:3] op_sel_hi:[1,0] neg_lo:[0,1] neg_hi:[0,1]
	s_nop 0
	v_pk_mul_f32 v[6:7], v[2:3], v[6:7] op_sel:[1,0]
	v_pk_add_f32 v[40:41], v[44:45], v[2:3] op_sel_hi:[1,0] neg_lo:[0,1] neg_hi:[0,1]
	v_pk_fma_f32 v[6:7], v[64:65], v[6:7], v[66:67]
	v_pk_mul_f32 v[2:3], v[2:3], v[40:41] op_sel:[1,0]
	v_and_b32_sdwa v40, v6, v216 dst_sel:DWORD dst_unused:UNUSED_PAD src0_sel:WORD_1 src1_sel:DWORD
	v_pk_fma_f32 v[2:3], v[0:1], v[2:3], v[4:5]
	v_add3_u32 v40, v6, v40, s78
	v_and_b32_e32 v42, 0xffff0000, v40
	v_and_b32_sdwa v40, v3, v216 dst_sel:DWORD dst_unused:UNUSED_PAD src0_sel:WORD_1 src1_sel:DWORD
	v_and_b32_sdwa v23, v7, v216 dst_sel:DWORD dst_unused:UNUSED_PAD src0_sel:WORD_1 src1_sel:DWORD
	v_and_b32_sdwa v41, v2, v216 dst_sel:DWORD dst_unused:UNUSED_PAD src0_sel:WORD_1 src1_sel:DWORD
	v_add3_u32 v40, v3, v40, s78
	v_add3_u32 v23, v7, v23, s78
	v_add3_u32 v43, v2, v41, s78
	v_and_b32_e32 v44, 0xffff0000, v40
	v_or_b32_sdwa v41, v44, v23 dst_sel:DWORD dst_unused:UNUSED_PAD src0_sel:DWORD src1_sel:WORD_1
	v_or_b32_sdwa v40, v43, v42 dst_sel:DWORD dst_unused:UNUSED_PAD src0_sel:WORD_1 src1_sel:DWORD
	ds_write_b64 v105, v[40:41]
	v_and_b32_e32 v40, 0xffff0000, v43
	v_sub_u32_e32 v6, v6, v42
	v_and_b32_e32 v23, 0xffff0000, v23
	v_sub_u32_e32 v2, v2, v40
	v_add_u32_e32 v6, 0x80, v6
	v_sub_u32_e32 v7, v7, v23
	v_sub_u32_e32 v3, v3, v44
	v_add_u32_e32 v2, 0x80, v2
	v_ashrrev_i32_e32 v6, 8, v6
	v_add_u32_e32 v7, 0x80, v7
	v_add_u32_e32 v3, 0x80, v3
	v_ashrrev_i32_e32 v2, 8, v2
	v_min_i32_e32 v6, 0x7f, v6
	v_ashrrev_i32_e32 v7, 8, v7
	v_ashrrev_i32_e32 v3, 8, v3
	v_min_i32_e32 v2, 0x7f, v2
	v_min_i32_sdwa v7, v7, s79 dst_sel:WORD_1 dst_unused:UNUSED_PAD src0_sel:DWORD src1_sel:DWORD
	v_min_i32_e32 v3, 0x7f, v3
	v_lshlrev_b32_e32 v6, 8, v6
	v_and_b32_e32 v6, 0xff00, v6
	v_and_b32_e32 v7, 0xff0000, v7
	v_perm_b32 v2, v3, v2, s80
	v_or3_b32 v2, v2, v6, v7
	ds_write_b32 v20, v2 offset:16
	buffer_store_dwordx4 v[168:171], v88, s[16:19], s33 offen
	v_mov_b32_e32 v2, v252
	v_mov_b32_e32 v3, v253
	v_pk_add_f32 v[6:7], v[62:63], v[2:3] op_sel_hi:[1,0] neg_lo:[0,1] neg_hi:[0,1]
	s_nop 0
	v_pk_mul_f32 v[6:7], v[2:3], v[6:7] op_sel:[1,0]
	v_pk_add_f32 v[40:41], v[60:61], v[2:3] op_sel_hi:[1,0] neg_lo:[0,1] neg_hi:[0,1]
	v_pk_fma_f32 v[6:7], v[64:65], v[6:7], v[66:67]
	v_pk_mul_f32 v[2:3], v[2:3], v[40:41] op_sel:[1,0]
	s_nop 0
	v_pk_fma_f32 v[0:1], v[0:1], v[2:3], v[4:5]
	v_and_b32_sdwa v2, v7, v216 dst_sel:DWORD dst_unused:UNUSED_PAD src0_sel:WORD_1 src1_sel:DWORD
	v_and_b32_sdwa v3, v6, v216 dst_sel:DWORD dst_unused:UNUSED_PAD src0_sel:WORD_1 src1_sel:DWORD
	v_add3_u32 v4, v7, v2, s78
	v_add3_u32 v2, v6, v3, s78
	v_and_b32_e32 v5, 0xffff0000, v2
;     ...
;           _Pragma("unroll") for (int bj = 0; bj < 2; ++bj) _Pragma("unroll") for (int n = 0; n < 2; ++n) {
;             const int cc = bj * HALF + wc3 * 32 + n * 16 + fq3 * 4;
;             const float4 gm = *reinterpret_cast<const float4*>(g.gam + pn * BM + cc), bt = *reinterpret_cast<const float4*>(g.bet + pn * BM + cc);
;             _Pragma("unroll") for (int m = 0; m < 4; ++m) {
;               const int rr = wr3 * 64 + m * 16 + fr3;
;               const float2 ms = *reinterpret_cast<const float2*>(mr + (ai * HALF + rr) * 2);
;               f32x4 y = acc[ai][bj][m][n];
;               const float o0 = (y[0] - ms.x) * ms.y * gm.x + bt.x, o1 = (y[1] - ms.x) * ms.y * gm.y + bt.y;
;               const float o2 = (y[2] - ms.x) * ms.y * gm.z + bt.z, o3 = (y[3] - ms.x) * ms.y * gm.w + bt.w;
;               const unsigned h0 = f2bf(o0), h1 = f2bf(o1), h2 = f2bf(o2), h3 = f2bf(o3);
;               u32x2 ob; ob[0] = h0 | (h1 << 16); ob[1] = h2 | (h3 << 16);
;               *reinterpret_cast<u32x2*>(smem + (rr >> 1) * PIECE + (rr & 1) * 512 + cc * 2) = ob;
;               const int l0 = min(((int)__float_as_uint(o0) - (int)(h0 << 16) + 128) >> 8, 127);
;               const int l1 = min(((int)__float_as_uint(o1) - (int)(h1 << 16) + 128) >> 8, 127);
;               const int l2 = min(((int)__float_as_uint(o2) - (int)(h2 << 16) + 128) >> 8, 127);
;               const int l3 = min(((int)__float_as_uint(o3) - (int)(h3 << 16) + 128) >> 8, 127);
;               *reinterpret_cast<unsigned*>(smem + LOBASE + (rr >> 2) * PIECE + (rr & 3) * 256 + cc) =
;                   (unsigned)(l0 & 255) | ((unsigned)(l1 & 255) << 8) | ((unsigned)(l2 & 255) << 16) | ((unsigned)l3 << 24);
;             }
	v_and_b32_sdwa v2, v1, v216 dst_sel:DWORD dst_unused:UNUSED_PAD src0_sel:WORD_1 src1_sel:DWORD
	v_and_b32_sdwa v3, v0, v216 dst_sel:DWORD dst_unused:UNUSED_PAD src0_sel:WORD_1 src1_sel:DWORD
	v_add3_u32 v2, v1, v2, s78
	v_add3_u32 v23, v0, v3, s78
	v_and_b32_e32 v40, 0xffff0000, v2
	v_or_b32_sdwa v3, v40, v4 dst_sel:DWORD dst_unused:UNUSED_PAD src0_sel:DWORD src1_sel:WORD_1
	v_or_b32_sdwa v2, v23, v5 dst_sel:DWORD dst_unused:UNUSED_PAD src0_sel:WORD_1 src1_sel:DWORD
	ds_write_b64 v106, v[2:3]
	v_and_b32_e32 v2, 0xffff0000, v23
	v_sub_u32_e32 v0, v0, v2
	v_sub_u32_e32 v2, v6, v5
	v_and_b32_e32 v3, 0xffff0000, v4
	v_add_u32_e32 v2, 0x80, v2
	v_sub_u32_e32 v3, v7, v3
	v_sub_u32_e32 v1, v1, v40
	v_add_u32_e32 v0, 0x80, v0
	v_ashrrev_i32_e32 v2, 8, v2
	v_add_u32_e32 v3, 0x80, v3
	v_add_u32_e32 v1, 0x80, v1
	v_ashrrev_i32_e32 v0, 8, v0
	v_min_i32_e32 v2, 0x7f, v2
	v_ashrrev_i32_e32 v3, 8, v3
	v_ashrrev_i32_e32 v1, 8, v1
	v_min_i32_e32 v0, 0x7f, v0
	v_min_i32_sdwa v3, v3, s79 dst_sel:WORD_1 dst_unused:UNUSED_PAD src0_sel:DWORD src1_sel:DWORD
	v_min_i32_e32 v1, 0x7f, v1
	v_lshlrev_b32_e32 v2, 8, v2
	v_and_b32_e32 v2, 0xff00, v2
	v_and_b32_e32 v3, 0xff0000, v3
	v_perm_b32 v0, v1, v0, s80
	v_or3_b32 v0, v0, v2, v3
	ds_write_b32 v22, v0 offset:16
	buffer_store_dwordx4 v[172:175], v89, s[16:19], s33 offen
	v_mov_b32_e32 v0, v228
	v_mov_b32_e32 v1, v229
	v_mov_b32_e32 v2, v230
	v_mov_b32_e32 v3, v231
	v_mov_b32_e32 v4, v244
	v_mov_b32_e32 v5, v245
	v_mov_b32_e32 v6, v246
	v_mov_b32_e32 v7, v247
	v_mov_b32_e32 v44, v210
	v_mov_b32_e32 v45, v211
	v_pk_add_f32 v[46:47], v[54:55], v[44:45] op_sel_hi:[1,0] neg_lo:[0,1] neg_hi:[0,1]
	s_nop 0
	v_pk_mul_f32 v[46:47], v[44:45], v[46:47] op_sel:[1,0]
	v_pk_add_f32 v[52:53], v[52:53], v[44:45] op_sel_hi:[1,0] neg_lo:[0,1] neg_hi:[0,1]
	v_mov_b32_e32 v40, v1
	v_mov_b32_e32 v41, v2
	v_mov_b32_e32 v42, v5
	v_mov_b32_e32 v43, v6
	v_pk_fma_f32 v[46:47], v[40:41], v[46:47], v[42:43]
	v_pk_mul_f32 v[44:45], v[44:45], v[52:53] op_sel:[1,0]
	v_mov_b32_e32 v1, v3
	v_mov_b32_e32 v5, v7
	v_and_b32_sdwa v6, v47, v216 dst_sel:DWORD dst_unused:UNUSED_PAD src0_sel:WORD_1 src1_sel:DWORD
	v_and_b32_sdwa v7, v46, v216 dst_sel:DWORD dst_unused:UNUSED_PAD src0_sel:WORD_1 src1_sel:DWORD
	v_pk_fma_f32 v[2:3], v[0:1], v[44:45], v[4:5]
	v_add3_u32 v23, v47, v6, s78
	v_add3_u32 v6, v46, v7, s78
	v_and_b32_e32 v44, 0xffff0000, v6
	v_and_b32_sdwa v6, v3, v216 dst_sel:DWORD dst_unused:UNUSED_PAD src0_sel:WORD_1 src1_sel:DWORD
	v_and_b32_sdwa v7, v2, v216 dst_sel:DWORD dst_unused:UNUSED_PAD src0_sel:WORD_1 src1_sel:DWORD
	v_add3_u32 v6, v3, v6, s78
	v_add3_u32 v45, v2, v7, s78
	v_and_b32_e32 v52, 0xffff0000, v6
	v_or_b32_sdwa v7, v52, v23 dst_sel:DWORD dst_unused:UNUSED_PAD src0_sel:DWORD src1_sel:WORD_1
	v_or_b32_sdwa v6, v45, v44 dst_sel:DWORD dst_unused:UNUSED_PAD src0_sel:WORD_1 src1_sel:DWORD
	ds_write_b64 v107, v[6:7]
	v_and_b32_e32 v6, 0xffff0000, v45
	v_sub_u32_e32 v2, v2, v6
	v_sub_u32_e32 v6, v46, v44
	v_and_b32_e32 v7, 0xffff0000, v23
	v_add_u32_e32 v6, 0x80, v6
	v_sub_u32_e32 v7, v47, v7
	v_sub_u32_e32 v3, v3, v52
	v_add_u32_e32 v2, 0x80, v2
	v_ashrrev_i32_e32 v6, 8, v6
	v_add_u32_e32 v7, 0x80, v7
	v_add_u32_e32 v3, 0x80, v3
	v_ashrrev_i32_e32 v2, 8, v2
	v_min_i32_e32 v6, 0x7f, v6
	v_ashrrev_i32_e32 v7, 8, v7
	v_ashrrev_i32_e32 v3, 8, v3
	v_min_i32_e32 v2, 0x7f, v2
	v_min_i32_sdwa v7, v7, s79 dst_sel:WORD_1 dst_unused:UNUSED_PAD src0_sel:DWORD src1_sel:DWORD
	v_min_i32_e32 v3, 0x7f, v3
	v_lshlrev_b32_e32 v6, 8, v6
	v_and_b32_e32 v6, 0xff00, v6
	v_and_b32_e32 v7, 0xff0000, v7
	v_perm_b32 v2, v3, v2, s80
	v_or3_b32 v2, v2, v6, v7
	ds_write_b32 v12, v2 offset:128
	buffer_store_dwordx4 v[176:179], v146, s[20:23], s0 offen
	v_mov_b32_e32 v2, v212
	v_mov_b32_e32 v3, v213
	v_pk_add_f32 v[6:7], v[38:39], v[2:3] op_sel_hi:[1,0] neg_lo:[0,1] neg_hi:[0,1]
	s_nop 0
	v_pk_mul_f32 v[6:7], v[2:3], v[6:7] op_sel:[1,0]
	v_pk_add_f32 v[36:37], v[36:37], v[2:3] op_sel_hi:[1,0] neg_lo:[0,1] neg_hi:[0,1]
	v_pk_fma_f32 v[6:7], v[40:41], v[6:7], v[42:43]
	v_pk_mul_f32 v[2:3], v[2:3], v[36:37] op_sel:[1,0]
	v_and_b32_sdwa v36, v6, v216 dst_sel:DWORD dst_unused:UNUSED_PAD src0_sel:WORD_1 src1_sel:DWORD
	v_pk_fma_f32 v[2:3], v[0:1], v[2:3], v[4:5]
	v_add3_u32 v36, v6, v36, s78
	v_and_b32_e32 v38, 0xffff0000, v36
	v_and_b32_sdwa v36, v3, v216 dst_sel:DWORD dst_unused:UNUSED_PAD src0_sel:WORD_1 src1_sel:DWORD
	v_and_b32_sdwa v23, v7, v216 dst_sel:DWORD dst_unused:UNUSED_PAD src0_sel:WORD_1 src1_sel:DWORD
	v_and_b32_sdwa v37, v2, v216 dst_sel:DWORD dst_unused:UNUSED_PAD src0_sel:WORD_1 src1_sel:DWORD
	v_add3_u32 v36, v3, v36, s78
	v_add3_u32 v23, v7, v23, s78
	v_add3_u32 v39, v2, v37, s78
	v_and_b32_e32 v44, 0xffff0000, v36
	v_or_b32_sdwa v37, v44, v23 dst_sel:DWORD dst_unused:UNUSED_PAD src0_sel:DWORD src1_sel:WORD_1
	v_or_b32_sdwa v36, v39, v38 dst_sel:DWORD dst_unused:UNUSED_PAD src0_sel:WORD_1 src1_sel:DWORD
	ds_write_b64 v100, v[36:37]
	v_and_b32_e32 v36, 0xffff0000, v39
	v_sub_u32_e32 v6, v6, v38
	v_and_b32_e32 v23, 0xffff0000, v23
	v_sub_u32_e32 v2, v2, v36
	v_add_u32_e32 v6, 0x80, v6
	v_sub_u32_e32 v7, v7, v23
	v_sub_u32_e32 v3, v3, v44
	v_add_u32_e32 v2, 0x80, v2
	v_ashrrev_i32_e32 v6, 8, v6
	v_add_u32_e32 v7, 0x80, v7
	v_add_u32_e32 v3, 0x80, v3
	v_ashrrev_i32_e32 v2, 8, v2
	v_min_i32_e32 v6, 0x7f, v6
	v_ashrrev_i32_e32 v7, 8, v7
	v_ashrrev_i32_e32 v3, 8, v3
	v_min_i32_e32 v2, 0x7f, v2
	v_min_i32_sdwa v7, v7, s79 dst_sel:WORD_1 dst_unused:UNUSED_PAD src0_sel:DWORD src1_sel:DWORD
	v_min_i32_e32 v3, 0x7f, v3
	v_lshlrev_b32_e32 v6, 8, v6
	v_and_b32_e32 v6, 0xff00, v6
	v_and_b32_e32 v7, 0xff0000, v7
	v_perm_b32 v2, v3, v2, s80
	v_or3_b32 v2, v2, v6, v7
;     ...
;           _Pragma("unroll") for (int bj = 0; bj < 2; ++bj) _Pragma("unroll") for (int n = 0; n < 2; ++n) {
;             const int cc = bj * HALF + wc3 * 32 + n * 16 + fq3 * 4;
;             const float4 gm = *reinterpret_cast<const float4*>(g.gam + pn * BM + cc), bt = *reinterpret_cast<const float4*>(g.bet + pn * BM + cc);
;             _Pragma("unroll") for (int m = 0; m < 4; ++m) {
;               const int rr = wr3 * 64 + m * 16 + fr3;
;               const float2 ms = *reinterpret_cast<const float2*>(mr + (ai * HALF + rr) * 2);
;               f32x4 y = acc[ai][bj][m][n];
;               const float o0 = (y[0] - ms.x) * ms.y * gm.x + bt.x, o1 = (y[1] - ms.x) * ms.y * gm.y + bt.y;
;               const float o2 = (y[2] - ms.x) * ms.y * gm.z + bt.z, o3 = (y[3] - ms.x) * ms.y * gm.w + bt.w;
;               const unsigned h0 = f2bf(o0), h1 = f2bf(o1), h2 = f2bf(o2), h3 = f2bf(o3);
;               u32x2 ob; ob[0] = h0 | (h1 << 16); ob[1] = h2 | (h3 << 16);
;               *reinterpret_cast<u32x2*>(smem + (rr >> 1) * PIECE + (rr & 1) * 512 + cc * 2) = ob;
;               const int l0 = min(((int)__float_as_uint(o0) - (int)(h0 << 16) + 128) >> 8, 127);
;               const int l1 = min(((int)__float_as_uint(o1) - (int)(h1 << 16) + 128) >> 8, 127);
;               const int l2 = min(((int)__float_as_uint(o2) - (int)(h2 << 16) + 128) >> 8, 127);
;               const int l3 = min(((int)__float_as_uint(o3) - (int)(h3 << 16) + 128) >> 8, 127);
;               *reinterpret_cast<unsigned*>(smem + LOBASE + (rr >> 2) * PIECE + (rr & 3) * 256 + cc) =
;                   (unsigned)(l0 & 255) | ((unsigned)(l1 & 255) << 8) | ((unsigned)(l2 & 255) << 16) | ((unsigned)l3 << 24);
;             }
	ds_write_b32 v14, v2 offset:128
	buffer_store_dwordx4 v[180:183], v90, s[20:23], s0 offen
	v_mov_b32_e32 v2, v214
	v_mov_b32_e32 v3, v215
	v_pk_add_f32 v[6:7], v[26:27], v[2:3] op_sel_hi:[1,0] neg_lo:[0,1] neg_hi:[0,1]
	s_nop 0
	v_pk_mul_f32 v[6:7], v[2:3], v[6:7] op_sel:[1,0]
	v_pk_add_f32 v[24:25], v[24:25], v[2:3] op_sel_hi:[1,0] neg_lo:[0,1] neg_hi:[0,1]
	v_pk_fma_f32 v[6:7], v[40:41], v[6:7], v[42:43]
	v_pk_mul_f32 v[2:3], v[2:3], v[24:25] op_sel:[1,0]
	v_and_b32_sdwa v24, v6, v216 dst_sel:DWORD dst_unused:UNUSED_PAD src0_sel:WORD_1 src1_sel:DWORD
	v_pk_fma_f32 v[2:3], v[0:1], v[2:3], v[4:5]
	v_add3_u32 v24, v6, v24, s78
	v_and_b32_e32 v26, 0xffff0000, v24
	v_and_b32_sdwa v24, v3, v216 dst_sel:DWORD dst_unused:UNUSED_PAD src0_sel:WORD_1 src1_sel:DWORD
	v_and_b32_sdwa v23, v7, v216 dst_sel:DWORD dst_unused:UNUSED_PAD src0_sel:WORD_1 src1_sel:DWORD
	v_and_b32_sdwa v25, v2, v216 dst_sel:DWORD dst_unused:UNUSED_PAD src0_sel:WORD_1 src1_sel:DWORD
	v_add3_u32 v24, v3, v24, s78
	v_add3_u32 v23, v7, v23, s78
	v_add3_u32 v27, v2, v25, s78
	v_and_b32_e32 v36, 0xffff0000, v24
	v_or_b32_sdwa v25, v36, v23 dst_sel:DWORD dst_unused:UNUSED_PAD src0_sel:DWORD src1_sel:WORD_1
	v_or_b32_sdwa v24, v27, v26 dst_sel:DWORD dst_unused:UNUSED_PAD src0_sel:WORD_1 src1_sel:DWORD
	ds_write_b64 v101, v[24:25]
	v_and_b32_e32 v24, 0xffff0000, v27
	v_sub_u32_e32 v6, v6, v26
	v_and_b32_e32 v23, 0xffff0000, v23
	v_sub_u32_e32 v2, v2, v24
	v_add_u32_e32 v6, 0x80, v6
	v_sub_u32_e32 v7, v7, v23
	v_sub_u32_e32 v3, v3, v36
	v_add_u32_e32 v2, 0x80, v2
	v_ashrrev_i32_e32 v6, 8, v6
	v_add_u32_e32 v7, 0x80, v7
	v_add_u32_e32 v3, 0x80, v3
	v_ashrrev_i32_e32 v2, 8, v2
	v_min_i32_e32 v6, 0x7f, v6
	v_ashrrev_i32_e32 v7, 8, v7
	v_ashrrev_i32_e32 v3, 8, v3
	v_min_i32_e32 v2, 0x7f, v2
	v_min_i32_sdwa v7, v7, s79 dst_sel:WORD_1 dst_unused:UNUSED_PAD src0_sel:DWORD src1_sel:DWORD
	v_min_i32_e32 v3, 0x7f, v3
	v_lshlrev_b32_e32 v6, 8, v6
	v_and_b32_e32 v6, 0xff00, v6
	v_and_b32_e32 v7, 0xff0000, v7
	v_perm_b32 v2, v3, v2, s80
	v_or3_b32 v2, v2, v6, v7
	ds_write_b32 v20, v2 offset:128
	buffer_store_dwordx4 v[184:187], v91, s[20:23], s0 offen
	v_mov_b32_e32 v2, v252
	v_mov_b32_e32 v3, v253
	v_pk_add_f32 v[6:7], v[30:31], v[2:3] op_sel_hi:[1,0] neg_lo:[0,1] neg_hi:[0,1]
	s_nop 0
	v_pk_mul_f32 v[6:7], v[2:3], v[6:7] op_sel:[1,0]
	v_pk_add_f32 v[24:25], v[28:29], v[2:3] op_sel_hi:[1,0] neg_lo:[0,1] neg_hi:[0,1]
	v_pk_fma_f32 v[6:7], v[40:41], v[6:7], v[42:43]
	v_pk_mul_f32 v[2:3], v[2:3], v[24:25] op_sel:[1,0]
	s_nop 0
	v_pk_fma_f32 v[0:1], v[0:1], v[2:3], v[4:5]
	v_and_b32_sdwa v2, v7, v216 dst_sel:DWORD dst_unused:UNUSED_PAD src0_sel:WORD_1 src1_sel:DWORD
	v_and_b32_sdwa v3, v6, v216 dst_sel:DWORD dst_unused:UNUSED_PAD src0_sel:WORD_1 src1_sel:DWORD
	v_add3_u32 v4, v7, v2, s78
	v_add3_u32 v2, v6, v3, s78
	v_and_b32_e32 v5, 0xffff0000, v2
	v_and_b32_sdwa v2, v1, v216 dst_sel:DWORD dst_unused:UNUSED_PAD src0_sel:WORD_1 src1_sel:DWORD
	v_and_b32_sdwa v3, v0, v216 dst_sel:DWORD dst_unused:UNUSED_PAD src0_sel:WORD_1 src1_sel:DWORD
	v_add3_u32 v2, v1, v2, s78
	v_add3_u32 v23, v0, v3, s78
	v_and_b32_e32 v24, 0xffff0000, v2
	v_or_b32_sdwa v3, v24, v4 dst_sel:DWORD dst_unused:UNUSED_PAD src0_sel:DWORD src1_sel:WORD_1
	v_or_b32_sdwa v2, v23, v5 dst_sel:DWORD dst_unused:UNUSED_PAD src0_sel:WORD_1 src1_sel:DWORD
	ds_write_b64 v92, v[2:3]
	v_and_b32_e32 v2, 0xffff0000, v23
	v_sub_u32_e32 v0, v0, v2
	v_sub_u32_e32 v2, v6, v5
	v_and_b32_e32 v3, 0xffff0000, v4
	v_add_u32_e32 v2, 0x80, v2
	v_sub_u32_e32 v3, v7, v3
	v_sub_u32_e32 v1, v1, v24
	v_add_u32_e32 v0, 0x80, v0
	v_ashrrev_i32_e32 v2, 8, v2
	v_add_u32_e32 v3, 0x80, v3
	v_add_u32_e32 v1, 0x80, v1
	v_ashrrev_i32_e32 v0, 8, v0
	v_min_i32_e32 v2, 0x7f, v2
	v_ashrrev_i32_e32 v3, 8, v3
	v_ashrrev_i32_e32 v1, 8, v1
	v_min_i32_e32 v0, 0x7f, v0
	v_min_i32_sdwa v3, v3, s79 dst_sel:WORD_1 dst_unused:UNUSED_PAD src0_sel:DWORD src1_sel:DWORD
	v_min_i32_e32 v1, 0x7f, v1
	v_lshlrev_b32_e32 v2, 8, v2
	v_and_b32_e32 v2, 0xff00, v2
	v_and_b32_e32 v3, 0xff0000, v3
	v_perm_b32 v0, v1, v0, s80
	v_or3_b32 v0, v0, v2, v3
	ds_write_b32 v22, v0 offset:128
	buffer_store_dwordx4 v[188:191], v95, s[20:23], s0 offen
	v_mov_b32_e32 v0, v232
	v_mov_b32_e32 v1, v233
	v_mov_b32_e32 v2, v234
	v_mov_b32_e32 v3, v235
	v_mov_b32_e32 v4, v248
	v_mov_b32_e32 v5, v249
	v_mov_b32_e32 v6, v250
	v_mov_b32_e32 v7, v251
	v_mov_b32_e32 v28, v210
	v_mov_b32_e32 v29, v211
	s_mov_b64 s[4:5], -1
	v_pk_add_f32 v[30:31], v[50:51], v[28:29] op_sel_hi:[1,0] neg_lo:[0,1] neg_hi:[0,1]
	s_nop 0
	v_pk_mul_f32 v[30:31], v[28:29], v[30:31] op_sel:[1,0]
	v_pk_add_f32 v[36:37], v[48:49], v[28:29] op_sel_hi:[1,0] neg_lo:[0,1] neg_hi:[0,1]
	v_mov_b32_e32 v24, v1
	v_mov_b32_e32 v25, v2
	v_mov_b32_e32 v26, v5
	v_mov_b32_e32 v27, v6
	v_pk_fma_f32 v[30:31], v[24:25], v[30:31], v[26:27]
	v_pk_mul_f32 v[28:29], v[28:29], v[36:37] op_sel:[1,0]
	v_mov_b32_e32 v1, v3
	v_mov_b32_e32 v5, v7
	v_and_b32_sdwa v6, v31, v216 dst_sel:DWORD dst_unused:UNUSED_PAD src0_sel:WORD_1 src1_sel:DWORD
	v_and_b32_sdwa v7, v30, v216 dst_sel:DWORD dst_unused:UNUSED_PAD src0_sel:WORD_1 src1_sel:DWORD
	v_pk_fma_f32 v[2:3], v[0:1], v[28:29], v[4:5]
	v_add3_u32 v23, v31, v6, s78
	v_add3_u32 v6, v30, v7, s78
	v_and_b32_e32 v28, 0xffff0000, v6
	v_and_b32_sdwa v6, v3, v216 dst_sel:DWORD dst_unused:UNUSED_PAD src0_sel:WORD_1 src1_sel:DWORD
	v_and_b32_sdwa v7, v2, v216 dst_sel:DWORD dst_unused:UNUSED_PAD src0_sel:WORD_1 src1_sel:DWORD
	v_add3_u32 v6, v3, v6, s78
	v_add3_u32 v29, v2, v7, s78
	v_and_b32_e32 v36, 0xffff0000, v6
	v_or_b32_sdwa v7, v36, v23 dst_sel:DWORD dst_unused:UNUSED_PAD src0_sel:DWORD src1_sel:WORD_1
; #define WAIT_L(n) asm volatile("s_waitcnt lgkmcnt(" #n ")" ::: "memory")
; #define BAR __builtin_amdgcn_s_barrier()
;     ...
;           _Pragma("unroll") for (int bj = 0; bj < 2; ++bj) _Pragma("unroll") for (int n = 0; n < 2; ++n) {
;             const int cc = bj * HALF + wc3 * 32 + n * 16 + fq3 * 4;
;             const float4 gm = *reinterpret_cast<const float4*>(g.gam + pn * BM + cc), bt = *reinterpret_cast<const float4*>(g.bet + pn * BM + cc);
;             _Pragma("unroll") for (int m = 0; m < 4; ++m) {
;               const int rr = wr3 * 64 + m * 16 + fr3;
;               const float2 ms = *reinterpret_cast<const float2*>(mr + (ai * HALF + rr) * 2);
;               f32x4 y = acc[ai][bj][m][n];
;               const float o0 = (y[0] - ms.x) * ms.y * gm.x + bt.x, o1 = (y[1] - ms.x) * ms.y * gm.y + bt.y;
;               const float o2 = (y[2] - ms.x) * ms.y * gm.z + bt.z, o3 = (y[3] - ms.x) * ms.y * gm.w + bt.w;
;               const unsigned h0 = f2bf(o0), h1 = f2bf(o1), h2 = f2bf(o2), h3 = f2bf(o3);
;               u32x2 ob; ob[0] = h0 | (h1 << 16); ob[1] = h2 | (h3 << 16);
;               *reinterpret_cast<u32x2*>(smem + (rr >> 1) * PIECE + (rr & 1) * 512 + cc * 2) = ob;
;               const int l0 = min(((int)__float_as_uint(o0) - (int)(h0 << 16) + 128) >> 8, 127);
;               const int l1 = min(((int)__float_as_uint(o1) - (int)(h1 << 16) + 128) >> 8, 127);
;               const int l2 = min(((int)__float_as_uint(o2) - (int)(h2 << 16) + 128) >> 8, 127);
;               const int l3 = min(((int)__float_as_uint(o3) - (int)(h3 << 16) + 128) >> 8, 127);
;               *reinterpret_cast<unsigned*>(smem + LOBASE + (rr >> 2) * PIECE + (rr & 3) * 256 + cc) =
;                   (unsigned)(l0 & 255) | ((unsigned)(l1 & 255) << 8) | ((unsigned)(l2 & 255) << 16) | ((unsigned)l3 << 24);
;             }
;           }
;           WAIT_L(0); BAR;
	v_or_b32_sdwa v6, v29, v28 dst_sel:DWORD dst_unused:UNUSED_PAD src0_sel:WORD_1 src1_sel:DWORD
	ds_write_b64 v93, v[6:7]
	v_and_b32_e32 v6, 0xffff0000, v29
	v_sub_u32_e32 v2, v2, v6
	v_sub_u32_e32 v6, v30, v28
	v_and_b32_e32 v7, 0xffff0000, v23
	v_add_u32_e32 v6, 0x80, v6
	v_sub_u32_e32 v7, v31, v7
	v_sub_u32_e32 v3, v3, v36
	v_add_u32_e32 v2, 0x80, v2
	v_ashrrev_i32_e32 v6, 8, v6
	v_add_u32_e32 v7, 0x80, v7
	v_add_u32_e32 v3, 0x80, v3
	v_ashrrev_i32_e32 v2, 8, v2
	v_min_i32_e32 v6, 0x7f, v6
	v_ashrrev_i32_e32 v7, 8, v7
	v_ashrrev_i32_e32 v3, 8, v3
	v_min_i32_e32 v2, 0x7f, v2
	v_min_i32_sdwa v7, v7, s79 dst_sel:WORD_1 dst_unused:UNUSED_PAD src0_sel:DWORD src1_sel:DWORD
	v_min_i32_e32 v3, 0x7f, v3
	v_lshlrev_b32_e32 v6, 8, v6
	v_and_b32_e32 v6, 0xff00, v6
	v_and_b32_e32 v7, 0xff0000, v7
	v_perm_b32 v2, v3, v2, s80
	v_or3_b32 v2, v2, v6, v7
	ds_write_b32 v12, v2 offset:144
	v_mov_b32_e32 v2, v212
	v_mov_b32_e32 v3, v213
	v_pk_add_f32 v[6:7], v[34:35], v[2:3] op_sel_hi:[1,0] neg_lo:[0,1] neg_hi:[0,1]
	s_nop 0
	v_pk_mul_f32 v[6:7], v[2:3], v[6:7] op_sel:[1,0]
	v_pk_add_f32 v[12:13], v[32:33], v[2:3] op_sel_hi:[1,0] neg_lo:[0,1] neg_hi:[0,1]
	v_pk_fma_f32 v[6:7], v[24:25], v[6:7], v[26:27]
	v_pk_mul_f32 v[2:3], v[2:3], v[12:13] op_sel:[1,0]
	v_and_b32_sdwa v12, v7, v216 dst_sel:DWORD dst_unused:UNUSED_PAD src0_sel:WORD_1 src1_sel:DWORD
	v_and_b32_sdwa v13, v6, v216 dst_sel:DWORD dst_unused:UNUSED_PAD src0_sel:WORD_1 src1_sel:DWORD
	v_pk_fma_f32 v[2:3], v[0:1], v[2:3], v[4:5]
	v_add3_u32 v23, v7, v12, s78
	v_add3_u32 v12, v6, v13, s78
	v_and_b32_e32 v28, 0xffff0000, v12
	v_and_b32_sdwa v12, v3, v216 dst_sel:DWORD dst_unused:UNUSED_PAD src0_sel:WORD_1 src1_sel:DWORD
	v_and_b32_sdwa v13, v2, v216 dst_sel:DWORD dst_unused:UNUSED_PAD src0_sel:WORD_1 src1_sel:DWORD
	v_add3_u32 v12, v3, v12, s78
	v_add3_u32 v29, v2, v13, s78
	v_and_b32_e32 v30, 0xffff0000, v12
	v_or_b32_sdwa v13, v30, v23 dst_sel:DWORD dst_unused:UNUSED_PAD src0_sel:DWORD src1_sel:WORD_1
	v_or_b32_sdwa v12, v29, v28 dst_sel:DWORD dst_unused:UNUSED_PAD src0_sel:WORD_1 src1_sel:DWORD
	ds_write_b64 v94, v[12:13]
	v_and_b32_e32 v12, 0xffff0000, v29
	v_sub_u32_e32 v2, v2, v12
	v_sub_u32_e32 v6, v6, v28
	v_and_b32_e32 v12, 0xffff0000, v23
	v_add_u32_e32 v6, 0x80, v6
	v_sub_u32_e32 v7, v7, v12
	v_sub_u32_e32 v3, v3, v30
	v_add_u32_e32 v2, 0x80, v2
	v_ashrrev_i32_e32 v6, 8, v6
	v_add_u32_e32 v7, 0x80, v7
	v_add_u32_e32 v3, 0x80, v3
	v_ashrrev_i32_e32 v2, 8, v2
	v_min_i32_e32 v6, 0x7f, v6
	v_ashrrev_i32_e32 v7, 8, v7
	v_ashrrev_i32_e32 v3, 8, v3
	v_min_i32_e32 v2, 0x7f, v2
	v_min_i32_sdwa v7, v7, s79 dst_sel:WORD_1 dst_unused:UNUSED_PAD src0_sel:DWORD src1_sel:DWORD
	v_min_i32_e32 v3, 0x7f, v3
	v_lshlrev_b32_e32 v6, 8, v6
	v_and_b32_e32 v6, 0xff00, v6
	v_and_b32_e32 v7, 0xff0000, v7
	v_perm_b32 v2, v3, v2, s80
	v_or3_b32 v2, v2, v6, v7
	ds_write_b32 v14, v2 offset:144
	v_mov_b32_e32 v2, v214
	v_mov_b32_e32 v3, v215
	v_pk_add_f32 v[6:7], v[18:19], v[2:3] op_sel_hi:[1,0] neg_lo:[0,1] neg_hi:[0,1]
	s_nop 0
	v_pk_mul_f32 v[6:7], v[2:3], v[6:7] op_sel:[1,0]
	v_pk_add_f32 v[12:13], v[16:17], v[2:3] op_sel_hi:[1,0] neg_lo:[0,1] neg_hi:[0,1]
	v_pk_fma_f32 v[6:7], v[24:25], v[6:7], v[26:27]
	v_pk_mul_f32 v[2:3], v[2:3], v[12:13] op_sel:[1,0]
	v_and_b32_sdwa v12, v7, v216 dst_sel:DWORD dst_unused:UNUSED_PAD src0_sel:WORD_1 src1_sel:DWORD
	v_and_b32_sdwa v13, v6, v216 dst_sel:DWORD dst_unused:UNUSED_PAD src0_sel:WORD_1 src1_sel:DWORD
	v_pk_fma_f32 v[2:3], v[0:1], v[2:3], v[4:5]
	v_add3_u32 v14, v7, v12, s78
	v_add3_u32 v12, v6, v13, s78
	v_and_b32_e32 v15, 0xffff0000, v12
	v_and_b32_sdwa v12, v3, v216 dst_sel:DWORD dst_unused:UNUSED_PAD src0_sel:WORD_1 src1_sel:DWORD
	v_and_b32_sdwa v13, v2, v216 dst_sel:DWORD dst_unused:UNUSED_PAD src0_sel:WORD_1 src1_sel:DWORD
	v_add3_u32 v12, v3, v12, s78
	v_add3_u32 v16, v2, v13, s78
	v_and_b32_e32 v17, 0xffff0000, v12
	v_or_b32_sdwa v13, v17, v14 dst_sel:DWORD dst_unused:UNUSED_PAD src0_sel:DWORD src1_sel:WORD_1
	v_or_b32_sdwa v12, v16, v15 dst_sel:DWORD dst_unused:UNUSED_PAD src0_sel:WORD_1 src1_sel:DWORD
	ds_write_b64 v80, v[12:13]
	v_and_b32_e32 v12, 0xffff0000, v16
	v_sub_u32_e32 v2, v2, v12
	v_sub_u32_e32 v6, v6, v15
	v_and_b32_e32 v12, 0xffff0000, v14
	v_add_u32_e32 v6, 0x80, v6
	v_sub_u32_e32 v7, v7, v12
	v_sub_u32_e32 v3, v3, v17
	v_add_u32_e32 v2, 0x80, v2
	v_ashrrev_i32_e32 v6, 8, v6
	v_add_u32_e32 v7, 0x80, v7
	v_add_u32_e32 v3, 0x80, v3
	v_ashrrev_i32_e32 v2, 8, v2
	v_min_i32_e32 v6, 0x7f, v6
	v_ashrrev_i32_e32 v7, 8, v7
	v_ashrrev_i32_e32 v3, 8, v3
	v_min_i32_e32 v2, 0x7f, v2
	v_min_i32_sdwa v7, v7, s79 dst_sel:WORD_1 dst_unused:UNUSED_PAD src0_sel:DWORD src1_sel:DWORD
	v_min_i32_e32 v3, 0x7f, v3
	v_lshlrev_b32_e32 v6, 8, v6
	v_and_b32_e32 v6, 0xff00, v6
	v_and_b32_e32 v7, 0xff0000, v7
	v_perm_b32 v2, v3, v2, s80
	v_or3_b32 v2, v2, v6, v7
	ds_write_b32 v20, v2 offset:144
	v_mov_b32_e32 v2, v252
	v_mov_b32_e32 v3, v253
	v_pk_add_f32 v[6:7], v[10:11], v[2:3] op_sel_hi:[1,0] neg_lo:[0,1] neg_hi:[0,1]
	s_nop 0
	v_pk_mul_f32 v[6:7], v[2:3], v[6:7] op_sel:[1,0]
	v_pk_add_f32 v[8:9], v[8:9], v[2:3] op_sel_hi:[1,0] neg_lo:[0,1] neg_hi:[0,1]
	v_pk_fma_f32 v[6:7], v[24:25], v[6:7], v[26:27]
	v_pk_mul_f32 v[2:3], v[2:3], v[8:9] op_sel:[1,0]
	s_nop 0
	v_pk_fma_f32 v[0:1], v[0:1], v[2:3], v[4:5]
	v_and_b32_sdwa v2, v7, v216 dst_sel:DWORD dst_unused:UNUSED_PAD src0_sel:WORD_1 src1_sel:DWORD
	v_and_b32_sdwa v3, v6, v216 dst_sel:DWORD dst_unused:UNUSED_PAD src0_sel:WORD_1 src1_sel:DWORD
	v_add3_u32 v4, v7, v2, s78
	v_add3_u32 v2, v6, v3, s78
	v_and_b32_e32 v5, 0xffff0000, v2
	v_and_b32_sdwa v2, v1, v216 dst_sel:DWORD dst_unused:UNUSED_PAD src0_sel:WORD_1 src1_sel:DWORD
	v_and_b32_sdwa v3, v0, v216 dst_sel:DWORD dst_unused:UNUSED_PAD src0_sel:WORD_1 src1_sel:DWORD
	v_add3_u32 v2, v1, v2, s78
	v_add3_u32 v8, v0, v3, s78
	v_and_b32_e32 v9, 0xffff0000, v2
	v_or_b32_sdwa v3, v9, v4 dst_sel:DWORD dst_unused:UNUSED_PAD src0_sel:DWORD src1_sel:WORD_1
	v_or_b32_sdwa v2, v8, v5 dst_sel:DWORD dst_unused:UNUSED_PAD src0_sel:WORD_1 src1_sel:DWORD
	ds_write_b64 v73, v[2:3]
	v_and_b32_e32 v2, 0xffff0000, v8
	v_sub_u32_e32 v0, v0, v2
	v_sub_u32_e32 v2, v6, v5
	v_and_b32_e32 v3, 0xffff0000, v4
	v_add_u32_e32 v2, 0x80, v2
	v_sub_u32_e32 v3, v7, v3
	v_sub_u32_e32 v1, v1, v9
	v_add_u32_e32 v0, 0x80, v0
	v_ashrrev_i32_e32 v2, 8, v2
	v_add_u32_e32 v3, 0x80, v3
	v_add_u32_e32 v1, 0x80, v1
	v_ashrrev_i32_e32 v0, 8, v0
	v_min_i32_e32 v2, 0x7f, v2
	v_ashrrev_i32_e32 v3, 8, v3
	v_ashrrev_i32_e32 v1, 8, v1
	v_min_i32_e32 v0, 0x7f, v0
	v_min_i32_sdwa v3, v3, s79 dst_sel:WORD_1 dst_unused:UNUSED_PAD src0_sel:DWORD src1_sel:DWORD
	v_min_i32_e32 v1, 0x7f, v1
	v_lshlrev_b32_e32 v2, 8, v2
	v_and_b32_e32 v2, 0xff00, v2
	v_and_b32_e32 v3, 0xff0000, v3
	v_perm_b32 v0, v1, v0, s80
	v_or3_b32 v0, v0, v2, v3
	ds_write_b32 v22, v0 offset:144
	s_waitcnt lgkmcnt(0)
	s_barrier
; #define STAGE(P, RS, SOFF, OFF, kt) do { const int _so = (SOFF) + (kt) * (BK * 2); \
;     _Pragma("unroll") for (int _i = 0; _i < 2; ++_i) { \
;       __builtin_amdgcn_raw_ptr_buffer_load_lds(RS, (__attribute__((address_space(3))) void*)((P) + wave * 1024 + _i * 8192), 16, OFF[_i], _so, 0, 0); } } while (0)
; #define WAIT_L(n) asm volatile("s_waitcnt lgkmcnt(" #n ")" ::: "memory")
; #define BAR __builtin_amdgcn_s_barrier()
;     ...
;   auto issue_prologue = [&](int sA0, int sA1, int sB0, int sB1) {
;     const int tid = opaque_tid(wave);
;     int offA[2], offB[2];
;     _Pragma("unroll") for (int i = 0; i < 2; ++i) {
;       int r, c; stage_rc(tid * 16 + i * 8192, r, c);
;       offA[i] = (r * lda + c) * 2; offB[i] = (r * ldb + c) * 2;
;     }
;     STAGE(SB(0, 0), rsB, sB0, offB, 0); STAGE(SA(0, 0), rsA, sA0, offA, 0);
;     STAGE(SB(0, 1), rsB, sB1, offB, 0); STAGE(SA(0, 1), rsA, sA1, offA, 0);
;     STAGE(SB(1, 0), rsB, sB0, offB, 1); STAGE(SA(1, 0), rsA, sA0, offA, 1); STAGE(SB(1, 1), rsB, sB1, offB, 1);
;   };
;     ...
;           WAIT_L(0); BAR;
;           const int hso = ((brow + ai * HALF + 16 * wave) * DM + pn * BM) * 2;
;           const int lso = (brow + ai * HALF + 16 * wave) * DM + pn * BM;
;           _Pragma("unroll") for (int i = 0; i < 8; ++i) {
;             const u32x4 v = *reinterpret_cast<const u32x4*>(smem + (wave * 8 + i) * PIECE + lane3 * 16);
;             __builtin_amdgcn_raw_buffer_store_b128(v, rsXB, hvo + i * (2 * DM * 2), hso, 0);
;           }
;           _Pragma("unroll") for (int i = 0; i < 4; ++i) {
;             const u32x4 v = *reinterpret_cast<const u32x4*>(smem + LOBASE + (wave * 4 + i) * PIECE + lane3 * 16);
;             __builtin_amdgcn_raw_buffer_store_b128(v, rsLO, lvo + i * (4 * DM), lso, 0);
;           }
;           WAIT_L(0); BAR;
;         }
;       }
;       if (has_next) issue_prologue(nA0, nA1, nB0, nB1);
	ds_read_b128 v[128:131], v72
	ds_read_b128 v[132:135], v72 offset:1040
	ds_read_b128 v[136:139], v72 offset:2080
	ds_read_b128 v[140:143], v72 offset:3120
	ds_read_b128 v[152:155], v72 offset:4160
	ds_read_b128 v[156:159], v72 offset:5200
	ds_read_b128 v[160:163], v72 offset:6240
	ds_read_b128 v[164:167], v72 offset:7280
	ds_read_b128 v[168:171], v147
	ds_read_b128 v[172:175], v147 offset:1040
	ds_read_b128 v[176:179], v147 offset:2080
	ds_read_b128 v[180:183], v147 offset:3120
	s_waitcnt lgkmcnt(0)
	s_barrier
	s_cbranch_vccnz .Lmy_s1n_480
	v_mbcnt_lo_u32_b32 v0, -1, 0
	v_mbcnt_hi_u32_b32 v0, -1, v0
	s_mov_b32 m0, s37
	v_lshl_add_u32 v0, v0, 4, s35
	v_ashrrev_i32_e32 v1, 31, v0
	v_lshrrev_b32_e32 v1, 22, v1
	v_add_u32_e32 v1, v0, v1
	v_ashrrev_i32_e32 v1, 10, v1
	v_mul_i32_i24_e32 v2, 0x400, v1
	v_sub_u32_e32 v2, v0, v2
	v_lshrrev_b32_e32 v3, 4, v2
	v_bitop3_b32 v2, v3, v2, 32 bitop3:0x6c
	v_ashrrev_i32_e32 v4, 31, v2
	v_lshrrev_b32_e32 v4, 26, v4
	v_add_u32_e32 v4, v2, v4
	v_lshrrev_b32_e32 v5, 6, v4
	v_and_b32_e32 v4, 0xc0, v4
	v_lshlrev_b32_e32 v3, 3, v1
	v_lshlrev_b32_e32 v1, 5, v1
	v_sub_u32_e32 v2, v2, v4
	v_and_b32_e32 v3, 0x7fff0, v3
	v_and_b32_e32 v1, 32, v1
	v_ashrrev_i16_sdwa v2, v216, sext(v2) dst_sel:DWORD dst_unused:UNUSED_PAD src0_sel:DWORD src1_sel:BYTE_0
	v_add_u32_sdwa v1, v1, sext(v2) dst_sel:DWORD dst_unused:UNUSED_PAD src0_sel:DWORD src1_sel:WORD_0
	v_add_lshl_u32 v2, v5, v3, 13
	v_add_u32_e32 v0, 0x2000, v0
	v_lshl_add_u32 v1, v1, 1, v2
	v_ashrrev_i32_e32 v2, 31, v0
	v_lshrrev_b32_e32 v2, 22, v2
	v_add_u32_e32 v2, v0, v2
	v_ashrrev_i32_e32 v2, 10, v2
	v_mul_i32_i24_e32 v3, 0x400, v2
	v_sub_u32_e32 v0, v0, v3
	v_lshrrev_b32_e32 v3, 4, v0
	v_bitop3_b32 v0, v3, v0, 32 bitop3:0x6c
	v_ashrrev_i32_e32 v4, 31, v0
	v_lshrrev_b32_e32 v4, 26, v4
	v_add_u32_e32 v4, v0, v4
	v_lshrrev_b32_e32 v5, 6, v4
	v_and_b32_e32 v4, 0xffc0, v4
	v_sub_u32_e32 v0, v0, v4
	v_lshrrev_b16_e32 v4, 7, v0
	v_and_b32_e32 v4, 1, v4
	v_lshlrev_b32_e32 v3, 3, v2
	v_lshlrev_b32_e32 v2, 5, v2
	v_add_u16_e32 v0, v0, v4
	v_and_b32_e32 v3, 0x7fff0, v3
	v_and_b32_e32 v2, 32, v2
	v_ashrrev_i16_sdwa v0, v216, sext(v0) dst_sel:DWORD dst_unused:UNUSED_PAD src0_sel:DWORD src1_sel:BYTE_0
	v_add_u32_sdwa v0, v2, sext(v0) dst_sel:DWORD dst_unused:UNUSED_PAD src0_sel:DWORD src1_sel:WORD_0
	v_add_lshl_u32 v2, v5, v3, 13
	s_mov_b32 s14, s10
	s_mov_b32 s15, s11
	v_lshl_add_u32 v0, v0, 1, v2
	buffer_load_dwordx4 v1, s[12:15], s84 offen lds
	s_mov_b32 m0, s70
	s_or_b32 s0, s84, 0x80
	buffer_load_dwordx4 v0, s[12:15], s84 offen lds
	s_mov_b32 m0, s35
	s_mov_b64 s[4:5], 0
	buffer_load_dwordx4 v1, s[8:11], s83 offen lds
	s_mov_b32 m0, s95
	s_nop 0
	buffer_load_dwordx4 v0, s[8:11], s83 offen lds
	s_mov_b32 m0, s38
	s_nop 0
	buffer_load_dwordx4 v1, s[12:15], s85 offen lds
	s_mov_b32 m0, s71
	s_nop 0
	buffer_load_dwordx4 v0, s[12:15], s85 offen lds
	s_mov_b32 m0, s39
	s_nop 0
	buffer_load_dwordx4 v1, s[8:11], s82 offen lds
	s_mov_b32 m0, s97
	s_nop 0
	buffer_load_dwordx4 v0, s[8:11], s82 offen lds
	s_mov_b32 m0, s92
	s_nop 0
	buffer_load_dwordx4 v1, s[12:15], s0 offen lds
	s_mov_b32 m0, s56
	s_nop 0
	buffer_load_dwordx4 v0, s[12:15], s0 offen lds
	s_or_b32 s0, s83, 0x80
	s_mov_b32 m0, s93
	s_nop 0
	buffer_load_dwordx4 v1, s[8:11], s0 offen lds
	s_mov_b32 m0, s57
	s_nop 0
	buffer_load_dwordx4 v0, s[8:11], s0 offen lds
	s_add_i32 s0, s85, 0x80
	s_mov_b32 m0, s94
	s_nop 0
	buffer_load_dwordx4 v1, s[12:15], s0 offen lds
	s_mov_b32 m0, s58
	s_nop 0
	buffer_load_dwordx4 v0, s[12:15], s0 offen lds
	buffer_store_dwordx4 v[128:131], v148, s[16:19], s3 offen
	buffer_store_dwordx4 v[132:135], v74, s[16:19], s3 offen
	buffer_store_dwordx4 v[136:139], v75, s[16:19], s3 offen
	buffer_store_dwordx4 v[140:143], v81, s[16:19], s3 offen
	buffer_store_dwordx4 v[152:155], v82, s[16:19], s3 offen
	buffer_store_dwordx4 v[156:159], v83, s[16:19], s3 offen
	buffer_store_dwordx4 v[160:163], v88, s[16:19], s3 offen
	buffer_store_dwordx4 v[164:167], v89, s[16:19], s3 offen
	buffer_store_dwordx4 v[168:171], v146, s[20:23], s1 offen
	buffer_store_dwordx4 v[172:175], v90, s[20:23], s1 offen
	buffer_store_dwordx4 v[176:179], v91, s[20:23], s1 offen
	buffer_store_dwordx4 v[180:183], v95, s[20:23], s1 offen
	s_branch .LBB0_486

;     ...
;       const int tid3 = opaque_tid(wave);
;       const int wr3 = tid3 >> 8, wc3 = (tid3 >> 6) & 3, fr3 = tid3 & 15, fq3 = (tid3 & 63) >> 4;
;       const int ebase3 = (brow + wr3 * 64 + fr3) * DM + pn * BM + wc3 * 32 + fq3 * 4;
;       const int vo4b = ebase3 * 4, vo2 = ebase3 * 2, vo1 = ebase3;
;       (void)vo4b; (void)vo2; (void)vo1;
;       if constexpr (OUTF) {
;         _Pragma("unroll") for (int bj = 0; bj < 2; ++bj) _Pragma("unroll") for (int n = 0; n < 2; ++n) {
;           const int col = pn * BM + bj * HALF + wc3 * 32 + n * 16 + fq3 * 4;
;           const float4 gm = *reinterpret_cast<const float4*>(g.gam + col), bt = *reinterpret_cast<const float4*>(g.bet + col);
;           _Pragma("unroll") for (int ai = 0; ai < 2; ++ai) _Pragma("unroll") for (int m = 0; m < 4; ++m) {
;             const int rl = ai * HALF + wr3 * 64 + m * 16 + fr3;
;             const float2 ms = *reinterpret_cast<const float2*>(mr + rl * 2);
;             f32x4 y = acc[ai][bj][m][n];
;             u32x4 o;
;             o[0] = __float_as_uint((y[0] - ms.x) * ms.y * gm.x + bt.x); o[1] = __float_as_uint((y[1] - ms.x) * ms.y * gm.y + bt.y);
;             o[2] = __float_as_uint((y[2] - ms.x) * ms.y * gm.z + bt.z); o[3] = __float_as_uint((y[3] - ms.x) * ms.y * gm.w + bt.w);
;             __builtin_amdgcn_raw_buffer_store_b128(o, rsO, vo4b + ((ai * HALF + m * 16) * DM + bj * HALF + n * 16) * 4, 0, 0);
;           }
;         }
;       } else {
;         constexpr int PIECE = 1024 + 16, LOBASE = 64 * PIECE;
;         const int lane3 = tid3 & 63;
;         const int hvo = (lane3 >> 5) * (DM * 2) + (lane3 & 31) * 16;
;         const int lvo = (lane3 >> 4) * DM + (lane3 & 15) * 16;
;         _Pragma("unroll") for (int ai = 0; ai < 2; ++ai) {
;           _Pragma("unroll") for (int bj = 0; bj < 2; ++bj) _Pragma("unroll") for (int n = 0; n < 2; ++n) {
;             const int cc = bj * HALF + wc3 * 32 + n * 16 + fq3 * 4;
;             const float4 gm = *reinterpret_cast<const float4*>(g.gam + pn * BM + cc), bt = *reinterpret_cast<const float4*>(g.bet + pn * BM + cc);
;             _Pragma("unroll") for (int m = 0; m < 4; ++m) {
;               const int rr = wr3 * 64 + m * 16 + fr3;
;               const float2 ms = *reinterpret_cast<const float2*>(mr + (ai * HALF + rr) * 2);
;               f32x4 y = acc[ai][bj][m][n];
.LBB0_686:
	s_or_b64 exec, exec, s[6:7]
	s_waitcnt lgkmcnt(0)
	s_barrier
	v_mbcnt_lo_u32_b32 v0, -1, 0
	v_mbcnt_hi_u32_b32 v0, -1, v0
	s_ashr_i32 s35, s34, 31
	v_add_u32_e32 v1, s37, v0
	v_bfe_u32 v4, v0, 4, 2
	v_ashrrev_i32_e32 v5, 2, v1
	v_lshrrev_b32_e32 v6, 1, v1
	v_lshlrev_b32_e32 v1, 4, v1
	v_readlane_b32 s40, v255, 16
	v_lshlrev_b32_e32 v7, 2, v4
	v_lshlrev_b32_e32 v12, 7, v0
	v_and_b32_e32 v13, 0x1f0, v1
	s_movk_i32 s2, 0x60
	s_lshl_b64 s[4:5], s[34:35], 2
	v_readlane_b32 s50, v255, 26
	v_and_or_b32 v148, v12, s72, v13
	v_and_or_b32 v12, v6, s2, v7
	v_readlane_b32 s51, v255, 27
	s_add_u32 s6, s50, s4
	v_and_b32_e32 v2, 15, v0
	v_and_b32_e32 v3, 63, v0
	v_and_b32_e32 v1, 0xf0, v1
	v_lshlrev_b32_e32 v13, 9, v0
	v_lshlrev_b32_e32 v0, 8, v0
	s_addc_u32 s7, s51, s5
	v_lshlrev_b32_e32 v150, 2, v12
	v_lshl_or_b32 v146, v4, 11, v1
	v_and_or_b32 v155, v5, s36, v2
	v_and_b32_e32 v14, 0x300, v0
	v_lshlrev_b32_e32 v151, 4, v3
	global_load_dwordx4 v[220:223], v150, s[6:7]
	global_load_dwordx4 v[224:227], v150, s[6:7] offset:64
	global_load_dwordx4 v[228:231], v150, s[6:7] offset:512
	global_load_dwordx4 v[232:235], v150, s[6:7] offset:576
	v_readlane_b32 s52, v255, 28
	v_readlane_b32 s53, v255, 29
	s_add_u32 s4, s52, s4
	s_addc_u32 s5, s53, s5
	global_load_dwordx4 v[236:239], v150, s[4:5]
	global_load_dwordx4 v[240:243], v150, s[4:5] offset:64
	global_load_dwordx4 v[244:247], v150, s[4:5] offset:512
	global_load_dwordx4 v[248:251], v150, s[4:5] offset:576
	s_movk_i32 s22, 0x200
	v_lshl_add_u32 v149, v155, 3, v219
	v_add_u32_e32 v147, s68, v151
	s_andn2_b64 vcc, exec, s[14:15]
	v_readlane_b32 s41, v255, 17
	v_readlane_b32 s42, v255, 18
	v_readlane_b32 s43, v255, 19
	v_readlane_b32 s44, v255, 20
	v_readlane_b32 s45, v255, 21
	v_readlane_b32 s46, v255, 22
	v_readlane_b32 s47, v255, 23
	v_readlane_b32 s48, v255, 24
	v_readlane_b32 s49, v255, 25
	v_readlane_b32 s54, v255, 30
	v_readlane_b32 s55, v255, 31
	s_waitcnt vmcnt(0)
	v_mov_b32_e32 v0, v220
	v_mov_b32_e32 v1, v221
	v_mov_b32_e32 v2, v222
	v_mov_b32_e32 v3, v223
	v_mov_b32_e32 v4, v236
	v_mov_b32_e32 v5, v237
	v_mov_b32_e32 v6, v238
	v_mov_b32_e32 v7, v239
	v_mov_b32_e32 v22, v1
	v_lshlrev_b32_e32 v1, 1, v12
	v_and_or_b32 v154, v13, s22, v1
	s_mov_b32 s22, 0x10400
	v_mov_b32_e32 v23, v2
	v_or3_b32 v2, v14, v12, s22
	ds_read_b64 v[12:13], v149
	v_mov_b32_e32 v144, v5
	v_mov_b32_e32 v145, v6
	v_mov_b32_e32 v1, v3
	v_mov_b32_e32 v5, v7
	s_waitcnt lgkmcnt(0)
	v_mov_b32_e32 v202, v12
	v_mov_b32_e32 v203, v13
	v_pk_add_f32 v[14:15], v[132:133], v[12:13] op_sel_hi:[1,0] neg_lo:[0,1] neg_hi:[0,1]
	v_pk_add_f32 v[18:19], v[130:131], v[12:13] op_sel_hi:[1,0] neg_lo:[0,1] neg_hi:[0,1]
	v_pk_mul_f32 v[14:15], v[12:13], v[14:15] op_sel:[1,0]
	v_pk_mul_f32 v[12:13], v[12:13], v[18:19] op_sel:[1,0]
	v_pk_fma_f32 v[14:15], v[22:23], v[14:15], v[144:145]
	v_pk_fma_f32 v[6:7], v[0:1], v[12:13], v[4:5]
	v_and_b32_sdwa v12, v14, v216 dst_sel:DWORD dst_unused:UNUSED_PAD src0_sel:WORD_1 src1_sel:DWORD
	v_add3_u32 v12, v14, v12, s77
	v_and_b32_e32 v18, 0xffff0000, v12
	v_and_b32_sdwa v12, v7, v216 dst_sel:DWORD dst_unused:UNUSED_PAD src0_sel:WORD_1 src1_sel:DWORD
	v_and_b32_sdwa v3, v15, v216 dst_sel:DWORD dst_unused:UNUSED_PAD src0_sel:WORD_1 src1_sel:DWORD
	v_and_b32_sdwa v13, v6, v216 dst_sel:DWORD dst_unused:UNUSED_PAD src0_sel:WORD_1 src1_sel:DWORD
	v_add3_u32 v12, v7, v12, s77
	v_lshrrev_b32_e32 v131, 1, v155
	v_add3_u32 v3, v15, v3, s77
	v_add3_u32 v19, v6, v13, s77
	v_and_b32_e32 v130, 0xffff0000, v12
	v_mul_lo_u32 v152, v131, s60
	v_or_b32_sdwa v13, v130, v3 dst_sel:DWORD dst_unused:UNUSED_PAD src0_sel:DWORD src1_sel:WORD_1
	v_or_b32_sdwa v12, v19, v18 dst_sel:DWORD dst_unused:UNUSED_PAD src0_sel:WORD_1 src1_sel:DWORD
	v_add_u32_e32 v132, v154, v152
	ds_write_b64 v132, v[12:13]
	v_and_b32_e32 v12, 0xffff0000, v19
	v_sub_u32_e32 v6, v6, v12
	v_sub_u32_e32 v12, v14, v18
	v_and_b32_e32 v3, 0xffff0000, v3
	v_add_u32_e32 v12, 0x80, v12
	v_sub_u32_e32 v3, v15, v3
	v_sub_u32_e32 v7, v7, v130
	v_add_u32_e32 v6, 0x80, v6
	v_ashrrev_i32_e32 v12, 8, v12
	v_add_u32_e32 v3, 0x80, v3
	v_add_u32_e32 v7, 0x80, v7
	v_ashrrev_i32_e32 v6, 8, v6
	v_min_i32_e32 v12, 0x7f, v12
	v_ashrrev_i32_e32 v3, 8, v3
	v_ashrrev_i32_e32 v7, 8, v7
	v_min_i32_e32 v6, 0x7f, v6
	v_min_i32_sdwa v3, v3, s78 dst_sel:WORD_1 dst_unused:UNUSED_PAD src0_sel:DWORD src1_sel:DWORD
	v_min_i32_e32 v7, 0x7f, v7
	v_lshlrev_b32_e32 v12, 8, v12
	v_and_b32_e32 v12, 0xff00, v12
	v_and_b32_e32 v3, 0xff0000, v3
	v_perm_b32 v6, v7, v6, s79
	v_or3_b32 v3, v6, v12, v3
	v_lshrrev_b32_e32 v6, 2, v155
	v_mad_u64_u32 v[12:13], s[22:23], v6, s60, v[2:3]
	ds_write_b32 v12, v3
	v_or_b32_e32 v3, 16, v155
	v_lshl_add_u32 v13, v3, 3, v219
	ds_read_b64 v[6:7], v13
	v_lshrrev_b32_e32 v133, 1, v3
	v_mul_lo_u32 v153, v133, s60
	v_add_u32_e32 v133, v154, v153
	v_lshrrev_b32_e32 v3, 2, v3
	s_waitcnt lgkmcnt(0)
;     ...
;             _Pragma("unroll") for (int m = 0; m < 4; ++m) {
;               const int rr = wr3 * 64 + m * 16 + fr3;
;               const float2 ms = *reinterpret_cast<const float2*>(mr + (ai * HALF + rr) * 2);
;               f32x4 y = acc[ai][bj][m][n];
;               const float o0 = (y[0] - ms.x) * ms.y * gm.x + bt.x, o1 = (y[1] - ms.x) * ms.y * gm.y + bt.y;
;               const float o2 = (y[2] - ms.x) * ms.y * gm.z + bt.z, o3 = (y[3] - ms.x) * ms.y * gm.w + bt.w;
;               const unsigned h0 = f2bf(o0), h1 = f2bf(o1), h2 = f2bf(o2), h3 = f2bf(o3);
;               u32x2 ob; ob[0] = h0 | (h1 << 16); ob[1] = h2 | (h3 << 16);
;               *reinterpret_cast<u32x2*>(smem + (rr >> 1) * PIECE + (rr & 1) * 512 + cc * 2) = ob;
;               const int l0 = min(((int)__float_as_uint(o0) - (int)(h0 << 16) + 128) >> 8, 127);
;               const int l1 = min(((int)__float_as_uint(o1) - (int)(h1 << 16) + 128) >> 8, 127);
;               const int l2 = min(((int)__float_as_uint(o2) - (int)(h2 << 16) + 128) >> 8, 127);
;               const int l3 = min(((int)__float_as_uint(o3) - (int)(h3 << 16) + 128) >> 8, 127);
;               *reinterpret_cast<unsigned*>(smem + LOBASE + (rr >> 2) * PIECE + (rr & 3) * 256 + cc) =
;                   (unsigned)(l0 & 255) | ((unsigned)(l1 & 255) << 8) | ((unsigned)(l2 & 255) << 16) | ((unsigned)l3 << 24);
;             }
	v_mov_b32_e32 v204, v6
	v_mov_b32_e32 v205, v7
	v_pk_add_f32 v[14:15], v[122:123], v[6:7] op_sel_hi:[1,0] neg_lo:[0,1] neg_hi:[0,1]
	v_pk_add_f32 v[18:19], v[134:135], v[6:7] op_sel_hi:[1,0] neg_lo:[0,1] neg_hi:[0,1]
	v_pk_mul_f32 v[14:15], v[6:7], v[14:15] op_sel:[1,0]
	v_pk_mul_f32 v[6:7], v[6:7], v[18:19] op_sel:[1,0]
	v_pk_fma_f32 v[14:15], v[22:23], v[14:15], v[144:145]
	v_pk_fma_f32 v[6:7], v[0:1], v[6:7], v[4:5]
	v_and_b32_sdwa v18, v15, v216 dst_sel:DWORD dst_unused:UNUSED_PAD src0_sel:WORD_1 src1_sel:DWORD
	v_and_b32_sdwa v19, v14, v216 dst_sel:DWORD dst_unused:UNUSED_PAD src0_sel:WORD_1 src1_sel:DWORD
	v_add3_u32 v122, v15, v18, s77
	v_add3_u32 v18, v14, v19, s77
	v_and_b32_e32 v123, 0xffff0000, v18
	v_and_b32_sdwa v18, v7, v216 dst_sel:DWORD dst_unused:UNUSED_PAD src0_sel:WORD_1 src1_sel:DWORD
	v_and_b32_sdwa v19, v6, v216 dst_sel:DWORD dst_unused:UNUSED_PAD src0_sel:WORD_1 src1_sel:DWORD
	v_add3_u32 v18, v7, v18, s77
	v_add3_u32 v130, v6, v19, s77
	v_and_b32_e32 v131, 0xffff0000, v18
	v_or_b32_sdwa v19, v131, v122 dst_sel:DWORD dst_unused:UNUSED_PAD src0_sel:DWORD src1_sel:WORD_1
	v_or_b32_sdwa v18, v130, v123 dst_sel:DWORD dst_unused:UNUSED_PAD src0_sel:WORD_1 src1_sel:DWORD
	ds_write_b64 v133, v[18:19]
	v_and_b32_e32 v18, 0xffff0000, v130
	v_sub_u32_e32 v6, v6, v18
	v_sub_u32_e32 v14, v14, v123
	v_and_b32_e32 v18, 0xffff0000, v122
	v_add_u32_e32 v14, 0x80, v14
	v_sub_u32_e32 v15, v15, v18
	v_sub_u32_e32 v7, v7, v131
	v_add_u32_e32 v6, 0x80, v6
	v_ashrrev_i32_e32 v14, 8, v14
	v_add_u32_e32 v15, 0x80, v15
	v_add_u32_e32 v7, 0x80, v7
	v_ashrrev_i32_e32 v6, 8, v6
	v_min_i32_e32 v14, 0x7f, v14
	v_ashrrev_i32_e32 v15, 8, v15
	v_ashrrev_i32_e32 v7, 8, v7
	v_min_i32_e32 v6, 0x7f, v6
	v_min_i32_sdwa v15, v15, s78 dst_sel:WORD_1 dst_unused:UNUSED_PAD src0_sel:DWORD src1_sel:DWORD
	v_min_i32_e32 v7, 0x7f, v7
	v_lshlrev_b32_e32 v14, 8, v14
	v_and_b32_e32 v14, 0xff00, v14
	v_and_b32_e32 v15, 0xff0000, v15
	v_perm_b32 v6, v7, v6, s79
	v_or3_b32 v6, v6, v14, v15
	v_mad_u64_u32 v[14:15], s[22:23], v3, s60, v[2:3]
	v_or_b32_e32 v3, 32, v155
	ds_write_b32 v14, v6
	v_lshl_add_u32 v15, v3, 3, v219
	ds_read_b64 v[6:7], v15
	v_lshrrev_b32_e32 v134, 1, v3
	v_lshrrev_b32_e32 v3, 2, v3
	s_waitcnt lgkmcnt(0)
	v_mov_b32_e32 v206, v6
	v_mov_b32_e32 v207, v7
	v_pk_add_f32 v[18:19], v[136:137], v[6:7] op_sel_hi:[1,0] neg_lo:[0,1] neg_hi:[0,1]
	s_nop 0
	v_pk_mul_f32 v[18:19], v[6:7], v[18:19] op_sel:[1,0]
	v_pk_add_f32 v[122:123], v[138:139], v[6:7] op_sel_hi:[1,0] neg_lo:[0,1] neg_hi:[0,1]
	v_pk_fma_f32 v[18:19], v[22:23], v[18:19], v[144:145]
	v_pk_mul_f32 v[6:7], v[6:7], v[122:123] op_sel:[1,0]
	v_and_b32_sdwa v122, v19, v216 dst_sel:DWORD dst_unused:UNUSED_PAD src0_sel:WORD_1 src1_sel:DWORD
	v_and_b32_sdwa v123, v18, v216 dst_sel:DWORD dst_unused:UNUSED_PAD src0_sel:WORD_1 src1_sel:DWORD
	v_pk_fma_f32 v[6:7], v[0:1], v[6:7], v[4:5]
	v_add3_u32 v130, v19, v122, s77
	v_add3_u32 v122, v18, v123, s77
	v_and_b32_e32 v131, 0xffff0000, v122
	v_and_b32_sdwa v122, v7, v216 dst_sel:DWORD dst_unused:UNUSED_PAD src0_sel:WORD_1 src1_sel:DWORD
	v_and_b32_sdwa v123, v6, v216 dst_sel:DWORD dst_unused:UNUSED_PAD src0_sel:WORD_1 src1_sel:DWORD
	v_add3_u32 v122, v7, v122, s77
	v_add3_u32 v135, v6, v123, s77
	v_and_b32_e32 v136, 0xffff0000, v122
	v_mul_lo_u32 v137, v134, s60
	v_or_b32_sdwa v123, v136, v130 dst_sel:DWORD dst_unused:UNUSED_PAD src0_sel:DWORD src1_sel:WORD_1
	v_or_b32_sdwa v122, v135, v131 dst_sel:DWORD dst_unused:UNUSED_PAD src0_sel:WORD_1 src1_sel:DWORD
	v_add_u32_e32 v134, v154, v137
	ds_write_b64 v134, v[122:123]
	v_and_b32_e32 v122, 0xffff0000, v135
	v_sub_u32_e32 v6, v6, v122
	v_sub_u32_e32 v18, v18, v131
	v_and_b32_e32 v122, 0xffff0000, v130
	v_add_u32_e32 v18, 0x80, v18
	v_sub_u32_e32 v19, v19, v122
	v_sub_u32_e32 v7, v7, v136
	v_add_u32_e32 v6, 0x80, v6
	v_ashrrev_i32_e32 v18, 8, v18
	v_add_u32_e32 v19, 0x80, v19
	v_add_u32_e32 v7, 0x80, v7
	v_ashrrev_i32_e32 v6, 8, v6
	v_min_i32_e32 v18, 0x7f, v18
	v_ashrrev_i32_e32 v19, 8, v19
	v_ashrrev_i32_e32 v7, 8, v7
	v_min_i32_e32 v6, 0x7f, v6
	v_min_i32_sdwa v19, v19, s78 dst_sel:WORD_1 dst_unused:UNUSED_PAD src0_sel:DWORD src1_sel:DWORD
	v_min_i32_e32 v7, 0x7f, v7
	v_lshlrev_b32_e32 v18, 8, v18
	v_and_b32_e32 v18, 0xff00, v18
	v_and_b32_e32 v19, 0xff0000, v19
	v_perm_b32 v6, v7, v6, s79
	v_or3_b32 v6, v6, v18, v19
	v_mad_u64_u32 v[18:19], s[22:23], v3, s60, v[2:3]
	v_or_b32_e32 v3, 48, v155
	ds_write_b32 v18, v6
	v_lshl_add_u32 v19, v3, 3, v219
	ds_read_b64 v[6:7], v19
	v_lshrrev_b32_e32 v130, 1, v3
	v_mul_lo_u32 v136, v130, s60
	v_add_u32_e32 v135, v154, v136
	s_waitcnt lgkmcnt(0)
;     ...
;             _Pragma("unroll") for (int m = 0; m < 4; ++m) {
;               const int rr = wr3 * 64 + m * 16 + fr3;
;               const float2 ms = *reinterpret_cast<const float2*>(mr + (ai * HALF + rr) * 2);
;               f32x4 y = acc[ai][bj][m][n];
;               const float o0 = (y[0] - ms.x) * ms.y * gm.x + bt.x, o1 = (y[1] - ms.x) * ms.y * gm.y + bt.y;
;               const float o2 = (y[2] - ms.x) * ms.y * gm.z + bt.z, o3 = (y[3] - ms.x) * ms.y * gm.w + bt.w;
;               const unsigned h0 = f2bf(o0), h1 = f2bf(o1), h2 = f2bf(o2), h3 = f2bf(o3);
;               u32x2 ob; ob[0] = h0 | (h1 << 16); ob[1] = h2 | (h3 << 16);
;               *reinterpret_cast<u32x2*>(smem + (rr >> 1) * PIECE + (rr & 1) * 512 + cc * 2) = ob;
;               const int l0 = min(((int)__float_as_uint(o0) - (int)(h0 << 16) + 128) >> 8, 127);
;               const int l1 = min(((int)__float_as_uint(o1) - (int)(h1 << 16) + 128) >> 8, 127);
;               const int l2 = min(((int)__float_as_uint(o2) - (int)(h2 << 16) + 128) >> 8, 127);
;               const int l3 = min(((int)__float_as_uint(o3) - (int)(h3 << 16) + 128) >> 8, 127);
;               *reinterpret_cast<unsigned*>(smem + LOBASE + (rr >> 2) * PIECE + (rr & 3) * 256 + cc) =
;                   (unsigned)(l0 & 255) | ((unsigned)(l1 & 255) << 8) | ((unsigned)(l2 & 255) << 16) | ((unsigned)l3 << 24);
;             }
	v_mov_b32_e32 v208, v6
	v_mov_b32_e32 v209, v7
	v_pk_add_f32 v[122:123], v[140:141], v[6:7] op_sel_hi:[1,0] neg_lo:[0,1] neg_hi:[0,1]
	s_nop 0
	v_pk_mul_f32 v[122:123], v[6:7], v[122:123] op_sel:[1,0]
	s_nop 0
	v_pk_fma_f32 v[22:23], v[22:23], v[122:123], v[144:145]
	v_pk_add_f32 v[122:123], v[142:143], v[6:7] op_sel_hi:[1,0] neg_lo:[0,1] neg_hi:[0,1]
	s_nop 0
	v_pk_mul_f32 v[6:7], v[6:7], v[122:123] op_sel:[1,0]
	s_nop 0
	v_pk_fma_f32 v[0:1], v[0:1], v[6:7], v[4:5]
	v_and_b32_sdwa v4, v23, v216 dst_sel:DWORD dst_unused:UNUSED_PAD src0_sel:WORD_1 src1_sel:DWORD
	v_and_b32_sdwa v5, v22, v216 dst_sel:DWORD dst_unused:UNUSED_PAD src0_sel:WORD_1 src1_sel:DWORD
	v_add3_u32 v6, v23, v4, s77
	v_add3_u32 v4, v22, v5, s77
	v_and_b32_e32 v7, 0xffff0000, v4
	v_and_b32_sdwa v4, v1, v216 dst_sel:DWORD dst_unused:UNUSED_PAD src0_sel:WORD_1 src1_sel:DWORD
	v_and_b32_sdwa v5, v0, v216 dst_sel:DWORD dst_unused:UNUSED_PAD src0_sel:WORD_1 src1_sel:DWORD
	v_add3_u32 v4, v1, v4, s77
	v_add3_u32 v122, v0, v5, s77
	v_and_b32_e32 v123, 0xffff0000, v4
	v_or_b32_sdwa v5, v123, v6 dst_sel:DWORD dst_unused:UNUSED_PAD src0_sel:DWORD src1_sel:WORD_1
	v_or_b32_sdwa v4, v122, v7 dst_sel:DWORD dst_unused:UNUSED_PAD src0_sel:WORD_1 src1_sel:DWORD
	ds_write_b64 v135, v[4:5]
	v_and_b32_e32 v4, 0xffff0000, v122
	v_sub_u32_e32 v0, v0, v4
	v_sub_u32_e32 v4, v22, v7
	v_and_b32_e32 v5, 0xffff0000, v6
	v_add_u32_e32 v4, 0x80, v4
	v_sub_u32_e32 v5, v23, v5
	v_sub_u32_e32 v1, v1, v123
	v_add_u32_e32 v0, 0x80, v0
	v_ashrrev_i32_e32 v4, 8, v4
	v_add_u32_e32 v5, 0x80, v5
	v_add_u32_e32 v1, 0x80, v1
	v_ashrrev_i32_e32 v0, 8, v0
	v_min_i32_e32 v4, 0x7f, v4
	v_ashrrev_i32_e32 v5, 8, v5
	v_ashrrev_i32_e32 v1, 8, v1
	v_min_i32_e32 v0, 0x7f, v0
	v_min_i32_sdwa v5, v5, s78 dst_sel:WORD_1 dst_unused:UNUSED_PAD src0_sel:DWORD src1_sel:DWORD
	v_min_i32_e32 v1, 0x7f, v1
	v_lshlrev_b32_e32 v4, 8, v4
	v_and_b32_e32 v4, 0xff00, v4
	v_and_b32_e32 v5, 0xff0000, v5
	v_perm_b32 v0, v1, v0, s79
	v_lshrrev_b32_e32 v1, 2, v3
	v_or3_b32 v0, v0, v4, v5
	v_mad_u64_u32 v[22:23], s[22:23], v1, s60, v[2:3]
	ds_write_b32 v22, v0
	v_mov_b32_e32 v0, v224
	v_mov_b32_e32 v1, v225
	v_mov_b32_e32 v2, v226
	v_mov_b32_e32 v3, v227
	v_mov_b32_e32 v4, v240
	v_mov_b32_e32 v5, v241
	v_mov_b32_e32 v6, v242
	v_mov_b32_e32 v7, v243
	v_mov_b32_e32 v138, v202
	v_mov_b32_e32 v139, v203
	s_mov_b32 s22, s18
	s_mov_b32 s23, s19
	v_pk_add_f32 v[128:129], v[128:129], v[138:139] op_sel_hi:[1,0] neg_lo:[0,1] neg_hi:[0,1]
	s_nop 0
	v_pk_mul_f32 v[128:129], v[138:139], v[128:129] op_sel:[1,0]
	v_pk_add_f32 v[126:127], v[126:127], v[138:139] op_sel_hi:[1,0] neg_lo:[0,1] neg_hi:[0,1]
	v_mov_b32_e32 v122, v1
	v_mov_b32_e32 v123, v2
	v_mov_b32_e32 v130, v5
	v_mov_b32_e32 v131, v6
	v_pk_fma_f32 v[128:129], v[122:123], v[128:129], v[130:131]
	v_pk_mul_f32 v[126:127], v[138:139], v[126:127] op_sel:[1,0]
	v_mov_b32_e32 v1, v3
	v_mov_b32_e32 v5, v7
	v_and_b32_sdwa v23, v128, v216 dst_sel:DWORD dst_unused:UNUSED_PAD src0_sel:WORD_1 src1_sel:DWORD
	v_pk_fma_f32 v[6:7], v[0:1], v[126:127], v[4:5]
	v_add3_u32 v23, v128, v23, s77
	v_and_b32_e32 v138, 0xffff0000, v23
	v_and_b32_sdwa v23, v7, v216 dst_sel:DWORD dst_unused:UNUSED_PAD src0_sel:WORD_1 src1_sel:DWORD
	v_and_b32_sdwa v3, v129, v216 dst_sel:DWORD dst_unused:UNUSED_PAD src0_sel:WORD_1 src1_sel:DWORD
	v_and_b32_sdwa v126, v6, v216 dst_sel:DWORD dst_unused:UNUSED_PAD src0_sel:WORD_1 src1_sel:DWORD
	v_add3_u32 v23, v7, v23, s77
	v_or_b32_e32 v2, 32, v154
	v_add3_u32 v3, v129, v3, s77
	v_add3_u32 v139, v6, v126, s77
	v_and_b32_e32 v140, 0xffff0000, v23
	v_or_b32_sdwa v127, v140, v3 dst_sel:DWORD dst_unused:UNUSED_PAD src0_sel:DWORD src1_sel:WORD_1
	v_or_b32_sdwa v126, v139, v138 dst_sel:DWORD dst_unused:UNUSED_PAD src0_sel:WORD_1 src1_sel:DWORD
	v_add_u32_e32 v23, v2, v152
	ds_write_b64 v23, v[126:127]
	v_and_b32_e32 v126, 0xffff0000, v139
	v_sub_u32_e32 v6, v6, v126
	v_sub_u32_e32 v126, v128, v138
	v_and_b32_e32 v3, 0xffff0000, v3
	v_add_u32_e32 v126, 0x80, v126
	v_sub_u32_e32 v3, v129, v3
	v_sub_u32_e32 v7, v7, v140
	v_add_u32_e32 v6, 0x80, v6
	v_ashrrev_i32_e32 v126, 8, v126
	v_add_u32_e32 v3, 0x80, v3
	v_add_u32_e32 v7, 0x80, v7
	v_ashrrev_i32_e32 v6, 8, v6
	v_min_i32_e32 v126, 0x7f, v126
	v_ashrrev_i32_e32 v3, 8, v3
	v_ashrrev_i32_e32 v7, 8, v7
	v_min_i32_e32 v6, 0x7f, v6
	v_min_i32_sdwa v3, v3, s78 dst_sel:WORD_1 dst_unused:UNUSED_PAD src0_sel:DWORD src1_sel:DWORD
	v_min_i32_e32 v7, 0x7f, v7
	v_lshlrev_b32_e32 v126, 8, v126
	v_and_b32_e32 v126, 0xff00, v126
	v_and_b32_e32 v3, 0xff0000, v3
	v_perm_b32 v6, v7, v6, s79
	v_or3_b32 v3, v6, v126, v3
	ds_write_b32 v12, v3 offset:16
	v_mov_b32_e32 v6, v204
	v_mov_b32_e32 v7, v205
	v_pk_add_f32 v[108:109], v[108:109], v[6:7] op_sel_hi:[1,0] neg_lo:[0,1] neg_hi:[0,1]
	s_nop 0
	v_pk_mul_f32 v[108:109], v[6:7], v[108:109] op_sel:[1,0]
	s_nop 0
	v_pk_fma_f32 v[126:127], v[122:123], v[108:109], v[130:131]
	v_pk_add_f32 v[108:109], v[110:111], v[6:7] op_sel_hi:[1,0] neg_lo:[0,1] neg_hi:[0,1]
	v_and_b32_sdwa v3, v127, v216 dst_sel:DWORD dst_unused:UNUSED_PAD src0_sel:WORD_1 src1_sel:DWORD
	v_pk_mul_f32 v[6:7], v[6:7], v[108:109] op_sel:[1,0]
	v_and_b32_sdwa v108, v126, v216 dst_sel:DWORD dst_unused:UNUSED_PAD src0_sel:WORD_1 src1_sel:DWORD
	v_pk_fma_f32 v[6:7], v[0:1], v[6:7], v[4:5]
	v_add3_u32 v108, v126, v108, s77
	v_and_b32_e32 v109, 0xffff0000, v108
	v_and_b32_sdwa v108, v7, v216 dst_sel:DWORD dst_unused:UNUSED_PAD src0_sel:WORD_1 src1_sel:DWORD
	v_and_b32_sdwa v110, v6, v216 dst_sel:DWORD dst_unused:UNUSED_PAD src0_sel:WORD_1 src1_sel:DWORD
	v_add3_u32 v108, v7, v108, s77
	v_add3_u32 v3, v127, v3, s77
	v_add3_u32 v128, v6, v110, s77
;     ...
;             _Pragma("unroll") for (int m = 0; m < 4; ++m) {
;               const int rr = wr3 * 64 + m * 16 + fr3;
;               const float2 ms = *reinterpret_cast<const float2*>(mr + (ai * HALF + rr) * 2);
;               f32x4 y = acc[ai][bj][m][n];
;               const float o0 = (y[0] - ms.x) * ms.y * gm.x + bt.x, o1 = (y[1] - ms.x) * ms.y * gm.y + bt.y;
;               const float o2 = (y[2] - ms.x) * ms.y * gm.z + bt.z, o3 = (y[3] - ms.x) * ms.y * gm.w + bt.w;
;               const unsigned h0 = f2bf(o0), h1 = f2bf(o1), h2 = f2bf(o2), h3 = f2bf(o3);
;               u32x2 ob; ob[0] = h0 | (h1 << 16); ob[1] = h2 | (h3 << 16);
;               *reinterpret_cast<u32x2*>(smem + (rr >> 1) * PIECE + (rr & 1) * 512 + cc * 2) = ob;
;               const int l0 = min(((int)__float_as_uint(o0) - (int)(h0 << 16) + 128) >> 8, 127);
;               const int l1 = min(((int)__float_as_uint(o1) - (int)(h1 << 16) + 128) >> 8, 127);
;               const int l2 = min(((int)__float_as_uint(o2) - (int)(h2 << 16) + 128) >> 8, 127);
;               const int l3 = min(((int)__float_as_uint(o3) - (int)(h3 << 16) + 128) >> 8, 127);
;               *reinterpret_cast<unsigned*>(smem + LOBASE + (rr >> 2) * PIECE + (rr & 3) * 256 + cc) =
;                   (unsigned)(l0 & 255) | ((unsigned)(l1 & 255) << 8) | ((unsigned)(l2 & 255) << 16) | ((unsigned)l3 << 24);
;             }
	v_and_b32_e32 v129, 0xffff0000, v108
	v_or_b32_sdwa v111, v129, v3 dst_sel:DWORD dst_unused:UNUSED_PAD src0_sel:DWORD src1_sel:WORD_1
	v_or_b32_sdwa v110, v128, v109 dst_sel:DWORD dst_unused:UNUSED_PAD src0_sel:WORD_1 src1_sel:DWORD
	v_add_u32_e32 v108, v2, v153
	ds_write_b64 v108, v[110:111]
	v_and_b32_e32 v110, 0xffff0000, v128
	v_sub_u32_e32 v109, v126, v109
	v_and_b32_e32 v3, 0xffff0000, v3
	v_sub_u32_e32 v6, v6, v110
	v_add_u32_e32 v109, 0x80, v109
	v_sub_u32_e32 v3, v127, v3
	v_sub_u32_e32 v7, v7, v129
	v_add_u32_e32 v6, 0x80, v6
	v_ashrrev_i32_e32 v109, 8, v109
	v_add_u32_e32 v3, 0x80, v3
	v_add_u32_e32 v7, 0x80, v7
	v_ashrrev_i32_e32 v6, 8, v6
	v_min_i32_e32 v109, 0x7f, v109
	v_ashrrev_i32_e32 v3, 8, v3
	v_ashrrev_i32_e32 v7, 8, v7
	v_min_i32_e32 v6, 0x7f, v6
	v_min_i32_sdwa v3, v3, s78 dst_sel:WORD_1 dst_unused:UNUSED_PAD src0_sel:DWORD src1_sel:DWORD
	v_min_i32_e32 v7, 0x7f, v7
	v_lshlrev_b32_e32 v109, 8, v109
	v_and_b32_e32 v109, 0xff00, v109
	v_and_b32_e32 v3, 0xff0000, v3
	v_perm_b32 v6, v7, v6, s79
	v_or3_b32 v3, v6, v109, v3
	ds_write_b32 v14, v3 offset:16
	v_mov_b32_e32 v6, v206
	v_mov_b32_e32 v7, v207
	v_pk_add_f32 v[98:99], v[98:99], v[6:7] op_sel_hi:[1,0] neg_lo:[0,1] neg_hi:[0,1]
	s_nop 0
	v_pk_mul_f32 v[98:99], v[6:7], v[98:99] op_sel:[1,0]
	s_nop 0
	v_pk_fma_f32 v[110:111], v[122:123], v[98:99], v[130:131]
	v_pk_add_f32 v[98:99], v[106:107], v[6:7] op_sel_hi:[1,0] neg_lo:[0,1] neg_hi:[0,1]
	v_and_b32_sdwa v3, v111, v216 dst_sel:DWORD dst_unused:UNUSED_PAD src0_sel:WORD_1 src1_sel:DWORD
	v_pk_mul_f32 v[6:7], v[6:7], v[98:99] op_sel:[1,0]
	v_and_b32_sdwa v98, v110, v216 dst_sel:DWORD dst_unused:UNUSED_PAD src0_sel:WORD_1 src1_sel:DWORD
	v_pk_fma_f32 v[6:7], v[0:1], v[6:7], v[4:5]
	v_add3_u32 v98, v110, v98, s77
	v_and_b32_e32 v99, 0xffff0000, v98
	v_and_b32_sdwa v98, v7, v216 dst_sel:DWORD dst_unused:UNUSED_PAD src0_sel:WORD_1 src1_sel:DWORD
	v_and_b32_sdwa v106, v6, v216 dst_sel:DWORD dst_unused:UNUSED_PAD src0_sel:WORD_1 src1_sel:DWORD
	v_add3_u32 v98, v7, v98, s77
	v_add3_u32 v3, v111, v3, s77
	v_add3_u32 v109, v6, v106, s77
	v_and_b32_e32 v126, 0xffff0000, v98
	v_or_b32_sdwa v107, v126, v3 dst_sel:DWORD dst_unused:UNUSED_PAD src0_sel:DWORD src1_sel:WORD_1
	v_or_b32_sdwa v106, v109, v99 dst_sel:DWORD dst_unused:UNUSED_PAD src0_sel:WORD_1 src1_sel:DWORD
	v_add_u32_e32 v98, v2, v137
	ds_write_b64 v98, v[106:107]
	v_and_b32_e32 v106, 0xffff0000, v109
	v_sub_u32_e32 v99, v110, v99
	v_and_b32_e32 v3, 0xffff0000, v3
	v_sub_u32_e32 v6, v6, v106
	v_add_u32_e32 v99, 0x80, v99
	v_sub_u32_e32 v3, v111, v3
	v_sub_u32_e32 v7, v7, v126
	v_add_u32_e32 v6, 0x80, v6
	v_ashrrev_i32_e32 v99, 8, v99
	v_add_u32_e32 v3, 0x80, v3
	v_add_u32_e32 v7, 0x80, v7
	v_ashrrev_i32_e32 v6, 8, v6
	v_min_i32_e32 v99, 0x7f, v99
	v_ashrrev_i32_e32 v3, 8, v3
	v_ashrrev_i32_e32 v7, 8, v7
	v_min_i32_e32 v6, 0x7f, v6
	v_min_i32_sdwa v3, v3, s78 dst_sel:WORD_1 dst_unused:UNUSED_PAD src0_sel:DWORD src1_sel:DWORD
	v_min_i32_e32 v7, 0x7f, v7
	v_lshlrev_b32_e32 v99, 8, v99
	v_and_b32_e32 v99, 0xff00, v99
	v_and_b32_e32 v3, 0xff0000, v3
	v_perm_b32 v6, v7, v6, s79
	v_or3_b32 v3, v6, v99, v3
	ds_write_b32 v18, v3 offset:16
	v_mov_b32_e32 v6, v208
	v_mov_b32_e32 v7, v209
	v_add_u32_e32 v99, v2, v136
	v_pk_add_f32 v[106:107], v[114:115], v[6:7] op_sel_hi:[1,0] neg_lo:[0,1] neg_hi:[0,1]
	s_nop 0
	v_pk_mul_f32 v[106:107], v[6:7], v[106:107] op_sel:[1,0]
	v_pk_add_f32 v[110:111], v[120:121], v[6:7] op_sel_hi:[1,0] neg_lo:[0,1] neg_hi:[0,1]
	v_pk_fma_f32 v[106:107], v[122:123], v[106:107], v[130:131]
	v_pk_mul_f32 v[6:7], v[6:7], v[110:111] op_sel:[1,0]
	v_and_b32_sdwa v3, v107, v216 dst_sel:DWORD dst_unused:UNUSED_PAD src0_sel:WORD_1 src1_sel:DWORD
	v_pk_fma_f32 v[0:1], v[0:1], v[6:7], v[4:5]
	v_and_b32_sdwa v4, v106, v216 dst_sel:DWORD dst_unused:UNUSED_PAD src0_sel:WORD_1 src1_sel:DWORD
	v_add3_u32 v4, v106, v4, s77
	v_and_b32_e32 v6, 0xffff0000, v4
	v_and_b32_sdwa v4, v1, v216 dst_sel:DWORD dst_unused:UNUSED_PAD src0_sel:WORD_1 src1_sel:DWORD
	v_and_b32_sdwa v5, v0, v216 dst_sel:DWORD dst_unused:UNUSED_PAD src0_sel:WORD_1 src1_sel:DWORD
	v_add3_u32 v4, v1, v4, s77
	v_add3_u32 v7, v0, v5, s77
	v_add3_u32 v3, v107, v3, s77
	v_and_b32_e32 v109, 0xffff0000, v4
	v_and_b32_e32 v2, 0xffff0000, v7
	v_or_b32_sdwa v5, v109, v3 dst_sel:DWORD dst_unused:UNUSED_PAD src0_sel:DWORD src1_sel:WORD_1
	v_sub_u32_e32 v0, v0, v2
	v_sub_u32_e32 v2, v106, v6
	v_and_b32_e32 v3, 0xffff0000, v3
	v_add_u32_e32 v2, 0x80, v2
	v_sub_u32_e32 v3, v107, v3
	v_sub_u32_e32 v1, v1, v109
	v_add_u32_e32 v0, 0x80, v0
	v_ashrrev_i32_e32 v2, 8, v2
	v_add_u32_e32 v3, 0x80, v3
	v_add_u32_e32 v1, 0x80, v1
	v_ashrrev_i32_e32 v0, 8, v0
	v_min_i32_e32 v2, 0x7f, v2
	v_ashrrev_i32_e32 v3, 8, v3
	v_ashrrev_i32_e32 v1, 8, v1
	v_min_i32_e32 v0, 0x7f, v0
	v_min_i32_sdwa v3, v3, s78 dst_sel:WORD_1 dst_unused:UNUSED_PAD src0_sel:DWORD src1_sel:DWORD
	v_min_i32_e32 v1, 0x7f, v1
	v_lshlrev_b32_e32 v2, 8, v2
	v_and_b32_e32 v2, 0xff00, v2
	v_and_b32_e32 v3, 0xff0000, v3
	v_perm_b32 v0, v1, v0, s79
	v_or_b32_sdwa v4, v7, v6 dst_sel:DWORD dst_unused:UNUSED_PAD src0_sel:WORD_1 src1_sel:DWORD
	v_or3_b32 v0, v0, v2, v3
	ds_write_b64 v99, v[4:5]
	ds_write_b32 v22, v0 offset:16
	v_mov_b32_e32 v0, v228
	v_mov_b32_e32 v1, v229
	v_mov_b32_e32 v2, v230
	v_mov_b32_e32 v3, v231
	v_mov_b32_e32 v4, v244
	v_mov_b32_e32 v5, v245
	v_mov_b32_e32 v6, v246
	v_mov_b32_e32 v7, v247
	v_mov_b32_e32 v106, v202
	v_mov_b32_e32 v107, v203
	v_or_b32_e32 v109, 0x100, v154
	v_pk_add_f32 v[120:121], v[124:125], v[106:107] op_sel_hi:[1,0] neg_lo:[0,1] neg_hi:[0,1]
	s_nop 0
	v_pk_mul_f32 v[120:121], v[106:107], v[120:121] op_sel:[1,0]
;     ...
;             _Pragma("unroll") for (int m = 0; m < 4; ++m) {
;               const int rr = wr3 * 64 + m * 16 + fr3;
;               const float2 ms = *reinterpret_cast<const float2*>(mr + (ai * HALF + rr) * 2);
;               f32x4 y = acc[ai][bj][m][n];
;               const float o0 = (y[0] - ms.x) * ms.y * gm.x + bt.x, o1 = (y[1] - ms.x) * ms.y * gm.y + bt.y;
;               const float o2 = (y[2] - ms.x) * ms.y * gm.z + bt.z, o3 = (y[3] - ms.x) * ms.y * gm.w + bt.w;
;               const unsigned h0 = f2bf(o0), h1 = f2bf(o1), h2 = f2bf(o2), h3 = f2bf(o3);
;               u32x2 ob; ob[0] = h0 | (h1 << 16); ob[1] = h2 | (h3 << 16);
;               *reinterpret_cast<u32x2*>(smem + (rr >> 1) * PIECE + (rr & 1) * 512 + cc * 2) = ob;
;               const int l0 = min(((int)__float_as_uint(o0) - (int)(h0 << 16) + 128) >> 8, 127);
;               const int l1 = min(((int)__float_as_uint(o1) - (int)(h1 << 16) + 128) >> 8, 127);
;               const int l2 = min(((int)__float_as_uint(o2) - (int)(h2 << 16) + 128) >> 8, 127);
;               const int l3 = min(((int)__float_as_uint(o3) - (int)(h3 << 16) + 128) >> 8, 127);
;               *reinterpret_cast<unsigned*>(smem + LOBASE + (rr >> 2) * PIECE + (rr & 3) * 256 + cc) =
;                   (unsigned)(l0 & 255) | ((unsigned)(l1 & 255) << 8) | ((unsigned)(l2 & 255) << 16) | ((unsigned)l3 << 24);
;             }
	v_pk_add_f32 v[118:119], v[118:119], v[106:107] op_sel_hi:[1,0] neg_lo:[0,1] neg_hi:[0,1]
	v_mov_b32_e32 v110, v1
	v_mov_b32_e32 v111, v2
	v_mov_b32_e32 v114, v5
	v_mov_b32_e32 v115, v6
	v_pk_fma_f32 v[120:121], v[110:111], v[120:121], v[114:115]
	v_pk_mul_f32 v[106:107], v[106:107], v[118:119] op_sel:[1,0]
	v_mov_b32_e32 v1, v3
	v_mov_b32_e32 v5, v7
	v_and_b32_sdwa v6, v121, v216 dst_sel:DWORD dst_unused:UNUSED_PAD src0_sel:WORD_1 src1_sel:DWORD
	v_and_b32_sdwa v7, v120, v216 dst_sel:DWORD dst_unused:UNUSED_PAD src0_sel:WORD_1 src1_sel:DWORD
	v_pk_fma_f32 v[2:3], v[0:1], v[106:107], v[4:5]
	v_add3_u32 v107, v121, v6, s77
	v_add3_u32 v6, v120, v7, s77
	v_and_b32_e32 v118, 0xffff0000, v6
	v_and_b32_sdwa v6, v3, v216 dst_sel:DWORD dst_unused:UNUSED_PAD src0_sel:WORD_1 src1_sel:DWORD
	v_and_b32_sdwa v7, v2, v216 dst_sel:DWORD dst_unused:UNUSED_PAD src0_sel:WORD_1 src1_sel:DWORD
	v_add3_u32 v6, v3, v6, s77
	v_add3_u32 v119, v2, v7, s77
	v_and_b32_e32 v122, 0xffff0000, v6
	v_or_b32_sdwa v7, v122, v107 dst_sel:DWORD dst_unused:UNUSED_PAD src0_sel:DWORD src1_sel:WORD_1
	v_or_b32_sdwa v6, v119, v118 dst_sel:DWORD dst_unused:UNUSED_PAD src0_sel:WORD_1 src1_sel:DWORD
	v_add_u32_e32 v106, v109, v152
	ds_write_b64 v106, v[6:7]
	v_and_b32_e32 v6, 0xffff0000, v119
	v_sub_u32_e32 v2, v2, v6
	v_sub_u32_e32 v6, v120, v118
	v_and_b32_e32 v7, 0xffff0000, v107
	v_add_u32_e32 v6, 0x80, v6
	v_sub_u32_e32 v7, v121, v7
	v_sub_u32_e32 v3, v3, v122
	v_add_u32_e32 v2, 0x80, v2
	v_ashrrev_i32_e32 v6, 8, v6
	v_add_u32_e32 v7, 0x80, v7
	v_add_u32_e32 v3, 0x80, v3
	v_ashrrev_i32_e32 v2, 8, v2
	v_min_i32_e32 v6, 0x7f, v6
	v_ashrrev_i32_e32 v7, 8, v7
	v_ashrrev_i32_e32 v3, 8, v3
	v_min_i32_e32 v2, 0x7f, v2
	v_min_i32_sdwa v7, v7, s78 dst_sel:WORD_1 dst_unused:UNUSED_PAD src0_sel:DWORD src1_sel:DWORD
	v_min_i32_e32 v3, 0x7f, v3
	v_lshlrev_b32_e32 v6, 8, v6
	v_and_b32_e32 v6, 0xff00, v6
	v_and_b32_e32 v7, 0xff0000, v7
	v_perm_b32 v2, v3, v2, s79
	v_or3_b32 v2, v2, v6, v7
	ds_write_b32 v12, v2 offset:128
	v_mov_b32_e32 v2, v204
	v_mov_b32_e32 v3, v205
	v_pk_add_f32 v[6:7], v[102:103], v[2:3] op_sel_hi:[1,0] neg_lo:[0,1] neg_hi:[0,1]
	s_nop 0
	v_pk_mul_f32 v[6:7], v[2:3], v[6:7] op_sel:[1,0]
	v_pk_add_f32 v[102:103], v[104:105], v[2:3] op_sel_hi:[1,0] neg_lo:[0,1] neg_hi:[0,1]
	v_pk_fma_f32 v[6:7], v[110:111], v[6:7], v[114:115]
	v_pk_mul_f32 v[2:3], v[2:3], v[102:103] op_sel:[1,0]
	v_and_b32_sdwa v102, v7, v216 dst_sel:DWORD dst_unused:UNUSED_PAD src0_sel:WORD_1 src1_sel:DWORD
	v_and_b32_sdwa v103, v6, v216 dst_sel:DWORD dst_unused:UNUSED_PAD src0_sel:WORD_1 src1_sel:DWORD
	v_pk_fma_f32 v[2:3], v[0:1], v[2:3], v[4:5]
	v_add3_u32 v107, v7, v102, s77
	v_add3_u32 v102, v6, v103, s77
	v_and_b32_e32 v103, 0xffff0000, v102
	v_and_b32_sdwa v102, v3, v216 dst_sel:DWORD dst_unused:UNUSED_PAD src0_sel:WORD_1 src1_sel:DWORD
	v_and_b32_sdwa v104, v2, v216 dst_sel:DWORD dst_unused:UNUSED_PAD src0_sel:WORD_1 src1_sel:DWORD
	v_add3_u32 v102, v3, v102, s77
	v_add3_u32 v118, v2, v104, s77
	v_and_b32_e32 v119, 0xffff0000, v102
	v_or_b32_sdwa v105, v119, v107 dst_sel:DWORD dst_unused:UNUSED_PAD src0_sel:DWORD src1_sel:WORD_1
	v_or_b32_sdwa v104, v118, v103 dst_sel:DWORD dst_unused:UNUSED_PAD src0_sel:WORD_1 src1_sel:DWORD
	v_add_u32_e32 v102, v109, v153
	ds_write_b64 v102, v[104:105]
	v_and_b32_e32 v104, 0xffff0000, v118
	v_sub_u32_e32 v6, v6, v103
	v_and_b32_e32 v103, 0xffff0000, v107
	v_sub_u32_e32 v2, v2, v104
	v_add_u32_e32 v6, 0x80, v6
	v_sub_u32_e32 v7, v7, v103
	v_sub_u32_e32 v3, v3, v119
	v_add_u32_e32 v2, 0x80, v2
	v_ashrrev_i32_e32 v6, 8, v6
	v_add_u32_e32 v7, 0x80, v7
	v_add_u32_e32 v3, 0x80, v3
	v_ashrrev_i32_e32 v2, 8, v2
	v_min_i32_e32 v6, 0x7f, v6
	v_ashrrev_i32_e32 v7, 8, v7
	v_ashrrev_i32_e32 v3, 8, v3
	v_min_i32_e32 v2, 0x7f, v2
	v_min_i32_sdwa v7, v7, s78 dst_sel:WORD_1 dst_unused:UNUSED_PAD src0_sel:DWORD src1_sel:DWORD
	v_min_i32_e32 v3, 0x7f, v3
	v_lshlrev_b32_e32 v6, 8, v6
	v_and_b32_e32 v6, 0xff00, v6
	v_and_b32_e32 v7, 0xff0000, v7
	v_perm_b32 v2, v3, v2, s79
	v_or3_b32 v2, v2, v6, v7
	ds_write_b32 v14, v2 offset:128
	v_mov_b32_e32 v2, v206
	v_mov_b32_e32 v3, v207
	v_pk_add_f32 v[6:7], v[92:93], v[2:3] op_sel_hi:[1,0] neg_lo:[0,1] neg_hi:[0,1]
	s_nop 0
	v_pk_mul_f32 v[6:7], v[2:3], v[6:7] op_sel:[1,0]
	v_pk_add_f32 v[88:89], v[88:89], v[2:3] op_sel_hi:[1,0] neg_lo:[0,1] neg_hi:[0,1]
	v_pk_fma_f32 v[6:7], v[110:111], v[6:7], v[114:115]
	v_pk_mul_f32 v[2:3], v[2:3], v[88:89] op_sel:[1,0]
	v_and_b32_sdwa v88, v7, v216 dst_sel:DWORD dst_unused:UNUSED_PAD src0_sel:WORD_1 src1_sel:DWORD
	v_and_b32_sdwa v89, v6, v216 dst_sel:DWORD dst_unused:UNUSED_PAD src0_sel:WORD_1 src1_sel:DWORD
	v_pk_fma_f32 v[2:3], v[0:1], v[2:3], v[4:5]
	v_add3_u32 v93, v7, v88, s77
	v_add3_u32 v88, v6, v89, s77
	v_and_b32_e32 v103, 0xffff0000, v88
	v_and_b32_sdwa v88, v3, v216 dst_sel:DWORD dst_unused:UNUSED_PAD src0_sel:WORD_1 src1_sel:DWORD
	v_and_b32_sdwa v89, v2, v216 dst_sel:DWORD dst_unused:UNUSED_PAD src0_sel:WORD_1 src1_sel:DWORD
	v_add3_u32 v88, v3, v88, s77
	v_add3_u32 v104, v2, v89, s77
	v_and_b32_e32 v105, 0xffff0000, v88
	v_or_b32_sdwa v89, v105, v93 dst_sel:DWORD dst_unused:UNUSED_PAD src0_sel:DWORD src1_sel:WORD_1
	v_or_b32_sdwa v88, v104, v103 dst_sel:DWORD dst_unused:UNUSED_PAD src0_sel:WORD_1 src1_sel:DWORD
	v_add_u32_e32 v92, v109, v137
	ds_write_b64 v92, v[88:89]
	v_and_b32_e32 v88, 0xffff0000, v104
	v_sub_u32_e32 v2, v2, v88
	v_sub_u32_e32 v6, v6, v103
	v_and_b32_e32 v88, 0xffff0000, v93
	v_add_u32_e32 v6, 0x80, v6
	v_sub_u32_e32 v7, v7, v88
	v_sub_u32_e32 v3, v3, v105
	v_add_u32_e32 v2, 0x80, v2
	v_ashrrev_i32_e32 v6, 8, v6
	v_add_u32_e32 v7, 0x80, v7
	v_add_u32_e32 v3, 0x80, v3
;     ...
;             _Pragma("unroll") for (int m = 0; m < 4; ++m) {
;               const int rr = wr3 * 64 + m * 16 + fr3;
;               const float2 ms = *reinterpret_cast<const float2*>(mr + (ai * HALF + rr) * 2);
;               f32x4 y = acc[ai][bj][m][n];
;               const float o0 = (y[0] - ms.x) * ms.y * gm.x + bt.x, o1 = (y[1] - ms.x) * ms.y * gm.y + bt.y;
;               const float o2 = (y[2] - ms.x) * ms.y * gm.z + bt.z, o3 = (y[3] - ms.x) * ms.y * gm.w + bt.w;
;               const unsigned h0 = f2bf(o0), h1 = f2bf(o1), h2 = f2bf(o2), h3 = f2bf(o3);
;               u32x2 ob; ob[0] = h0 | (h1 << 16); ob[1] = h2 | (h3 << 16);
;               *reinterpret_cast<u32x2*>(smem + (rr >> 1) * PIECE + (rr & 1) * 512 + cc * 2) = ob;
;               const int l0 = min(((int)__float_as_uint(o0) - (int)(h0 << 16) + 128) >> 8, 127);
;               const int l1 = min(((int)__float_as_uint(o1) - (int)(h1 << 16) + 128) >> 8, 127);
;               const int l2 = min(((int)__float_as_uint(o2) - (int)(h2 << 16) + 128) >> 8, 127);
;               const int l3 = min(((int)__float_as_uint(o3) - (int)(h3 << 16) + 128) >> 8, 127);
;               *reinterpret_cast<unsigned*>(smem + LOBASE + (rr >> 2) * PIECE + (rr & 3) * 256 + cc) =
;                   (unsigned)(l0 & 255) | ((unsigned)(l1 & 255) << 8) | ((unsigned)(l2 & 255) << 16) | ((unsigned)l3 << 24);
;             }
	v_ashrrev_i32_e32 v2, 8, v2
	v_min_i32_e32 v6, 0x7f, v6
	v_ashrrev_i32_e32 v7, 8, v7
	v_ashrrev_i32_e32 v3, 8, v3
	v_min_i32_e32 v2, 0x7f, v2
	v_min_i32_sdwa v7, v7, s78 dst_sel:WORD_1 dst_unused:UNUSED_PAD src0_sel:DWORD src1_sel:DWORD
	v_min_i32_e32 v3, 0x7f, v3
	v_lshlrev_b32_e32 v6, 8, v6
	v_and_b32_e32 v6, 0xff00, v6
	v_and_b32_e32 v7, 0xff0000, v7
	v_perm_b32 v2, v3, v2, s79
	v_or3_b32 v2, v2, v6, v7
	ds_write_b32 v18, v2 offset:128
	v_mov_b32_e32 v2, v208
	v_mov_b32_e32 v3, v209
	v_add_u32_e32 v93, v109, v136
	v_pk_add_f32 v[6:7], v[90:91], v[2:3] op_sel_hi:[1,0] neg_lo:[0,1] neg_hi:[0,1]
	s_nop 0
	v_pk_mul_f32 v[6:7], v[2:3], v[6:7] op_sel:[1,0]
	v_pk_add_f32 v[88:89], v[94:95], v[2:3] op_sel_hi:[1,0] neg_lo:[0,1] neg_hi:[0,1]
	v_pk_fma_f32 v[6:7], v[110:111], v[6:7], v[114:115]
	v_pk_mul_f32 v[2:3], v[2:3], v[88:89] op_sel:[1,0]
	s_nop 0
	v_pk_fma_f32 v[0:1], v[0:1], v[2:3], v[4:5]
	v_and_b32_sdwa v2, v7, v216 dst_sel:DWORD dst_unused:UNUSED_PAD src0_sel:WORD_1 src1_sel:DWORD
	v_and_b32_sdwa v3, v6, v216 dst_sel:DWORD dst_unused:UNUSED_PAD src0_sel:WORD_1 src1_sel:DWORD
	v_add3_u32 v4, v7, v2, s77
	v_add3_u32 v2, v6, v3, s77
	v_and_b32_e32 v5, 0xffff0000, v2
	v_and_b32_sdwa v2, v1, v216 dst_sel:DWORD dst_unused:UNUSED_PAD src0_sel:WORD_1 src1_sel:DWORD
	v_and_b32_sdwa v3, v0, v216 dst_sel:DWORD dst_unused:UNUSED_PAD src0_sel:WORD_1 src1_sel:DWORD
	v_add3_u32 v2, v1, v2, s77
	v_add3_u32 v88, v0, v3, s77
	v_and_b32_e32 v89, 0xffff0000, v2
	v_or_b32_sdwa v3, v89, v4 dst_sel:DWORD dst_unused:UNUSED_PAD src0_sel:DWORD src1_sel:WORD_1
	v_or_b32_sdwa v2, v88, v5 dst_sel:DWORD dst_unused:UNUSED_PAD src0_sel:WORD_1 src1_sel:DWORD
	ds_write_b64 v93, v[2:3]
	v_and_b32_e32 v2, 0xffff0000, v88
	v_sub_u32_e32 v0, v0, v2
	v_sub_u32_e32 v2, v6, v5
	v_and_b32_e32 v3, 0xffff0000, v4
	v_add_u32_e32 v2, 0x80, v2
	v_sub_u32_e32 v3, v7, v3
	v_sub_u32_e32 v1, v1, v89
	v_add_u32_e32 v0, 0x80, v0
	v_ashrrev_i32_e32 v2, 8, v2
	v_add_u32_e32 v3, 0x80, v3
	v_add_u32_e32 v1, 0x80, v1
	v_ashrrev_i32_e32 v0, 8, v0
	v_min_i32_e32 v2, 0x7f, v2
	v_ashrrev_i32_e32 v3, 8, v3
	v_ashrrev_i32_e32 v1, 8, v1
	v_min_i32_e32 v0, 0x7f, v0
	v_min_i32_sdwa v3, v3, s78 dst_sel:WORD_1 dst_unused:UNUSED_PAD src0_sel:DWORD src1_sel:DWORD
	v_min_i32_e32 v1, 0x7f, v1
	v_lshlrev_b32_e32 v2, 8, v2
	v_and_b32_e32 v2, 0xff00, v2
	v_and_b32_e32 v3, 0xff0000, v3
	v_perm_b32 v0, v1, v0, s79
	v_or3_b32 v0, v0, v2, v3
	ds_write_b32 v22, v0 offset:128
	v_mov_b32_e32 v0, v232
	v_mov_b32_e32 v1, v233
	v_mov_b32_e32 v2, v234
	v_mov_b32_e32 v3, v235
	v_mov_b32_e32 v4, v248
	v_mov_b32_e32 v5, v249
	v_mov_b32_e32 v6, v250
	v_mov_b32_e32 v7, v251
	v_mov_b32_e32 v94, v202
	v_mov_b32_e32 v95, v203
	v_pk_add_f32 v[104:105], v[116:117], v[94:95] op_sel_hi:[1,0] neg_lo:[0,1] neg_hi:[0,1]
	s_nop 0
	v_pk_mul_f32 v[104:105], v[94:95], v[104:105] op_sel:[1,0]
	v_pk_add_f32 v[110:111], v[112:113], v[94:95] op_sel_hi:[1,0] neg_lo:[0,1] neg_hi:[0,1]
	v_mov_b32_e32 v88, v1
	v_mov_b32_e32 v89, v2
	v_mov_b32_e32 v90, v5
	v_mov_b32_e32 v91, v6
	v_pk_fma_f32 v[104:105], v[88:89], v[104:105], v[90:91]
	v_pk_mul_f32 v[94:95], v[94:95], v[110:111] op_sel:[1,0]
	v_mov_b32_e32 v1, v3
	v_mov_b32_e32 v5, v7
	v_pk_fma_f32 v[6:7], v[0:1], v[94:95], v[4:5]
	v_and_b32_sdwa v94, v104, v216 dst_sel:DWORD dst_unused:UNUSED_PAD src0_sel:WORD_1 src1_sel:DWORD
	v_add3_u32 v94, v104, v94, s77
	v_and_b32_e32 v95, 0xffff0000, v94
	v_and_b32_sdwa v94, v7, v216 dst_sel:DWORD dst_unused:UNUSED_PAD src0_sel:WORD_1 src1_sel:DWORD
	v_and_b32_sdwa v3, v105, v216 dst_sel:DWORD dst_unused:UNUSED_PAD src0_sel:WORD_1 src1_sel:DWORD
	v_and_b32_sdwa v103, v6, v216 dst_sel:DWORD dst_unused:UNUSED_PAD src0_sel:WORD_1 src1_sel:DWORD
	v_add3_u32 v94, v7, v94, s77
	v_add3_u32 v3, v105, v3, s77
	v_add3_u32 v103, v6, v103, s77
	v_and_b32_e32 v107, 0xffff0000, v94
	v_or_b32_sdwa v111, v107, v3 dst_sel:DWORD dst_unused:UNUSED_PAD src0_sel:DWORD src1_sel:WORD_1
	v_or_b32_sdwa v110, v103, v95 dst_sel:DWORD dst_unused:UNUSED_PAD src0_sel:WORD_1 src1_sel:DWORD
	v_and_b32_e32 v103, 0xffff0000, v103
	v_sub_u32_e32 v95, v104, v95
	v_and_b32_e32 v3, 0xffff0000, v3
	v_sub_u32_e32 v6, v6, v103
	v_add_u32_e32 v95, 0x80, v95
	v_sub_u32_e32 v3, v105, v3
	v_sub_u32_e32 v7, v7, v107
	v_add_u32_e32 v6, 0x80, v6
	v_ashrrev_i32_e32 v95, 8, v95
	v_add_u32_e32 v3, 0x80, v3
	v_add_u32_e32 v7, 0x80, v7
	v_ashrrev_i32_e32 v6, 8, v6
	v_min_i32_e32 v95, 0x7f, v95
	v_ashrrev_i32_e32 v3, 8, v3
	v_ashrrev_i32_e32 v7, 8, v7
	v_min_i32_e32 v6, 0x7f, v6
	v_min_i32_sdwa v3, v3, s78 dst_sel:WORD_1 dst_unused:UNUSED_PAD src0_sel:DWORD src1_sel:DWORD
	v_min_i32_e32 v7, 0x7f, v7
	v_lshlrev_b32_e32 v95, 8, v95
	v_or_b32_e32 v2, 0x120, v154
	v_and_b32_e32 v95, 0xff00, v95
	v_and_b32_e32 v3, 0xff0000, v3
	v_perm_b32 v6, v7, v6, s79
	v_add_u32_e32 v94, v2, v152
	v_or3_b32 v3, v6, v95, v3
	ds_write_b64 v94, v[110:111]
	ds_write_b32 v12, v3 offset:144
	v_mov_b32_e32 v6, v204
	v_mov_b32_e32 v7, v205
	v_pk_add_f32 v[100:101], v[100:101], v[6:7] op_sel_hi:[1,0] neg_lo:[0,1] neg_hi:[0,1]
	s_nop 0
	v_pk_mul_f32 v[100:101], v[6:7], v[100:101] op_sel:[1,0]
	v_pk_add_f32 v[96:97], v[96:97], v[6:7] op_sel_hi:[1,0] neg_lo:[0,1] neg_hi:[0,1]
	v_pk_fma_f32 v[100:101], v[88:89], v[100:101], v[90:91]
	v_pk_mul_f32 v[6:7], v[6:7], v[96:97] op_sel:[1,0]
	v_and_b32_sdwa v95, v100, v216 dst_sel:DWORD dst_unused:UNUSED_PAD src0_sel:WORD_1 src1_sel:DWORD
	v_pk_fma_f32 v[6:7], v[0:1], v[6:7], v[4:5]
	v_add3_u32 v95, v100, v95, s77
	v_and_b32_e32 v103, 0xffff0000, v95
	v_and_b32_sdwa v95, v7, v216 dst_sel:DWORD dst_unused:UNUSED_PAD src0_sel:WORD_1 src1_sel:DWORD
	v_and_b32_sdwa v3, v101, v216 dst_sel:DWORD dst_unused:UNUSED_PAD src0_sel:WORD_1 src1_sel:DWORD
; #define WAIT_L(n) asm volatile("s_waitcnt lgkmcnt(" #n ")" ::: "memory")
; #define BAR __builtin_amdgcn_s_barrier()
;     ...
;             _Pragma("unroll") for (int m = 0; m < 4; ++m) {
;               const int rr = wr3 * 64 + m * 16 + fr3;
;               const float2 ms = *reinterpret_cast<const float2*>(mr + (ai * HALF + rr) * 2);
;               f32x4 y = acc[ai][bj][m][n];
;               const float o0 = (y[0] - ms.x) * ms.y * gm.x + bt.x, o1 = (y[1] - ms.x) * ms.y * gm.y + bt.y;
;               const float o2 = (y[2] - ms.x) * ms.y * gm.z + bt.z, o3 = (y[3] - ms.x) * ms.y * gm.w + bt.w;
;               const unsigned h0 = f2bf(o0), h1 = f2bf(o1), h2 = f2bf(o2), h3 = f2bf(o3);
;               u32x2 ob; ob[0] = h0 | (h1 << 16); ob[1] = h2 | (h3 << 16);
;               *reinterpret_cast<u32x2*>(smem + (rr >> 1) * PIECE + (rr & 1) * 512 + cc * 2) = ob;
;               const int l0 = min(((int)__float_as_uint(o0) - (int)(h0 << 16) + 128) >> 8, 127);
;               const int l1 = min(((int)__float_as_uint(o1) - (int)(h1 << 16) + 128) >> 8, 127);
;               const int l2 = min(((int)__float_as_uint(o2) - (int)(h2 << 16) + 128) >> 8, 127);
;               const int l3 = min(((int)__float_as_uint(o3) - (int)(h3 << 16) + 128) >> 8, 127);
;               *reinterpret_cast<unsigned*>(smem + LOBASE + (rr >> 2) * PIECE + (rr & 3) * 256 + cc) =
;                   (unsigned)(l0 & 255) | ((unsigned)(l1 & 255) << 8) | ((unsigned)(l2 & 255) << 16) | ((unsigned)l3 << 24);
;             }
;           }
;           WAIT_L(0); BAR;
	v_and_b32_sdwa v96, v6, v216 dst_sel:DWORD dst_unused:UNUSED_PAD src0_sel:WORD_1 src1_sel:DWORD
	v_add3_u32 v95, v7, v95, s77
	v_add3_u32 v3, v101, v3, s77
	v_add3_u32 v104, v6, v96, s77
	v_and_b32_e32 v105, 0xffff0000, v95
	v_or_b32_sdwa v97, v105, v3 dst_sel:DWORD dst_unused:UNUSED_PAD src0_sel:DWORD src1_sel:WORD_1
	v_or_b32_sdwa v96, v104, v103 dst_sel:DWORD dst_unused:UNUSED_PAD src0_sel:WORD_1 src1_sel:DWORD
	v_add_u32_e32 v95, v2, v153
	ds_write_b64 v95, v[96:97]
	v_and_b32_e32 v96, 0xffff0000, v104
	v_sub_u32_e32 v6, v6, v96
	v_sub_u32_e32 v96, v100, v103
	v_and_b32_e32 v3, 0xffff0000, v3
	v_add_u32_e32 v96, 0x80, v96
	v_sub_u32_e32 v3, v101, v3
	v_sub_u32_e32 v7, v7, v105
	v_add_u32_e32 v6, 0x80, v6
	v_ashrrev_i32_e32 v96, 8, v96
	v_add_u32_e32 v3, 0x80, v3
	v_add_u32_e32 v7, 0x80, v7
	v_ashrrev_i32_e32 v6, 8, v6
	v_min_i32_e32 v96, 0x7f, v96
	v_ashrrev_i32_e32 v3, 8, v3
	v_ashrrev_i32_e32 v7, 8, v7
	v_min_i32_e32 v6, 0x7f, v6
	v_min_i32_sdwa v3, v3, s78 dst_sel:WORD_1 dst_unused:UNUSED_PAD src0_sel:DWORD src1_sel:DWORD
	v_min_i32_e32 v7, 0x7f, v7
	v_lshlrev_b32_e32 v96, 8, v96
	v_and_b32_e32 v96, 0xff00, v96
	v_and_b32_e32 v3, 0xff0000, v3
	v_perm_b32 v6, v7, v6, s79
	v_or3_b32 v3, v6, v96, v3
	ds_write_b32 v14, v3 offset:144
	v_mov_b32_e32 v6, v206
	v_mov_b32_e32 v7, v207
	v_pk_add_f32 v[84:85], v[84:85], v[6:7] op_sel_hi:[1,0] neg_lo:[0,1] neg_hi:[0,1]
	s_nop 0
	v_pk_mul_f32 v[84:85], v[6:7], v[84:85] op_sel:[1,0]
	v_pk_add_f32 v[80:81], v[80:81], v[6:7] op_sel_hi:[1,0] neg_lo:[0,1] neg_hi:[0,1]
	v_pk_fma_f32 v[84:85], v[88:89], v[84:85], v[90:91]
	v_pk_mul_f32 v[6:7], v[6:7], v[80:81] op_sel:[1,0]
	v_and_b32_sdwa v80, v84, v216 dst_sel:DWORD dst_unused:UNUSED_PAD src0_sel:WORD_1 src1_sel:DWORD
	v_pk_fma_f32 v[6:7], v[0:1], v[6:7], v[4:5]
	v_add3_u32 v80, v84, v80, s77
	v_and_b32_e32 v81, 0xffff0000, v80
	v_and_b32_sdwa v80, v7, v216 dst_sel:DWORD dst_unused:UNUSED_PAD src0_sel:WORD_1 src1_sel:DWORD
	v_and_b32_sdwa v3, v85, v216 dst_sel:DWORD dst_unused:UNUSED_PAD src0_sel:WORD_1 src1_sel:DWORD
	v_and_b32_sdwa v96, v6, v216 dst_sel:DWORD dst_unused:UNUSED_PAD src0_sel:WORD_1 src1_sel:DWORD
	v_add3_u32 v80, v7, v80, s77
	v_add3_u32 v3, v85, v3, s77
	v_add3_u32 v100, v6, v96, s77
	v_and_b32_e32 v101, 0xffff0000, v80
	v_or_b32_sdwa v97, v101, v3 dst_sel:DWORD dst_unused:UNUSED_PAD src0_sel:DWORD src1_sel:WORD_1
	v_or_b32_sdwa v96, v100, v81 dst_sel:DWORD dst_unused:UNUSED_PAD src0_sel:WORD_1 src1_sel:DWORD
	v_add_u32_e32 v80, v2, v137
	ds_write_b64 v80, v[96:97]
	v_and_b32_e32 v96, 0xffff0000, v100
	v_sub_u32_e32 v81, v84, v81
	v_and_b32_e32 v3, 0xffff0000, v3
	v_sub_u32_e32 v6, v6, v96
	v_add_u32_e32 v81, 0x80, v81
	v_sub_u32_e32 v3, v85, v3
	v_sub_u32_e32 v7, v7, v101
	v_add_u32_e32 v6, 0x80, v6
	v_ashrrev_i32_e32 v81, 8, v81
	v_add_u32_e32 v3, 0x80, v3
	v_add_u32_e32 v7, 0x80, v7
	v_ashrrev_i32_e32 v6, 8, v6
	v_min_i32_e32 v81, 0x7f, v81
	v_ashrrev_i32_e32 v3, 8, v3
	v_ashrrev_i32_e32 v7, 8, v7
	v_min_i32_e32 v6, 0x7f, v6
	v_min_i32_sdwa v3, v3, s78 dst_sel:WORD_1 dst_unused:UNUSED_PAD src0_sel:DWORD src1_sel:DWORD
	v_min_i32_e32 v7, 0x7f, v7
	v_lshlrev_b32_e32 v81, 8, v81
	v_and_b32_e32 v81, 0xff00, v81
	v_and_b32_e32 v3, 0xff0000, v3
	v_perm_b32 v6, v7, v6, s79
	v_or3_b32 v3, v6, v81, v3
	ds_write_b32 v18, v3 offset:144
	v_mov_b32_e32 v6, v208
	v_mov_b32_e32 v7, v209
	v_or_b32_e32 v81, 0x6000, v148
	v_or_b32_e32 v96, 0x6000, v146
	v_pk_add_f32 v[72:73], v[72:73], v[6:7] op_sel_hi:[1,0] neg_lo:[0,1] neg_hi:[0,1]
	s_nop 0
	v_pk_mul_f32 v[72:73], v[6:7], v[72:73] op_sel:[1,0]
	s_nop 0
	v_pk_fma_f32 v[84:85], v[88:89], v[72:73], v[90:91]
	v_pk_add_f32 v[72:73], v[74:75], v[6:7] op_sel_hi:[1,0] neg_lo:[0,1] neg_hi:[0,1]
	v_and_b32_sdwa v3, v85, v216 dst_sel:DWORD dst_unused:UNUSED_PAD src0_sel:WORD_1 src1_sel:DWORD
	v_pk_mul_f32 v[6:7], v[6:7], v[72:73] op_sel:[1,0]
	v_add3_u32 v3, v85, v3, s77
	v_pk_fma_f32 v[0:1], v[0:1], v[6:7], v[4:5]
	v_and_b32_sdwa v4, v84, v216 dst_sel:DWORD dst_unused:UNUSED_PAD src0_sel:WORD_1 src1_sel:DWORD
	v_add3_u32 v4, v84, v4, s77
	v_and_b32_e32 v6, 0xffff0000, v4
	v_and_b32_sdwa v4, v1, v216 dst_sel:DWORD dst_unused:UNUSED_PAD src0_sel:WORD_1 src1_sel:DWORD
	v_and_b32_sdwa v5, v0, v216 dst_sel:DWORD dst_unused:UNUSED_PAD src0_sel:WORD_1 src1_sel:DWORD
	v_add3_u32 v4, v1, v4, s77
	v_add3_u32 v7, v0, v5, s77
	v_and_b32_e32 v72, 0xffff0000, v4
	v_add_u32_e32 v73, v2, v136
	v_and_b32_e32 v2, 0xffff0000, v7
	v_or_b32_sdwa v5, v72, v3 dst_sel:DWORD dst_unused:UNUSED_PAD src0_sel:DWORD src1_sel:WORD_1
	v_sub_u32_e32 v0, v0, v2
	v_sub_u32_e32 v2, v84, v6
	v_and_b32_e32 v3, 0xffff0000, v3
	v_add_u32_e32 v2, 0x80, v2
	v_sub_u32_e32 v3, v85, v3
	v_sub_u32_e32 v1, v1, v72
	v_add_u32_e32 v0, 0x80, v0
	v_ashrrev_i32_e32 v2, 8, v2
	v_add_u32_e32 v3, 0x80, v3
	v_add_u32_e32 v1, 0x80, v1
	v_ashrrev_i32_e32 v0, 8, v0
	v_min_i32_e32 v2, 0x7f, v2
	v_ashrrev_i32_e32 v3, 8, v3
	v_ashrrev_i32_e32 v1, 8, v1
	v_min_i32_e32 v0, 0x7f, v0
	v_min_i32_sdwa v3, v3, s78 dst_sel:WORD_1 dst_unused:UNUSED_PAD src0_sel:DWORD src1_sel:DWORD
	v_min_i32_e32 v1, 0x7f, v1
	v_lshlrev_b32_e32 v2, 8, v2
	v_and_b32_e32 v2, 0xff00, v2
	v_and_b32_e32 v3, 0xff0000, v3
	v_perm_b32 v0, v1, v0, s79
	v_or_b32_sdwa v4, v7, v6 dst_sel:DWORD dst_unused:UNUSED_PAD src0_sel:WORD_1 src1_sel:DWORD
	v_or3_b32 v0, v0, v2, v3
	ds_write_b64 v73, v[4:5]
	ds_write_b32 v22, v0 offset:144
	v_add_u32_e32 v72, s59, v151
	s_waitcnt lgkmcnt(0)
	s_barrier
; #define WAIT_L(n) asm volatile("s_waitcnt lgkmcnt(" #n ")" ::: "memory")
; #define BAR __builtin_amdgcn_s_barrier()
;     ...
;             _Pragma("unroll") for (int m = 0; m < 4; ++m) {
;               const int rr = wr3 * 64 + m * 16 + fr3;
;               const float2 ms = *reinterpret_cast<const float2*>(mr + (ai * HALF + rr) * 2);
;               f32x4 y = acc[ai][bj][m][n];
;               const float o0 = (y[0] - ms.x) * ms.y * gm.x + bt.x, o1 = (y[1] - ms.x) * ms.y * gm.y + bt.y;
;               const float o2 = (y[2] - ms.x) * ms.y * gm.z + bt.z, o3 = (y[3] - ms.x) * ms.y * gm.w + bt.w;
;               const unsigned h0 = f2bf(o0), h1 = f2bf(o1), h2 = f2bf(o2), h3 = f2bf(o3);
;               u32x2 ob; ob[0] = h0 | (h1 << 16); ob[1] = h2 | (h3 << 16);
;               *reinterpret_cast<u32x2*>(smem + (rr >> 1) * PIECE + (rr & 1) * 512 + cc * 2) = ob;
;               const int l0 = min(((int)__float_as_uint(o0) - (int)(h0 << 16) + 128) >> 8, 127);
;               const int l1 = min(((int)__float_as_uint(o1) - (int)(h1 << 16) + 128) >> 8, 127);
;               const int l2 = min(((int)__float_as_uint(o2) - (int)(h2 << 16) + 128) >> 8, 127);
;               const int l3 = min(((int)__float_as_uint(o3) - (int)(h3 << 16) + 128) >> 8, 127);
;               *reinterpret_cast<unsigned*>(smem + LOBASE + (rr >> 2) * PIECE + (rr & 3) * 256 + cc) =
;                   (unsigned)(l0 & 255) | ((unsigned)(l1 & 255) << 8) | ((unsigned)(l2 & 255) << 16) | ((unsigned)l3 << 24);
;             }
;     ...
;           WAIT_L(0); BAR;
;           const int hso = ((brow + ai * HALF + 16 * wave) * DM + pn * BM) * 2;
;           const int lso = (brow + ai * HALF + 16 * wave) * DM + pn * BM;
;           _Pragma("unroll") for (int i = 0; i < 8; ++i) {
;             const u32x4 v = *reinterpret_cast<const u32x4*>(smem + (wave * 8 + i) * PIECE + lane3 * 16);
;             __builtin_amdgcn_raw_buffer_store_b128(v, rsXB, hvo + i * (2 * DM * 2), hso, 0);
;           }
;           _Pragma("unroll") for (int i = 0; i < 4; ++i) {
;             const u32x4 v = *reinterpret_cast<const u32x4*>(smem + LOBASE + (wave * 4 + i) * PIECE + lane3 * 16);
;             __builtin_amdgcn_raw_buffer_store_b128(v, rsLO, lvo + i * (4 * DM), lso, 0);
;           }
	ds_read_b128 v[128:131], v72
	v_or_b32_e32 v74, 0x2000, v148
	v_or_b32_e32 v75, 0x4000, v148
	v_or_b32_e32 v84, 0x8000, v148
	v_or_b32_e32 v85, 0xa000, v148
	ds_read_b128 v[136:139], v72 offset:1040
	v_or_b32_e32 v88, 0xc000, v148
	v_or_b32_e32 v89, 0xe000, v148
	v_or_b32_e32 v90, 0x2000, v146
	v_or_b32_e32 v91, 0x4000, v146
	ds_read_b128 v[140:143], v72 offset:2080
	ds_read_b128 v[152:155], v72 offset:3120
	ds_read_b128 v[156:159], v72 offset:4160
	ds_read_b128 v[160:163], v72 offset:5200
	ds_read_b128 v[164:167], v72 offset:6240
	ds_read_b128 v[168:171], v72 offset:7280
	ds_read_b128 v[172:175], v147
	ds_read_b128 v[176:179], v147 offset:1040
	ds_read_b128 v[180:183], v147 offset:2080
	ds_read_b128 v[184:187], v147 offset:3120
	s_waitcnt lgkmcnt(0)
	s_barrier
	s_nop 1
	v_mov_b32_e32 v0, v220
	v_mov_b32_e32 v1, v221
	v_mov_b32_e32 v2, v222
	v_mov_b32_e32 v3, v223
	v_mov_b32_e32 v4, v236
	v_mov_b32_e32 v5, v237
	v_mov_b32_e32 v6, v238
	v_mov_b32_e32 v7, v239
	ds_read_b64 v[110:111], v149 offset:1024
	s_waitcnt lgkmcnt(0)
	v_mov_b32_e32 v210, v110
	v_mov_b32_e32 v211, v111
	v_pk_add_f32 v[64:65], v[64:65], v[110:111] op_sel_hi:[1,0] neg_lo:[0,1] neg_hi:[0,1]
	s_nop 0
	v_pk_mul_f32 v[64:65], v[110:111], v[64:65] op_sel:[1,0]
	v_pk_add_f32 v[66:67], v[66:67], v[110:111] op_sel_hi:[1,0] neg_lo:[0,1] neg_hi:[0,1]
	v_mov_b32_e32 v100, v1
	v_mov_b32_e32 v101, v2
	v_mov_b32_e32 v104, v5
	v_mov_b32_e32 v105, v6
	v_pk_fma_f32 v[64:65], v[100:101], v[64:65], v[104:105]
	v_pk_mul_f32 v[66:67], v[110:111], v[66:67] op_sel:[1,0]
	v_mov_b32_e32 v1, v3
	v_mov_b32_e32 v5, v7
	v_and_b32_sdwa v6, v65, v216 dst_sel:DWORD dst_unused:UNUSED_PAD src0_sel:WORD_1 src1_sel:DWORD
	v_and_b32_sdwa v7, v64, v216 dst_sel:DWORD dst_unused:UNUSED_PAD src0_sel:WORD_1 src1_sel:DWORD
	v_pk_fma_f32 v[2:3], v[0:1], v[66:67], v[4:5]
	v_add3_u32 v66, v65, v6, s77
	v_add3_u32 v6, v64, v7, s77
	v_and_b32_e32 v67, 0xffff0000, v6
	v_and_b32_sdwa v6, v3, v216 dst_sel:DWORD dst_unused:UNUSED_PAD src0_sel:WORD_1 src1_sel:DWORD
	v_and_b32_sdwa v7, v2, v216 dst_sel:DWORD dst_unused:UNUSED_PAD src0_sel:WORD_1 src1_sel:DWORD
	v_add3_u32 v6, v3, v6, s77
	v_add3_u32 v97, v2, v7, s77
	v_and_b32_e32 v103, 0xffff0000, v6
	v_or_b32_sdwa v7, v103, v66 dst_sel:DWORD dst_unused:UNUSED_PAD src0_sel:DWORD src1_sel:WORD_1
	v_or_b32_sdwa v6, v97, v67 dst_sel:DWORD dst_unused:UNUSED_PAD src0_sel:WORD_1 src1_sel:DWORD
	ds_write_b64 v132, v[6:7]
	v_and_b32_e32 v6, 0xffff0000, v97
	v_sub_u32_e32 v2, v2, v6
	v_sub_u32_e32 v6, v64, v67
	v_and_b32_e32 v7, 0xffff0000, v66
	v_add_u32_e32 v6, 0x80, v6
	v_sub_u32_e32 v7, v65, v7
	v_sub_u32_e32 v3, v3, v103
	v_add_u32_e32 v2, 0x80, v2
	v_ashrrev_i32_e32 v6, 8, v6
	v_add_u32_e32 v7, 0x80, v7
	v_add_u32_e32 v3, 0x80, v3
	v_ashrrev_i32_e32 v2, 8, v2
	v_min_i32_e32 v6, 0x7f, v6
	v_ashrrev_i32_e32 v7, 8, v7
	v_ashrrev_i32_e32 v3, 8, v3
	v_min_i32_e32 v2, 0x7f, v2
	v_min_i32_sdwa v7, v7, s78 dst_sel:WORD_1 dst_unused:UNUSED_PAD src0_sel:DWORD src1_sel:DWORD
	v_min_i32_e32 v3, 0x7f, v3
	v_lshlrev_b32_e32 v6, 8, v6
	v_and_b32_e32 v6, 0xff00, v6
	v_and_b32_e32 v7, 0xff0000, v7
	v_perm_b32 v2, v3, v2, s79
	v_or3_b32 v2, v2, v6, v7
	ds_write_b32 v12, v2
	buffer_store_dwordx4 v[128:131], v148, s[16:19], s76 offen
	ds_read_b64 v[2:3], v13 offset:1024
	s_waitcnt lgkmcnt(0)
	v_mov_b32_e32 v212, v2
	v_mov_b32_e32 v213, v3
	v_pk_add_f32 v[6:7], v[68:69], v[2:3] op_sel_hi:[1,0] neg_lo:[0,1] neg_hi:[0,1]
	s_nop 0
	v_pk_mul_f32 v[6:7], v[2:3], v[6:7] op_sel:[1,0]
	v_pk_add_f32 v[64:65], v[70:71], v[2:3] op_sel_hi:[1,0] neg_lo:[0,1] neg_hi:[0,1]
	v_pk_fma_f32 v[6:7], v[100:101], v[6:7], v[104:105]
	v_pk_mul_f32 v[2:3], v[2:3], v[64:65] op_sel:[1,0]
	v_and_b32_sdwa v64, v7, v216 dst_sel:DWORD dst_unused:UNUSED_PAD src0_sel:WORD_1 src1_sel:DWORD
	v_and_b32_sdwa v65, v6, v216 dst_sel:DWORD dst_unused:UNUSED_PAD src0_sel:WORD_1 src1_sel:DWORD
	v_pk_fma_f32 v[2:3], v[0:1], v[2:3], v[4:5]
	v_add3_u32 v66, v7, v64, s77
	v_add3_u32 v64, v6, v65, s77
	v_and_b32_e32 v67, 0xffff0000, v64
	v_and_b32_sdwa v64, v3, v216 dst_sel:DWORD dst_unused:UNUSED_PAD src0_sel:WORD_1 src1_sel:DWORD
	v_and_b32_sdwa v65, v2, v216 dst_sel:DWORD dst_unused:UNUSED_PAD src0_sel:WORD_1 src1_sel:DWORD
	v_add3_u32 v64, v3, v64, s77
	v_add3_u32 v68, v2, v65, s77
	v_and_b32_e32 v69, 0xffff0000, v64
	v_or_b32_sdwa v65, v69, v66 dst_sel:DWORD dst_unused:UNUSED_PAD src0_sel:DWORD src1_sel:WORD_1
	v_or_b32_sdwa v64, v68, v67 dst_sel:DWORD dst_unused:UNUSED_PAD src0_sel:WORD_1 src1_sel:DWORD
	ds_write_b64 v133, v[64:65]
	v_and_b32_e32 v64, 0xffff0000, v68
	v_sub_u32_e32 v2, v2, v64
	v_sub_u32_e32 v6, v6, v67
	v_and_b32_e32 v64, 0xffff0000, v66
	v_add_u32_e32 v6, 0x80, v6
	v_sub_u32_e32 v7, v7, v64
	v_sub_u32_e32 v3, v3, v69
	v_add_u32_e32 v2, 0x80, v2
	v_ashrrev_i32_e32 v6, 8, v6
	v_add_u32_e32 v7, 0x80, v7
	v_add_u32_e32 v3, 0x80, v3
	v_ashrrev_i32_e32 v2, 8, v2
	v_min_i32_e32 v6, 0x7f, v6
	v_ashrrev_i32_e32 v7, 8, v7
	v_ashrrev_i32_e32 v3, 8, v3
	v_min_i32_e32 v2, 0x7f, v2
	v_min_i32_sdwa v7, v7, s78 dst_sel:WORD_1 dst_unused:UNUSED_PAD src0_sel:DWORD src1_sel:DWORD
	v_min_i32_e32 v3, 0x7f, v3
	v_lshlrev_b32_e32 v6, 8, v6
	v_and_b32_e32 v6, 0xff00, v6
	v_and_b32_e32 v7, 0xff0000, v7
	v_perm_b32 v2, v3, v2, s79
	v_or3_b32 v2, v2, v6, v7
	ds_write_b32 v14, v2
	buffer_store_dwordx4 v[136:139], v74, s[16:19], s76 offen
	ds_read_b64 v[2:3], v15 offset:1024
	s_waitcnt lgkmcnt(0)
;     ...
;             _Pragma("unroll") for (int m = 0; m < 4; ++m) {
;               const int rr = wr3 * 64 + m * 16 + fr3;
;               const float2 ms = *reinterpret_cast<const float2*>(mr + (ai * HALF + rr) * 2);
;               f32x4 y = acc[ai][bj][m][n];
;               const float o0 = (y[0] - ms.x) * ms.y * gm.x + bt.x, o1 = (y[1] - ms.x) * ms.y * gm.y + bt.y;
;               const float o2 = (y[2] - ms.x) * ms.y * gm.z + bt.z, o3 = (y[3] - ms.x) * ms.y * gm.w + bt.w;
;               const unsigned h0 = f2bf(o0), h1 = f2bf(o1), h2 = f2bf(o2), h3 = f2bf(o3);
;               u32x2 ob; ob[0] = h0 | (h1 << 16); ob[1] = h2 | (h3 << 16);
;               *reinterpret_cast<u32x2*>(smem + (rr >> 1) * PIECE + (rr & 1) * 512 + cc * 2) = ob;
;               const int l0 = min(((int)__float_as_uint(o0) - (int)(h0 << 16) + 128) >> 8, 127);
;               const int l1 = min(((int)__float_as_uint(o1) - (int)(h1 << 16) + 128) >> 8, 127);
;               const int l2 = min(((int)__float_as_uint(o2) - (int)(h2 << 16) + 128) >> 8, 127);
;               const int l3 = min(((int)__float_as_uint(o3) - (int)(h3 << 16) + 128) >> 8, 127);
;               *reinterpret_cast<unsigned*>(smem + LOBASE + (rr >> 2) * PIECE + (rr & 3) * 256 + cc) =
;                   (unsigned)(l0 & 255) | ((unsigned)(l1 & 255) << 8) | ((unsigned)(l2 & 255) << 16) | ((unsigned)l3 << 24);
;             }
	v_mov_b32_e32 v214, v2
	v_mov_b32_e32 v215, v3
	v_pk_add_f32 v[6:7], v[76:77], v[2:3] op_sel_hi:[1,0] neg_lo:[0,1] neg_hi:[0,1]
	s_nop 0
	v_pk_mul_f32 v[6:7], v[2:3], v[6:7] op_sel:[1,0]
	v_pk_add_f32 v[64:65], v[78:79], v[2:3] op_sel_hi:[1,0] neg_lo:[0,1] neg_hi:[0,1]
	v_pk_fma_f32 v[6:7], v[100:101], v[6:7], v[104:105]
	v_pk_mul_f32 v[2:3], v[2:3], v[64:65] op_sel:[1,0]
	v_and_b32_sdwa v64, v7, v216 dst_sel:DWORD dst_unused:UNUSED_PAD src0_sel:WORD_1 src1_sel:DWORD
	v_and_b32_sdwa v65, v6, v216 dst_sel:DWORD dst_unused:UNUSED_PAD src0_sel:WORD_1 src1_sel:DWORD
	v_pk_fma_f32 v[2:3], v[0:1], v[2:3], v[4:5]
	v_add3_u32 v66, v7, v64, s77
	v_add3_u32 v64, v6, v65, s77
	v_and_b32_e32 v67, 0xffff0000, v64
	v_and_b32_sdwa v64, v3, v216 dst_sel:DWORD dst_unused:UNUSED_PAD src0_sel:WORD_1 src1_sel:DWORD
	v_and_b32_sdwa v65, v2, v216 dst_sel:DWORD dst_unused:UNUSED_PAD src0_sel:WORD_1 src1_sel:DWORD
	v_add3_u32 v64, v3, v64, s77
	v_add3_u32 v68, v2, v65, s77
	v_and_b32_e32 v69, 0xffff0000, v64
	v_or_b32_sdwa v65, v69, v66 dst_sel:DWORD dst_unused:UNUSED_PAD src0_sel:DWORD src1_sel:WORD_1
	v_or_b32_sdwa v64, v68, v67 dst_sel:DWORD dst_unused:UNUSED_PAD src0_sel:WORD_1 src1_sel:DWORD
	ds_write_b64 v134, v[64:65]
	v_and_b32_e32 v64, 0xffff0000, v68
	v_sub_u32_e32 v2, v2, v64
	v_sub_u32_e32 v6, v6, v67
	v_and_b32_e32 v64, 0xffff0000, v66
	v_add_u32_e32 v6, 0x80, v6
	v_sub_u32_e32 v7, v7, v64
	v_sub_u32_e32 v3, v3, v69
	v_add_u32_e32 v2, 0x80, v2
	v_ashrrev_i32_e32 v6, 8, v6
	v_add_u32_e32 v7, 0x80, v7
	v_add_u32_e32 v3, 0x80, v3
	v_ashrrev_i32_e32 v2, 8, v2
	v_min_i32_e32 v6, 0x7f, v6
	v_ashrrev_i32_e32 v7, 8, v7
	v_ashrrev_i32_e32 v3, 8, v3
	v_min_i32_e32 v2, 0x7f, v2
	v_min_i32_sdwa v7, v7, s78 dst_sel:WORD_1 dst_unused:UNUSED_PAD src0_sel:DWORD src1_sel:DWORD
	v_min_i32_e32 v3, 0x7f, v3
	v_lshlrev_b32_e32 v6, 8, v6
	v_and_b32_e32 v6, 0xff00, v6
	v_and_b32_e32 v7, 0xff0000, v7
	v_perm_b32 v2, v3, v2, s79
	v_or3_b32 v2, v2, v6, v7
	ds_write_b32 v18, v2
	buffer_store_dwordx4 v[140:143], v75, s[16:19], s76 offen
	ds_read_b64 v[2:3], v19 offset:1024
	s_waitcnt lgkmcnt(0)
	v_mov_b32_e32 v252, v2
	v_mov_b32_e32 v253, v3
	v_pk_add_f32 v[6:7], v[82:83], v[2:3] op_sel_hi:[1,0] neg_lo:[0,1] neg_hi:[0,1]
	s_nop 0
	v_pk_mul_f32 v[6:7], v[2:3], v[6:7] op_sel:[1,0]
	v_pk_add_f32 v[64:65], v[86:87], v[2:3] op_sel_hi:[1,0] neg_lo:[0,1] neg_hi:[0,1]
	v_pk_fma_f32 v[6:7], v[100:101], v[6:7], v[104:105]
	v_pk_mul_f32 v[2:3], v[2:3], v[64:65] op_sel:[1,0]
	s_nop 0
	v_pk_fma_f32 v[0:1], v[0:1], v[2:3], v[4:5]
	v_and_b32_sdwa v2, v7, v216 dst_sel:DWORD dst_unused:UNUSED_PAD src0_sel:WORD_1 src1_sel:DWORD
	v_and_b32_sdwa v3, v6, v216 dst_sel:DWORD dst_unused:UNUSED_PAD src0_sel:WORD_1 src1_sel:DWORD
	v_add3_u32 v4, v7, v2, s77
	v_add3_u32 v2, v6, v3, s77
	v_and_b32_e32 v5, 0xffff0000, v2
	v_and_b32_sdwa v2, v1, v216 dst_sel:DWORD dst_unused:UNUSED_PAD src0_sel:WORD_1 src1_sel:DWORD
	v_and_b32_sdwa v3, v0, v216 dst_sel:DWORD dst_unused:UNUSED_PAD src0_sel:WORD_1 src1_sel:DWORD
	v_add3_u32 v2, v1, v2, s77
	v_add3_u32 v64, v0, v3, s77
	v_and_b32_e32 v65, 0xffff0000, v2
	v_or_b32_sdwa v3, v65, v4 dst_sel:DWORD dst_unused:UNUSED_PAD src0_sel:DWORD src1_sel:WORD_1
	v_or_b32_sdwa v2, v64, v5 dst_sel:DWORD dst_unused:UNUSED_PAD src0_sel:WORD_1 src1_sel:DWORD
	ds_write_b64 v135, v[2:3]
	v_and_b32_e32 v2, 0xffff0000, v64
	v_sub_u32_e32 v0, v0, v2
	v_sub_u32_e32 v2, v6, v5
	v_and_b32_e32 v3, 0xffff0000, v4
	v_add_u32_e32 v2, 0x80, v2
	v_sub_u32_e32 v3, v7, v3
	v_sub_u32_e32 v1, v1, v65
	v_add_u32_e32 v0, 0x80, v0
	v_ashrrev_i32_e32 v2, 8, v2
	v_add_u32_e32 v3, 0x80, v3
	v_add_u32_e32 v1, 0x80, v1
	v_ashrrev_i32_e32 v0, 8, v0
	v_min_i32_e32 v2, 0x7f, v2
	v_ashrrev_i32_e32 v3, 8, v3
	v_ashrrev_i32_e32 v1, 8, v1
	v_min_i32_e32 v0, 0x7f, v0
	v_min_i32_sdwa v3, v3, s78 dst_sel:WORD_1 dst_unused:UNUSED_PAD src0_sel:DWORD src1_sel:DWORD
	v_min_i32_e32 v1, 0x7f, v1
	v_lshlrev_b32_e32 v2, 8, v2
	v_and_b32_e32 v2, 0xff00, v2
	v_and_b32_e32 v3, 0xff0000, v3
	v_perm_b32 v0, v1, v0, s79
	v_or3_b32 v0, v0, v2, v3
	ds_write_b32 v22, v0
	buffer_store_dwordx4 v[152:155], v81, s[16:19], s76 offen
	v_mov_b32_e32 v0, v224
	v_mov_b32_e32 v1, v225
	v_mov_b32_e32 v2, v226
	v_mov_b32_e32 v3, v227
	v_mov_b32_e32 v4, v240
	v_mov_b32_e32 v5, v241
	v_mov_b32_e32 v6, v242
	v_mov_b32_e32 v7, v243
	v_mov_b32_e32 v68, v210
	v_mov_b32_e32 v69, v211
	v_pk_add_f32 v[60:61], v[60:61], v[68:69] op_sel_hi:[1,0] neg_lo:[0,1] neg_hi:[0,1]
	s_nop 0
	v_pk_mul_f32 v[60:61], v[68:69], v[60:61] op_sel:[1,0]
	v_pk_add_f32 v[58:59], v[58:59], v[68:69] op_sel_hi:[1,0] neg_lo:[0,1] neg_hi:[0,1]
	v_mov_b32_e32 v64, v1
	v_mov_b32_e32 v65, v2
	v_mov_b32_e32 v66, v5
	v_mov_b32_e32 v67, v6
	v_pk_fma_f32 v[60:61], v[64:65], v[60:61], v[66:67]
	v_pk_mul_f32 v[58:59], v[68:69], v[58:59] op_sel:[1,0]
	v_mov_b32_e32 v1, v3
	v_mov_b32_e32 v5, v7
	v_and_b32_sdwa v6, v61, v216 dst_sel:DWORD dst_unused:UNUSED_PAD src0_sel:WORD_1 src1_sel:DWORD
	v_and_b32_sdwa v7, v60, v216 dst_sel:DWORD dst_unused:UNUSED_PAD src0_sel:WORD_1 src1_sel:DWORD
	v_pk_fma_f32 v[2:3], v[0:1], v[58:59], v[4:5]
	v_add3_u32 v58, v61, v6, s77
	v_add3_u32 v6, v60, v7, s77
	v_and_b32_e32 v59, 0xffff0000, v6
	v_and_b32_sdwa v6, v3, v216 dst_sel:DWORD dst_unused:UNUSED_PAD src0_sel:WORD_1 src1_sel:DWORD
	v_and_b32_sdwa v7, v2, v216 dst_sel:DWORD dst_unused:UNUSED_PAD src0_sel:WORD_1 src1_sel:DWORD
	v_add3_u32 v6, v3, v6, s77
	v_add3_u32 v68, v2, v7, s77
	v_and_b32_e32 v69, 0xffff0000, v6
	v_or_b32_sdwa v7, v69, v58 dst_sel:DWORD dst_unused:UNUSED_PAD src0_sel:DWORD src1_sel:WORD_1
	v_or_b32_sdwa v6, v68, v59 dst_sel:DWORD dst_unused:UNUSED_PAD src0_sel:WORD_1 src1_sel:DWORD
;     ...
;             _Pragma("unroll") for (int m = 0; m < 4; ++m) {
;               const int rr = wr3 * 64 + m * 16 + fr3;
;               const float2 ms = *reinterpret_cast<const float2*>(mr + (ai * HALF + rr) * 2);
;               f32x4 y = acc[ai][bj][m][n];
;               const float o0 = (y[0] - ms.x) * ms.y * gm.x + bt.x, o1 = (y[1] - ms.x) * ms.y * gm.y + bt.y;
;               const float o2 = (y[2] - ms.x) * ms.y * gm.z + bt.z, o3 = (y[3] - ms.x) * ms.y * gm.w + bt.w;
;               const unsigned h0 = f2bf(o0), h1 = f2bf(o1), h2 = f2bf(o2), h3 = f2bf(o3);
;               u32x2 ob; ob[0] = h0 | (h1 << 16); ob[1] = h2 | (h3 << 16);
;               *reinterpret_cast<u32x2*>(smem + (rr >> 1) * PIECE + (rr & 1) * 512 + cc * 2) = ob;
;               const int l0 = min(((int)__float_as_uint(o0) - (int)(h0 << 16) + 128) >> 8, 127);
;               const int l1 = min(((int)__float_as_uint(o1) - (int)(h1 << 16) + 128) >> 8, 127);
;               const int l2 = min(((int)__float_as_uint(o2) - (int)(h2 << 16) + 128) >> 8, 127);
;               const int l3 = min(((int)__float_as_uint(o3) - (int)(h3 << 16) + 128) >> 8, 127);
;               *reinterpret_cast<unsigned*>(smem + LOBASE + (rr >> 2) * PIECE + (rr & 3) * 256 + cc) =
;                   (unsigned)(l0 & 255) | ((unsigned)(l1 & 255) << 8) | ((unsigned)(l2 & 255) << 16) | ((unsigned)l3 << 24);
;             }
	ds_write_b64 v23, v[6:7]
	v_and_b32_e32 v6, 0xffff0000, v68
	v_sub_u32_e32 v2, v2, v6
	v_sub_u32_e32 v6, v60, v59
	v_and_b32_e32 v7, 0xffff0000, v58
	v_add_u32_e32 v6, 0x80, v6
	v_sub_u32_e32 v7, v61, v7
	v_sub_u32_e32 v3, v3, v69
	v_add_u32_e32 v2, 0x80, v2
	v_ashrrev_i32_e32 v6, 8, v6
	v_add_u32_e32 v7, 0x80, v7
	v_add_u32_e32 v3, 0x80, v3
	v_ashrrev_i32_e32 v2, 8, v2
	v_min_i32_e32 v6, 0x7f, v6
	v_ashrrev_i32_e32 v7, 8, v7
	v_ashrrev_i32_e32 v3, 8, v3
	v_min_i32_e32 v2, 0x7f, v2
	v_min_i32_sdwa v7, v7, s78 dst_sel:WORD_1 dst_unused:UNUSED_PAD src0_sel:DWORD src1_sel:DWORD
	v_min_i32_e32 v3, 0x7f, v3
	v_lshlrev_b32_e32 v6, 8, v6
	v_and_b32_e32 v6, 0xff00, v6
	v_and_b32_e32 v7, 0xff0000, v7
	v_perm_b32 v2, v3, v2, s79
	v_or3_b32 v2, v2, v6, v7
	ds_write_b32 v12, v2 offset:16
	buffer_store_dwordx4 v[156:159], v84, s[16:19], s76 offen
	v_mov_b32_e32 v2, v212
	v_mov_b32_e32 v3, v213
	v_pk_add_f32 v[6:7], v[44:45], v[2:3] op_sel_hi:[1,0] neg_lo:[0,1] neg_hi:[0,1]
	s_nop 0
	v_pk_mul_f32 v[6:7], v[2:3], v[6:7] op_sel:[1,0]
	v_pk_add_f32 v[42:43], v[42:43], v[2:3] op_sel_hi:[1,0] neg_lo:[0,1] neg_hi:[0,1]
	v_pk_fma_f32 v[6:7], v[64:65], v[6:7], v[66:67]
	v_pk_mul_f32 v[2:3], v[2:3], v[42:43] op_sel:[1,0]
	v_and_b32_sdwa v42, v6, v216 dst_sel:DWORD dst_unused:UNUSED_PAD src0_sel:WORD_1 src1_sel:DWORD
	v_pk_fma_f32 v[2:3], v[0:1], v[2:3], v[4:5]
	v_add3_u32 v42, v6, v42, s77
	v_and_b32_e32 v44, 0xffff0000, v42
	v_and_b32_sdwa v42, v3, v216 dst_sel:DWORD dst_unused:UNUSED_PAD src0_sel:WORD_1 src1_sel:DWORD
	v_and_b32_sdwa v23, v7, v216 dst_sel:DWORD dst_unused:UNUSED_PAD src0_sel:WORD_1 src1_sel:DWORD
	v_and_b32_sdwa v43, v2, v216 dst_sel:DWORD dst_unused:UNUSED_PAD src0_sel:WORD_1 src1_sel:DWORD
	v_add3_u32 v42, v3, v42, s77
	v_add3_u32 v23, v7, v23, s77
	v_add3_u32 v45, v2, v43, s77
	v_and_b32_e32 v58, 0xffff0000, v42
	v_or_b32_sdwa v43, v58, v23 dst_sel:DWORD dst_unused:UNUSED_PAD src0_sel:DWORD src1_sel:WORD_1
	v_or_b32_sdwa v42, v45, v44 dst_sel:DWORD dst_unused:UNUSED_PAD src0_sel:WORD_1 src1_sel:DWORD
	ds_write_b64 v108, v[42:43]
	v_and_b32_e32 v42, 0xffff0000, v45
	v_sub_u32_e32 v6, v6, v44
	v_and_b32_e32 v23, 0xffff0000, v23
	v_sub_u32_e32 v2, v2, v42
	v_add_u32_e32 v6, 0x80, v6
	v_sub_u32_e32 v7, v7, v23
	v_sub_u32_e32 v3, v3, v58
	v_add_u32_e32 v2, 0x80, v2
	v_ashrrev_i32_e32 v6, 8, v6
	v_add_u32_e32 v7, 0x80, v7
	v_add_u32_e32 v3, 0x80, v3
	v_ashrrev_i32_e32 v2, 8, v2
	v_min_i32_e32 v6, 0x7f, v6
	v_ashrrev_i32_e32 v7, 8, v7
	v_ashrrev_i32_e32 v3, 8, v3
	v_min_i32_e32 v2, 0x7f, v2
	v_min_i32_sdwa v7, v7, s78 dst_sel:WORD_1 dst_unused:UNUSED_PAD src0_sel:DWORD src1_sel:DWORD
	v_min_i32_e32 v3, 0x7f, v3
	v_lshlrev_b32_e32 v6, 8, v6
	v_and_b32_e32 v6, 0xff00, v6
	v_and_b32_e32 v7, 0xff0000, v7
	v_perm_b32 v2, v3, v2, s79
	v_or3_b32 v2, v2, v6, v7
	ds_write_b32 v14, v2 offset:16
	buffer_store_dwordx4 v[160:163], v85, s[16:19], s76 offen
	v_mov_b32_e32 v2, v214
	v_mov_b32_e32 v3, v215
	v_pk_add_f32 v[6:7], v[34:35], v[2:3] op_sel_hi:[1,0] neg_lo:[0,1] neg_hi:[0,1]
	s_nop 0
	v_pk_mul_f32 v[6:7], v[2:3], v[6:7] op_sel:[1,0]
	v_pk_add_f32 v[34:35], v[46:47], v[2:3] op_sel_hi:[1,0] neg_lo:[0,1] neg_hi:[0,1]
	v_pk_fma_f32 v[6:7], v[64:65], v[6:7], v[66:67]
	v_pk_mul_f32 v[2:3], v[2:3], v[34:35] op_sel:[1,0]
	v_and_b32_sdwa v34, v6, v216 dst_sel:DWORD dst_unused:UNUSED_PAD src0_sel:WORD_1 src1_sel:DWORD
	v_pk_fma_f32 v[2:3], v[0:1], v[2:3], v[4:5]
	v_add3_u32 v34, v6, v34, s77
	v_and_b32_e32 v42, 0xffff0000, v34
	v_and_b32_sdwa v34, v3, v216 dst_sel:DWORD dst_unused:UNUSED_PAD src0_sel:WORD_1 src1_sel:DWORD
	v_and_b32_sdwa v23, v7, v216 dst_sel:DWORD dst_unused:UNUSED_PAD src0_sel:WORD_1 src1_sel:DWORD
	v_and_b32_sdwa v35, v2, v216 dst_sel:DWORD dst_unused:UNUSED_PAD src0_sel:WORD_1 src1_sel:DWORD
	v_add3_u32 v34, v3, v34, s77
	v_add3_u32 v23, v7, v23, s77
	v_add3_u32 v43, v2, v35, s77
	v_and_b32_e32 v44, 0xffff0000, v34
	v_or_b32_sdwa v35, v44, v23 dst_sel:DWORD dst_unused:UNUSED_PAD src0_sel:DWORD src1_sel:WORD_1
	v_or_b32_sdwa v34, v43, v42 dst_sel:DWORD dst_unused:UNUSED_PAD src0_sel:WORD_1 src1_sel:DWORD
	ds_write_b64 v98, v[34:35]
	v_and_b32_e32 v34, 0xffff0000, v43
	v_sub_u32_e32 v6, v6, v42
	v_and_b32_e32 v23, 0xffff0000, v23
	v_sub_u32_e32 v2, v2, v34
	v_add_u32_e32 v6, 0x80, v6
	v_sub_u32_e32 v7, v7, v23
	v_sub_u32_e32 v3, v3, v44
	v_add_u32_e32 v2, 0x80, v2
	v_ashrrev_i32_e32 v6, 8, v6
	v_add_u32_e32 v7, 0x80, v7
	v_add_u32_e32 v3, 0x80, v3
	v_ashrrev_i32_e32 v2, 8, v2
	v_min_i32_e32 v6, 0x7f, v6
	v_ashrrev_i32_e32 v7, 8, v7
	v_ashrrev_i32_e32 v3, 8, v3
	v_min_i32_e32 v2, 0x7f, v2
	v_min_i32_sdwa v7, v7, s78 dst_sel:WORD_1 dst_unused:UNUSED_PAD src0_sel:DWORD src1_sel:DWORD
	v_min_i32_e32 v3, 0x7f, v3
	v_lshlrev_b32_e32 v6, 8, v6
	v_and_b32_e32 v6, 0xff00, v6
	v_and_b32_e32 v7, 0xff0000, v7
	v_perm_b32 v2, v3, v2, s79
	v_or3_b32 v2, v2, v6, v7
	ds_write_b32 v18, v2 offset:16
	buffer_store_dwordx4 v[164:167], v88, s[16:19], s76 offen
	v_mov_b32_e32 v2, v252
	v_mov_b32_e32 v3, v253
	v_pk_add_f32 v[6:7], v[50:51], v[2:3] op_sel_hi:[1,0] neg_lo:[0,1] neg_hi:[0,1]
	s_nop 0
	v_pk_mul_f32 v[6:7], v[2:3], v[6:7] op_sel:[1,0]
	v_pk_add_f32 v[34:35], v[62:63], v[2:3] op_sel_hi:[1,0] neg_lo:[0,1] neg_hi:[0,1]
	v_pk_fma_f32 v[6:7], v[64:65], v[6:7], v[66:67]
	v_pk_mul_f32 v[2:3], v[2:3], v[34:35] op_sel:[1,0]
	s_nop 0
	v_pk_fma_f32 v[0:1], v[0:1], v[2:3], v[4:5]
	v_and_b32_sdwa v2, v7, v216 dst_sel:DWORD dst_unused:UNUSED_PAD src0_sel:WORD_1 src1_sel:DWORD
	v_and_b32_sdwa v3, v6, v216 dst_sel:DWORD dst_unused:UNUSED_PAD src0_sel:WORD_1 src1_sel:DWORD
	v_add3_u32 v4, v7, v2, s77
	v_add3_u32 v2, v6, v3, s77
	v_and_b32_e32 v5, 0xffff0000, v2
;     ...
;             _Pragma("unroll") for (int m = 0; m < 4; ++m) {
;               const int rr = wr3 * 64 + m * 16 + fr3;
;               const float2 ms = *reinterpret_cast<const float2*>(mr + (ai * HALF + rr) * 2);
;               f32x4 y = acc[ai][bj][m][n];
;               const float o0 = (y[0] - ms.x) * ms.y * gm.x + bt.x, o1 = (y[1] - ms.x) * ms.y * gm.y + bt.y;
;               const float o2 = (y[2] - ms.x) * ms.y * gm.z + bt.z, o3 = (y[3] - ms.x) * ms.y * gm.w + bt.w;
;               const unsigned h0 = f2bf(o0), h1 = f2bf(o1), h2 = f2bf(o2), h3 = f2bf(o3);
;               u32x2 ob; ob[0] = h0 | (h1 << 16); ob[1] = h2 | (h3 << 16);
;               *reinterpret_cast<u32x2*>(smem + (rr >> 1) * PIECE + (rr & 1) * 512 + cc * 2) = ob;
;               const int l0 = min(((int)__float_as_uint(o0) - (int)(h0 << 16) + 128) >> 8, 127);
;               const int l1 = min(((int)__float_as_uint(o1) - (int)(h1 << 16) + 128) >> 8, 127);
;               const int l2 = min(((int)__float_as_uint(o2) - (int)(h2 << 16) + 128) >> 8, 127);
;               const int l3 = min(((int)__float_as_uint(o3) - (int)(h3 << 16) + 128) >> 8, 127);
;               *reinterpret_cast<unsigned*>(smem + LOBASE + (rr >> 2) * PIECE + (rr & 3) * 256 + cc) =
;                   (unsigned)(l0 & 255) | ((unsigned)(l1 & 255) << 8) | ((unsigned)(l2 & 255) << 16) | ((unsigned)l3 << 24);
;             }
	v_and_b32_sdwa v2, v1, v216 dst_sel:DWORD dst_unused:UNUSED_PAD src0_sel:WORD_1 src1_sel:DWORD
	v_and_b32_sdwa v3, v0, v216 dst_sel:DWORD dst_unused:UNUSED_PAD src0_sel:WORD_1 src1_sel:DWORD
	v_add3_u32 v2, v1, v2, s77
	v_add3_u32 v23, v0, v3, s77
	v_and_b32_e32 v34, 0xffff0000, v2
	v_or_b32_sdwa v3, v34, v4 dst_sel:DWORD dst_unused:UNUSED_PAD src0_sel:DWORD src1_sel:WORD_1
	v_or_b32_sdwa v2, v23, v5 dst_sel:DWORD dst_unused:UNUSED_PAD src0_sel:WORD_1 src1_sel:DWORD
	ds_write_b64 v99, v[2:3]
	v_and_b32_e32 v2, 0xffff0000, v23
	v_sub_u32_e32 v0, v0, v2
	v_sub_u32_e32 v2, v6, v5
	v_and_b32_e32 v3, 0xffff0000, v4
	v_add_u32_e32 v2, 0x80, v2
	v_sub_u32_e32 v3, v7, v3
	v_sub_u32_e32 v1, v1, v34
	v_add_u32_e32 v0, 0x80, v0
	v_ashrrev_i32_e32 v2, 8, v2
	v_add_u32_e32 v3, 0x80, v3
	v_add_u32_e32 v1, 0x80, v1
	v_ashrrev_i32_e32 v0, 8, v0
	v_min_i32_e32 v2, 0x7f, v2
	v_ashrrev_i32_e32 v3, 8, v3
	v_ashrrev_i32_e32 v1, 8, v1
	v_min_i32_e32 v0, 0x7f, v0
	v_min_i32_sdwa v3, v3, s78 dst_sel:WORD_1 dst_unused:UNUSED_PAD src0_sel:DWORD src1_sel:DWORD
	v_min_i32_e32 v1, 0x7f, v1
	v_lshlrev_b32_e32 v2, 8, v2
	v_and_b32_e32 v2, 0xff00, v2
	v_and_b32_e32 v3, 0xff0000, v3
	v_perm_b32 v0, v1, v0, s79
	v_or3_b32 v0, v0, v2, v3
	ds_write_b32 v22, v0 offset:16
	buffer_store_dwordx4 v[168:171], v89, s[16:19], s76 offen
	v_mov_b32_e32 v0, v228
	v_mov_b32_e32 v1, v229
	v_mov_b32_e32 v2, v230
	v_mov_b32_e32 v3, v231
	v_mov_b32_e32 v4, v244
	v_mov_b32_e32 v5, v245
	v_mov_b32_e32 v6, v246
	v_mov_b32_e32 v7, v247
	v_mov_b32_e32 v44, v210
	v_mov_b32_e32 v45, v211
	v_pk_add_f32 v[46:47], v[56:57], v[44:45] op_sel_hi:[1,0] neg_lo:[0,1] neg_hi:[0,1]
	s_nop 0
	v_pk_mul_f32 v[46:47], v[44:45], v[46:47] op_sel:[1,0]
	v_pk_add_f32 v[50:51], v[54:55], v[44:45] op_sel_hi:[1,0] neg_lo:[0,1] neg_hi:[0,1]
	v_mov_b32_e32 v34, v1
	v_mov_b32_e32 v35, v2
	v_mov_b32_e32 v42, v5
	v_mov_b32_e32 v43, v6
	v_pk_fma_f32 v[46:47], v[34:35], v[46:47], v[42:43]
	v_pk_mul_f32 v[44:45], v[44:45], v[50:51] op_sel:[1,0]
	v_mov_b32_e32 v1, v3
	v_mov_b32_e32 v5, v7
	v_and_b32_sdwa v6, v47, v216 dst_sel:DWORD dst_unused:UNUSED_PAD src0_sel:WORD_1 src1_sel:DWORD
	v_and_b32_sdwa v7, v46, v216 dst_sel:DWORD dst_unused:UNUSED_PAD src0_sel:WORD_1 src1_sel:DWORD
	v_pk_fma_f32 v[2:3], v[0:1], v[44:45], v[4:5]
	v_add3_u32 v23, v47, v6, s77
	v_add3_u32 v6, v46, v7, s77
	v_and_b32_e32 v44, 0xffff0000, v6
	v_and_b32_sdwa v6, v3, v216 dst_sel:DWORD dst_unused:UNUSED_PAD src0_sel:WORD_1 src1_sel:DWORD
	v_and_b32_sdwa v7, v2, v216 dst_sel:DWORD dst_unused:UNUSED_PAD src0_sel:WORD_1 src1_sel:DWORD
	v_add3_u32 v6, v3, v6, s77
	v_add3_u32 v45, v2, v7, s77
	v_and_b32_e32 v50, 0xffff0000, v6
	v_or_b32_sdwa v7, v50, v23 dst_sel:DWORD dst_unused:UNUSED_PAD src0_sel:DWORD src1_sel:WORD_1
	v_or_b32_sdwa v6, v45, v44 dst_sel:DWORD dst_unused:UNUSED_PAD src0_sel:WORD_1 src1_sel:DWORD
	ds_write_b64 v106, v[6:7]
	v_and_b32_e32 v6, 0xffff0000, v45
	v_sub_u32_e32 v2, v2, v6
	v_sub_u32_e32 v6, v46, v44
	v_and_b32_e32 v7, 0xffff0000, v23
	v_add_u32_e32 v6, 0x80, v6
	v_sub_u32_e32 v7, v47, v7
	v_sub_u32_e32 v3, v3, v50
	v_add_u32_e32 v2, 0x80, v2
	v_ashrrev_i32_e32 v6, 8, v6
	v_add_u32_e32 v7, 0x80, v7
	v_add_u32_e32 v3, 0x80, v3
	v_ashrrev_i32_e32 v2, 8, v2
	v_min_i32_e32 v6, 0x7f, v6
	v_ashrrev_i32_e32 v7, 8, v7
	v_ashrrev_i32_e32 v3, 8, v3
	v_min_i32_e32 v2, 0x7f, v2
	v_min_i32_sdwa v7, v7, s78 dst_sel:WORD_1 dst_unused:UNUSED_PAD src0_sel:DWORD src1_sel:DWORD
	v_min_i32_e32 v3, 0x7f, v3
	v_lshlrev_b32_e32 v6, 8, v6
	v_and_b32_e32 v6, 0xff00, v6
	v_and_b32_e32 v7, 0xff0000, v7
	v_perm_b32 v2, v3, v2, s79
	v_or3_b32 v2, v2, v6, v7
	ds_write_b32 v12, v2 offset:128
	buffer_store_dwordx4 v[172:175], v146, s[20:23], s33 offen
	v_mov_b32_e32 v2, v212
	v_mov_b32_e32 v3, v213
	v_pk_add_f32 v[6:7], v[40:41], v[2:3] op_sel_hi:[1,0] neg_lo:[0,1] neg_hi:[0,1]
	s_nop 0
	v_pk_mul_f32 v[6:7], v[2:3], v[6:7] op_sel:[1,0]
	v_pk_add_f32 v[38:39], v[38:39], v[2:3] op_sel_hi:[1,0] neg_lo:[0,1] neg_hi:[0,1]
	v_pk_fma_f32 v[6:7], v[34:35], v[6:7], v[42:43]
	v_pk_mul_f32 v[2:3], v[2:3], v[38:39] op_sel:[1,0]
	v_and_b32_sdwa v38, v6, v216 dst_sel:DWORD dst_unused:UNUSED_PAD src0_sel:WORD_1 src1_sel:DWORD
	v_pk_fma_f32 v[2:3], v[0:1], v[2:3], v[4:5]
	v_add3_u32 v38, v6, v38, s77
	v_and_b32_e32 v40, 0xffff0000, v38
	v_and_b32_sdwa v38, v3, v216 dst_sel:DWORD dst_unused:UNUSED_PAD src0_sel:WORD_1 src1_sel:DWORD
	v_and_b32_sdwa v23, v7, v216 dst_sel:DWORD dst_unused:UNUSED_PAD src0_sel:WORD_1 src1_sel:DWORD
	v_and_b32_sdwa v39, v2, v216 dst_sel:DWORD dst_unused:UNUSED_PAD src0_sel:WORD_1 src1_sel:DWORD
	v_add3_u32 v38, v3, v38, s77
	v_add3_u32 v23, v7, v23, s77
	v_add3_u32 v41, v2, v39, s77
	v_and_b32_e32 v44, 0xffff0000, v38
	v_or_b32_sdwa v39, v44, v23 dst_sel:DWORD dst_unused:UNUSED_PAD src0_sel:DWORD src1_sel:WORD_1
	v_or_b32_sdwa v38, v41, v40 dst_sel:DWORD dst_unused:UNUSED_PAD src0_sel:WORD_1 src1_sel:DWORD
	ds_write_b64 v102, v[38:39]
	v_and_b32_e32 v38, 0xffff0000, v41
	v_sub_u32_e32 v6, v6, v40
	v_and_b32_e32 v23, 0xffff0000, v23
	v_sub_u32_e32 v2, v2, v38
	v_add_u32_e32 v6, 0x80, v6
	v_sub_u32_e32 v7, v7, v23
	v_sub_u32_e32 v3, v3, v44
	v_add_u32_e32 v2, 0x80, v2
	v_ashrrev_i32_e32 v6, 8, v6
	v_add_u32_e32 v7, 0x80, v7
	v_add_u32_e32 v3, 0x80, v3
	v_ashrrev_i32_e32 v2, 8, v2
	v_min_i32_e32 v6, 0x7f, v6
	v_ashrrev_i32_e32 v7, 8, v7
	v_ashrrev_i32_e32 v3, 8, v3
	v_min_i32_e32 v2, 0x7f, v2
	v_min_i32_sdwa v7, v7, s78 dst_sel:WORD_1 dst_unused:UNUSED_PAD src0_sel:DWORD src1_sel:DWORD
	v_min_i32_e32 v3, 0x7f, v3
	v_lshlrev_b32_e32 v6, 8, v6
	v_and_b32_e32 v6, 0xff00, v6
	v_and_b32_e32 v7, 0xff0000, v7
	v_perm_b32 v2, v3, v2, s79
	v_or3_b32 v2, v2, v6, v7
;     ...
;             _Pragma("unroll") for (int m = 0; m < 4; ++m) {
;               const int rr = wr3 * 64 + m * 16 + fr3;
;               const float2 ms = *reinterpret_cast<const float2*>(mr + (ai * HALF + rr) * 2);
;               f32x4 y = acc[ai][bj][m][n];
;               const float o0 = (y[0] - ms.x) * ms.y * gm.x + bt.x, o1 = (y[1] - ms.x) * ms.y * gm.y + bt.y;
;               const float o2 = (y[2] - ms.x) * ms.y * gm.z + bt.z, o3 = (y[3] - ms.x) * ms.y * gm.w + bt.w;
;               const unsigned h0 = f2bf(o0), h1 = f2bf(o1), h2 = f2bf(o2), h3 = f2bf(o3);
;               u32x2 ob; ob[0] = h0 | (h1 << 16); ob[1] = h2 | (h3 << 16);
;               *reinterpret_cast<u32x2*>(smem + (rr >> 1) * PIECE + (rr & 1) * 512 + cc * 2) = ob;
;               const int l0 = min(((int)__float_as_uint(o0) - (int)(h0 << 16) + 128) >> 8, 127);
;               const int l1 = min(((int)__float_as_uint(o1) - (int)(h1 << 16) + 128) >> 8, 127);
;               const int l2 = min(((int)__float_as_uint(o2) - (int)(h2 << 16) + 128) >> 8, 127);
;               const int l3 = min(((int)__float_as_uint(o3) - (int)(h3 << 16) + 128) >> 8, 127);
;               *reinterpret_cast<unsigned*>(smem + LOBASE + (rr >> 2) * PIECE + (rr & 3) * 256 + cc) =
;                   (unsigned)(l0 & 255) | ((unsigned)(l1 & 255) << 8) | ((unsigned)(l2 & 255) << 16) | ((unsigned)l3 << 24);
;             }
	ds_write_b32 v14, v2 offset:128
	buffer_store_dwordx4 v[176:179], v90, s[20:23], s33 offen
	v_mov_b32_e32 v2, v214
	v_mov_b32_e32 v3, v215
	v_pk_add_f32 v[6:7], v[24:25], v[2:3] op_sel_hi:[1,0] neg_lo:[0,1] neg_hi:[0,1]
	s_nop 0
	v_pk_mul_f32 v[6:7], v[2:3], v[6:7] op_sel:[1,0]
	v_pk_add_f32 v[24:25], v[26:27], v[2:3] op_sel_hi:[1,0] neg_lo:[0,1] neg_hi:[0,1]
	v_pk_fma_f32 v[6:7], v[34:35], v[6:7], v[42:43]
	v_pk_mul_f32 v[2:3], v[2:3], v[24:25] op_sel:[1,0]
	v_and_b32_sdwa v24, v6, v216 dst_sel:DWORD dst_unused:UNUSED_PAD src0_sel:WORD_1 src1_sel:DWORD
	v_pk_fma_f32 v[2:3], v[0:1], v[2:3], v[4:5]
	v_add3_u32 v24, v6, v24, s77
	v_and_b32_e32 v26, 0xffff0000, v24
	v_and_b32_sdwa v24, v3, v216 dst_sel:DWORD dst_unused:UNUSED_PAD src0_sel:WORD_1 src1_sel:DWORD
	v_and_b32_sdwa v23, v7, v216 dst_sel:DWORD dst_unused:UNUSED_PAD src0_sel:WORD_1 src1_sel:DWORD
	v_and_b32_sdwa v25, v2, v216 dst_sel:DWORD dst_unused:UNUSED_PAD src0_sel:WORD_1 src1_sel:DWORD
	v_add3_u32 v24, v3, v24, s77
	v_add3_u32 v23, v7, v23, s77
	v_add3_u32 v27, v2, v25, s77
	v_and_b32_e32 v38, 0xffff0000, v24
	v_or_b32_sdwa v25, v38, v23 dst_sel:DWORD dst_unused:UNUSED_PAD src0_sel:DWORD src1_sel:WORD_1
	v_or_b32_sdwa v24, v27, v26 dst_sel:DWORD dst_unused:UNUSED_PAD src0_sel:WORD_1 src1_sel:DWORD
	ds_write_b64 v92, v[24:25]
	v_and_b32_e32 v24, 0xffff0000, v27
	v_sub_u32_e32 v6, v6, v26
	v_and_b32_e32 v23, 0xffff0000, v23
	v_sub_u32_e32 v2, v2, v24
	v_add_u32_e32 v6, 0x80, v6
	v_sub_u32_e32 v7, v7, v23
	v_sub_u32_e32 v3, v3, v38
	v_add_u32_e32 v2, 0x80, v2
	v_ashrrev_i32_e32 v6, 8, v6
	v_add_u32_e32 v7, 0x80, v7
	v_add_u32_e32 v3, 0x80, v3
	v_ashrrev_i32_e32 v2, 8, v2
	v_min_i32_e32 v6, 0x7f, v6
	v_ashrrev_i32_e32 v7, 8, v7
	v_ashrrev_i32_e32 v3, 8, v3
	v_min_i32_e32 v2, 0x7f, v2
	v_min_i32_sdwa v7, v7, s78 dst_sel:WORD_1 dst_unused:UNUSED_PAD src0_sel:DWORD src1_sel:DWORD
	v_min_i32_e32 v3, 0x7f, v3
	v_lshlrev_b32_e32 v6, 8, v6
	v_and_b32_e32 v6, 0xff00, v6
	v_and_b32_e32 v7, 0xff0000, v7
	v_perm_b32 v2, v3, v2, s79
	v_or3_b32 v2, v2, v6, v7
	ds_write_b32 v18, v2 offset:128
	buffer_store_dwordx4 v[180:183], v91, s[20:23], s33 offen
	v_mov_b32_e32 v2, v252
	v_mov_b32_e32 v3, v253
	v_pk_add_f32 v[6:7], v[28:29], v[2:3] op_sel_hi:[1,0] neg_lo:[0,1] neg_hi:[0,1]
	s_nop 0
	v_pk_mul_f32 v[6:7], v[2:3], v[6:7] op_sel:[1,0]
	v_pk_add_f32 v[24:25], v[30:31], v[2:3] op_sel_hi:[1,0] neg_lo:[0,1] neg_hi:[0,1]
	v_pk_fma_f32 v[6:7], v[34:35], v[6:7], v[42:43]
	v_pk_mul_f32 v[2:3], v[2:3], v[24:25] op_sel:[1,0]
	s_nop 0
	v_pk_fma_f32 v[0:1], v[0:1], v[2:3], v[4:5]
	v_and_b32_sdwa v2, v7, v216 dst_sel:DWORD dst_unused:UNUSED_PAD src0_sel:WORD_1 src1_sel:DWORD
	v_and_b32_sdwa v3, v6, v216 dst_sel:DWORD dst_unused:UNUSED_PAD src0_sel:WORD_1 src1_sel:DWORD
	v_add3_u32 v4, v7, v2, s77
	v_add3_u32 v2, v6, v3, s77
	v_and_b32_e32 v5, 0xffff0000, v2
	v_and_b32_sdwa v2, v1, v216 dst_sel:DWORD dst_unused:UNUSED_PAD src0_sel:WORD_1 src1_sel:DWORD
	v_and_b32_sdwa v3, v0, v216 dst_sel:DWORD dst_unused:UNUSED_PAD src0_sel:WORD_1 src1_sel:DWORD
	v_add3_u32 v2, v1, v2, s77
	v_add3_u32 v23, v0, v3, s77
	v_and_b32_e32 v24, 0xffff0000, v2
	v_or_b32_sdwa v3, v24, v4 dst_sel:DWORD dst_unused:UNUSED_PAD src0_sel:DWORD src1_sel:WORD_1
	v_or_b32_sdwa v2, v23, v5 dst_sel:DWORD dst_unused:UNUSED_PAD src0_sel:WORD_1 src1_sel:DWORD
	ds_write_b64 v93, v[2:3]
	v_and_b32_e32 v2, 0xffff0000, v23
	v_sub_u32_e32 v0, v0, v2
	v_sub_u32_e32 v2, v6, v5
	v_and_b32_e32 v3, 0xffff0000, v4
	v_add_u32_e32 v2, 0x80, v2
	v_sub_u32_e32 v3, v7, v3
	v_sub_u32_e32 v1, v1, v24
	v_add_u32_e32 v0, 0x80, v0
	v_ashrrev_i32_e32 v2, 8, v2
	v_add_u32_e32 v3, 0x80, v3
	v_add_u32_e32 v1, 0x80, v1
	v_ashrrev_i32_e32 v0, 8, v0
	v_min_i32_e32 v2, 0x7f, v2
	v_ashrrev_i32_e32 v3, 8, v3
	v_ashrrev_i32_e32 v1, 8, v1
	v_min_i32_e32 v0, 0x7f, v0
	v_min_i32_sdwa v3, v3, s78 dst_sel:WORD_1 dst_unused:UNUSED_PAD src0_sel:DWORD src1_sel:DWORD
	v_min_i32_e32 v1, 0x7f, v1
	v_lshlrev_b32_e32 v2, 8, v2
	v_and_b32_e32 v2, 0xff00, v2
	v_and_b32_e32 v3, 0xff0000, v3
	v_perm_b32 v0, v1, v0, s79
	v_or3_b32 v0, v0, v2, v3
	ds_write_b32 v22, v0 offset:128
	buffer_store_dwordx4 v[184:187], v96, s[20:23], s33 offen
	v_mov_b32_e32 v0, v232
	v_mov_b32_e32 v1, v233
	v_mov_b32_e32 v2, v234
	v_mov_b32_e32 v3, v235
	v_mov_b32_e32 v4, v248
	v_mov_b32_e32 v5, v249
	v_mov_b32_e32 v6, v250
	v_mov_b32_e32 v7, v251
	v_mov_b32_e32 v28, v210
	v_mov_b32_e32 v29, v211
	s_mov_b64 s[4:5], -1
	v_pk_add_f32 v[30:31], v[52:53], v[28:29] op_sel_hi:[1,0] neg_lo:[0,1] neg_hi:[0,1]
	s_nop 0
	v_pk_mul_f32 v[30:31], v[28:29], v[30:31] op_sel:[1,0]
	v_pk_add_f32 v[34:35], v[48:49], v[28:29] op_sel_hi:[1,0] neg_lo:[0,1] neg_hi:[0,1]
	v_mov_b32_e32 v24, v1
	v_mov_b32_e32 v25, v2
	v_mov_b32_e32 v26, v5
	v_mov_b32_e32 v27, v6
	v_pk_fma_f32 v[30:31], v[24:25], v[30:31], v[26:27]
	v_pk_mul_f32 v[28:29], v[28:29], v[34:35] op_sel:[1,0]
	v_mov_b32_e32 v1, v3
	v_mov_b32_e32 v5, v7
	v_and_b32_sdwa v6, v31, v216 dst_sel:DWORD dst_unused:UNUSED_PAD src0_sel:WORD_1 src1_sel:DWORD
	v_and_b32_sdwa v7, v30, v216 dst_sel:DWORD dst_unused:UNUSED_PAD src0_sel:WORD_1 src1_sel:DWORD
	v_pk_fma_f32 v[2:3], v[0:1], v[28:29], v[4:5]
	v_add3_u32 v23, v31, v6, s77
	v_add3_u32 v6, v30, v7, s77
	v_and_b32_e32 v28, 0xffff0000, v6
	v_and_b32_sdwa v6, v3, v216 dst_sel:DWORD dst_unused:UNUSED_PAD src0_sel:WORD_1 src1_sel:DWORD
	v_and_b32_sdwa v7, v2, v216 dst_sel:DWORD dst_unused:UNUSED_PAD src0_sel:WORD_1 src1_sel:DWORD
	v_add3_u32 v6, v3, v6, s77
	v_add3_u32 v29, v2, v7, s77
	v_and_b32_e32 v34, 0xffff0000, v6
	v_or_b32_sdwa v7, v34, v23 dst_sel:DWORD dst_unused:UNUSED_PAD src0_sel:DWORD src1_sel:WORD_1
; #define WAIT_L(n) asm volatile("s_waitcnt lgkmcnt(" #n ")" ::: "memory")
; #define BAR __builtin_amdgcn_s_barrier()
;     ...
;             _Pragma("unroll") for (int m = 0; m < 4; ++m) {
;               const int rr = wr3 * 64 + m * 16 + fr3;
;               const float2 ms = *reinterpret_cast<const float2*>(mr + (ai * HALF + rr) * 2);
;               f32x4 y = acc[ai][bj][m][n];
;               const float o0 = (y[0] - ms.x) * ms.y * gm.x + bt.x, o1 = (y[1] - ms.x) * ms.y * gm.y + bt.y;
;               const float o2 = (y[2] - ms.x) * ms.y * gm.z + bt.z, o3 = (y[3] - ms.x) * ms.y * gm.w + bt.w;
;               const unsigned h0 = f2bf(o0), h1 = f2bf(o1), h2 = f2bf(o2), h3 = f2bf(o3);
;               u32x2 ob; ob[0] = h0 | (h1 << 16); ob[1] = h2 | (h3 << 16);
;               *reinterpret_cast<u32x2*>(smem + (rr >> 1) * PIECE + (rr & 1) * 512 + cc * 2) = ob;
;               const int l0 = min(((int)__float_as_uint(o0) - (int)(h0 << 16) + 128) >> 8, 127);
;               const int l1 = min(((int)__float_as_uint(o1) - (int)(h1 << 16) + 128) >> 8, 127);
;               const int l2 = min(((int)__float_as_uint(o2) - (int)(h2 << 16) + 128) >> 8, 127);
;               const int l3 = min(((int)__float_as_uint(o3) - (int)(h3 << 16) + 128) >> 8, 127);
;               *reinterpret_cast<unsigned*>(smem + LOBASE + (rr >> 2) * PIECE + (rr & 3) * 256 + cc) =
;                   (unsigned)(l0 & 255) | ((unsigned)(l1 & 255) << 8) | ((unsigned)(l2 & 255) << 16) | ((unsigned)l3 << 24);
;             }
;           }
;           WAIT_L(0); BAR;
	v_or_b32_sdwa v6, v29, v28 dst_sel:DWORD dst_unused:UNUSED_PAD src0_sel:WORD_1 src1_sel:DWORD
	ds_write_b64 v94, v[6:7]
	v_and_b32_e32 v6, 0xffff0000, v29
	v_sub_u32_e32 v2, v2, v6
	v_sub_u32_e32 v6, v30, v28
	v_and_b32_e32 v7, 0xffff0000, v23
	v_add_u32_e32 v6, 0x80, v6
	v_sub_u32_e32 v7, v31, v7
	v_sub_u32_e32 v3, v3, v34
	v_add_u32_e32 v2, 0x80, v2
	v_ashrrev_i32_e32 v6, 8, v6
	v_add_u32_e32 v7, 0x80, v7
	v_add_u32_e32 v3, 0x80, v3
	v_ashrrev_i32_e32 v2, 8, v2
	v_min_i32_e32 v6, 0x7f, v6
	v_ashrrev_i32_e32 v7, 8, v7
	v_ashrrev_i32_e32 v3, 8, v3
	v_min_i32_e32 v2, 0x7f, v2
	v_min_i32_sdwa v7, v7, s78 dst_sel:WORD_1 dst_unused:UNUSED_PAD src0_sel:DWORD src1_sel:DWORD
	v_min_i32_e32 v3, 0x7f, v3
	v_lshlrev_b32_e32 v6, 8, v6
	v_and_b32_e32 v6, 0xff00, v6
	v_and_b32_e32 v7, 0xff0000, v7
	v_perm_b32 v2, v3, v2, s79
	v_or3_b32 v2, v2, v6, v7
	ds_write_b32 v12, v2 offset:144
	v_mov_b32_e32 v2, v212
	v_mov_b32_e32 v3, v213
	v_pk_add_f32 v[6:7], v[36:37], v[2:3] op_sel_hi:[1,0] neg_lo:[0,1] neg_hi:[0,1]
	s_nop 0
	v_pk_mul_f32 v[6:7], v[2:3], v[6:7] op_sel:[1,0]
	v_pk_add_f32 v[12:13], v[32:33], v[2:3] op_sel_hi:[1,0] neg_lo:[0,1] neg_hi:[0,1]
	v_pk_fma_f32 v[6:7], v[24:25], v[6:7], v[26:27]
	v_pk_mul_f32 v[2:3], v[2:3], v[12:13] op_sel:[1,0]
	v_and_b32_sdwa v12, v7, v216 dst_sel:DWORD dst_unused:UNUSED_PAD src0_sel:WORD_1 src1_sel:DWORD
	v_and_b32_sdwa v13, v6, v216 dst_sel:DWORD dst_unused:UNUSED_PAD src0_sel:WORD_1 src1_sel:DWORD
	v_pk_fma_f32 v[2:3], v[0:1], v[2:3], v[4:5]
	v_add3_u32 v23, v7, v12, s77
	v_add3_u32 v12, v6, v13, s77
	v_and_b32_e32 v28, 0xffff0000, v12
	v_and_b32_sdwa v12, v3, v216 dst_sel:DWORD dst_unused:UNUSED_PAD src0_sel:WORD_1 src1_sel:DWORD
	v_and_b32_sdwa v13, v2, v216 dst_sel:DWORD dst_unused:UNUSED_PAD src0_sel:WORD_1 src1_sel:DWORD
	v_add3_u32 v12, v3, v12, s77
	v_add3_u32 v29, v2, v13, s77
	v_and_b32_e32 v30, 0xffff0000, v12
	v_or_b32_sdwa v13, v30, v23 dst_sel:DWORD dst_unused:UNUSED_PAD src0_sel:DWORD src1_sel:WORD_1
	v_or_b32_sdwa v12, v29, v28 dst_sel:DWORD dst_unused:UNUSED_PAD src0_sel:WORD_1 src1_sel:DWORD
	ds_write_b64 v95, v[12:13]
	v_and_b32_e32 v12, 0xffff0000, v29
	v_sub_u32_e32 v2, v2, v12
	v_sub_u32_e32 v6, v6, v28
	v_and_b32_e32 v12, 0xffff0000, v23
	v_add_u32_e32 v6, 0x80, v6
	v_sub_u32_e32 v7, v7, v12
	v_sub_u32_e32 v3, v3, v30
	v_add_u32_e32 v2, 0x80, v2
	v_ashrrev_i32_e32 v6, 8, v6
	v_add_u32_e32 v7, 0x80, v7
	v_add_u32_e32 v3, 0x80, v3
	v_ashrrev_i32_e32 v2, 8, v2
	v_min_i32_e32 v6, 0x7f, v6
	v_ashrrev_i32_e32 v7, 8, v7
	v_ashrrev_i32_e32 v3, 8, v3
	v_min_i32_e32 v2, 0x7f, v2
	v_min_i32_sdwa v7, v7, s78 dst_sel:WORD_1 dst_unused:UNUSED_PAD src0_sel:DWORD src1_sel:DWORD
	v_min_i32_e32 v3, 0x7f, v3
	v_lshlrev_b32_e32 v6, 8, v6
	v_and_b32_e32 v6, 0xff00, v6
	v_and_b32_e32 v7, 0xff0000, v7
	v_perm_b32 v2, v3, v2, s79
	v_or3_b32 v2, v2, v6, v7
	ds_write_b32 v14, v2 offset:144
	v_mov_b32_e32 v2, v214
	v_mov_b32_e32 v3, v215
	v_pk_add_f32 v[6:7], v[20:21], v[2:3] op_sel_hi:[1,0] neg_lo:[0,1] neg_hi:[0,1]
	s_nop 0
	v_pk_mul_f32 v[6:7], v[2:3], v[6:7] op_sel:[1,0]
	v_pk_add_f32 v[12:13], v[16:17], v[2:3] op_sel_hi:[1,0] neg_lo:[0,1] neg_hi:[0,1]
	v_pk_fma_f32 v[6:7], v[24:25], v[6:7], v[26:27]
	v_pk_mul_f32 v[2:3], v[2:3], v[12:13] op_sel:[1,0]
	v_and_b32_sdwa v12, v7, v216 dst_sel:DWORD dst_unused:UNUSED_PAD src0_sel:WORD_1 src1_sel:DWORD
	v_and_b32_sdwa v13, v6, v216 dst_sel:DWORD dst_unused:UNUSED_PAD src0_sel:WORD_1 src1_sel:DWORD
	v_pk_fma_f32 v[2:3], v[0:1], v[2:3], v[4:5]
	v_add3_u32 v14, v7, v12, s77
	v_add3_u32 v12, v6, v13, s77
	v_and_b32_e32 v15, 0xffff0000, v12
	v_and_b32_sdwa v12, v3, v216 dst_sel:DWORD dst_unused:UNUSED_PAD src0_sel:WORD_1 src1_sel:DWORD
	v_and_b32_sdwa v13, v2, v216 dst_sel:DWORD dst_unused:UNUSED_PAD src0_sel:WORD_1 src1_sel:DWORD
	v_add3_u32 v12, v3, v12, s77
	v_add3_u32 v16, v2, v13, s77
	v_and_b32_e32 v17, 0xffff0000, v12
	v_or_b32_sdwa v13, v17, v14 dst_sel:DWORD dst_unused:UNUSED_PAD src0_sel:DWORD src1_sel:WORD_1
	v_or_b32_sdwa v12, v16, v15 dst_sel:DWORD dst_unused:UNUSED_PAD src0_sel:WORD_1 src1_sel:DWORD
	ds_write_b64 v80, v[12:13]
	v_and_b32_e32 v12, 0xffff0000, v16
	v_sub_u32_e32 v2, v2, v12
	v_sub_u32_e32 v6, v6, v15
	v_and_b32_e32 v12, 0xffff0000, v14
	v_add_u32_e32 v6, 0x80, v6
	v_sub_u32_e32 v7, v7, v12
	v_sub_u32_e32 v3, v3, v17
	v_add_u32_e32 v2, 0x80, v2
	v_ashrrev_i32_e32 v6, 8, v6
	v_add_u32_e32 v7, 0x80, v7
	v_add_u32_e32 v3, 0x80, v3
	v_ashrrev_i32_e32 v2, 8, v2
	v_min_i32_e32 v6, 0x7f, v6
	v_ashrrev_i32_e32 v7, 8, v7
	v_ashrrev_i32_e32 v3, 8, v3
	v_min_i32_e32 v2, 0x7f, v2
	v_min_i32_sdwa v7, v7, s78 dst_sel:WORD_1 dst_unused:UNUSED_PAD src0_sel:DWORD src1_sel:DWORD
	v_min_i32_e32 v3, 0x7f, v3
	v_lshlrev_b32_e32 v6, 8, v6
	v_and_b32_e32 v6, 0xff00, v6
	v_and_b32_e32 v7, 0xff0000, v7
	v_perm_b32 v2, v3, v2, s79
	v_or3_b32 v2, v2, v6, v7
	ds_write_b32 v18, v2 offset:144
	v_mov_b32_e32 v2, v252
	v_mov_b32_e32 v3, v253
	v_pk_add_f32 v[6:7], v[8:9], v[2:3] op_sel_hi:[1,0] neg_lo:[0,1] neg_hi:[0,1]
	s_nop 0
	v_pk_mul_f32 v[6:7], v[2:3], v[6:7] op_sel:[1,0]
	v_pk_add_f32 v[8:9], v[10:11], v[2:3] op_sel_hi:[1,0] neg_lo:[0,1] neg_hi:[0,1]
	v_pk_fma_f32 v[6:7], v[24:25], v[6:7], v[26:27]
	v_pk_mul_f32 v[2:3], v[2:3], v[8:9] op_sel:[1,0]
	s_nop 0
	v_pk_fma_f32 v[0:1], v[0:1], v[2:3], v[4:5]
	v_and_b32_sdwa v2, v7, v216 dst_sel:DWORD dst_unused:UNUSED_PAD src0_sel:WORD_1 src1_sel:DWORD
	v_and_b32_sdwa v3, v6, v216 dst_sel:DWORD dst_unused:UNUSED_PAD src0_sel:WORD_1 src1_sel:DWORD
	v_add3_u32 v4, v7, v2, s77
	v_add3_u32 v2, v6, v3, s77
	v_and_b32_e32 v5, 0xffff0000, v2
	v_and_b32_sdwa v2, v1, v216 dst_sel:DWORD dst_unused:UNUSED_PAD src0_sel:WORD_1 src1_sel:DWORD
	v_and_b32_sdwa v3, v0, v216 dst_sel:DWORD dst_unused:UNUSED_PAD src0_sel:WORD_1 src1_sel:DWORD
	v_add3_u32 v2, v1, v2, s77
	v_add3_u32 v8, v0, v3, s77
	v_and_b32_e32 v9, 0xffff0000, v2
	v_or_b32_sdwa v3, v9, v4 dst_sel:DWORD dst_unused:UNUSED_PAD src0_sel:DWORD src1_sel:WORD_1
	v_or_b32_sdwa v2, v8, v5 dst_sel:DWORD dst_unused:UNUSED_PAD src0_sel:WORD_1 src1_sel:DWORD
	ds_write_b64 v73, v[2:3]
	v_and_b32_e32 v2, 0xffff0000, v8
	v_sub_u32_e32 v0, v0, v2
	v_sub_u32_e32 v2, v6, v5
	v_and_b32_e32 v3, 0xffff0000, v4
	v_add_u32_e32 v2, 0x80, v2
	v_sub_u32_e32 v3, v7, v3
	v_sub_u32_e32 v1, v1, v9
	v_add_u32_e32 v0, 0x80, v0
	v_ashrrev_i32_e32 v2, 8, v2
	v_add_u32_e32 v3, 0x80, v3
	v_add_u32_e32 v1, 0x80, v1
	v_ashrrev_i32_e32 v0, 8, v0
	v_min_i32_e32 v2, 0x7f, v2
	v_ashrrev_i32_e32 v3, 8, v3
	v_ashrrev_i32_e32 v1, 8, v1
	v_min_i32_e32 v0, 0x7f, v0
	v_min_i32_sdwa v3, v3, s78 dst_sel:WORD_1 dst_unused:UNUSED_PAD src0_sel:DWORD src1_sel:DWORD
	v_min_i32_e32 v1, 0x7f, v1
	v_lshlrev_b32_e32 v2, 8, v2
	v_and_b32_e32 v2, 0xff00, v2
	v_and_b32_e32 v3, 0xff0000, v3
	v_perm_b32 v0, v1, v0, s79
	v_or3_b32 v0, v0, v2, v3
	ds_write_b32 v22, v0 offset:144
	s_waitcnt lgkmcnt(0)
	s_barrier
; #define STAGE(P, RS, SOFF, OFF, kt) do { const int _so = (SOFF) + (kt) * (BK * 2); \
;     _Pragma("unroll") for (int _i = 0; _i < 2; ++_i) { \
;       __builtin_amdgcn_raw_ptr_buffer_load_lds(RS, (__attribute__((address_space(3))) void*)((P) + wave * 1024 + _i * 8192), 16, OFF[_i], _so, 0, 0); } } while (0)
; #define WAIT_L(n) asm volatile("s_waitcnt lgkmcnt(" #n ")" ::: "memory")
; #define BAR __builtin_amdgcn_s_barrier()
;     ...
;   auto issue_prologue = [&](int sA0, int sA1, int sB0, int sB1) {
;     const int tid = opaque_tid(wave);
;     int offA[2], offB[2];
;     _Pragma("unroll") for (int i = 0; i < 2; ++i) {
;       int r, c; stage_rc(tid * 16 + i * 8192, r, c);
;       offA[i] = (r * lda + c) * 2; offB[i] = (r * ldb + c) * 2;
;     }
;     STAGE(SB(0, 0), rsB, sB0, offB, 0); STAGE(SA(0, 0), rsA, sA0, offA, 0);
;     STAGE(SB(0, 1), rsB, sB1, offB, 0); STAGE(SA(0, 1), rsA, sA1, offA, 0);
;     STAGE(SB(1, 0), rsB, sB0, offB, 1); STAGE(SA(1, 0), rsA, sA0, offA, 1); STAGE(SB(1, 1), rsB, sB1, offB, 1);
;   };
;     ...
;           WAIT_L(0); BAR;
;           const int hso = ((brow + ai * HALF + 16 * wave) * DM + pn * BM) * 2;
;           const int lso = (brow + ai * HALF + 16 * wave) * DM + pn * BM;
;           _Pragma("unroll") for (int i = 0; i < 8; ++i) {
;             const u32x4 v = *reinterpret_cast<const u32x4*>(smem + (wave * 8 + i) * PIECE + lane3 * 16);
;             __builtin_amdgcn_raw_buffer_store_b128(v, rsXB, hvo + i * (2 * DM * 2), hso, 0);
;           }
;           _Pragma("unroll") for (int i = 0; i < 4; ++i) {
;             const u32x4 v = *reinterpret_cast<const u32x4*>(smem + LOBASE + (wave * 4 + i) * PIECE + lane3 * 16);
;             __builtin_amdgcn_raw_buffer_store_b128(v, rsLO, lvo + i * (4 * DM), lso, 0);
;           }
	ds_read_b128 v[128:131], v72
	ds_read_b128 v[132:135], v72 offset:1040
	ds_read_b128 v[136:139], v72 offset:2080
	ds_read_b128 v[140:143], v72 offset:3120
	ds_read_b128 v[152:155], v72 offset:4160
	ds_read_b128 v[156:159], v72 offset:5200
	ds_read_b128 v[160:163], v72 offset:6240
	ds_read_b128 v[164:167], v72 offset:7280
	ds_read_b128 v[168:171], v147
	ds_read_b128 v[172:175], v147 offset:1040
	ds_read_b128 v[176:179], v147 offset:2080
	ds_read_b128 v[180:183], v147 offset:3120
	s_waitcnt lgkmcnt(0)
	s_barrier
	s_mov_b32 s98, s0
	s_cbranch_vccnz .Lmy_s1n_643
	v_mbcnt_lo_u32_b32 v0, -1, 0
	v_mbcnt_hi_u32_b32 v0, -1, v0
	s_mov_b32 m0, s85
	v_lshl_add_u32 v0, v0, 4, s38
	v_ashrrev_i32_e32 v1, 31, v0
	v_lshrrev_b32_e32 v1, 22, v1
	v_add_u32_e32 v1, v0, v1
	v_ashrrev_i32_e32 v1, 10, v1
	v_mul_i32_i24_e32 v2, 0x400, v1
	v_sub_u32_e32 v2, v0, v2
	v_lshrrev_b32_e32 v3, 4, v2
	v_bitop3_b32 v2, v3, v2, 32 bitop3:0x6c
	v_ashrrev_i32_e32 v4, 31, v2
	v_lshrrev_b32_e32 v4, 26, v4
	v_add_u32_e32 v4, v2, v4
	v_lshrrev_b32_e32 v5, 6, v4
	v_and_b32_e32 v4, 0xc0, v4
	v_lshlrev_b32_e32 v3, 3, v1
	v_lshlrev_b32_e32 v1, 5, v1
	v_sub_u32_e32 v2, v2, v4
	v_and_b32_e32 v3, 0xffff0, v3
	v_and_b32_e32 v1, 32, v1
	v_ashrrev_i16_sdwa v2, v216, sext(v2) dst_sel:DWORD dst_unused:UNUSED_PAD src0_sel:DWORD src1_sel:BYTE_0
	v_add_u32_sdwa v1, v1, sext(v2) dst_sel:DWORD dst_unused:UNUSED_PAD src0_sel:DWORD src1_sel:WORD_0
	v_add_lshl_u32 v2, v5, v3, 12
	v_add_u32_e32 v0, 0x2000, v0
	v_lshl_add_u32 v1, v1, 1, v2
	v_ashrrev_i32_e32 v2, 31, v0
	v_lshrrev_b32_e32 v2, 22, v2
	v_add_u32_e32 v2, v0, v2
	v_ashrrev_i32_e32 v2, 10, v2
	v_mul_i32_i24_e32 v3, 0x400, v2
	v_sub_u32_e32 v0, v0, v3
	v_lshrrev_b32_e32 v3, 4, v0
	v_bitop3_b32 v0, v3, v0, 32 bitop3:0x6c
	v_ashrrev_i32_e32 v4, 31, v0
	v_lshrrev_b32_e32 v4, 26, v4
	v_add_u32_e32 v4, v0, v4
	v_lshrrev_b32_e32 v5, 6, v4
	v_and_b32_e32 v4, 0xffc0, v4
	v_sub_u32_e32 v0, v0, v4
	v_lshrrev_b16_e32 v4, 7, v0
	v_and_b32_e32 v4, 1, v4
	v_lshlrev_b32_e32 v3, 3, v2
	v_lshlrev_b32_e32 v2, 5, v2
	v_add_u16_e32 v0, v0, v4
	v_and_b32_e32 v3, 0xffff0, v3
	v_and_b32_e32 v2, 32, v2
	v_ashrrev_i16_sdwa v0, v216, sext(v0) dst_sel:DWORD dst_unused:UNUSED_PAD src0_sel:DWORD src1_sel:BYTE_0
	v_add_u32_sdwa v0, v2, sext(v0) dst_sel:DWORD dst_unused:UNUSED_PAD src0_sel:DWORD src1_sel:WORD_0
	v_add_lshl_u32 v2, v5, v3, 12
	s_mov_b32 s14, s10
	s_mov_b32 s15, s11
	v_lshl_add_u32 v0, v0, 1, v2
	buffer_load_dwordx4 v1, s[12:15], s83 offen lds
	s_mov_b32 m0, s75
	s_or_b32 s0, s83, 0x80
	buffer_load_dwordx4 v0, s[12:15], s83 offen lds
	s_mov_b32 m0, s38
	s_mov_b64 s[4:5], 0
	buffer_load_dwordx4 v1, s[8:11], s82 offen lds
	s_mov_b32 m0, s95
	s_nop 0
	buffer_load_dwordx4 v0, s[8:11], s82 offen lds
	s_mov_b32 m0, s86
	s_nop 0
	buffer_load_dwordx4 v1, s[12:15], s84 offen lds
	s_mov_b32 m0, s28
	s_nop 0
	buffer_load_dwordx4 v0, s[12:15], s84 offen lds
	s_mov_b32 m0, s87
	s_nop 0
	buffer_load_dwordx4 v1, s[8:11], s81 offen lds
	s_mov_b32 m0, s97
	s_nop 0
	buffer_load_dwordx4 v0, s[8:11], s81 offen lds
	s_mov_b32 m0, s92
	s_nop 0
	buffer_load_dwordx4 v1, s[12:15], s0 offen lds
	s_mov_b32 m0, s29
	s_nop 0
	buffer_load_dwordx4 v0, s[12:15], s0 offen lds
	s_or_b32 s0, s82, 0x80
	s_mov_b32 m0, s93
	s_nop 0
	buffer_load_dwordx4 v1, s[8:11], s0 offen lds
	s_mov_b32 m0, s56
	s_nop 0
	buffer_load_dwordx4 v0, s[8:11], s0 offen lds
	s_add_i32 s0, s84, 0x80
	s_mov_b32 m0, s94
	s_nop 0
	buffer_load_dwordx4 v1, s[12:15], s0 offen lds
	s_mov_b32 m0, s57
	s_nop 0
	buffer_load_dwordx4 v0, s[12:15], s0 offen lds
	buffer_store_dwordx4 v[128:131], v148, s[16:19], s98 offen
	buffer_store_dwordx4 v[132:135], v74, s[16:19], s98 offen
	buffer_store_dwordx4 v[136:139], v75, s[16:19], s98 offen
	buffer_store_dwordx4 v[140:143], v81, s[16:19], s98 offen
	buffer_store_dwordx4 v[152:155], v84, s[16:19], s98 offen
	buffer_store_dwordx4 v[156:159], v85, s[16:19], s98 offen
	buffer_store_dwordx4 v[160:163], v88, s[16:19], s98 offen
	buffer_store_dwordx4 v[164:167], v89, s[16:19], s98 offen
	buffer_store_dwordx4 v[168:171], v146, s[20:23], s30 offen
	buffer_store_dwordx4 v[172:175], v90, s[20:23], s30 offen
	buffer_store_dwordx4 v[176:179], v91, s[20:23], s30 offen
	buffer_store_dwordx4 v[180:183], v96, s[20:23], s30 offen
	s_branch .LBB0_649
